# hoist LDS reads (pool-renamed, counted lgkmcnt) in GDN fwd-subst and attention QK/PV blocks
# speedup vs baseline: 1.0134x; 1.0134x over previous
; #define LAS __attribute__((address_space(3)))
; DI f32x4 mfma16(bf16x8 a, bf16x8 b, f32x4 c) { return __builtin_amdgcn_mfma_f32_16x16x32_bf16(a, b, c, 0, 0, 0); }
; DI void nsa_attn_phase(const int tid0, LAS unsigned char* lds, const P& p, int G, int c) {
;     ...
;                 for (int h = 0; h < 2; ++h) {
;                     const int n = na + h; const bool nvalid = (n <= i);
;                     const bool edge = (n == i) || (br == 1 && n == i - 4);
;                     LAS bf16_t* Kt = Tc + h * 9216;
; #pragma unroll
;                     for (int qt = 0; qt < 2; ++qt) {
;                         const bool bsel = nvalid && ((br == 1) || ((sm[qt] >> n) & 1u));
;                         act[h][qt] = nvalid && ((br == 1) || (__ballot(bsel) != 0ull));
;                         pf[h][0][qt] = (bf16x8){0, 0, 0, 0, 0, 0, 0, 0}; pf[h][1][qt] = pf[h][0][qt];
;                         if (act[h][qt]) {
;                             const float sb = bsel ? slope2 * (float)(n * 64 + fq * 4 - tq[qt]) : -1e9f;
;                             f32x4 S[4];
; #pragma unroll
;                             for (int kt = 0; kt < 4; ++kt) { S[kt] = (f32x4){sb + sc16[kt * 4], sb + sc16[kt * 4 + 1], sb + sc16[kt * 4 + 2], sb + sc16[kt * 4 + 3]};
; #pragma unroll
;                                 for (int ks = 0; ks < 2; ++ks) { const bf16x8 kf = *(const LAS bf16x8*)(Kt + (kt * 16 + fr) * 72 + ks * 32 + fq * 8); S[kt] = mfma16(kf, Qf[qt][ks], S[kt]); } }
;                             float ls = 0.f;
;                             if (edge) {
; #pragma unroll
;                                 for (int kt = 0; kt < 4; ++kt)
; #pragma unroll
;                                     for (int j = 0; j < 4; ++j) { const int pos = n * 64 + kt * 16 + fq * 4 + j; const bool valid = (pos <= tq[qt]) && (br == 0 || pos > tq[qt] - 256);
;                                         const float pv = valid ? __builtin_amdgcn_exp2f(S[kt][j]) : 0.f; S[kt][j] = pv; ls += pv; }
;                             } else {
; #pragma unroll
;                                 for (int kt = 0; kt < 4; ++kt)
; #pragma unroll
;                                     for (int j = 0; j < 4; ++j) { const float pv = __builtin_amdgcn_exp2f(S[kt][j]); S[kt][j] = pv; ls += pv; }
;                             }
;                             lrun[qt] += ls;
.LBB0_238:
	s_bitcmp0_b32 s0, 0
	s_cselect_b64 s[8:9], -1, 0
	s_and_b64 s[0:1], s[8:9], exec
	s_cselect_b32 s0, s94, 0
	s_add_i32 s14, s58, -3
	s_add_i32 s15, s41, s58
	s_cmp_le_i32 s14, s44
	s_cselect_b64 s[12:13], -1, 0
	s_cmp_lg_u32 s15, 34
	v_add_u32_e32 v139, s0, v187
	s_cselect_b64 s[0:1], -1, 0
	s_lshl_b32 s16, 1, s14
	s_cmp_gt_i32 s14, s44
	v_add_u32_e32 v138, s19, v190
	s_mov_b64 s[10:11], 0
	s_cbranch_scc1 .LBB0_246
	v_and_b32_e32 v0, s16, v150
	v_cmp_ne_u32_e32 vcc, 0, v0
	s_cbranch_vccz .LBB0_253
	v_add_u32_e32 v0, s19, v97
	v_add_u32_e32 v0, 0xfffff840, v0
	v_cvt_f32_i32_e32 v0, v0
	v_add_u32_e32 v118, v139, v179
	ds_read_b128 v[162:165], v118
	ds_read_b128 v[166:169], v118 offset:64
	ds_read_b128 v[206:209], v118 offset:2304
	ds_read_b128 v[214:217], v118 offset:2368
	ds_read_b128 v[218:221], v118 offset:4608
	ds_read_b128 v[222:225], v118 offset:4672
	ds_read_b128 v[226:229], v118 offset:6912
	ds_read_b128 v[238:241], v118 offset:6976
	s_mov_b64 s[4:5], -1
	v_mul_f32_e32 v0, v186, v0
	v_cndmask_b32_e32 v114, v236, v0, vcc
	v_pk_add_f32 v[6:7], v[194:195], v[114:115] op_sel_hi:[1,0]
	v_pk_add_f32 v[4:5], v[192:193], v[114:115] op_sel_hi:[1,0]
	v_pk_add_f32 v[10:11], v[196:197], v[114:115] op_sel_hi:[1,0]
	v_pk_add_f32 v[8:9], v[188:189], v[114:115] op_sel_hi:[1,0]
	v_pk_add_f32 v[14:15], v[200:201], v[114:115] op_sel_hi:[1,0]
	v_pk_add_f32 v[12:13], v[198:199], v[114:115] op_sel_hi:[1,0]
	v_pk_add_f32 v[116:117], v[204:205], v[114:115] op_sel_hi:[1,0]
	s_waitcnt lgkmcnt(7)
	v_mfma_f32_16x16x32_bf16 v[0:3], v[162:165], v[16:19], v[4:7]
	v_pk_add_f32 v[114:115], v[202:203], v[114:115] op_sel_hi:[1,0]
	s_andn2_b64 vcc, exec, s[0:1]
	s_waitcnt lgkmcnt(6)
	v_mfma_f32_16x16x32_bf16 v[0:3], v[166:169], v[20:23], v[0:3]
	s_nop 7
	v_exp_f32_e32 v0, v0
	s_waitcnt lgkmcnt(5)
	v_mfma_f32_16x16x32_bf16 v[4:7], v[206:209], v[16:19], v[8:11]
	v_exp_f32_e32 v1, v1
	v_exp_f32_e32 v2, v2
	s_waitcnt lgkmcnt(4)
	v_mfma_f32_16x16x32_bf16 v[4:7], v[214:217], v[20:23], v[4:7]
	v_exp_f32_e32 v3, v3
	s_nop 6
	v_exp_f32_e32 v4, v4
	s_waitcnt lgkmcnt(3)
	v_mfma_f32_16x16x32_bf16 v[8:11], v[218:221], v[16:19], v[12:15]
	v_exp_f32_e32 v5, v5
	v_exp_f32_e32 v6, v6
	s_waitcnt lgkmcnt(2)
	v_mfma_f32_16x16x32_bf16 v[8:11], v[222:225], v[20:23], v[8:11]
	v_exp_f32_e32 v7, v7
	s_nop 6
	v_exp_f32_e32 v8, v8
	s_waitcnt lgkmcnt(1)
	v_mfma_f32_16x16x32_bf16 v[12:15], v[226:229], v[16:19], v[114:117]
	v_exp_f32_e32 v9, v9
	v_exp_f32_e32 v10, v10
	s_waitcnt lgkmcnt(0)
	v_mfma_f32_16x16x32_bf16 v[12:15], v[238:241], v[20:23], v[12:15]
	v_exp_f32_e32 v11, v11
	s_nop 6
	v_exp_f32_e32 v12, v12
	v_exp_f32_e32 v13, v13
	v_exp_f32_e32 v14, v14
	v_exp_f32_e32 v15, v15
	v_mov_b32_e32 v114, v238
	s_cbranch_vccnz .LBB0_242
	v_add_f32_e32 v114, 0, v0
	v_add_f32_e32 v114, v1, v114
	v_add_f32_e32 v114, v2, v114
	v_add_f32_e32 v114, v3, v114
	v_add_f32_e32 v114, v114, v4
	v_add_f32_e32 v114, v5, v114
	v_add_f32_e32 v114, v6, v114
	v_add_f32_e32 v114, v7, v114
	v_add_f32_e32 v114, v114, v8
	v_add_f32_e32 v114, v9, v114
	v_add_f32_e32 v114, v10, v114
	v_add_f32_e32 v114, v11, v114
	v_add_f32_e32 v114, v114, v12
	v_add_f32_e32 v114, v13, v114
	v_add_f32_e32 v114, v14, v114
	v_add_f32_e32 v114, v15, v114
	s_mov_b64 s[4:5], 0

; #define LAS __attribute__((address_space(3)))
; DI f32x4 mfma16(bf16x8 a, bf16x8 b, f32x4 c) { return __builtin_amdgcn_mfma_f32_16x16x32_bf16(a, b, c, 0, 0, 0); }
; DI void nsa_attn_phase(const int tid0, LAS unsigned char* lds, const P& p, int G, int c) {
;     ...
;                 for (int h = 0; h < 2; ++h) {
;                     const int n = na + h; const bool nvalid = (n <= i);
;                     const bool edge = (n == i) || (br == 1 && n == i - 4);
;                     LAS bf16_t* Kt = Tc + h * 9216;
; #pragma unroll
;                     for (int qt = 0; qt < 2; ++qt) {
;                         const bool bsel = nvalid && ((br == 1) || ((sm[qt] >> n) & 1u));
;                         act[h][qt] = nvalid && ((br == 1) || (__ballot(bsel) != 0ull));
;                         pf[h][0][qt] = (bf16x8){0, 0, 0, 0, 0, 0, 0, 0}; pf[h][1][qt] = pf[h][0][qt];
;                         if (act[h][qt]) {
;                             const float sb = bsel ? slope2 * (float)(n * 64 + fq * 4 - tq[qt]) : -1e9f;
;                             f32x4 S[4];
; #pragma unroll
;                             for (int kt = 0; kt < 4; ++kt) { S[kt] = (f32x4){sb + sc16[kt * 4], sb + sc16[kt * 4 + 1], sb + sc16[kt * 4 + 2], sb + sc16[kt * 4 + 3]};
; #pragma unroll
;                                 for (int ks = 0; ks < 2; ++ks) { const bf16x8 kf = *(const LAS bf16x8*)(Kt + (kt * 16 + fr) * 72 + ks * 32 + fq * 8); S[kt] = mfma16(kf, Qf[qt][ks], S[kt]); } }
;                             float ls = 0.f;
;                             if (edge) {
; #pragma unroll
;                                 for (int kt = 0; kt < 4; ++kt)
; #pragma unroll
;                                     for (int j = 0; j < 4; ++j) { const int pos = n * 64 + kt * 16 + fq * 4 + j; const bool valid = (pos <= tq[qt]) && (br == 0 || pos > tq[qt] - 256);
;                                         const float pv = valid ? __builtin_amdgcn_exp2f(S[kt][j]) : 0.f; S[kt][j] = pv; ls += pv; }
;                             } else {
; #pragma unroll
;                                 for (int kt = 0; kt < 4; ++kt)
; #pragma unroll
;                                     for (int j = 0; j < 4; ++j) { const float pv = __builtin_amdgcn_exp2f(S[kt][j]); S[kt][j] = pv; ls += pv; }
;                             }
;                             lrun[qt] += ls;
.LBB0_247:
	v_and_b32_e32 v0, s16, v151
	v_cmp_ne_u32_e32 vcc, 0, v0
	s_cbranch_vccz .LBB0_254
	v_add_u32_e32 v0, s19, v97
	v_add_u32_e32 v0, 0xfffff830, v0
	v_cvt_f32_i32_e32 v0, v0
	v_add_u32_e32 v126, v139, v179
	ds_read_b128 v[162:165], v126
	ds_read_b128 v[166:169], v126 offset:64
	ds_read_b128 v[206:209], v126 offset:2304
	ds_read_b128 v[214:217], v126 offset:2368
	ds_read_b128 v[218:221], v126 offset:4608
	ds_read_b128 v[222:225], v126 offset:4672
	ds_read_b128 v[226:229], v126 offset:6912
	ds_read_b128 v[238:241], v126 offset:6976
	s_mov_b64 s[10:11], -1
	v_mul_f32_e32 v0, v186, v0
	v_cndmask_b32_e32 v122, v236, v0, vcc
	v_pk_add_f32 v[6:7], v[194:195], v[122:123] op_sel_hi:[1,0]
	v_pk_add_f32 v[4:5], v[192:193], v[122:123] op_sel_hi:[1,0]
	v_pk_add_f32 v[10:11], v[196:197], v[122:123] op_sel_hi:[1,0]
	v_pk_add_f32 v[8:9], v[188:189], v[122:123] op_sel_hi:[1,0]
	v_pk_add_f32 v[14:15], v[200:201], v[122:123] op_sel_hi:[1,0]
	v_pk_add_f32 v[12:13], v[198:199], v[122:123] op_sel_hi:[1,0]
	v_pk_add_f32 v[124:125], v[204:205], v[122:123] op_sel_hi:[1,0]
	s_waitcnt lgkmcnt(7)
	v_mfma_f32_16x16x32_bf16 v[0:3], v[162:165], v[24:27], v[4:7]
	v_pk_add_f32 v[122:123], v[202:203], v[122:123] op_sel_hi:[1,0]
	s_andn2_b64 vcc, exec, s[0:1]
	s_waitcnt lgkmcnt(6)
	v_mfma_f32_16x16x32_bf16 v[0:3], v[166:169], v[28:31], v[0:3]
	s_nop 7
	v_exp_f32_e32 v0, v0
	s_waitcnt lgkmcnt(5)
	v_mfma_f32_16x16x32_bf16 v[4:7], v[206:209], v[24:27], v[8:11]
	v_exp_f32_e32 v1, v1
	v_exp_f32_e32 v2, v2
	s_waitcnt lgkmcnt(4)
	v_mfma_f32_16x16x32_bf16 v[4:7], v[214:217], v[28:31], v[4:7]
	v_exp_f32_e32 v3, v3
	s_nop 6
	v_exp_f32_e32 v4, v4
	s_waitcnt lgkmcnt(3)
	v_mfma_f32_16x16x32_bf16 v[8:11], v[218:221], v[24:27], v[12:15]
	v_exp_f32_e32 v5, v5
	v_exp_f32_e32 v6, v6
	s_waitcnt lgkmcnt(2)
	v_mfma_f32_16x16x32_bf16 v[8:11], v[222:225], v[28:31], v[8:11]
	v_exp_f32_e32 v7, v7
	s_nop 6
	v_exp_f32_e32 v8, v8
	s_waitcnt lgkmcnt(1)
	v_mfma_f32_16x16x32_bf16 v[12:15], v[226:229], v[24:27], v[122:125]
	v_exp_f32_e32 v9, v9
	v_exp_f32_e32 v10, v10
	s_waitcnt lgkmcnt(0)
	v_mfma_f32_16x16x32_bf16 v[12:15], v[238:241], v[28:31], v[12:15]
	v_exp_f32_e32 v11, v11
	s_nop 6
	v_exp_f32_e32 v12, v12
	v_exp_f32_e32 v13, v13
	v_exp_f32_e32 v14, v14
	v_exp_f32_e32 v15, v15
	v_mov_b32_e32 v122, v238
	s_cbranch_vccnz .LBB0_250
	v_add_f32_e32 v122, 0, v0
	v_add_f32_e32 v122, v1, v122
	v_add_f32_e32 v122, v2, v122
	v_add_f32_e32 v122, v3, v122
	v_add_f32_e32 v122, v122, v4
	v_add_f32_e32 v122, v5, v122
	v_add_f32_e32 v122, v6, v122
	v_add_f32_e32 v122, v7, v122
	v_add_f32_e32 v122, v122, v8
	v_add_f32_e32 v122, v9, v122
	v_add_f32_e32 v122, v10, v122
	v_add_f32_e32 v122, v11, v122
	v_add_f32_e32 v122, v122, v12
	v_add_f32_e32 v122, v13, v122
	v_add_f32_e32 v122, v14, v122
	v_add_f32_e32 v122, v15, v122
	s_mov_b64 s[10:11], 0

; #define LAS __attribute__((address_space(3)))
; DI f32x4 mfma16(bf16x8 a, bf16x8 b, f32x4 c) { return __builtin_amdgcn_mfma_f32_16x16x32_bf16(a, b, c, 0, 0, 0); }
; DI void nsa_attn_phase(const int tid0, LAS unsigned char* lds, const P& p, int G, int c) {
;     ...
;                 for (int h = 0; h < 2; ++h) {
;                     const int n = na + h; const bool nvalid = (n <= i);
;                     const bool edge = (n == i) || (br == 1 && n == i - 4);
;                     LAS bf16_t* Kt = Tc + h * 9216;
; #pragma unroll
;                     for (int qt = 0; qt < 2; ++qt) {
;                         const bool bsel = nvalid && ((br == 1) || ((sm[qt] >> n) & 1u));
;                         act[h][qt] = nvalid && ((br == 1) || (__ballot(bsel) != 0ull));
;                         pf[h][0][qt] = (bf16x8){0, 0, 0, 0, 0, 0, 0, 0}; pf[h][1][qt] = pf[h][0][qt];
;                         if (act[h][qt]) {
;                             const float sb = bsel ? slope2 * (float)(n * 64 + fq * 4 - tq[qt]) : -1e9f;
;                             f32x4 S[4];
; #pragma unroll
;                             for (int kt = 0; kt < 4; ++kt) { S[kt] = (f32x4){sb + sc16[kt * 4], sb + sc16[kt * 4 + 1], sb + sc16[kt * 4 + 2], sb + sc16[kt * 4 + 3]};
; #pragma unroll
;                                 for (int ks = 0; ks < 2; ++ks) { const bf16x8 kf = *(const LAS bf16x8*)(Kt + (kt * 16 + fr) * 72 + ks * 32 + fq * 8); S[kt] = mfma16(kf, Qf[qt][ks], S[kt]); } }
;                             float ls = 0.f;
;                             if (edge) {
; #pragma unroll
;                                 for (int kt = 0; kt < 4; ++kt)
; #pragma unroll
;                                     for (int j = 0; j < 4; ++j) { const int pos = n * 64 + kt * 16 + fq * 4 + j; const bool valid = (pos <= tq[qt]) && (br == 0 || pos > tq[qt] - 256);
;                                         const float pv = valid ? __builtin_amdgcn_exp2f(S[kt][j]) : 0.f; S[kt][j] = pv; ls += pv; }
;                             } else {
; #pragma unroll
;                                 for (int kt = 0; kt < 4; ++kt)
; #pragma unroll
;                                     for (int j = 0; j < 4; ++j) { const float pv = __builtin_amdgcn_exp2f(S[kt][j]); S[kt][j] = pv; ls += pv; }
;                             }
;                             lrun[qt] += ls;
.LBB0_255:
	s_cmp_lt_i32 s14, s44
	s_cselect_b64 s[16:17], -1, 0
	s_cmp_lg_u32 s15, 33
	s_cselect_b64 s[0:1], -1, 0
	s_lshl_b32 s60, 2, s14
	s_cmp_ge_i32 s14, s44
	v_add_u32_e32 v140, 64, v138
	s_mov_b64 s[12:13], 0
	s_cbranch_scc1 .LBB0_263
	v_and_b32_e32 v0, s60, v150
	v_cmp_ne_u32_e32 vcc, 0, v0
	s_cbranch_vccz .LBB0_270
	v_add_u32_e32 v0, s19, v97
	v_add_u32_e32 v0, 0xfffff880, v0
	v_cvt_f32_i32_e32 v0, v0
	v_add_u32_e32 v134, v139, v179
	ds_read_b128 v[162:165], v134 offset:18432
	ds_read_b128 v[166:169], v134 offset:18496
	ds_read_b128 v[206:209], v134 offset:20736
	ds_read_b128 v[214:217], v134 offset:20800
	ds_read_b128 v[218:221], v134 offset:23040
	ds_read_b128 v[222:225], v134 offset:23104
	ds_read_b128 v[226:229], v134 offset:25344
	ds_read_b128 v[238:241], v134 offset:25408
	s_mov_b64 s[14:15], -1
	v_mul_f32_e32 v0, v186, v0
	v_cndmask_b32_e32 v130, v236, v0, vcc
	v_pk_add_f32 v[6:7], v[194:195], v[130:131] op_sel_hi:[1,0]
	v_pk_add_f32 v[4:5], v[192:193], v[130:131] op_sel_hi:[1,0]
	v_pk_add_f32 v[10:11], v[196:197], v[130:131] op_sel_hi:[1,0]
	v_pk_add_f32 v[8:9], v[188:189], v[130:131] op_sel_hi:[1,0]
	v_pk_add_f32 v[14:15], v[200:201], v[130:131] op_sel_hi:[1,0]
	v_pk_add_f32 v[12:13], v[198:199], v[130:131] op_sel_hi:[1,0]
	v_pk_add_f32 v[132:133], v[204:205], v[130:131] op_sel_hi:[1,0]
	s_waitcnt lgkmcnt(7)
	v_mfma_f32_16x16x32_bf16 v[0:3], v[162:165], v[16:19], v[4:7]
	v_pk_add_f32 v[130:131], v[202:203], v[130:131] op_sel_hi:[1,0]
	s_andn2_b64 vcc, exec, s[0:1]
	s_waitcnt lgkmcnt(6)
	v_mfma_f32_16x16x32_bf16 v[0:3], v[166:169], v[20:23], v[0:3]
	s_nop 7
	v_exp_f32_e32 v0, v0
	s_waitcnt lgkmcnt(5)
	v_mfma_f32_16x16x32_bf16 v[4:7], v[206:209], v[16:19], v[8:11]
	v_exp_f32_e32 v1, v1
	v_exp_f32_e32 v2, v2
	s_waitcnt lgkmcnt(4)
	v_mfma_f32_16x16x32_bf16 v[4:7], v[214:217], v[20:23], v[4:7]
	v_exp_f32_e32 v3, v3
	s_nop 6
	v_exp_f32_e32 v4, v4
	s_waitcnt lgkmcnt(3)
	v_mfma_f32_16x16x32_bf16 v[8:11], v[218:221], v[16:19], v[12:15]
	v_exp_f32_e32 v5, v5
	v_exp_f32_e32 v6, v6
	s_waitcnt lgkmcnt(2)
	v_mfma_f32_16x16x32_bf16 v[8:11], v[222:225], v[20:23], v[8:11]
	v_exp_f32_e32 v7, v7
	s_nop 6
	v_exp_f32_e32 v8, v8
	s_waitcnt lgkmcnt(1)
	v_mfma_f32_16x16x32_bf16 v[12:15], v[226:229], v[16:19], v[130:133]
	v_exp_f32_e32 v9, v9
	v_exp_f32_e32 v10, v10
	s_waitcnt lgkmcnt(0)
	v_mfma_f32_16x16x32_bf16 v[12:15], v[238:241], v[20:23], v[12:15]
	v_exp_f32_e32 v11, v11
	s_nop 6
	v_exp_f32_e32 v12, v12
	v_exp_f32_e32 v13, v13
	v_exp_f32_e32 v14, v14
	v_exp_f32_e32 v15, v15
	v_mov_b32_e32 v130, v238
	s_cbranch_vccnz .LBB0_259
	v_add_f32_e32 v130, 0, v0
	v_add_f32_e32 v130, v1, v130
	v_add_f32_e32 v130, v2, v130
	v_add_f32_e32 v130, v3, v130
	v_add_f32_e32 v130, v130, v4
	v_add_f32_e32 v130, v5, v130
	v_add_f32_e32 v130, v6, v130
	v_add_f32_e32 v130, v7, v130
	v_add_f32_e32 v130, v130, v8
	v_add_f32_e32 v130, v9, v130
	v_add_f32_e32 v130, v10, v130
	v_add_f32_e32 v130, v11, v130
	v_add_f32_e32 v130, v130, v12
	v_add_f32_e32 v130, v13, v130
	v_add_f32_e32 v130, v14, v130
	v_add_f32_e32 v130, v15, v130
	s_mov_b64 s[14:15], 0

; #define LAS __attribute__((address_space(3)))
; DI f32x4 mfma16(bf16x8 a, bf16x8 b, f32x4 c) { return __builtin_amdgcn_mfma_f32_16x16x32_bf16(a, b, c, 0, 0, 0); }
; DI void nsa_attn_phase(const int tid0, LAS unsigned char* lds, const P& p, int G, int c) {
;     ...
;                 for (int h = 0; h < 2; ++h) {
;                     const int n = na + h; const bool nvalid = (n <= i);
;                     const bool edge = (n == i) || (br == 1 && n == i - 4);
;                     LAS bf16_t* Kt = Tc + h * 9216;
; #pragma unroll
;                     for (int qt = 0; qt < 2; ++qt) {
;                         const bool bsel = nvalid && ((br == 1) || ((sm[qt] >> n) & 1u));
;                         act[h][qt] = nvalid && ((br == 1) || (__ballot(bsel) != 0ull));
;                         pf[h][0][qt] = (bf16x8){0, 0, 0, 0, 0, 0, 0, 0}; pf[h][1][qt] = pf[h][0][qt];
;                         if (act[h][qt]) {
;                             const float sb = bsel ? slope2 * (float)(n * 64 + fq * 4 - tq[qt]) : -1e9f;
;                             f32x4 S[4];
; #pragma unroll
;                             for (int kt = 0; kt < 4; ++kt) { S[kt] = (f32x4){sb + sc16[kt * 4], sb + sc16[kt * 4 + 1], sb + sc16[kt * 4 + 2], sb + sc16[kt * 4 + 3]};
; #pragma unroll
;                                 for (int ks = 0; ks < 2; ++ks) { const bf16x8 kf = *(const LAS bf16x8*)(Kt + (kt * 16 + fr) * 72 + ks * 32 + fq * 8); S[kt] = mfma16(kf, Qf[qt][ks], S[kt]); } }
;                             float ls = 0.f;
;                             if (edge) {
; #pragma unroll
;                                 for (int kt = 0; kt < 4; ++kt)
; #pragma unroll
;                                     for (int j = 0; j < 4; ++j) { const int pos = n * 64 + kt * 16 + fq * 4 + j; const bool valid = (pos <= tq[qt]) && (br == 0 || pos > tq[qt] - 256);
;                                         const float pv = valid ? __builtin_amdgcn_exp2f(S[kt][j]) : 0.f; S[kt][j] = pv; ls += pv; }
;                             } else {
; #pragma unroll
;                                 for (int kt = 0; kt < 4; ++kt)
; #pragma unroll
;                                     for (int j = 0; j < 4; ++j) { const float pv = __builtin_amdgcn_exp2f(S[kt][j]); S[kt][j] = pv; ls += pv; }
;                             }
;                             lrun[qt] += ls;
.LBB0_264:
	v_and_b32_e32 v0, s60, v151
	v_cmp_ne_u32_e32 vcc, 0, v0
	s_cbranch_vccz .LBB0_271
	v_add_u32_e32 v0, s19, v97
	v_add_u32_e32 v0, 0xfffff870, v0
	v_cvt_f32_i32_e32 v0, v0
	v_add_u32_e32 v139, v139, v179
	ds_read_b128 v[162:165], v139 offset:18432
	ds_read_b128 v[166:169], v139 offset:18496
	ds_read_b128 v[206:209], v139 offset:20736
	ds_read_b128 v[214:217], v139 offset:20800
	ds_read_b128 v[218:221], v139 offset:23040
	ds_read_b128 v[222:225], v139 offset:23104
	ds_read_b128 v[226:229], v139 offset:25344
	ds_read_b128 v[238:241], v139 offset:25408
	s_mov_b64 s[12:13], -1
	v_mul_f32_e32 v0, v186, v0
	v_cndmask_b32_e32 v158, v236, v0, vcc
	v_pk_add_f32 v[6:7], v[194:195], v[158:159] op_sel_hi:[1,0]
	v_pk_add_f32 v[4:5], v[192:193], v[158:159] op_sel_hi:[1,0]
	v_pk_add_f32 v[10:11], v[196:197], v[158:159] op_sel_hi:[1,0]
	v_pk_add_f32 v[8:9], v[188:189], v[158:159] op_sel_hi:[1,0]
	v_pk_add_f32 v[14:15], v[200:201], v[158:159] op_sel_hi:[1,0]
	v_pk_add_f32 v[12:13], v[198:199], v[158:159] op_sel_hi:[1,0]
	v_pk_add_f32 v[160:161], v[204:205], v[158:159] op_sel_hi:[1,0]
	s_waitcnt lgkmcnt(7)
	v_mfma_f32_16x16x32_bf16 v[0:3], v[162:165], v[24:27], v[4:7]
	v_pk_add_f32 v[158:159], v[202:203], v[158:159] op_sel_hi:[1,0]
	s_andn2_b64 vcc, exec, s[0:1]
	s_waitcnt lgkmcnt(6)
	v_mfma_f32_16x16x32_bf16 v[0:3], v[166:169], v[28:31], v[0:3]
	s_nop 7
	v_exp_f32_e32 v0, v0
	s_waitcnt lgkmcnt(5)
	v_mfma_f32_16x16x32_bf16 v[4:7], v[206:209], v[24:27], v[8:11]
	v_exp_f32_e32 v1, v1
	v_exp_f32_e32 v2, v2
	s_waitcnt lgkmcnt(4)
	v_mfma_f32_16x16x32_bf16 v[4:7], v[214:217], v[28:31], v[4:7]
	v_exp_f32_e32 v3, v3
	s_nop 6
	v_exp_f32_e32 v4, v4
	s_waitcnt lgkmcnt(3)
	v_mfma_f32_16x16x32_bf16 v[8:11], v[218:221], v[24:27], v[12:15]
	v_exp_f32_e32 v5, v5
	v_exp_f32_e32 v6, v6
	s_waitcnt lgkmcnt(2)
	v_mfma_f32_16x16x32_bf16 v[8:11], v[222:225], v[28:31], v[8:11]
	v_exp_f32_e32 v7, v7
	s_nop 6
	v_exp_f32_e32 v8, v8
	s_waitcnt lgkmcnt(1)
	v_mfma_f32_16x16x32_bf16 v[12:15], v[226:229], v[24:27], v[158:161]
	v_exp_f32_e32 v9, v9
	v_exp_f32_e32 v10, v10
	s_waitcnt lgkmcnt(0)
	v_mfma_f32_16x16x32_bf16 v[12:15], v[238:241], v[28:31], v[12:15]
	v_exp_f32_e32 v11, v11
	s_nop 6
	v_exp_f32_e32 v12, v12
	v_exp_f32_e32 v13, v13
	v_exp_f32_e32 v14, v14
	v_exp_f32_e32 v15, v15
	s_cbranch_vccnz .LBB0_267
	v_add_f32_e32 v139, 0, v0
	v_add_f32_e32 v139, v1, v139
	v_add_f32_e32 v139, v2, v139
	v_add_f32_e32 v139, v3, v139
	v_add_f32_e32 v139, v139, v4
	v_add_f32_e32 v139, v5, v139
	v_add_f32_e32 v139, v6, v139
	v_add_f32_e32 v139, v7, v139
	v_add_f32_e32 v139, v139, v8
	v_add_f32_e32 v139, v9, v139
	v_add_f32_e32 v139, v10, v139
	v_add_f32_e32 v139, v11, v139
	v_add_f32_e32 v139, v139, v12
	v_add_f32_e32 v139, v13, v139
	v_add_f32_e32 v139, v14, v139
	v_add_f32_e32 v139, v15, v139
	s_mov_b64 s[12:13], 0

; #define LAS __attribute__((address_space(3)))
; DI f32x4 mfma16(bf16x8 a, bf16x8 b, f32x4 c) { return __builtin_amdgcn_mfma_f32_16x16x32_bf16(a, b, c, 0, 0, 0); }
; DI void nsa_attn_phase(const int tid0, LAS unsigned char* lds, const P& p, int G, int c) {
;     ...
;                 for (int h = 0; h < 2; ++h) {
;                     const int n = na + h; const bool nvalid = (n <= i);
;                     const bool edge = (n == i) || (br == 1 && n == i - 4);
;                     LAS bf16_t* Kt = Tc + h * 9216;
; #pragma unroll
;                     for (int qt = 0; qt < 2; ++qt) {
;                         const bool bsel = nvalid && ((br == 1) || ((sm[qt] >> n) & 1u));
;                         act[h][qt] = nvalid && ((br == 1) || (__ballot(bsel) != 0ull));
;                         pf[h][0][qt] = (bf16x8){0, 0, 0, 0, 0, 0, 0, 0}; pf[h][1][qt] = pf[h][0][qt];
;                         if (act[h][qt]) {
;                             const float sb = bsel ? slope2 * (float)(n * 64 + fq * 4 - tq[qt]) : -1e9f;
;                             f32x4 S[4];
; #pragma unroll
;                             for (int kt = 0; kt < 4; ++kt) { S[kt] = (f32x4){sb + sc16[kt * 4], sb + sc16[kt * 4 + 1], sb + sc16[kt * 4 + 2], sb + sc16[kt * 4 + 3]};
; #pragma unroll
;                                 for (int ks = 0; ks < 2; ++ks) { const bf16x8 kf = *(const LAS bf16x8*)(Kt + (kt * 16 + fr) * 72 + ks * 32 + fq * 8); S[kt] = mfma16(kf, Qf[qt][ks], S[kt]); } }
;                             float ls = 0.f;
;                             if (edge) {
; #pragma unroll
;                                 for (int kt = 0; kt < 4; ++kt)
; #pragma unroll
;                                     for (int j = 0; j < 4; ++j) { const int pos = n * 64 + kt * 16 + fq * 4 + j; const bool valid = (pos <= tq[qt]) && (br == 0 || pos > tq[qt] - 256);
;                                         const float pv = valid ? __builtin_amdgcn_exp2f(S[kt][j]) : 0.f; S[kt][j] = pv; ls += pv; }
;                             } else {
; #pragma unroll
;                                 for (int kt = 0; kt < 4; ++kt)
; #pragma unroll
;                                     for (int j = 0; j < 4; ++j) { const float pv = __builtin_amdgcn_exp2f(S[kt][j]); S[kt][j] = pv; ls += pv; }
;                             }
;                             lrun[qt] += ls;
.LBB0_346:
	s_bitcmp0_b32 s0, 0
	s_cselect_b64 s[10:11], -1, 0
	s_and_b64 s[0:1], s[10:11], exec
	s_cselect_b32 s0, s94, 0
	s_add_i32 s18, s15, -3
	s_add_i32 s19, s41, s15
	s_cmp_le_i32 s18, s44
	s_cselect_b64 s[6:7], -1, 0
	s_cmp_lg_u32 s19, 34
	v_add_u32_e32 v0, s0, v187
	s_cselect_b64 s[0:1], -1, 0
	s_cmp_lg_u32 s19, 30
	s_cselect_b64 s[4:5], -1, 0
	s_and_b64 s[0:1], s[0:1], s[4:5]
	v_add_u32_e32 v169, v0, v179
	v_cndmask_b32_e64 v0, 0, 1, s[0:1]
	s_cmp_gt_i32 s18, s44
	v_add_u32_e32 v168, s16, v190
	v_cmp_ne_u32_e64 s[0:1], 1, v0
	s_cbranch_scc1 .LBB0_353
	ds_read_b128 v[226:229], v169
	ds_read_b128 v[238:241], v169 offset:64
	ds_read_b128 v[242:245], v169 offset:2304
	ds_read_b128 v[246:249], v169 offset:2368
	s_movk_i32 s4, 0xf840
	v_add3_u32 v0, v190, v220, s4
	v_cvt_f32_i32_e32 v0, v0
	s_mov_b64 s[4:5], -1
	s_and_b64 vcc, exec, s[0:1]
	v_mul_f32_e32 v144, v186, v0
	v_pk_add_f32 v[6:7], v[194:195], v[144:145] op_sel_hi:[1,0]
	v_pk_add_f32 v[4:5], v[192:193], v[144:145] op_sel_hi:[1,0]
	v_pk_add_f32 v[10:11], v[196:197], v[144:145] op_sel_hi:[1,0]
	v_pk_add_f32 v[8:9], v[188:189], v[144:145] op_sel_hi:[1,0]
	v_pk_add_f32 v[14:15], v[200:201], v[144:145] op_sel_hi:[1,0]
	v_pk_add_f32 v[12:13], v[198:199], v[144:145] op_sel_hi:[1,0]
	v_pk_add_f32 v[146:147], v[204:205], v[144:145] op_sel_hi:[1,0]
	s_waitcnt lgkmcnt(3)
	v_mfma_f32_16x16x32_bf16 v[0:3], v[226:229], v[16:19], v[4:7]
	ds_read_b128 v[226:229], v169 offset:4608
	v_pk_add_f32 v[144:145], v[202:203], v[144:145] op_sel_hi:[1,0]
	s_waitcnt lgkmcnt(3)
	v_mfma_f32_16x16x32_bf16 v[0:3], v[238:241], v[20:23], v[0:3]
	ds_read_b128 v[238:241], v169 offset:4672
	s_nop 6
	v_exp_f32_e32 v0, v0
	s_waitcnt lgkmcnt(3)
	v_mfma_f32_16x16x32_bf16 v[4:7], v[242:245], v[16:19], v[8:11]
	ds_read_b128 v[242:245], v169 offset:6912
	v_exp_f32_e32 v1, v1
	v_exp_f32_e32 v2, v2
	s_waitcnt lgkmcnt(3)
	v_mfma_f32_16x16x32_bf16 v[4:7], v[246:249], v[20:23], v[4:7]
	ds_read_b128 v[246:249], v169 offset:6976
	v_exp_f32_e32 v3, v3
	s_nop 5
	v_exp_f32_e32 v4, v4
	s_waitcnt lgkmcnt(3)
	v_mfma_f32_16x16x32_bf16 v[8:11], v[226:229], v[16:19], v[12:15]
	v_exp_f32_e32 v5, v5
	v_exp_f32_e32 v6, v6
	s_waitcnt lgkmcnt(2)
	v_mfma_f32_16x16x32_bf16 v[8:11], v[238:241], v[20:23], v[8:11]
	v_exp_f32_e32 v7, v7
	s_nop 6
	v_exp_f32_e32 v8, v8
	s_waitcnt lgkmcnt(1)
	v_mfma_f32_16x16x32_bf16 v[12:15], v[242:245], v[16:19], v[144:147]
	v_exp_f32_e32 v9, v9
	v_exp_f32_e32 v10, v10
	s_waitcnt lgkmcnt(0)
	v_mfma_f32_16x16x32_bf16 v[12:15], v[246:249], v[20:23], v[12:15]
	v_exp_f32_e32 v11, v11
	s_nop 6
	v_exp_f32_e32 v12, v12
	v_exp_f32_e32 v13, v13
	v_exp_f32_e32 v14, v14
	v_exp_f32_e32 v15, v15
	v_mov_b32_e32 v144, v246
	s_cbranch_vccnz .LBB0_349
	v_add_f32_e32 v144, 0, v0
	v_add_f32_e32 v144, v1, v144
	v_add_f32_e32 v144, v2, v144
	v_add_f32_e32 v144, v3, v144
	v_add_f32_e32 v144, v144, v4
	v_add_f32_e32 v144, v5, v144
	v_add_f32_e32 v144, v6, v144
	v_add_f32_e32 v144, v7, v144
	v_add_f32_e32 v144, v144, v8
	v_add_f32_e32 v144, v9, v144
	v_add_f32_e32 v144, v10, v144
	v_add_f32_e32 v144, v11, v144
	v_add_f32_e32 v144, v144, v12
	v_add_f32_e32 v144, v13, v144
	v_add_f32_e32 v144, v14, v144
	v_add_f32_e32 v144, v15, v144
	s_mov_b64 s[4:5], 0

; #define LAS __attribute__((address_space(3)))
; DI f32x4 mfma16(bf16x8 a, bf16x8 b, f32x4 c) { return __builtin_amdgcn_mfma_f32_16x16x32_bf16(a, b, c, 0, 0, 0); }
; DI void nsa_attn_phase(const int tid0, LAS unsigned char* lds, const P& p, int G, int c) {
;     ...
;                 for (int h = 0; h < 2; ++h) {
;                     const int n = na + h; const bool nvalid = (n <= i);
;                     const bool edge = (n == i) || (br == 1 && n == i - 4);
;                     LAS bf16_t* Kt = Tc + h * 9216;
; #pragma unroll
;                     for (int qt = 0; qt < 2; ++qt) {
;                         const bool bsel = nvalid && ((br == 1) || ((sm[qt] >> n) & 1u));
;                         act[h][qt] = nvalid && ((br == 1) || (__ballot(bsel) != 0ull));
;                         pf[h][0][qt] = (bf16x8){0, 0, 0, 0, 0, 0, 0, 0}; pf[h][1][qt] = pf[h][0][qt];
;                         if (act[h][qt]) {
;                             const float sb = bsel ? slope2 * (float)(n * 64 + fq * 4 - tq[qt]) : -1e9f;
;                             f32x4 S[4];
; #pragma unroll
;                             for (int kt = 0; kt < 4; ++kt) { S[kt] = (f32x4){sb + sc16[kt * 4], sb + sc16[kt * 4 + 1], sb + sc16[kt * 4 + 2], sb + sc16[kt * 4 + 3]};
; #pragma unroll
;                                 for (int ks = 0; ks < 2; ++ks) { const bf16x8 kf = *(const LAS bf16x8*)(Kt + (kt * 16 + fr) * 72 + ks * 32 + fq * 8); S[kt] = mfma16(kf, Qf[qt][ks], S[kt]); } }
;                             float ls = 0.f;
;                             if (edge) {
; #pragma unroll
;                                 for (int kt = 0; kt < 4; ++kt)
; #pragma unroll
;                                     for (int j = 0; j < 4; ++j) { const int pos = n * 64 + kt * 16 + fq * 4 + j; const bool valid = (pos <= tq[qt]) && (br == 0 || pos > tq[qt] - 256);
;                                         const float pv = valid ? __builtin_amdgcn_exp2f(S[kt][j]) : 0.f; S[kt][j] = pv; ls += pv; }
;                             } else {
; #pragma unroll
;                                 for (int kt = 0; kt < 4; ++kt)
; #pragma unroll
;                                     for (int j = 0; j < 4; ++j) { const float pv = __builtin_amdgcn_exp2f(S[kt][j]); S[kt][j] = pv; ls += pv; }
;                             }
;                             lrun[qt] += ls;
.LBB0_354:
	ds_read_b128 v[226:229], v169
	ds_read_b128 v[238:241], v169 offset:64
	ds_read_b128 v[242:245], v169 offset:2304
	ds_read_b128 v[246:249], v169 offset:2368
	s_movk_i32 s6, 0xf830
	v_add3_u32 v0, v190, v220, s6
	v_cvt_f32_i32_e32 v0, v0
	s_mov_b64 s[6:7], -1
	s_and_b64 vcc, exec, s[0:1]
	v_mul_f32_e32 v152, v186, v0
	v_pk_add_f32 v[6:7], v[194:195], v[152:153] op_sel_hi:[1,0]
	v_pk_add_f32 v[4:5], v[192:193], v[152:153] op_sel_hi:[1,0]
	v_pk_add_f32 v[10:11], v[196:197], v[152:153] op_sel_hi:[1,0]
	v_pk_add_f32 v[8:9], v[188:189], v[152:153] op_sel_hi:[1,0]
	v_pk_add_f32 v[14:15], v[200:201], v[152:153] op_sel_hi:[1,0]
	v_pk_add_f32 v[12:13], v[198:199], v[152:153] op_sel_hi:[1,0]
	v_pk_add_f32 v[154:155], v[204:205], v[152:153] op_sel_hi:[1,0]
	s_waitcnt lgkmcnt(3)
	v_mfma_f32_16x16x32_bf16 v[0:3], v[226:229], v[24:27], v[4:7]
	ds_read_b128 v[226:229], v169 offset:4608
	v_pk_add_f32 v[152:153], v[202:203], v[152:153] op_sel_hi:[1,0]
	s_waitcnt lgkmcnt(3)
	v_mfma_f32_16x16x32_bf16 v[0:3], v[238:241], v[28:31], v[0:3]
	ds_read_b128 v[238:241], v169 offset:4672
	s_nop 6
	v_exp_f32_e32 v0, v0
	s_waitcnt lgkmcnt(3)
	v_mfma_f32_16x16x32_bf16 v[4:7], v[242:245], v[24:27], v[8:11]
	ds_read_b128 v[242:245], v169 offset:6912
	v_exp_f32_e32 v1, v1
	v_exp_f32_e32 v2, v2
	s_waitcnt lgkmcnt(3)
	v_mfma_f32_16x16x32_bf16 v[4:7], v[246:249], v[28:31], v[4:7]
	ds_read_b128 v[246:249], v169 offset:6976
	v_exp_f32_e32 v3, v3
	s_nop 5
	v_exp_f32_e32 v4, v4
	s_waitcnt lgkmcnt(3)
	v_mfma_f32_16x16x32_bf16 v[8:11], v[226:229], v[24:27], v[12:15]
	v_exp_f32_e32 v5, v5
	v_exp_f32_e32 v6, v6
	s_waitcnt lgkmcnt(2)
	v_mfma_f32_16x16x32_bf16 v[8:11], v[238:241], v[28:31], v[8:11]
	v_exp_f32_e32 v7, v7
	s_nop 6
	v_exp_f32_e32 v8, v8
	s_waitcnt lgkmcnt(1)
	v_mfma_f32_16x16x32_bf16 v[12:15], v[242:245], v[24:27], v[152:155]
	v_exp_f32_e32 v9, v9
	v_exp_f32_e32 v10, v10
	s_waitcnt lgkmcnt(0)
	v_mfma_f32_16x16x32_bf16 v[12:15], v[246:249], v[28:31], v[12:15]
	v_exp_f32_e32 v11, v11
	s_nop 6
	v_exp_f32_e32 v12, v12
	v_exp_f32_e32 v13, v13
	v_exp_f32_e32 v14, v14
	v_exp_f32_e32 v15, v15
	v_mov_b32_e32 v152, v246
	s_cbranch_vccnz .LBB0_356
	v_add_f32_e32 v152, 0, v0
	v_add_f32_e32 v152, v1, v152
	v_add_f32_e32 v152, v2, v152
	v_add_f32_e32 v152, v3, v152
	v_add_f32_e32 v152, v152, v4
	v_add_f32_e32 v152, v5, v152
	v_add_f32_e32 v152, v6, v152
	v_add_f32_e32 v152, v7, v152
	v_add_f32_e32 v152, v152, v8
	v_add_f32_e32 v152, v9, v152
	v_add_f32_e32 v152, v10, v152
	v_add_f32_e32 v152, v11, v152
	v_add_f32_e32 v152, v152, v12
	v_add_f32_e32 v152, v13, v152
	v_add_f32_e32 v152, v14, v152
	v_add_f32_e32 v152, v15, v152
	s_mov_b64 s[6:7], 0

; #define LAS __attribute__((address_space(3)))
; DI f32x4 mfma16(bf16x8 a, bf16x8 b, f32x4 c) { return __builtin_amdgcn_mfma_f32_16x16x32_bf16(a, b, c, 0, 0, 0); }
; DI void nsa_attn_phase(const int tid0, LAS unsigned char* lds, const P& p, int G, int c) {
;     ...
;                 for (int h = 0; h < 2; ++h) {
;                     const int n = na + h; const bool nvalid = (n <= i);
;                     const bool edge = (n == i) || (br == 1 && n == i - 4);
;                     LAS bf16_t* Kt = Tc + h * 9216;
; #pragma unroll
;                     for (int qt = 0; qt < 2; ++qt) {
;                         const bool bsel = nvalid && ((br == 1) || ((sm[qt] >> n) & 1u));
;                         act[h][qt] = nvalid && ((br == 1) || (__ballot(bsel) != 0ull));
;                         pf[h][0][qt] = (bf16x8){0, 0, 0, 0, 0, 0, 0, 0}; pf[h][1][qt] = pf[h][0][qt];
;                         if (act[h][qt]) {
;                             const float sb = bsel ? slope2 * (float)(n * 64 + fq * 4 - tq[qt]) : -1e9f;
;                             f32x4 S[4];
; #pragma unroll
;                             for (int kt = 0; kt < 4; ++kt) { S[kt] = (f32x4){sb + sc16[kt * 4], sb + sc16[kt * 4 + 1], sb + sc16[kt * 4 + 2], sb + sc16[kt * 4 + 3]};
; #pragma unroll
;                                 for (int ks = 0; ks < 2; ++ks) { const bf16x8 kf = *(const LAS bf16x8*)(Kt + (kt * 16 + fr) * 72 + ks * 32 + fq * 8); S[kt] = mfma16(kf, Qf[qt][ks], S[kt]); } }
;                             float ls = 0.f;
;                             if (edge) {
; #pragma unroll
;                                 for (int kt = 0; kt < 4; ++kt)
; #pragma unroll
;                                     for (int j = 0; j < 4; ++j) { const int pos = n * 64 + kt * 16 + fq * 4 + j; const bool valid = (pos <= tq[qt]) && (br == 0 || pos > tq[qt] - 256);
;                                         const float pv = valid ? __builtin_amdgcn_exp2f(S[kt][j]) : 0.f; S[kt][j] = pv; ls += pv; }
;                             } else {
; #pragma unroll
;                                 for (int kt = 0; kt < 4; ++kt)
; #pragma unroll
;                                     for (int j = 0; j < 4; ++j) { const float pv = __builtin_amdgcn_exp2f(S[kt][j]); S[kt][j] = pv; ls += pv; }
;                             }
;                             lrun[qt] += ls;
.LBB0_359:
	s_cmp_lt_i32 s18, s44
	s_cselect_b64 s[12:13], -1, 0
	s_cmp_lg_u32 s19, 33
	s_cselect_b64 s[0:1], -1, 0
	s_cmp_lg_u32 s19, 29
	s_cselect_b64 s[6:7], -1, 0
	s_and_b64 s[0:1], s[0:1], s[6:7]
	v_cndmask_b32_e64 v0, 0, 1, s[0:1]
	s_cmp_ge_i32 s18, s44
	v_add_u32_e32 v170, 64, v168
	v_cmp_ne_u32_e64 s[0:1], 1, v0
	s_cbranch_scc1 .LBB0_366
	ds_read_b128 v[226:229], v169 offset:18432
	ds_read_b128 v[238:241], v169 offset:18496
	ds_read_b128 v[242:245], v169 offset:20736
	ds_read_b128 v[246:249], v169 offset:20800
	s_movk_i32 s6, 0xf880
	v_add3_u32 v0, v190, v220, s6
	v_cvt_f32_i32_e32 v0, v0
	s_mov_b64 s[6:7], -1
	s_and_b64 vcc, exec, s[0:1]
	v_mul_f32_e32 v160, v186, v0
	v_pk_add_f32 v[6:7], v[194:195], v[160:161] op_sel_hi:[1,0]
	v_pk_add_f32 v[4:5], v[192:193], v[160:161] op_sel_hi:[1,0]
	v_pk_add_f32 v[10:11], v[196:197], v[160:161] op_sel_hi:[1,0]
	v_pk_add_f32 v[8:9], v[188:189], v[160:161] op_sel_hi:[1,0]
	v_pk_add_f32 v[14:15], v[200:201], v[160:161] op_sel_hi:[1,0]
	v_pk_add_f32 v[12:13], v[198:199], v[160:161] op_sel_hi:[1,0]
	v_pk_add_f32 v[162:163], v[204:205], v[160:161] op_sel_hi:[1,0]
	s_waitcnt lgkmcnt(3)
	v_mfma_f32_16x16x32_bf16 v[0:3], v[226:229], v[16:19], v[4:7]
	ds_read_b128 v[226:229], v169 offset:23040
	v_pk_add_f32 v[160:161], v[202:203], v[160:161] op_sel_hi:[1,0]
	s_waitcnt lgkmcnt(3)
	v_mfma_f32_16x16x32_bf16 v[0:3], v[238:241], v[20:23], v[0:3]
	ds_read_b128 v[238:241], v169 offset:23104
	s_nop 6
	v_exp_f32_e32 v0, v0
	s_waitcnt lgkmcnt(3)
	v_mfma_f32_16x16x32_bf16 v[4:7], v[242:245], v[16:19], v[8:11]
	ds_read_b128 v[242:245], v169 offset:25344
	v_exp_f32_e32 v1, v1
	v_exp_f32_e32 v2, v2
	s_waitcnt lgkmcnt(3)
	v_mfma_f32_16x16x32_bf16 v[4:7], v[246:249], v[20:23], v[4:7]
	ds_read_b128 v[246:249], v169 offset:25408
	v_exp_f32_e32 v3, v3
	s_nop 5
	v_exp_f32_e32 v4, v4
	s_waitcnt lgkmcnt(3)
	v_mfma_f32_16x16x32_bf16 v[8:11], v[226:229], v[16:19], v[12:15]
	v_exp_f32_e32 v5, v5
	v_exp_f32_e32 v6, v6
	s_waitcnt lgkmcnt(2)
	v_mfma_f32_16x16x32_bf16 v[8:11], v[238:241], v[20:23], v[8:11]
	v_exp_f32_e32 v7, v7
	s_nop 6
	v_exp_f32_e32 v8, v8
	s_waitcnt lgkmcnt(1)
	v_mfma_f32_16x16x32_bf16 v[12:15], v[242:245], v[16:19], v[160:163]
	v_exp_f32_e32 v9, v9
	v_exp_f32_e32 v10, v10
	s_waitcnt lgkmcnt(0)
	v_mfma_f32_16x16x32_bf16 v[12:15], v[246:249], v[20:23], v[12:15]
	v_exp_f32_e32 v11, v11
	s_nop 6
	v_exp_f32_e32 v12, v12
	v_exp_f32_e32 v13, v13
	v_exp_f32_e32 v14, v14
	v_exp_f32_e32 v15, v15
	v_mov_b32_e32 v160, v246
	s_cbranch_vccnz .LBB0_362
	v_add_f32_e32 v160, 0, v0
	v_add_f32_e32 v160, v1, v160
	v_add_f32_e32 v160, v2, v160
	v_add_f32_e32 v160, v3, v160
	v_add_f32_e32 v160, v160, v4
	v_add_f32_e32 v160, v5, v160
	v_add_f32_e32 v160, v6, v160
	v_add_f32_e32 v160, v7, v160
	v_add_f32_e32 v160, v160, v8
	v_add_f32_e32 v160, v9, v160
	v_add_f32_e32 v160, v10, v160
	v_add_f32_e32 v160, v11, v160
	v_add_f32_e32 v160, v160, v12
	v_add_f32_e32 v160, v13, v160
	v_add_f32_e32 v160, v14, v160
	v_add_f32_e32 v160, v15, v160
	s_mov_b64 s[6:7], 0

; #define LAS __attribute__((address_space(3)))
; DI f32x4 mfma16(bf16x8 a, bf16x8 b, f32x4 c) { return __builtin_amdgcn_mfma_f32_16x16x32_bf16(a, b, c, 0, 0, 0); }
; DI void nsa_attn_phase(const int tid0, LAS unsigned char* lds, const P& p, int G, int c) {
;     ...
;                 for (int h = 0; h < 2; ++h) {
;                     const int n = na + h; const bool nvalid = (n <= i);
;                     const bool edge = (n == i) || (br == 1 && n == i - 4);
;                     LAS bf16_t* Kt = Tc + h * 9216;
; #pragma unroll
;                     for (int qt = 0; qt < 2; ++qt) {
;                         const bool bsel = nvalid && ((br == 1) || ((sm[qt] >> n) & 1u));
;                         act[h][qt] = nvalid && ((br == 1) || (__ballot(bsel) != 0ull));
;                         pf[h][0][qt] = (bf16x8){0, 0, 0, 0, 0, 0, 0, 0}; pf[h][1][qt] = pf[h][0][qt];
;                         if (act[h][qt]) {
;                             const float sb = bsel ? slope2 * (float)(n * 64 + fq * 4 - tq[qt]) : -1e9f;
;                             f32x4 S[4];
; #pragma unroll
;                             for (int kt = 0; kt < 4; ++kt) { S[kt] = (f32x4){sb + sc16[kt * 4], sb + sc16[kt * 4 + 1], sb + sc16[kt * 4 + 2], sb + sc16[kt * 4 + 3]};
; #pragma unroll
;                                 for (int ks = 0; ks < 2; ++ks) { const bf16x8 kf = *(const LAS bf16x8*)(Kt + (kt * 16 + fr) * 72 + ks * 32 + fq * 8); S[kt] = mfma16(kf, Qf[qt][ks], S[kt]); } }
;                             float ls = 0.f;
;                             if (edge) {
; #pragma unroll
;                                 for (int kt = 0; kt < 4; ++kt)
; #pragma unroll
;                                     for (int j = 0; j < 4; ++j) { const int pos = n * 64 + kt * 16 + fq * 4 + j; const bool valid = (pos <= tq[qt]) && (br == 0 || pos > tq[qt] - 256);
;                                         const float pv = valid ? __builtin_amdgcn_exp2f(S[kt][j]) : 0.f; S[kt][j] = pv; ls += pv; }
;                             } else {
; #pragma unroll
;                                 for (int kt = 0; kt < 4; ++kt)
; #pragma unroll
;                                     for (int j = 0; j < 4; ++j) { const float pv = __builtin_amdgcn_exp2f(S[kt][j]); S[kt][j] = pv; ls += pv; }
;                             }
;                             lrun[qt] += ls;
.LBB0_367:
	ds_read_b128 v[226:229], v169 offset:18432
	ds_read_b128 v[238:241], v169 offset:18496
	ds_read_b128 v[242:245], v169 offset:20736
	ds_read_b128 v[246:249], v169 offset:20800
	s_movk_i32 s12, 0xf870
	v_add3_u32 v0, v190, v220, s12
	v_cvt_f32_i32_e32 v0, v0
	s_mov_b64 s[12:13], -1
	s_and_b64 vcc, exec, s[0:1]
	v_mul_f32_e32 v222, v186, v0
	v_pk_add_f32 v[6:7], v[194:195], v[222:223] op_sel_hi:[1,0]
	v_pk_add_f32 v[4:5], v[192:193], v[222:223] op_sel_hi:[1,0]
	v_pk_add_f32 v[10:11], v[196:197], v[222:223] op_sel_hi:[1,0]
	v_pk_add_f32 v[8:9], v[188:189], v[222:223] op_sel_hi:[1,0]
	v_pk_add_f32 v[14:15], v[200:201], v[222:223] op_sel_hi:[1,0]
	v_pk_add_f32 v[12:13], v[198:199], v[222:223] op_sel_hi:[1,0]
	v_pk_add_f32 v[224:225], v[204:205], v[222:223] op_sel_hi:[1,0]
	s_waitcnt lgkmcnt(3)
	v_mfma_f32_16x16x32_bf16 v[0:3], v[226:229], v[24:27], v[4:7]
	ds_read_b128 v[226:229], v169 offset:23040
	v_pk_add_f32 v[222:223], v[202:203], v[222:223] op_sel_hi:[1,0]
	s_waitcnt lgkmcnt(3)
	v_mfma_f32_16x16x32_bf16 v[0:3], v[238:241], v[28:31], v[0:3]
	ds_read_b128 v[238:241], v169 offset:23104
	s_nop 6
	v_exp_f32_e32 v0, v0
	s_waitcnt lgkmcnt(3)
	v_mfma_f32_16x16x32_bf16 v[4:7], v[242:245], v[24:27], v[8:11]
	ds_read_b128 v[242:245], v169 offset:25344
	v_exp_f32_e32 v1, v1
	v_exp_f32_e32 v2, v2
	s_waitcnt lgkmcnt(3)
	v_mfma_f32_16x16x32_bf16 v[4:7], v[246:249], v[28:31], v[4:7]
	ds_read_b128 v[246:249], v169 offset:25408
	v_exp_f32_e32 v3, v3
	s_nop 5
	v_exp_f32_e32 v4, v4
	s_waitcnt lgkmcnt(3)
	v_mfma_f32_16x16x32_bf16 v[8:11], v[226:229], v[24:27], v[12:15]
	v_exp_f32_e32 v5, v5
	v_exp_f32_e32 v6, v6
	s_waitcnt lgkmcnt(2)
	v_mfma_f32_16x16x32_bf16 v[8:11], v[238:241], v[28:31], v[8:11]
	v_exp_f32_e32 v7, v7
	s_nop 6
	v_exp_f32_e32 v8, v8
	s_waitcnt lgkmcnt(1)
	v_mfma_f32_16x16x32_bf16 v[12:15], v[242:245], v[24:27], v[222:225]
	v_exp_f32_e32 v9, v9
	v_exp_f32_e32 v10, v10
	s_waitcnt lgkmcnt(0)
	v_mfma_f32_16x16x32_bf16 v[12:15], v[246:249], v[28:31], v[12:15]
	v_exp_f32_e32 v11, v11
	s_nop 6
	v_exp_f32_e32 v12, v12
	v_exp_f32_e32 v13, v13
	v_exp_f32_e32 v14, v14
	v_exp_f32_e32 v15, v15
	s_cbranch_vccnz .LBB0_369
	v_add_f32_e32 v169, 0, v0
	v_add_f32_e32 v169, v1, v169
	v_add_f32_e32 v169, v2, v169
	v_add_f32_e32 v169, v3, v169
	v_add_f32_e32 v169, v169, v4
	v_add_f32_e32 v169, v5, v169
	v_add_f32_e32 v169, v6, v169
	v_add_f32_e32 v169, v7, v169
	v_add_f32_e32 v169, v169, v8
	v_add_f32_e32 v169, v9, v169
	v_add_f32_e32 v169, v10, v169
	v_add_f32_e32 v169, v11, v169
	v_add_f32_e32 v169, v169, v12
	v_add_f32_e32 v169, v13, v169
	v_add_f32_e32 v169, v14, v169
	v_add_f32_e32 v169, v15, v169
	s_mov_b64 s[12:13], 0

; #define LAS __attribute__((address_space(3)))
; DI f32x4 mfma16(bf16x8 a, bf16x8 b, f32x4 c) { return __builtin_amdgcn_mfma_f32_16x16x32_bf16(a, b, c, 0, 0, 0); }
; DI void nsa_attn_phase(const int tid0, LAS unsigned char* lds, const P& p, int G, int c) {
;     ...
; #pragma unroll
;                 for (int h = 0; h < 2; ++h) {
;                     LAS bf16_t* VtT = Tc + h * 9216 + 4608;
;                     if (act[h][0] || act[h][1]) {
; #pragma unroll
;                         for (int s = 0; s < 2; ++s)
; #pragma unroll
;                             for (int dt = 0; dt < 4; ++dt) { u32x4 t; const u32x2 v0 = *(const LAS u32x2*)(VtT + (dt * 16 + fr) * 72 + s * 32 + fq * 4), v1 = *(const LAS u32x2*)(VtT + (dt * 16 + fr) * 72 + s * 32 + 16 + fq * 4);
;                                 t.x = v0.x; t.y = v0.y; t.z = v1.x; t.w = v1.y; const bf16x8 vf = __builtin_bit_cast(bf16x8, t);
; #pragma unroll
;                                 for (int qt = 0; qt < 2; ++qt) if (act[h][qt]) O[dt][qt] = mfma16(vf, pf[h][s][qt], O[dt][qt]); } }
;                 }
.LBB0_372:
	s_add_i32 s4, 0, 0x2400
	s_and_b64 s[0:1], s[10:11], exec
	s_cselect_b32 s0, s95, s4
	v_add3_u32 v221, s0, v179, v180
	ds_read2_b64 v[226:229], v221 offset1:4
	v_add_u32_e32 v232, 0x800, v221
	ds_read2_b64 v[238:241], v232 offset0:32 offset1:36
	v_add_u32_e32 v233, 0x1000, v221
	ds_read2_b64 v[242:245], v233 offset0:64 offset1:68
	v_add_u32_e32 v232, 0x1800, v221
	ds_read2_b64 v[246:249], v232 offset0:96 offset1:100
	s_add_i32 s4, 0, 0x2440
	s_add_i32 s5, 0, 0x14040
	s_and_b64 s[0:1], s[10:11], exec
	s_cselect_b32 s0, s5, s4
	s_waitcnt lgkmcnt(3)
	v_mfma_f32_16x16x32_bf16 v[8:11], v[226:229], v[148:151], v[124:127]
	s_waitcnt lgkmcnt(2)
	v_mfma_f32_16x16x32_bf16 v[120:123], v[238:241], v[148:151], v[120:123]
	v_mfma_f32_16x16x32_bf16 v[12:15], v[238:241], v[156:159], v[104:107]
	v_mfma_f32_16x16x32_bf16 v[4:7], v[226:229], v[156:159], v[108:111]
	s_waitcnt lgkmcnt(1)
	v_mfma_f32_16x16x32_bf16 v[116:119], v[242:245], v[148:151], v[116:119]
	v_mfma_f32_16x16x32_bf16 v[100:103], v[242:245], v[156:159], v[100:103]
	s_waitcnt lgkmcnt(0)
	v_mfma_f32_16x16x32_bf16 v[112:115], v[246:249], v[148:151], v[112:115]
	v_add3_u32 v148, s0, v179, v180
	ds_read2_b64 v[238:241], v148 offset1:4
	v_add_u32_e32 v233, 0x800, v148
	ds_read2_b64 v[226:229], v233 offset0:32 offset1:36
	v_add_u32_e32 v232, 0x1000, v148
	ds_read2_b64 v[242:245], v232 offset0:64 offset1:68
	v_mfma_f32_16x16x32_bf16 v[96:99], v[246:249], v[156:159], v[96:99]
	v_add_u32_e32 v233, 0x1800, v148
	ds_read2_b64 v[246:249], v233 offset0:96 offset1:100
	s_waitcnt lgkmcnt(3)
	v_mfma_f32_16x16x32_bf16 v[108:111], v[238:241], v[152:155], v[4:7]
	v_mfma_f32_16x16x32_bf16 v[124:127], v[238:241], v[144:147], v[8:11]
	s_waitcnt lgkmcnt(2)
	v_mfma_f32_16x16x32_bf16 v[120:123], v[226:229], v[144:147], v[120:123]
	v_mfma_f32_16x16x32_bf16 v[104:107], v[226:229], v[152:155], v[12:15]
	s_waitcnt lgkmcnt(1)
	v_mfma_f32_16x16x32_bf16 v[116:119], v[242:245], v[144:147], v[116:119]
	v_mfma_f32_16x16x32_bf16 v[100:103], v[242:245], v[152:155], v[100:103]
	s_waitcnt lgkmcnt(0)
	v_mfma_f32_16x16x32_bf16 v[112:115], v[246:249], v[144:147], v[112:115]
	v_mfma_f32_16x16x32_bf16 v[96:99], v[246:249], v[152:155], v[96:99]
.LBB0_373:
	s_and_b64 vcc, exec, s[6:7]
	s_cbranch_vccnz .LBB0_375
	s_add_i32 s4, 0, 0x6c00
	s_and_b64 s[0:1], s[10:11], exec
	s_cselect_b32 s0, s97, s4
	v_add3_u32 v144, s0, v179, v180
	ds_read2_b64 v[226:229], v144 offset1:4
	v_add_u32_e32 v232, 0x800, v144
	ds_read2_b64 v[238:241], v232 offset0:32 offset1:36
	v_add_u32_e32 v233, 0x1000, v144
	ds_read2_b64 v[242:245], v233 offset0:64 offset1:68
	v_add_u32_e32 v232, 0x1800, v144
	ds_read2_b64 v[246:249], v232 offset0:96 offset1:100
	s_add_i32 s4, 0, 0x6c40
	s_add_i32 s5, 0, 0x18840
	s_and_b64 s[0:1], s[10:11], exec
	s_cselect_b32 s0, s5, s4
	s_waitcnt lgkmcnt(3)
	v_mfma_f32_16x16x32_bf16 v[8:11], v[226:229], v[164:167], v[124:127]
	s_waitcnt lgkmcnt(2)
	v_mfma_f32_16x16x32_bf16 v[120:123], v[238:241], v[164:167], v[120:123]
	v_mfma_f32_16x16x32_bf16 v[12:15], v[238:241], v[168:171], v[104:107]
	v_mfma_f32_16x16x32_bf16 v[4:7], v[226:229], v[168:171], v[108:111]
	s_waitcnt lgkmcnt(1)
	v_mfma_f32_16x16x32_bf16 v[116:119], v[242:245], v[164:167], v[116:119]
	v_mfma_f32_16x16x32_bf16 v[100:103], v[242:245], v[168:171], v[100:103]
	v_add3_u32 v144, s0, v179, v180
	ds_read2_b64 v[238:241], v144 offset1:4
	v_add_u32_e32 v233, 0x800, v144
	ds_read2_b64 v[226:229], v233 offset0:32 offset1:36
	v_add_u32_e32 v232, 0x1000, v144
	ds_read2_b64 v[242:245], v232 offset0:64 offset1:68
	s_waitcnt lgkmcnt(3)
	v_mfma_f32_16x16x32_bf16 v[112:115], v[246:249], v[164:167], v[112:115]
	v_mfma_f32_16x16x32_bf16 v[96:99], v[246:249], v[168:171], v[96:99]
	v_add_u32_e32 v233, 0x1800, v144
	ds_read2_b64 v[246:249], v233 offset0:96 offset1:100
	s_waitcnt lgkmcnt(3)
	v_mfma_f32_16x16x32_bf16 v[108:111], v[238:241], v[0:3], v[4:7]
	v_mfma_f32_16x16x32_bf16 v[124:127], v[238:241], v[160:163], v[8:11]
	s_waitcnt lgkmcnt(2)
	v_mfma_f32_16x16x32_bf16 v[120:123], v[226:229], v[160:163], v[120:123]
	v_mfma_f32_16x16x32_bf16 v[104:107], v[226:229], v[0:3], v[12:15]
	s_waitcnt lgkmcnt(1)
	v_mfma_f32_16x16x32_bf16 v[116:119], v[242:245], v[160:163], v[116:119]
	v_mfma_f32_16x16x32_bf16 v[100:103], v[242:245], v[0:3], v[100:103]
	s_waitcnt lgkmcnt(0)
	v_mfma_f32_16x16x32_bf16 v[112:115], v[246:249], v[160:163], v[112:115]
	v_mfma_f32_16x16x32_bf16 v[96:99], v[246:249], v[0:3], v[96:99]
	s_andn2_b64 vcc, exec, s[8:9]
	s_cbranch_vccz .LBB0_376
	s_branch .LBB0_377

; #define LAS __attribute__((address_space(3)))
; DI void gdn_prep_phase(const int tid, LAS unsigned char* lds, const P& p, int G, int c) {
;     const int hb = tid >> 8, ht = tid & 255, lane = tid & 63, wv = __builtin_amdgcn_readfirstlane(ht >> 6), fr = lane & 15, fq = lane >> 4;
;     LAS unsigned char* base = lds + hb * 65536;
;     LAS bf16_t* Qs = (LAS bf16_t*)base; LAS bf16_t* Ks = Qs + 64 * 136;
;     LAS float* Ls = (LAS float*)(base + 2 * 17408); LAS float* tb = (LAS float*)(base + 3 * 17408);
;     const bf16_t* qkv = (const bf16_t*)(p.ws + A_QKV); const float* blal = (const float*)(p.ws + A_BLAL);
;     const float* convw = p.in[13]; const float* a_log = p.in[14]; const float* dt_bias = p.in[15];
;     bf16_t* Uc = (bf16_t*)(p.ws + CH_U); bf16_t* Wc = (bf16_t*)(p.ws + CH_W); bf16_t* QDc = (bf16_t*)(p.ws + CH_QD); bf16_t* KDTc = (bf16_t*)(p.ws + CH_KDT); bf16_t* INc = (bf16_t*)(p.ws + CH_INTRA); float* GLc = (float*)(p.ws + CH_GL);
;     for (int u = c * 2 + hb; u < 6144; u += 2 * G) {
;         const int n = u & 31, bh = u >> 5, h = bh % 6, b = bh / 6; const size_t cid = (size_t)u;
;         const long tok0 = (long)b * SEQ + n * 64;
;         float xs[64];
;         {
;             const int ch = ht & 127, th = ht >> 7, isv = th, colq = h * 128 + ch, colkv = 768 + isv * 768 + h * 128 + ch, t0 = th * 32;
;             bf16_t qraw[35], kvraw[67];
;             const bool haloq = (n > 0) || (t0 > 0), halokv = (n > 0);
; #pragma unroll
;             for (int e = 0; e < 3; ++e) { qraw[e] = haloq ? qkv[(tok0 + t0 - 3 + e) * 2304 + colq] : (bf16_t)0; kvraw[e] = halokv ? qkv[(tok0 - 3 + e) * 2304 + colkv] : (bf16_t)0; }
; #pragma unroll
;             for (int e = 0; e < 32; ++e) qraw[3 + e] = qkv[(tok0 + t0 + e) * 2304 + colq];
; #pragma unroll
;             for (int e = 0; e < 64; ++e) kvraw[3 + e] = qkv[(tok0 + e) * 2304 + colkv];
.LBB0_591:
	v_ashrrev_i32_e32 v0, 8, v182
	v_readlane_b32 s0, v251, 39
	v_and_b32_e32 v68, 0xff, v182
	v_writelane_b32 v254, s64, 51
	v_add_u32_e32 v70, s0, v0
	s_movk_i32 s0, 0x1800
	s_movk_i32 s6, 0x110
	s_mov_b32 s34, s66
	s_mov_b32 s28, s67
	v_cmp_gt_i32_e32 vcc, s0, v70
	v_readfirstlane_b32 s0, v68
	s_barrier
	s_mov_b64 s[4:5], exec
	v_writelane_b32 v254, s4, 52
	s_nop 1
	v_writelane_b32 v254, s5, 53
	s_and_b64 s[4:5], s[4:5], vcc
	s_mov_b64 exec, s[4:5]
	s_cbranch_execz .LBB0_636
	s_movk_i32 s1, 0x7f
	v_cmp_lt_u32_e64 s[40:41], s1, v68
	s_movk_i32 s1, 0x80
	v_cmp_gt_u32_e64 s[4:5], s1, v68
	v_lshl_add_u32 v69, v0, 16, 0
	v_lshrrev_b32_e32 v0, 7, v68
	v_writelane_b32 v254, s4, 54
	v_and_b32_e32 v72, 0x7f, v182
	v_mul_u32_u24_e32 v1, 0x300, v0
	v_writelane_b32 v254, s5, 55
	v_cmp_eq_u32_e64 s[4:5], 0, v68
	v_or_b32_e32 v1, v1, v72
	v_add_u32_e32 v73, 0x300, v1
	v_writelane_b32 v254, s4, 56
	v_and_b32_e32 v1, 3, v182
	s_lshr_b32 s18, s0, 6
	v_writelane_b32 v254, s5, 57
	v_cmp_eq_u32_e64 s[4:5], 0, v17
	v_cmp_eq_u32_e64 s[58:59], 2, v1
	s_lshl_b32 s1, s18, 4
	v_writelane_b32 v254, s4, 58
	v_cndmask_b32_e64 v10, 3, 2, s[58:59]
	v_cmp_eq_u32_e64 s[60:61], 1, v1
	v_writelane_b32 v254, s5, 59
	v_cmp_gt_u32_e64 s[4:5], 2, v17
	v_cndmask_b32_e64 v10, v10, 1, s[60:61]
	v_cmp_eq_u32_e64 s[62:63], 0, v1
	v_writelane_b32 v254, s4, 60
	v_bfe_u32 v1, v182, 2, 2
	s_waitcnt vmcnt(0)
	v_cndmask_b32_e64 v140, v10, 0, s[62:63]
	v_writelane_b32 v254, s5, 61
	v_cmp_gt_u32_e64 s[4:5], 4, v17
	v_lshrrev_b32_e32 v10, 4, v17
	v_cmp_eq_u32_e32 vcc, v1, v10
	v_writelane_b32 v254, s4, 62
	v_and_b32_e32 v4, 15, v182
	v_or_b32_e32 v11, s1, v4
	v_writelane_b32 v254, s5, 63
	v_cmp_gt_u32_e64 s[4:5], 8, v17
	v_and_b32_e32 v1, 48, v17
	v_mul_lo_u32 v11, v11, s6
	v_writelane_b32 v255, s4, 0
	v_add3_u32 v97, v69, v1, v11
	v_lshl_or_b32 v1, v10, 2, s1
	v_writelane_b32 v255, s5, 1
	v_cmp_gt_u32_e64 s[4:5], 16, v17
	v_or_b32_e32 v11, 1, v1
	v_or_b32_e32 v12, 2, v1
	v_writelane_b32 v255, s4, 2
	v_or_b32_e32 v13, 3, v1
	v_lshlrev_b32_e32 v3, 2, v4
	v_writelane_b32 v255, s5, 3
	s_and_b32 s4, s0, 0xffffffc0
	s_cmp_gt_u32 s0, 63
	v_add_u32_e32 v99, s4, v69
	s_cselect_b64 s[4:5], -1, 0
	v_writelane_b32 v255, s4, 4
	s_cmp_lt_u32 s0, 64
	v_and_b32_e32 v7, 0xfc, v68
	v_writelane_b32 v255, s5, 5
	s_cselect_b64 s[4:5], -1, 0
	s_and_b64 s[4:5], vcc, s[4:5]
	v_writelane_b32 v255, s4, 6
	s_cmp_eq_u32 s18, 1
	v_add_u32_e32 v83, v69, v3
	v_writelane_b32 v255, s5, 7
	s_cselect_b64 s[4:5], -1, 0
	s_and_b64 s[4:5], vcc, s[4:5]
	v_writelane_b32 v255, s4, 8
	s_cmpk_gt_u32 s0, 0x7f
	v_lshrrev_b32_e32 v6, 2, v68
	v_writelane_b32 v255, s5, 9
	s_cselect_b64 s[4:5], -1, 0
	v_writelane_b32 v255, s4, 10
	s_cmp_eq_u32 s18, 2
	v_add_u32_e32 v85, v69, v7
	v_writelane_b32 v255, s5, 11
	s_cselect_b64 s[4:5], -1, 0
	s_and_b64 s[4:5], vcc, s[4:5]
	v_writelane_b32 v255, s4, 12
	s_cmpk_gt_u32 s0, 0xbf
	s_cselect_b64 s[0:1], -1, 0
	v_writelane_b32 v255, s5, 13
	v_writelane_b32 v255, s0, 14
	s_cmp_eq_u32 s18, 3
	v_cmp_gt_u32_e64 s[4:5], v4, v11
	v_writelane_b32 v255, s1, 15
	s_cselect_b64 s[0:1], -1, 0
	s_and_b64 s[0:1], vcc, s[0:1]
	v_writelane_b32 v255, s0, 16
	v_lshlrev_b32_e32 v7, 6, v182
	v_add_u32_e32 v101, v99, v3
	v_writelane_b32 v255, s1, 17
	v_writelane_b32 v255, s4, 18
	v_cmp_lt_u32_e64 s[0:1], v4, v1
	v_lshrrev_b32_e32 v3, 1, v1
	v_writelane_b32 v255, s5, 19
	v_cmp_gt_u32_e64 s[4:5], v4, v12
	v_writelane_b32 v254, s0, 47
	v_mul_u32_u24_e32 v6, 0x110, v6
	v_writelane_b32 v255, s4, 20
	v_writelane_b32 v254, s1, 48
	s_movk_i32 s0, 0x220
	v_writelane_b32 v255, s5, 21
	v_cmp_lt_u32_e64 s[4:5], v4, v12
	v_and_b32_e32 v7, 0xc0, v7
	v_mul_lo_u32 v103, v3, s0
	v_writelane_b32 v255, s4, 22
	v_lshrrev_b32_e32 v3, 1, v12
	v_lshlrev_b32_e32 v74, 5, v0
	v_writelane_b32 v255, s5, 23
	v_cmp_gt_u32_e64 s[4:5], v4, v13
	v_add3_u32 v87, v69, v6, v7
	v_mul_u32_u24_e32 v6, 0x2200, v0
	v_writelane_b32 v255, s4, 24
	v_or_b32_e32 v0, 16, v4
	v_mul_lo_u32 v105, v3, s0
	v_writelane_b32 v255, s5, 25
	v_cmp_lt_u32_e64 s[4:5], v4, v13
	v_lshrrev_b32_e32 v3, 1, v13
	v_mul_lo_u32 v107, v3, s0
	v_writelane_b32 v255, s4, 26
	v_cmp_lt_u32_e64 s[0:1], v0, v1
	v_or_b32_e32 v8, 32, v4
	v_writelane_b32 v255, s5, 27
	v_writelane_b32 v255, s0, 28
	v_or_b32_e32 v9, 48, v4
	v_lshl_add_u32 v93, v0, 3, v69
	v_writelane_b32 v255, s1, 29
	v_cmp_gt_u32_e64 s[0:1], v0, v11
	v_cmp_gt_u32_e64 s[64:65], v4, v1
	v_cmp_gt_u32_e64 s[46:47], v0, v1
	v_writelane_b32 v255, s0, 30
	v_cmp_gt_u32_e64 s[84:85], v0, v13
	v_cmp_lt_u32_e64 s[86:87], v0, v13
	v_writelane_b32 v255, s1, 31
	v_cmp_gt_u32_e64 s[0:1], v0, v12
	v_cmp_gt_u32_e64 s[92:93], v8, v1
	v_cmp_gt_u32_e64 s[12:13], v9, v1
	v_writelane_b32 v255, s0, 32
	v_cmp_lt_u32_e64 s[14:15], v9, v1
	v_ashrrev_i32_e32 v71, 31, v70
	v_writelane_b32 v255, s1, 33
	v_cmp_lt_u32_e64 s[0:1], v0, v12
	v_mov_b32_e32 v75, v181
	v_lshlrev_b32_e32 v2, 1, v72
	v_writelane_b32 v255, s0, 34
	v_lshl_add_u64 v[76:77], v[74:75], 0, -3
	v_add_u32_e32 v75, v69, v2
	v_writelane_b32 v255, s1, 35
	v_cmp_lt_u32_e64 s[0:1], v8, v1
	v_mov_b64_e32 v[0:1], 0x3b600000
	v_lshl_add_u64 v[142:143], v[70:71], 2, v[0:1]
	v_writelane_b32 v255, s0, 36
	v_lshlrev_b64 v[0:1], 14, v[70:71]
	v_lshl_add_u32 v91, v8, 3, v69
	v_writelane_b32 v255, s1, 37
	v_cmp_gt_u32_e64 s[0:1], v8, v11
	v_cmp_gt_u32_e64 s[4:5], v8, v12
	v_cmp_lt_u32_e64 s[6:7], v8, v12
	v_writelane_b32 v255, s0, 38
	v_cmp_gt_u32_e64 s[8:9], v8, v13
	v_cmp_lt_u32_e64 s[10:11], v8, v13
	v_writelane_b32 v255, s1, 39
	v_or_b32_e32 v146, v0, v2
	v_lshlrev_b64 v[2:3], 13, v[70:71]
	s_mov_b64 s[0:1], 0x38600040
	v_lshlrev_b32_e32 v8, 8, v10
	v_lshl_add_u64 v[2:3], v[2:3], 0, s[0:1]
	v_lshl_or_b32 v180, s18, 10, v8
	v_lshl_add_u64 v[148:149], v[180:181], 1, v[2:3]
	v_lshlrev_b32_e32 v180, 6, v11
	v_lshl_add_u64 v[150:151], v[180:181], 1, v[2:3]
	v_lshlrev_b32_e32 v180, 6, v12
	v_and_b32_e32 v81, 48, v182
	v_lshl_add_u64 v[154:155], v[180:181], 1, v[2:3]
	v_lshlrev_b32_e32 v180, 6, v13
	v_add_u32_e32 v5, v69, v81
	v_mul_u32_u24_e32 v7, 0x110, v4
	v_lshl_add_u32 v95, v4, 3, v69
	v_lshl_or_b32 v144, v72, 7, v0
	v_lshlrev_b32_e32 v4, 1, v4
	v_lshl_or_b32 v0, v68, 6, v0
	s_mov_b64 s[0:1], 0x2c600020
	v_lshl_add_u64 v[156:157], v[180:181], 1, v[2:3]
	v_cmp_gt_u32_e64 s[44:45], 64, v68
	v_lshl_add_u32 v79, v68, 2, v69
	v_lshl_add_u32 v89, v9, 3, v69
	v_cmp_gt_u32_e64 s[16:17], v9, v11
	v_mov_b32_e32 v145, v1
	v_mov_b32_e32 v147, v1
	v_or_b32_e32 v148, v148, v4
	v_or_b32_e32 v150, v150, v4
	v_lshl_add_u64 v[152:153], v[0:1], 0, s[0:1]
	v_or_b32_e32 v154, v154, v4
	v_or_b32_e32 v156, v156, v4
	v_add_u32_e32 v71, v75, v6
	v_add_u32_e32 v109, v5, v7
	v_cmp_gt_u32_e64 s[18:19], v9, v12
	v_cmp_lt_u32_e64 s[20:21], v9, v12
	v_cmp_gt_u32_e64 s[22:23], v9, v13
	v_cmp_lt_u32_e64 s[24:25], v9, v13
	s_mov_b64 s[66:67], 0
	s_branch .LBB0_594

; DI void gdn_prep_phase(const int tid, LAS unsigned char* lds, const P& p, int G, int c) {
;     ...
;             const int ch = ht & 127, th = ht >> 7, isv = th, colq = h * 128 + ch, colkv = 768 + isv * 768 + h * 128 + ch, t0 = th * 32;
;             bf16_t qraw[35], kvraw[67];
;             const bool haloq = (n > 0) || (t0 > 0), halokv = (n > 0);
; #pragma unroll
;             for (int e = 0; e < 3; ++e) { qraw[e] = haloq ? qkv[(tok0 + t0 - 3 + e) * 2304 + colq] : (bf16_t)0; kvraw[e] = halokv ? qkv[(tok0 - 3 + e) * 2304 + colkv] : (bf16_t)0; }
; #pragma unroll
;             for (int e = 0; e < 32; ++e) qraw[3 + e] = qkv[(tok0 + t0 + e) * 2304 + colq];
; #pragma unroll
;             for (int e = 0; e < 64; ++e) kvraw[3 + e] = qkv[(tok0 + e) * 2304 + colkv];
;             { const float w0 = convw[colq], w1 = convw[2304 + colq], w2 = convw[4608 + colq], w3 = convw[6912 + colq];
.LBB0_606:
	s_or_b64 exec, exec, s[68:69]
	v_or_b32_e32 v1, v2, v74
	v_mad_u64_u32 v[164:165], s[0:1], v1, s56, v[160:161]
	v_or3_b32 v1, v2, v74, 1
	v_mad_u64_u32 v[28:29], s[0:1], v1, s56, v[160:161]
	v_or3_b32 v1, v2, v74, 2
	v_mad_u64_u32 v[10:11], s[0:1], v1, s56, v[160:161]
	v_or3_b32 v1, v2, v74, 3
	v_mad_u64_u32 v[12:13], s[0:1], v1, s56, v[160:161]
	v_or3_b32 v1, v2, v74, 4
	v_mad_u64_u32 v[14:15], s[0:1], v1, s56, v[160:161]
	v_or3_b32 v1, v2, v74, 5
	v_mad_u64_u32 v[16:17], s[0:1], v1, s56, v[160:161]
	v_or3_b32 v1, v2, v74, 6
	v_mad_u64_u32 v[18:19], s[0:1], v1, s56, v[160:161]
	v_or3_b32 v1, v2, v74, 7
	v_mad_u64_u32 v[20:21], s[0:1], v1, s56, v[160:161]
	v_or3_b32 v1, v2, v74, 8
	v_mad_u64_u32 v[22:23], s[0:1], v1, s56, v[160:161]
	v_or3_b32 v1, v2, v74, 9
	v_mad_u64_u32 v[24:25], s[0:1], v1, s56, v[160:161]
	v_or3_b32 v1, v2, v74, 10
	v_mad_u64_u32 v[26:27], s[0:1], v1, s56, v[160:161]
	v_or3_b32 v1, v2, v74, 11
	v_mad_u64_u32 v[30:31], s[0:1], v1, s56, v[160:161]
	v_or3_b32 v1, v2, v74, 12
	v_mad_u64_u32 v[32:33], s[0:1], v1, s56, v[160:161]
	v_or3_b32 v1, v2, v74, 13
	v_mad_u64_u32 v[34:35], s[0:1], v1, s56, v[160:161]
	v_or3_b32 v1, v2, v74, 14
	v_mad_u64_u32 v[36:37], s[0:1], v1, s56, v[160:161]
	v_or3_b32 v1, v2, v74, 15
	v_mad_u64_u32 v[38:39], s[0:1], v1, s56, v[160:161]
	v_or3_b32 v1, v2, v74, 16
	v_mad_u64_u32 v[40:41], s[0:1], v1, s56, v[160:161]
	v_or3_b32 v1, v2, v74, 17
	v_mad_u64_u32 v[42:43], s[0:1], v1, s56, v[160:161]
	v_or3_b32 v1, v2, v74, 18
	v_mad_u64_u32 v[44:45], s[0:1], v1, s56, v[160:161]
	v_or3_b32 v1, v2, v74, 19
	v_mad_u64_u32 v[46:47], s[0:1], v1, s56, v[160:161]
	v_or3_b32 v1, v2, v74, 20
	v_mad_u64_u32 v[48:49], s[0:1], v1, s56, v[160:161]
	v_or3_b32 v1, v2, v74, 21
	v_mad_u64_u32 v[50:51], s[0:1], v1, s56, v[160:161]
	v_or3_b32 v1, v2, v74, 22
	v_mad_u64_u32 v[52:53], s[0:1], v1, s56, v[160:161]
	v_or3_b32 v1, v2, v74, 23
	v_mad_u64_u32 v[54:55], s[0:1], v1, s56, v[160:161]
	v_or3_b32 v1, v2, v74, 24
	v_mad_u64_u32 v[56:57], s[0:1], v1, s56, v[160:161]
	v_or3_b32 v1, v2, v74, 25
	v_mad_u64_u32 v[58:59], s[0:1], v1, s56, v[160:161]
	v_or3_b32 v1, v2, v74, 26
	v_mad_u64_u32 v[60:61], s[0:1], v1, s56, v[160:161]
	v_or3_b32 v1, v2, v74, 27
	v_mad_u64_u32 v[62:63], s[0:1], v1, s56, v[160:161]
	v_or3_b32 v1, v2, v74, 28
	v_mad_u64_u32 v[64:65], s[0:1], v1, s56, v[160:161]
	v_or3_b32 v1, v2, v74, 29
	v_mad_u64_u32 v[66:67], s[0:1], v1, s56, v[160:161]
	v_or3_b32 v1, v2, v74, 30
	v_mad_u64_u32 v[158:159], s[0:1], v1, s56, v[160:161]
	v_or3_b32 v1, v2, v74, 31
	v_readlane_b32 s68, v253, 52
	v_mad_u64_u32 v[160:161], s[0:1], v1, s56, v[160:161]
	v_readlane_b32 s78, v253, 62
	v_readlane_b32 s79, v253, 63
	s_movk_i32 s1, 0x2000
	v_mul_lo_u32 v6, v3, s56
	v_lshl_add_u64 v[162:163], v[162:163], 2, s[78:79]
	v_add_co_u32_e32 v166, vcc, s1, v162
	v_add_u32_e32 v165, v6, v165
	s_nop 0
	v_addc_co_u32_e32 v167, vcc, 0, v163, vcc
	v_add_u32_e32 v29, v6, v29
	v_add_u32_e32 v11, v6, v11
	v_add_u32_e32 v13, v6, v13
	v_add_u32_e32 v15, v6, v15
	v_add_u32_e32 v17, v6, v17
	v_add_u32_e32 v19, v6, v19
	v_add_u32_e32 v21, v6, v21
	v_add_u32_e32 v23, v6, v23
	v_add_u32_e32 v25, v6, v25
	v_add_u32_e32 v27, v6, v27
	v_add_u32_e32 v31, v6, v31
	v_add_u32_e32 v33, v6, v33
	v_add_u32_e32 v35, v6, v35
	v_add_u32_e32 v37, v6, v37
	v_add_u32_e32 v39, v6, v39
	v_add_u32_e32 v41, v6, v41
	v_add_u32_e32 v43, v6, v43
	v_add_u32_e32 v45, v6, v45
	v_add_u32_e32 v47, v6, v47
	v_add_u32_e32 v49, v6, v49
	v_add_u32_e32 v51, v6, v51
	v_add_u32_e32 v53, v6, v53
	v_add_u32_e32 v55, v6, v55
	v_add_u32_e32 v57, v6, v57
	v_add_u32_e32 v59, v6, v59
	v_add_u32_e32 v61, v6, v61
	v_add_u32_e32 v63, v6, v63
	v_add_u32_e32 v65, v6, v65
	v_add_u32_e32 v67, v6, v67
	v_add_u32_e32 v159, v6, v159
	v_add_u32_e32 v161, v6, v161
	global_load_dword v1, v[162:163], off
	global_load_dword v6, v[166:167], off offset:1024
	s_movk_i32 s26, 0x4000
	v_add_co_u32_e32 v166, vcc, s26, v162
	s_movk_i32 s27, 0x6000
	s_nop 0
	v_addc_co_u32_e32 v167, vcc, 0, v163, vcc
	v_add_co_u32_e32 v162, vcc, s27, v162
	global_load_dword v111, v[166:167], off offset:2048
	s_nop 0
	v_addc_co_u32_e32 v163, vcc, 0, v163, vcc
	global_load_dword v113, v[162:163], off offset:3072
	v_readlane_b32 s69, v253, 53
	v_readlane_b32 s70, v253, 54
	v_readlane_b32 s71, v253, 55
	v_readlane_b32 s72, v253, 56
	v_readlane_b32 s73, v253, 57
	v_readlane_b32 s74, v253, 58
	v_readlane_b32 s75, v253, 59
	v_readlane_b32 s76, v253, 60
	v_readlane_b32 s77, v253, 61
	v_readlane_b32 s80, v254, 0
	v_readlane_b32 s81, v254, 1
	v_readlane_b32 s82, v254, 2
	v_readlane_b32 s83, v254, 3
	s_waitcnt vmcnt(0)
	v_mul_f32_e32 v121, v115, v6
	v_fmac_f32_e32 v121, v119, v1
	global_load_ushort v119, v[164:165], off
	s_waitcnt vmcnt(2)
	v_fmac_f32_e32 v121, v117, v111
	s_waitcnt vmcnt(0)
; DI float bf2f(bf16_t b) { return __uint_as_float(((unsigned)b) << 16); }
; DI float silu_fast(float x) { return x * __builtin_amdgcn_rcpf(1.f + __expf(-x)); }
; DI void gdn_prep_phase(const int tid, LAS unsigned char* lds, const P& p, int G, int c) {
;     ...
;             for (int e = 0; e < 3; ++e) { qraw[e] = haloq ? qkv[(tok0 + t0 - 3 + e) * 2304 + colq] : (bf16_t)0; kvraw[e] = halokv ? qkv[(tok0 - 3 + e) * 2304 + colkv] : (bf16_t)0; }
; #pragma unroll
;             for (int e = 0; e < 32; ++e) qraw[3 + e] = qkv[(tok0 + t0 + e) * 2304 + colq];
; #pragma unroll
;             for (int e = 0; e < 64; ++e) kvraw[3 + e] = qkv[(tok0 + e) * 2304 + colkv];
;             { const float w0 = convw[colq], w1 = convw[2304 + colq], w2 = convw[4608 + colq], w3 = convw[6912 + colq];
; #pragma unroll
;               for (int e = 0; e < 32; ++e) { const float y = w0 * bf2f(qraw[e]) + w1 * bf2f(qraw[e + 1]) + w2 * bf2f(qraw[e + 2]) + w3 * bf2f(qraw[e + 3]); Qs[(t0 + e) * 136 + ch] = f2bf(silu_fast(y)); } }
	v_lshlrev_b32_e32 v171, 16, v119
	v_fmac_f32_e32 v121, v113, v171
	v_mul_f32_e32 v119, 0xbfb8aa3b, v121
	v_exp_f32_e32 v119, v119
	s_nop 0
	v_add_f32_e32 v119, 1.0, v119
	v_rcp_f32_e32 v119, v119
	s_nop 0
	v_mul_f32_e32 v119, v121, v119
	v_cvt_pk_bf16_f32 v177, v119, s0
	s_mov_b32 s0, 0x42000
	global_load_ushort v187, v[28:29], off
	global_load_ushort v186, v[10:11], off
	global_load_ushort v185, v[12:13], off
	global_load_ushort v184, v[14:15], off
	global_load_ushort v183, v[16:17], off
	global_load_ushort v179, v[18:19], off
	global_load_ushort v178, v[20:21], off
	global_load_ushort v176, v[22:23], off
	global_load_ushort v175, v[24:25], off
	global_load_ushort v174, v[26:27], off
	global_load_ushort v173, v[30:31], off
	global_load_ushort v172, v[32:33], off
	global_load_ushort v170, v[34:35], off
	global_load_ushort v169, v[36:37], off
	global_load_ushort v168, v[38:39], off
	global_load_ushort v167, v[40:41], off
	global_load_ushort v166, v[42:43], off
	global_load_ushort v165, v[44:45], off
	global_load_ushort v164, v[46:47], off
	global_load_ushort v162, v[48:49], off
	global_load_ushort v137, v[50:51], off
	global_load_ushort v127, v[52:53], off
	global_load_ushort v121, v[54:55], off
	global_load_ushort v119, v[56:57], off
	global_load_ushort v21, v[58:59], off
	global_load_ushort v20, v[60:61], off
	global_load_ushort v17, v[62:63], off
	global_load_ushort v16, v[64:65], off
	global_load_ushort v14, v[66:67], off
	global_load_ushort v12, v[158:159], off
	global_load_ushort v10, v[160:161], off
	global_load_ushort v11, v[8:9], off
	v_add_co_u32_e32 v18, vcc, s0, v8
	s_mov_b32 s0, 0x43000
	s_nop 0
	v_addc_co_u32_e32 v19, vcc, 0, v9, vcc
	global_load_ushort v13, v[18:19], off offset:1536
	v_add_co_u32_e32 v18, vcc, s0, v8
	s_mov_b32 s0, 0x44000
	s_nop 0
	v_addc_co_u32_e32 v19, vcc, 0, v9, vcc
	global_load_ushort v15, v[18:19], off offset:2048
	v_add_co_u32_e32 v18, vcc, s0, v8
	s_mov_b32 s0, 0x45000
	s_nop 0
	v_addc_co_u32_e32 v19, vcc, 0, v9, vcc
	v_add_co_u32_e32 v22, vcc, s0, v8
	s_mov_b32 s0, 0x46000
	s_nop 0
	v_addc_co_u32_e32 v23, vcc, 0, v9, vcc
	global_load_ushort v18, v[18:19], off offset:2560
	ds_write_b16 v71, v177
	global_load_ushort v19, v[22:23], off offset:3072
	v_add_co_u32_e32 v22, vcc, s0, v8
	s_mov_b32 s0, 0x40000
	s_nop 0
	v_addc_co_u32_e32 v23, vcc, 0, v9, vcc
	v_add_co_u32_e32 v24, vcc, s0, v8
	s_mov_b32 s0, 0x41000
	s_nop 0
	v_addc_co_u32_e32 v25, vcc, 0, v9, vcc
	v_add_co_u32_e32 v26, vcc, s0, v8
	s_mov_b32 s0, 0x3d000
	s_nop 0
	v_addc_co_u32_e32 v27, vcc, 0, v9, vcc
	global_load_ushort v22, v[22:23], off offset:3584
	s_waitcnt vmcnt(0)
	v_lshlrev_b32_e32 v20, 16, v20
	global_load_ushort v24, v[24:25], off offset:512
	s_waitcnt vmcnt(11)
	v_lshlrev_b32_e32 v17, 16, v17
	global_load_ushort v23, v[26:27], off offset:1024
	v_add_co_u32_e32 v26, vcc, s0, v8
	s_mov_b32 s0, 0x3f000
	s_nop 0
	v_addc_co_u32_e32 v27, vcc, 0, v9, vcc
	v_add_co_u32_e32 v28, vcc, s0, v8
	s_mov_b32 s0, 0x3b000
	s_nop 0
	v_addc_co_u32_e32 v29, vcc, 0, v9, vcc
	global_load_ushort v26, v[26:27], off offset:3584
	s_waitcnt vmcnt(11)
	v_lshlrev_b32_e32 v14, 16, v14
	global_load_ushort v25, v[28:29], off
	v_add_co_u32_e32 v28, vcc, s0, v8
	s_mov_b32 s0, 0x3c000
	s_nop 0
	v_addc_co_u32_e32 v29, vcc, 0, v9, vcc
	v_add_co_u32_e32 v30, vcc, s0, v8
	s_mov_b32 s0, 0x39000
	s_nop 0
	v_addc_co_u32_e32 v31, vcc, 0, v9, vcc
	global_load_ushort v27, v[30:31], off offset:3072
	v_add_co_u32_e32 v30, vcc, s0, v8
	s_mov_b32 s0, 0x3a000
	s_nop 0
	v_addc_co_u32_e32 v31, vcc, 0, v9, vcc
	v_add_co_u32_e32 v32, vcc, s0, v8
	s_mov_b32 s0, 0x37000
	s_nop 0
	v_addc_co_u32_e32 v33, vcc, 0, v9, vcc
	global_load_ushort v28, v[28:29], off offset:2560
	s_waitcnt vmcnt(13)
	v_lshlrev_b32_e32 v12, 16, v12
	global_load_ushort v30, v[30:31], off offset:1536
	s_waitcnt vmcnt(8)
	v_lshlrev_b32_e32 v19, 16, v19
	global_load_ushort v29, v[32:33], off offset:2048
	v_add_co_u32_e32 v32, vcc, s0, v8
	s_mov_b32 s0, 0x38000
	s_nop 0
	v_addc_co_u32_e32 v33, vcc, 0, v9, vcc
	v_add_co_u32_e32 v34, vcc, s0, v8
	s_mov_b32 s0, 0x34000
	s_nop 0
	v_addc_co_u32_e32 v35, vcc, 0, v9, vcc
	global_load_ushort v32, v[32:33], off offset:512
	s_waitcnt vmcnt(0)
	v_lshlrev_b32_e32 v23, 16, v23
	global_load_ushort v31, v[34:35], off offset:1024
	v_add_co_u32_e32 v34, vcc, s0, v8
	s_mov_b32 s0, 0x36000
	s_nop 0
	v_addc_co_u32_e32 v35, vcc, 0, v9, vcc
	v_add_co_u32_e32 v36, vcc, s0, v8
	s_mov_b32 s0, 0x32000
	s_nop 0
	v_addc_co_u32_e32 v37, vcc, 0, v9, vcc
	global_load_ushort v34, v[34:35], off offset:3584
	s_waitcnt vmcnt(7)
	v_lshlrev_b32_e32 v25, 16, v25
	global_load_ushort v33, v[36:37], off
	v_add_co_u32_e32 v36, vcc, s0, v8
	s_mov_b32 s0, 0x33000
	s_nop 0
	v_addc_co_u32_e32 v37, vcc, 0, v9, vcc
	v_add_co_u32_e32 v38, vcc, s0, v8
	s_mov_b32 s0, 0x30000
	s_nop 0
	v_addc_co_u32_e32 v39, vcc, 0, v9, vcc
	global_load_ushort v35, v[38:39], off offset:3072
	v_add_co_u32_e32 v38, vcc, s0, v8
	s_mov_b32 s0, 0x31000
	s_nop 0
	v_addc_co_u32_e32 v39, vcc, 0, v9, vcc
	v_add_co_u32_e32 v40, vcc, s0, v8
	s_mov_b32 s0, 0x2e000
	s_nop 0
	v_addc_co_u32_e32 v41, vcc, 0, v9, vcc
	global_load_ushort v36, v[36:37], off offset:2560
	s_waitcnt vmcnt(9)
	v_lshlrev_b32_e32 v27, 16, v27
	global_load_ushort v38, v[38:39], off offset:1536
	s_waitcnt vmcnt(7)
	v_lshlrev_b32_e32 v29, 16, v29
	global_load_ushort v37, v[40:41], off offset:2048
	v_add_co_u32_e32 v40, vcc, s0, v8
	s_mov_b32 s0, 0x2f000
	s_nop 0
	v_addc_co_u32_e32 v41, vcc, 0, v9, vcc
	v_add_co_u32_e32 v42, vcc, s0, v8
	s_mov_b32 s0, 0x2b000
	s_nop 0
	v_addc_co_u32_e32 v43, vcc, 0, v9, vcc
	global_load_ushort v40, v[40:41], off offset:512
	s_waitcnt vmcnt(0)
; DI void gdn_prep_phase(const int tid, LAS unsigned char* lds, const P& p, int G, int c) {
;     ...
;             for (int e = 0; e < 64; ++e) kvraw[3 + e] = qkv[(tok0 + e) * 2304 + colkv];
	v_lshlrev_b32_e32 v31, 16, v31
	global_load_ushort v39, v[42:43], off offset:1024
	v_add_co_u32_e32 v42, vcc, s0, v8
	s_mov_b32 s0, 0x2d000
	s_nop 0
	v_addc_co_u32_e32 v43, vcc, 0, v9, vcc
	v_add_co_u32_e32 v44, vcc, s0, v8
	s_mov_b32 s0, 0x29000
	s_nop 0
	v_addc_co_u32_e32 v45, vcc, 0, v9, vcc
	global_load_ushort v42, v[42:43], off offset:3584
	s_waitcnt vmcnt(7)
	v_lshlrev_b32_e32 v33, 16, v33
	global_load_ushort v41, v[44:45], off
	v_add_co_u32_e32 v44, vcc, s0, v8
	s_mov_b32 s0, 0x2a000
	s_nop 0
	v_addc_co_u32_e32 v45, vcc, 0, v9, vcc
	v_add_co_u32_e32 v46, vcc, s0, v8
	s_mov_b32 s0, 0x27000
	s_nop 0
	v_addc_co_u32_e32 v47, vcc, 0, v9, vcc
	global_load_ushort v43, v[46:47], off offset:3072
	v_add_co_u32_e32 v46, vcc, s0, v8
	s_mov_b32 s0, 0x28000
	s_nop 0
	v_addc_co_u32_e32 v47, vcc, 0, v9, vcc
	v_add_co_u32_e32 v48, vcc, s0, v8
	s_mov_b32 s0, 0x25000
	s_nop 0
	v_addc_co_u32_e32 v49, vcc, 0, v9, vcc
	global_load_ushort v44, v[44:45], off offset:2560
	s_waitcnt vmcnt(9)
	v_lshlrev_b32_e32 v35, 16, v35
	global_load_ushort v46, v[46:47], off offset:1536
	s_waitcnt vmcnt(7)
	v_lshlrev_b32_e32 v37, 16, v37
	global_load_ushort v45, v[48:49], off offset:2048
	v_add_co_u32_e32 v48, vcc, s0, v8
	s_mov_b32 s0, 0x26000
	s_nop 0
	v_addc_co_u32_e32 v49, vcc, 0, v9, vcc
	v_add_co_u32_e32 v50, vcc, s0, v8
	s_mov_b32 s0, 0x22000
	s_nop 0
	v_addc_co_u32_e32 v51, vcc, 0, v9, vcc
	global_load_ushort v48, v[48:49], off offset:512
	s_waitcnt vmcnt(0)
	v_lshlrev_b32_e32 v39, 16, v39
	global_load_ushort v47, v[50:51], off offset:1024
	v_add_co_u32_e32 v50, vcc, s0, v8
	s_mov_b32 s0, 0x24000
	s_nop 0
	v_addc_co_u32_e32 v51, vcc, 0, v9, vcc
	v_add_co_u32_e32 v52, vcc, s0, v8
	s_mov_b32 s0, 0x20000
	s_nop 0
	v_addc_co_u32_e32 v53, vcc, 0, v9, vcc
	global_load_ushort v50, v[50:51], off offset:3584
	s_waitcnt vmcnt(7)
	v_lshlrev_b32_e32 v41, 16, v41
	global_load_ushort v49, v[52:53], off
	v_add_co_u32_e32 v52, vcc, s0, v8
	s_mov_b32 s0, 0x21000
	s_nop 0
	v_addc_co_u32_e32 v53, vcc, 0, v9, vcc
	v_add_co_u32_e32 v54, vcc, s0, v8
	s_mov_b32 s0, 0x1e000
	s_nop 0
	v_addc_co_u32_e32 v55, vcc, 0, v9, vcc
	global_load_ushort v51, v[54:55], off offset:3072
	v_add_co_u32_e32 v54, vcc, s0, v8
	s_mov_b32 s0, 0x1f000
	s_nop 0
	v_addc_co_u32_e32 v55, vcc, 0, v9, vcc
	v_add_co_u32_e32 v56, vcc, s0, v8
	s_mov_b32 s0, 0x1c000
	s_nop 0
	v_addc_co_u32_e32 v57, vcc, 0, v9, vcc
	global_load_ushort v52, v[52:53], off offset:2560
	s_waitcnt vmcnt(9)
	v_lshlrev_b32_e32 v43, 16, v43
	global_load_ushort v54, v[54:55], off offset:1536
	s_waitcnt vmcnt(7)
	v_lshlrev_b32_e32 v45, 16, v45
	global_load_ushort v53, v[56:57], off offset:2048
	v_add_co_u32_e32 v56, vcc, s0, v8
	s_mov_b32 s0, 0x1d000
	s_nop 0
	v_addc_co_u32_e32 v57, vcc, 0, v9, vcc
	v_add_co_u32_e32 v58, vcc, s0, v8
	s_mov_b32 s0, 0x19000
	s_nop 0
	v_addc_co_u32_e32 v59, vcc, 0, v9, vcc
	global_load_ushort v56, v[56:57], off offset:512
	s_waitcnt vmcnt(0)
	v_lshlrev_b32_e32 v47, 16, v47
	global_load_ushort v55, v[58:59], off offset:1024
	v_add_co_u32_e32 v58, vcc, s0, v8
	s_mov_b32 s0, 0x1b000
	s_nop 0
	v_addc_co_u32_e32 v59, vcc, 0, v9, vcc
	v_add_co_u32_e32 v60, vcc, s0, v8
	s_mov_b32 s0, 0x17000
	s_nop 0
	v_addc_co_u32_e32 v61, vcc, 0, v9, vcc
	global_load_ushort v58, v[58:59], off offset:3584
	s_waitcnt vmcnt(7)
	v_lshlrev_b32_e32 v49, 16, v49
	global_load_ushort v57, v[60:61], off
	v_add_co_u32_e32 v60, vcc, s0, v8
	s_mov_b32 s0, 0x18000
	s_nop 0
	v_addc_co_u32_e32 v61, vcc, 0, v9, vcc
	v_add_co_u32_e32 v62, vcc, s0, v8
	s_mov_b32 s0, 0x15000
	s_nop 0
	v_addc_co_u32_e32 v63, vcc, 0, v9, vcc
	global_load_ushort v59, v[62:63], off offset:3072
	v_add_co_u32_e32 v62, vcc, s0, v8
	s_mov_b32 s0, 0x16000
	s_nop 0
	v_addc_co_u32_e32 v63, vcc, 0, v9, vcc
	v_add_co_u32_e32 v64, vcc, s0, v8
	s_mov_b32 s0, 0x13000
	s_nop 0
	v_addc_co_u32_e32 v65, vcc, 0, v9, vcc
	global_load_ushort v60, v[60:61], off offset:2560
	s_waitcnt vmcnt(9)
	v_lshlrev_b32_e32 v51, 16, v51
	global_load_ushort v62, v[62:63], off offset:1536
	s_waitcnt vmcnt(7)
	v_lshlrev_b32_e32 v53, 16, v53
	global_load_ushort v61, v[64:65], off offset:2048
	v_add_co_u32_e32 v64, vcc, s0, v8
	s_mov_b32 s0, 0x14000
	s_nop 0
	v_addc_co_u32_e32 v65, vcc, 0, v9, vcc
	v_add_co_u32_e32 v66, vcc, s0, v8
	s_mov_b32 s0, 0x10000
	s_nop 0
	v_addc_co_u32_e32 v67, vcc, 0, v9, vcc
	global_load_ushort v64, v[64:65], off offset:512
	s_waitcnt vmcnt(0)
	v_lshlrev_b32_e32 v55, 16, v55
	global_load_ushort v63, v[66:67], off offset:1024
	v_add_co_u32_e32 v66, vcc, s0, v8
	s_mov_b32 s0, 0x12000
	s_nop 0
	v_addc_co_u32_e32 v67, vcc, 0, v9, vcc
	v_add_co_u32_e32 v158, vcc, s0, v8
	s_mov_b32 s0, 0xe000
	s_nop 0
	v_addc_co_u32_e32 v159, vcc, 0, v9, vcc
	global_load_ushort v66, v[66:67], off offset:3584
	s_waitcnt vmcnt(7)
	v_lshlrev_b32_e32 v57, 16, v57
	global_load_ushort v65, v[158:159], off
	v_add_co_u32_e32 v158, vcc, s0, v8
	s_mov_b32 s0, 0xf000
	s_nop 0
	v_addc_co_u32_e32 v159, vcc, 0, v9, vcc
	global_load_ushort v123, v[158:159], off offset:2560
	v_add_co_u32_e32 v158, vcc, s0, v8
	s_mov_b32 s0, 0xc000
	s_nop 0
	v_addc_co_u32_e32 v159, vcc, 0, v9, vcc
	global_load_ushort v67, v[158:159], off offset:3072
	v_add_co_u32_e32 v158, vcc, s0, v8
	s_mov_b32 s0, 0xd000
	s_nop 0
	v_addc_co_u32_e32 v159, vcc, 0, v9, vcc
	global_load_ushort v125, v[158:159], off offset:1536
	v_add_co_u32_e32 v158, vcc, s0, v8
	s_mov_b32 s0, 0xa000
	s_nop 0
	v_addc_co_u32_e32 v159, vcc, 0, v9, vcc
	global_load_ushort v129, v[158:159], off offset:2048
	v_add_co_u32_e32 v158, vcc, s0, v8
	s_mov_b32 s0, 0xb000
	s_nop 0
	v_addc_co_u32_e32 v159, vcc, 0, v9, vcc
	global_load_ushort v131, v[158:159], off offset:512
	v_add_co_u32_e32 v158, vcc, s0, v8
	s_movk_i32 s0, 0x7000
	s_nop 0
	v_addc_co_u32_e32 v159, vcc, 0, v9, vcc
	global_load_ushort v133, v[158:159], off offset:1024
	v_add_co_u32_e32 v158, vcc, s0, v8
	s_mov_b32 s0, 0x9000
	s_nop 0
	v_addc_co_u32_e32 v159, vcc, 0, v9, vcc
	global_load_ushort v135, v[158:159], off offset:3584
	v_add_co_u32_e32 v158, vcc, s0, v8
	s_movk_i32 s0, 0x5000
	s_nop 0
	v_addc_co_u32_e32 v159, vcc, 0, v9, vcc
	global_load_ushort v139, v[158:159], off
	v_add_co_u32_e32 v158, vcc, s0, v8
	s_movk_i32 s0, 0x3000
	s_nop 0
	v_addc_co_u32_e32 v159, vcc, 0, v9, vcc
	global_load_ushort v141, v[158:159], off offset:2560
	v_add_co_u32_e32 v158, vcc, s27, v8
	s_waitcnt vmcnt(13)
; DI float bf2f(bf16_t b) { return __uint_as_float(((unsigned)b) << 16); }
; DI float silu_fast(float x) { return x * __builtin_amdgcn_rcpf(1.f + __expf(-x)); }
; DI void gdn_prep_phase(const int tid, LAS unsigned char* lds, const P& p, int G, int c) {
;     ...
;             for (int e = 0; e < 64; ++e) kvraw[3 + e] = qkv[(tok0 + e) * 2304 + colkv];
;             { const float w0 = convw[colq], w1 = convw[2304 + colq], w2 = convw[4608 + colq], w3 = convw[6912 + colq];
; #pragma unroll
;               for (int e = 0; e < 32; ++e) { const float y = w0 * bf2f(qraw[e]) + w1 * bf2f(qraw[e + 1]) + w2 * bf2f(qraw[e + 2]) + w3 * bf2f(qraw[e + 3]); Qs[(t0 + e) * 136 + ch] = f2bf(silu_fast(y)); } }
	v_lshlrev_b32_e32 v61, 16, v61
	v_addc_co_u32_e32 v159, vcc, 0, v9, vcc
	v_add_co_u32_e32 v160, vcc, s0, v8
	global_load_ushort v158, v[158:159], off offset:3072
	s_nop 0
	v_addc_co_u32_e32 v161, vcc, 0, v9, vcc
	global_load_ushort v159, v[160:161], off offset:1536
	v_add_co_u32_e32 v160, vcc, s26, v8
	s_movk_i32 s0, 0x1000
	s_nop 0
	v_addc_co_u32_e32 v161, vcc, 0, v9, vcc
	v_add_co_u32_e32 v188, vcc, s0, v8
	global_load_ushort v161, v[160:161], off offset:2048
	s_nop 0
	v_addc_co_u32_e32 v189, vcc, 0, v9, vcc
	v_add_co_u32_e32 v8, vcc, s1, v8
	s_waitcnt vmcnt(0)
	v_lshlrev_b32_e32 v63, 16, v63
	v_addc_co_u32_e32 v9, vcc, 0, v9, vcc
	global_load_ushort v163, v[8:9], off offset:1024
	v_mul_f32_e32 v8, v117, v6
	v_fmac_f32_e32 v8, v115, v1
	v_fmac_f32_e32 v8, v111, v171
	v_lshlrev_b32_e32 v9, 16, v187
	v_fmac_f32_e32 v8, v113, v9
	v_mul_f32_e32 v115, 0xbfb8aa3b, v8
	v_exp_f32_e32 v115, v115
	global_load_ushort v160, v[188:189], off offset:512
	s_waitcnt vmcnt(14)
	v_lshlrev_b32_e32 v65, 16, v65
	v_lshlrev_b32_e32 v59, 16, v59
	v_add_f32_e32 v115, 1.0, v115
	v_rcp_f32_e32 v115, v115
	s_waitcnt vmcnt(12)
	v_lshlrev_b32_e32 v67, 16, v67
	v_mul_f32_e32 v8, v8, v115
	v_cvt_pk_bf16_f32 v8, v8, s0
	ds_write_b16 v71, v8 offset:272
	v_mul_f32_e32 v8, v6, v171
	v_fmac_f32_e32 v8, v117, v1
	v_fmac_f32_e32 v8, v111, v9
	v_lshlrev_b32_e32 v115, 16, v186
	v_fmac_f32_e32 v8, v113, v115
	v_mul_f32_e32 v117, 0xbfb8aa3b, v8
	v_exp_f32_e32 v117, v117
	s_waitcnt vmcnt(0)
	v_lshlrev_b32_e32 v160, 16, v160
	v_add_f32_e32 v117, 1.0, v117
	v_rcp_f32_e32 v117, v117
	s_nop 0
	v_mul_f32_e32 v8, v8, v117
	v_cvt_pk_bf16_f32 v8, v8, s0
	ds_write_b16 v71, v8 offset:544
	v_mul_f32_e32 v8, v6, v9
	v_fmac_f32_e32 v8, v1, v171
	v_fmac_f32_e32 v8, v111, v115
	v_lshlrev_b32_e32 v117, 16, v185
	v_fmac_f32_e32 v8, v113, v117
	v_mul_f32_e32 v171, 0xbfb8aa3b, v8
	v_exp_f32_e32 v171, v171
	s_nop 0
	v_add_f32_e32 v171, 1.0, v171
	v_rcp_f32_e32 v171, v171
	s_nop 0
	v_mul_f32_e32 v8, v8, v171
	v_cvt_pk_bf16_f32 v8, v8, s0
	ds_write_b16 v71, v8 offset:816
	v_mul_f32_e32 v8, v6, v115
	v_fmac_f32_e32 v8, v1, v9
	v_fmac_f32_e32 v8, v111, v117
	v_lshlrev_b32_e32 v9, 16, v184
	v_fmac_f32_e32 v8, v113, v9
	v_mul_f32_e32 v171, 0xbfb8aa3b, v8
	v_exp_f32_e32 v171, v171
	s_nop 0
	v_add_f32_e32 v171, 1.0, v171
	v_rcp_f32_e32 v171, v171
	s_nop 0
	v_mul_f32_e32 v8, v8, v171
	v_cvt_pk_bf16_f32 v8, v8, s0
	ds_write_b16 v71, v8 offset:1088
	v_mul_f32_e32 v8, v6, v117
	v_fmac_f32_e32 v8, v1, v115
	v_fmac_f32_e32 v8, v111, v9
	v_lshlrev_b32_e32 v115, 16, v183
	v_fmac_f32_e32 v8, v113, v115
	v_mul_f32_e32 v171, 0xbfb8aa3b, v8
	v_exp_f32_e32 v171, v171
	s_nop 0
	v_add_f32_e32 v171, 1.0, v171
	v_rcp_f32_e32 v171, v171
	s_nop 0
	v_mul_f32_e32 v8, v8, v171
	v_cvt_pk_bf16_f32 v8, v8, s0
	ds_write_b16 v71, v8 offset:1360
	v_mul_f32_e32 v8, v6, v9
	v_fmac_f32_e32 v8, v1, v117
	v_fmac_f32_e32 v8, v111, v115
	v_lshlrev_b32_e32 v117, 16, v179
	v_fmac_f32_e32 v8, v113, v117
	v_mul_f32_e32 v171, 0xbfb8aa3b, v8
	v_exp_f32_e32 v171, v171
	s_nop 0
	v_add_f32_e32 v171, 1.0, v171
	v_rcp_f32_e32 v171, v171
	s_nop 0
	v_mul_f32_e32 v8, v8, v171
	v_cvt_pk_bf16_f32 v8, v8, s0
	ds_write_b16 v71, v8 offset:1632
	v_mul_f32_e32 v8, v6, v115
	v_fmac_f32_e32 v8, v1, v9
	v_fmac_f32_e32 v8, v111, v117
	v_lshlrev_b32_e32 v9, 16, v178
	v_fmac_f32_e32 v8, v113, v9
	v_mul_f32_e32 v171, 0xbfb8aa3b, v8
	v_exp_f32_e32 v171, v171
	s_nop 0
	v_add_f32_e32 v171, 1.0, v171
	v_rcp_f32_e32 v171, v171
	s_nop 0
	v_mul_f32_e32 v8, v8, v171
	v_cvt_pk_bf16_f32 v8, v8, s0
	ds_write_b16 v71, v8 offset:1904
	v_mul_f32_e32 v8, v6, v117
	v_fmac_f32_e32 v8, v1, v115
	v_fmac_f32_e32 v8, v111, v9
	v_lshlrev_b32_e32 v115, 16, v176
	v_fmac_f32_e32 v8, v113, v115
	v_mul_f32_e32 v171, 0xbfb8aa3b, v8
	v_exp_f32_e32 v171, v171
	s_nop 0
	v_add_f32_e32 v171, 1.0, v171
	v_rcp_f32_e32 v171, v171
	s_nop 0
	v_mul_f32_e32 v8, v8, v171
	v_cvt_pk_bf16_f32 v8, v8, s0
	ds_write_b16 v71, v8 offset:2176
	v_mul_f32_e32 v8, v6, v9
	v_fmac_f32_e32 v8, v1, v117
	v_fmac_f32_e32 v8, v111, v115
	v_lshlrev_b32_e32 v117, 16, v175
	v_fmac_f32_e32 v8, v113, v117
	v_mul_f32_e32 v171, 0xbfb8aa3b, v8
	v_exp_f32_e32 v171, v171
	v_lshlrev_b32_e32 v175, 16, v161
	v_lshlrev_b32_e32 v161, 16, v163
	v_add_f32_e32 v171, 1.0, v171
	v_rcp_f32_e32 v171, v171
	s_nop 0
	v_mul_f32_e32 v8, v8, v171
	v_cvt_pk_bf16_f32 v8, v8, s0
	ds_write_b16 v71, v8 offset:2448
	v_mul_f32_e32 v8, v6, v115
	v_fmac_f32_e32 v8, v1, v9
	v_fmac_f32_e32 v8, v111, v117
	v_lshlrev_b32_e32 v9, 16, v174
	v_fmac_f32_e32 v8, v113, v9
	v_mul_f32_e32 v171, 0xbfb8aa3b, v8
	v_exp_f32_e32 v171, v171
	v_lshlrev_b32_e32 v174, 16, v159
	v_add_f32_e32 v171, 1.0, v171
	v_rcp_f32_e32 v171, v171
	s_nop 0
	v_mul_f32_e32 v8, v8, v171
	v_cvt_pk_bf16_f32 v8, v8, s0
	ds_write_b16 v71, v8 offset:2720
	v_mul_f32_e32 v8, v6, v117
	v_fmac_f32_e32 v8, v1, v115
	v_fmac_f32_e32 v8, v111, v9
	v_lshlrev_b32_e32 v115, 16, v173
	v_fmac_f32_e32 v8, v113, v115
	v_mul_f32_e32 v171, 0xbfb8aa3b, v8
	v_exp_f32_e32 v171, v171
	v_lshlrev_b32_e32 v173, 16, v158
	v_add_f32_e32 v171, 1.0, v171
	v_rcp_f32_e32 v171, v171
	s_nop 0
	v_mul_f32_e32 v8, v8, v171
	v_cvt_pk_bf16_f32 v8, v8, s0
	ds_write_b16 v71, v8 offset:2992
	v_mul_f32_e32 v8, v6, v9
	v_fmac_f32_e32 v8, v1, v117
	v_fmac_f32_e32 v8, v111, v115
	v_lshlrev_b32_e32 v117, 16, v172
	v_fmac_f32_e32 v8, v113, v117
	v_mul_f32_e32 v171, 0xbfb8aa3b, v8
	v_exp_f32_e32 v171, v171
	v_lshlrev_b32_e32 v172, 16, v141
	v_add_f32_e32 v171, 1.0, v171
	v_rcp_f32_e32 v171, v171
	s_nop 0
	v_mul_f32_e32 v8, v8, v171
	v_cvt_pk_bf16_f32 v8, v8, s0
	ds_write_b16 v71, v8 offset:3264
	v_mul_f32_e32 v8, v6, v115
	v_fmac_f32_e32 v8, v1, v9
; DI float bf2f(bf16_t b) { return __uint_as_float(((unsigned)b) << 16); }
; DI float silu_fast(float x) { return x * __builtin_amdgcn_rcpf(1.f + __expf(-x)); }
; DI void gdn_prep_phase(const int tid, LAS unsigned char* lds, const P& p, int G, int c) {
;     ...
; #pragma unroll
;               for (int e = 0; e < 32; ++e) { const float y = w0 * bf2f(qraw[e]) + w1 * bf2f(qraw[e + 1]) + w2 * bf2f(qraw[e + 2]) + w3 * bf2f(qraw[e + 3]); Qs[(t0 + e) * 136 + ch] = f2bf(silu_fast(y)); } }
	v_fmac_f32_e32 v8, v111, v117
	v_lshlrev_b32_e32 v9, 16, v170
	v_fmac_f32_e32 v8, v113, v9
	v_mul_f32_e32 v170, 0xbfb8aa3b, v8
	v_exp_f32_e32 v170, v170
	v_lshlrev_b32_e32 v171, 16, v139
	v_add_f32_e32 v170, 1.0, v170
	v_rcp_f32_e32 v170, v170
	s_nop 0
	v_mul_f32_e32 v8, v8, v170
	v_cvt_pk_bf16_f32 v8, v8, s0
	ds_write_b16 v71, v8 offset:3536
	v_mul_f32_e32 v8, v6, v117
	v_fmac_f32_e32 v8, v1, v115
	v_fmac_f32_e32 v8, v111, v9
	v_lshlrev_b32_e32 v115, 16, v169
	v_fmac_f32_e32 v8, v113, v115
	v_mul_f32_e32 v169, 0xbfb8aa3b, v8
	v_exp_f32_e32 v169, v169
	v_lshlrev_b32_e32 v170, 16, v135
	v_add_f32_e32 v169, 1.0, v169
	v_rcp_f32_e32 v169, v169
	s_nop 0
	v_mul_f32_e32 v8, v8, v169
	v_cvt_pk_bf16_f32 v8, v8, s0
	ds_write_b16 v71, v8 offset:3808
	v_mul_f32_e32 v8, v6, v9
	v_fmac_f32_e32 v8, v1, v117
	v_fmac_f32_e32 v8, v111, v115
	v_lshlrev_b32_e32 v117, 16, v168
	v_fmac_f32_e32 v8, v113, v117
	v_mul_f32_e32 v168, 0xbfb8aa3b, v8
	v_exp_f32_e32 v168, v168
	v_lshlrev_b32_e32 v169, 16, v11
	v_add_f32_e32 v168, 1.0, v168
	v_rcp_f32_e32 v168, v168
	s_nop 0
	v_mul_f32_e32 v8, v8, v168
	v_cvt_pk_bf16_f32 v8, v8, s0
	ds_write_b16 v71, v8 offset:4080
	v_mul_f32_e32 v8, v6, v115
	v_fmac_f32_e32 v8, v1, v9
	v_fmac_f32_e32 v8, v111, v117
	v_lshlrev_b32_e32 v9, 16, v167
	v_fmac_f32_e32 v8, v113, v9
	v_mul_f32_e32 v167, 0xbfb8aa3b, v8
	v_exp_f32_e32 v167, v167
	v_mov_b32_e32 v168, v7
	v_add_f32_e32 v167, 1.0, v167
	v_rcp_f32_e32 v167, v167
	s_nop 0
	v_mul_f32_e32 v8, v8, v167
	v_cvt_pk_bf16_f32 v8, v8, s0
	ds_write_b16 v71, v8 offset:4352
	v_mul_f32_e32 v8, v6, v117
	v_fmac_f32_e32 v8, v1, v115
	v_fmac_f32_e32 v8, v111, v9
	v_lshlrev_b32_e32 v115, 16, v166
	v_fmac_f32_e32 v8, v113, v115
	v_mul_f32_e32 v166, 0xbfb8aa3b, v8
	v_exp_f32_e32 v166, v166
	v_lshlrev_b32_e32 v167, 16, v129
	v_add_f32_e32 v166, 1.0, v166
	v_rcp_f32_e32 v166, v166
	s_nop 0
	v_mul_f32_e32 v8, v8, v166
	v_cvt_pk_bf16_f32 v8, v8, s0
	ds_write_b16 v71, v8 offset:4624
	v_mul_f32_e32 v8, v6, v9
	v_fmac_f32_e32 v8, v1, v117
	v_fmac_f32_e32 v8, v111, v115
	v_lshlrev_b32_e32 v117, 16, v165
	v_fmac_f32_e32 v8, v113, v117
	v_mul_f32_e32 v165, 0xbfb8aa3b, v8
	v_exp_f32_e32 v165, v165
	v_lshlrev_b32_e32 v166, 16, v125
	v_add_f32_e32 v165, 1.0, v165
	v_rcp_f32_e32 v165, v165
	s_nop 0
	v_mul_f32_e32 v8, v8, v165
	v_cvt_pk_bf16_f32 v8, v8, s0
	ds_write_b16 v71, v8 offset:4896
	v_mul_f32_e32 v8, v6, v115
	v_fmac_f32_e32 v8, v1, v9
	v_fmac_f32_e32 v8, v111, v117
	v_lshlrev_b32_e32 v9, 16, v164
	v_fmac_f32_e32 v8, v113, v9
	v_mul_f32_e32 v164, 0xbfb8aa3b, v8
	v_exp_f32_e32 v164, v164
	v_lshlrev_b32_e32 v165, 16, v133
	v_add_f32_e32 v164, 1.0, v164
	v_rcp_f32_e32 v164, v164
	s_nop 0
	v_mul_f32_e32 v8, v8, v164
	v_cvt_pk_bf16_f32 v8, v8, s0
	ds_write_b16 v71, v8 offset:5168
	v_mul_f32_e32 v8, v6, v117
	v_fmac_f32_e32 v8, v1, v115
	v_fmac_f32_e32 v8, v111, v9
	v_lshlrev_b32_e32 v115, 16, v162
	v_fmac_f32_e32 v8, v113, v115
	v_mul_f32_e32 v162, 0xbfb8aa3b, v8
	v_exp_f32_e32 v162, v162
	v_lshlrev_b32_e32 v164, 16, v131
	v_add_f32_e32 v162, 1.0, v162
	v_rcp_f32_e32 v162, v162
	s_nop 0
	v_mul_f32_e32 v8, v8, v162
	v_cvt_pk_bf16_f32 v8, v8, s0
	ds_write_b16 v71, v8 offset:5440
	v_mul_f32_e32 v8, v6, v9
	v_fmac_f32_e32 v8, v1, v117
	v_fmac_f32_e32 v8, v111, v115
	v_lshlrev_b32_e32 v117, 16, v137
	v_fmac_f32_e32 v8, v113, v117
	v_mul_f32_e32 v137, 0xbfb8aa3b, v8
	v_exp_f32_e32 v137, v137
	v_pk_mov_b32 v[162:163], v[160:161], v[174:175] op_sel:[1,0]
	v_add_f32_e32 v137, 1.0, v137
	v_rcp_f32_e32 v137, v137
	s_nop 0
	v_mul_f32_e32 v8, v8, v137
	v_cvt_pk_bf16_f32 v8, v8, s0
	ds_write_b16 v71, v8 offset:5712
	v_mul_f32_e32 v8, v6, v115
	v_fmac_f32_e32 v8, v1, v9
	v_fmac_f32_e32 v8, v111, v117
	v_lshlrev_b32_e32 v9, 16, v127
	v_fmac_f32_e32 v8, v113, v9
	v_mul_f32_e32 v127, 0xbfb8aa3b, v8
	v_exp_f32_e32 v127, v127
	s_nop 0
	v_add_f32_e32 v127, 1.0, v127
	v_rcp_f32_e32 v127, v127
	s_nop 0
	v_mul_f32_e32 v8, v8, v127
	v_cvt_pk_bf16_f32 v8, v8, s0
	ds_write_b16 v71, v8 offset:5984
	v_mul_f32_e32 v8, v6, v117
	v_fmac_f32_e32 v8, v1, v115
	v_fmac_f32_e32 v8, v111, v9
	v_lshlrev_b32_e32 v115, 16, v121
	v_fmac_f32_e32 v8, v113, v115
	v_mul_f32_e32 v121, 0xbfb8aa3b, v8
	v_exp_f32_e32 v121, v121
	s_nop 0
	v_add_f32_e32 v121, 1.0, v121
	v_rcp_f32_e32 v121, v121
	s_nop 0
	v_mul_f32_e32 v8, v8, v121
	v_cvt_pk_bf16_f32 v8, v8, s0
	ds_write_b16 v71, v8 offset:6256
	v_mul_f32_e32 v8, v6, v9
	v_fmac_f32_e32 v8, v1, v117
	v_fmac_f32_e32 v8, v111, v115
	v_lshlrev_b32_e32 v117, 16, v119
	v_fmac_f32_e32 v8, v113, v117
	v_mul_f32_e32 v119, 0xbfb8aa3b, v8
	v_exp_f32_e32 v119, v119
	s_nop 0
	v_add_f32_e32 v119, 1.0, v119
	v_rcp_f32_e32 v119, v119
	s_nop 0
	v_mul_f32_e32 v8, v8, v119
	v_cvt_pk_bf16_f32 v8, v8, s0
	ds_write_b16 v71, v8 offset:6528
	v_mul_f32_e32 v8, v6, v115
	v_fmac_f32_e32 v8, v1, v9
	v_fmac_f32_e32 v8, v111, v117
	v_lshlrev_b32_e32 v9, 16, v21
	v_fmac_f32_e32 v8, v113, v9
	v_mul_f32_e32 v21, 0xbfb8aa3b, v8
	v_exp_f32_e32 v21, v21
	s_nop 0
	v_add_f32_e32 v21, 1.0, v21
	v_rcp_f32_e32 v21, v21
	s_nop 0
	v_mul_f32_e32 v8, v8, v21
	v_cvt_pk_bf16_f32 v8, v8, s0
	ds_write_b16 v71, v8 offset:6800
	v_mul_f32_e32 v8, v6, v117
	v_fmac_f32_e32 v8, v1, v115
	v_fmac_f32_e32 v8, v111, v9
	v_fmac_f32_e32 v8, v113, v20
	v_mul_f32_e32 v21, 0xbfb8aa3b, v8
	v_exp_f32_e32 v21, v21
	s_nop 0
	v_add_f32_e32 v21, 1.0, v21
	v_rcp_f32_e32 v21, v21
	s_nop 0
	v_mul_f32_e32 v8, v8, v21
	v_cvt_pk_bf16_f32 v8, v8, s0
	ds_write_b16 v71, v8 offset:7072
	v_mul_f32_e32 v8, v6, v9
	v_fmac_f32_e32 v8, v1, v117
	v_fmac_f32_e32 v8, v111, v20
	v_fmac_f32_e32 v8, v113, v17
	v_mul_f32_e32 v21, 0xbfb8aa3b, v8
	v_exp_f32_e32 v21, v21
	s_nop 0
	v_add_f32_e32 v21, 1.0, v21
; DI float bf2f(bf16_t b) { return __uint_as_float(((unsigned)b) << 16); }
; DI float silu_fast(float x) { return x * __builtin_amdgcn_rcpf(1.f + __expf(-x)); }
; DI void gdn_prep_phase(const int tid, LAS unsigned char* lds, const P& p, int G, int c) {
;     ...
;               for (int e = 0; e < 32; ++e) { const float y = w0 * bf2f(qraw[e]) + w1 * bf2f(qraw[e + 1]) + w2 * bf2f(qraw[e + 2]) + w3 * bf2f(qraw[e + 3]); Qs[(t0 + e) * 136 + ch] = f2bf(silu_fast(y)); } }
;             { const float w0 = convw[colkv], w1 = convw[2304 + colkv], w2 = convw[4608 + colkv], w3 = convw[6912 + colkv];
; #pragma unroll
;               for (int e = 0; e < 64; ++e) { const float y = w0 * bf2f(kvraw[e]) + w1 * bf2f(kvraw[e + 1]) + w2 * bf2f(kvraw[e + 2]) + w3 * bf2f(kvraw[e + 3]); xs[e] = silu_fast(y); }
	v_rcp_f32_e32 v21, v21
	s_nop 0
	v_mul_f32_e32 v8, v8, v21
	v_cvt_pk_bf16_f32 v8, v8, s0
	ds_write_b16 v71, v8 offset:7344
	v_mul_f32_e32 v8, v6, v20
	v_fmac_f32_e32 v8, v1, v9
	v_fmac_f32_e32 v8, v111, v17
	v_lshlrev_b32_e32 v9, 16, v16
	v_fmac_f32_e32 v8, v113, v9
	v_mul_f32_e32 v16, 0xbfb8aa3b, v8
	v_exp_f32_e32 v16, v16
	s_nop 0
	v_add_f32_e32 v16, 1.0, v16
	v_rcp_f32_e32 v16, v16
	s_nop 0
	v_mul_f32_e32 v8, v8, v16
	v_cvt_pk_bf16_f32 v8, v8, s0
	ds_write_b16 v71, v8 offset:7616
	v_mul_f32_e32 v8, v6, v17
	v_fmac_f32_e32 v8, v1, v20
	v_fmac_f32_e32 v8, v111, v9
	v_fmac_f32_e32 v8, v113, v14
	v_mul_f32_e32 v16, 0xbfb8aa3b, v8
	v_exp_f32_e32 v16, v16
	s_nop 0
	v_add_f32_e32 v16, 1.0, v16
	v_rcp_f32_e32 v16, v16
	s_nop 0
	v_mul_f32_e32 v8, v8, v16
	v_cvt_pk_bf16_f32 v8, v8, s0
	ds_write_b16 v71, v8 offset:7888
	v_mul_f32_e32 v8, v6, v9
	v_fmac_f32_e32 v8, v1, v17
	v_fmac_f32_e32 v8, v111, v14
	v_fmac_f32_e32 v8, v113, v12
	v_mul_f32_e32 v16, 0xbfb8aa3b, v8
	v_exp_f32_e32 v16, v16
	v_mul_f32_e32 v6, v6, v14
	v_fmac_f32_e32 v6, v1, v9
	v_lshlrev_b32_e32 v1, 16, v10
	v_add_f32_e32 v16, 1.0, v16
	v_rcp_f32_e32 v16, v16
	v_fmac_f32_e32 v6, v111, v12
	v_fmac_f32_e32 v6, v113, v1
	v_mul_f32_e32 v1, 0xbfb8aa3b, v6
	v_mul_f32_e32 v8, v8, v16
	v_lshl_add_u64 v[16:17], v[180:181], 2, s[78:79]
	v_add_co_u32_e32 v20, vcc, s1, v16
	v_cvt_pk_bf16_f32 v8, v8, s0
	s_nop 0
	v_addc_co_u32_e32 v21, vcc, 0, v17, vcc
	ds_write_b16 v71, v8 offset:8160
	global_load_dword v8, v[16:17], off
	global_load_dword v10, v[20:21], off offset:1024
	v_add_co_u32_e32 v20, vcc, s26, v16
	v_exp_f32_e32 v1, v1
	s_nop 0
	v_addc_co_u32_e32 v21, vcc, 0, v17, vcc
	v_add_co_u32_e32 v16, vcc, s27, v16
	global_load_dword v12, v[20:21], off offset:2048
	s_nop 0
	v_addc_co_u32_e32 v17, vcc, 0, v17, vcc
	global_load_dword v14, v[16:17], off offset:3072
	v_add_f32_e32 v1, 1.0, v1
	v_rcp_f32_e32 v1, v1
	v_lshlrev_b32_e32 v9, 16, v22
	v_lshlrev_b32_e32 v22, 16, v24
	v_lshlrev_b32_e32 v24, 16, v26
	v_mul_f32_e32 v1, v6, v1
	v_mov_b32_e32 v6, v5
	v_cvt_pk_bf16_f32 v1, v1, s0
	ds_write_b16 v71, v1 offset:8432
	v_lshlrev_b32_e32 v26, 16, v28
	v_lshlrev_b32_e32 v28, 16, v30
	v_lshlrev_b32_e32 v30, 16, v32
	v_lshlrev_b32_e32 v32, 16, v34
	v_lshlrev_b32_e32 v34, 16, v36
	v_lshlrev_b32_e32 v36, 16, v38
	v_lshlrev_b32_e32 v38, 16, v40
	v_lshlrev_b32_e32 v40, 16, v42
	v_lshlrev_b32_e32 v42, 16, v44
	v_lshlrev_b32_e32 v44, 16, v46
	v_lshlrev_b32_e32 v46, 16, v48
	v_lshlrev_b32_e32 v48, 16, v50
	v_lshlrev_b32_e32 v50, 16, v52
	v_lshlrev_b32_e32 v52, 16, v54
	v_lshlrev_b32_e32 v54, 16, v56
	v_lshlrev_b32_e32 v56, 16, v58
	v_lshlrev_b32_e32 v58, 16, v60
	v_lshlrev_b32_e32 v60, 16, v62
	v_lshlrev_b32_e32 v62, 16, v64
	v_lshlrev_b32_e32 v64, 16, v66
	v_lshlrev_b32_e32 v66, 16, v123
	v_lshlrev_b32_e32 v16, 16, v13
	v_lshlrev_b32_e32 v17, 16, v15
	v_lshlrev_b32_e32 v21, 16, v18
	v_mov_b32_e32 v20, v17
	v_mov_b32_e32 v18, v21
	s_waitcnt vmcnt(0)
	v_pk_mul_f32 v[158:159], v[6:7], v[10:11] op_sel_hi:[1,0]
	s_nop 0
	v_pk_fma_f32 v[4:5], v[4:5], v[8:9], v[158:159] op_sel_hi:[1,0,1]
	v_mov_b32_e32 v158, v169
	v_mov_b32_e32 v159, v160
	v_mov_b32_e32 v11, v8
	v_mov_b32_e32 v6, v160
	v_pk_mul_f32 v[6:7], v[6:7], v[10:11]
	s_waitcnt vmcnt(1)
	v_pk_fma_f32 v[4:5], v[12:13], v[168:169], v[4:5] op_sel_hi:[0,1,1]
	s_waitcnt vmcnt(0)
	v_pk_fma_f32 v[4:5], v[14:15], v[158:159], v[4:5] op_sel_hi:[0,1,1]
	v_mul_f32_e32 v1, 0xbfb8aa3b, v4
	v_exp_f32_e32 v1, v1
	s_nop 0
	v_add_f32_e32 v1, 1.0, v1
	v_rcp_f32_e32 v158, v1
	v_mul_f32_e32 v1, 0xbfb8aa3b, v5
	v_exp_f32_e32 v1, v1
	s_nop 0
	v_add_f32_e32 v1, 1.0, v1
	v_rcp_f32_e32 v159, v1
	s_nop 0
	v_pk_mul_f32 v[158:159], v[4:5], v[158:159]
	v_mov_b32_e32 v4, v169
	v_pk_fma_f32 v[4:5], v[10:11], v[4:5], v[6:7] op_sel:[0,0,1] op_sel_hi:[1,0,0]
	s_nop 0
	v_pk_fma_f32 v[4:5], v[12:13], v[160:161], v[4:5] op_sel_hi:[0,1,1]
	v_pk_fma_f32 v[4:5], v[14:15], v[162:163], v[4:5] op_sel_hi:[0,1,1]
	v_mul_f32_e32 v1, 0xbfb8aa3b, v4
	v_exp_f32_e32 v1, v1
	s_nop 0
	v_add_f32_e32 v1, 1.0, v1
	v_rcp_f32_e32 v6, v1
	v_mul_f32_e32 v1, 0xbfb8aa3b, v5
	v_exp_f32_e32 v1, v1
	s_nop 0
	v_add_f32_e32 v1, 1.0, v1
	v_rcp_f32_e32 v7, v1
	s_nop 0
	v_pk_mul_f32 v[188:189], v[4:5], v[6:7]
	v_pk_mul_f32 v[6:7], v[10:11], v[162:163] op_sel_hi:[0,1]
	v_pk_fma_f32 v[6:7], v[8:9], v[160:161], v[6:7] op_sel_hi:[0,1,1]
	v_pk_mov_b32 v[4:5], v[174:175], v[172:173] op_sel:[1,0]
	v_pk_fma_f32 v[6:7], v[12:13], v[174:175], v[6:7] op_sel_hi:[0,1,1]
	v_pk_fma_f32 v[6:7], v[14:15], v[4:5], v[6:7] op_sel_hi:[0,1,1]
	v_mul_f32_e32 v1, 0xbfb8aa3b, v6
	v_exp_f32_e32 v1, v1
	v_pk_mul_f32 v[4:5], v[10:11], v[4:5] op_sel_hi:[0,1]
	v_pk_fma_f32 v[4:5], v[8:9], v[174:175], v[4:5] op_sel_hi:[0,1,1]
	v_pk_fma_f32 v[4:5], v[12:13], v[172:173], v[4:5] op_sel_hi:[0,1,1]
	v_add_f32_e32 v1, 1.0, v1
	v_rcp_f32_e32 v160, v1
	v_mul_f32_e32 v1, 0xbfb8aa3b, v7
	v_exp_f32_e32 v1, v1
	s_nop 0
	v_add_f32_e32 v1, 1.0, v1
	v_rcp_f32_e32 v161, v1
	s_nop 0
	v_pk_mul_f32 v[160:161], v[6:7], v[160:161]
	v_pk_mov_b32 v[6:7], v[172:173], v[170:171] op_sel:[1,0]
	s_nop 0
	v_pk_fma_f32 v[4:5], v[14:15], v[6:7], v[4:5] op_sel_hi:[0,1,1]
	v_mul_f32_e32 v1, 0xbfb8aa3b, v4
	v_exp_f32_e32 v1, v1
	v_pk_mul_f32 v[6:7], v[10:11], v[6:7] op_sel_hi:[0,1]
	v_pk_fma_f32 v[6:7], v[8:9], v[172:173], v[6:7] op_sel_hi:[0,1,1]
	v_pk_fma_f32 v[6:7], v[12:13], v[170:171], v[6:7] op_sel_hi:[0,1,1]
	v_add_f32_e32 v1, 1.0, v1
	v_rcp_f32_e32 v162, v1
	v_mul_f32_e32 v1, 0xbfb8aa3b, v5
	v_exp_f32_e32 v1, v1
	s_nop 0
	v_add_f32_e32 v1, 1.0, v1
	v_rcp_f32_e32 v163, v1
	s_nop 0
	v_pk_mul_f32 v[162:163], v[4:5], v[162:163]
	v_pk_mov_b32 v[4:5], v[170:171], v[164:165] op_sel:[1,0]
; DI float bf2f(bf16_t b) { return __uint_as_float(((unsigned)b) << 16); }
; DI float silu_fast(float x) { return x * __builtin_amdgcn_rcpf(1.f + __expf(-x)); }
; DI void gdn_prep_phase(const int tid, LAS unsigned char* lds, const P& p, int G, int c) {
;     ...
;             { const float w0 = convw[colkv], w1 = convw[2304 + colkv], w2 = convw[4608 + colkv], w3 = convw[6912 + colkv];
; #pragma unroll
;               for (int e = 0; e < 64; ++e) { const float y = w0 * bf2f(kvraw[e]) + w1 * bf2f(kvraw[e + 1]) + w2 * bf2f(kvraw[e + 2]) + w3 * bf2f(kvraw[e + 3]); xs[e] = silu_fast(y); }
	s_nop 0
	v_pk_fma_f32 v[6:7], v[14:15], v[4:5], v[6:7] op_sel_hi:[0,1,1]
	v_mul_f32_e32 v1, 0xbfb8aa3b, v6
	v_exp_f32_e32 v1, v1
	v_pk_mul_f32 v[4:5], v[10:11], v[4:5] op_sel_hi:[0,1]
	v_pk_fma_f32 v[4:5], v[8:9], v[170:171], v[4:5] op_sel_hi:[0,1,1]
	v_pk_fma_f32 v[4:5], v[12:13], v[164:165], v[4:5] op_sel_hi:[0,1,1]
	v_add_f32_e32 v1, 1.0, v1
	v_rcp_f32_e32 v168, v1
	v_mul_f32_e32 v1, 0xbfb8aa3b, v7
	v_exp_f32_e32 v1, v1
	s_nop 0
	v_add_f32_e32 v1, 1.0, v1
	v_rcp_f32_e32 v169, v1
	s_nop 0
	v_pk_mul_f32 v[178:179], v[6:7], v[168:169]
	v_pk_mov_b32 v[6:7], v[164:165], v[166:167] op_sel:[1,0]
	s_nop 0
	v_pk_fma_f32 v[4:5], v[14:15], v[6:7], v[4:5] op_sel_hi:[0,1,1]
	v_mul_f32_e32 v1, 0xbfb8aa3b, v4
	v_exp_f32_e32 v1, v1
	v_pk_mul_f32 v[6:7], v[10:11], v[6:7] op_sel_hi:[0,1]
	v_pk_fma_f32 v[6:7], v[8:9], v[164:165], v[6:7] op_sel_hi:[0,1,1]
	v_pk_fma_f32 v[6:7], v[12:13], v[166:167], v[6:7] op_sel_hi:[0,1,1]
	v_add_f32_e32 v1, 1.0, v1
	v_rcp_f32_e32 v168, v1
	v_mul_f32_e32 v1, 0xbfb8aa3b, v5
	v_exp_f32_e32 v1, v1
	s_nop 0
	v_add_f32_e32 v1, 1.0, v1
	v_rcp_f32_e32 v169, v1
	s_nop 0
	v_pk_mul_f32 v[172:173], v[4:5], v[168:169]
	v_pk_mov_b32 v[4:5], v[166:167], v[66:67] op_sel:[1,0]
	s_nop 0
	v_pk_fma_f32 v[6:7], v[14:15], v[4:5], v[6:7] op_sel_hi:[0,1,1]
	v_mul_f32_e32 v1, 0xbfb8aa3b, v6
	v_exp_f32_e32 v1, v1
	v_pk_mul_f32 v[4:5], v[10:11], v[4:5] op_sel_hi:[0,1]
	v_pk_fma_f32 v[4:5], v[8:9], v[166:167], v[4:5] op_sel_hi:[0,1,1]
	v_pk_fma_f32 v[4:5], v[12:13], v[66:67], v[4:5] op_sel_hi:[0,1,1]
	v_add_f32_e32 v1, 1.0, v1
	v_rcp_f32_e32 v164, v1
	v_mul_f32_e32 v1, 0xbfb8aa3b, v7
	v_exp_f32_e32 v1, v1
	s_nop 0
	v_add_f32_e32 v1, 1.0, v1
	v_rcp_f32_e32 v165, v1
	s_nop 0
	v_pk_mul_f32 v[164:165], v[6:7], v[164:165]
	v_pk_mov_b32 v[6:7], v[66:67], v[64:65] op_sel:[1,0]
	s_nop 0
	v_pk_fma_f32 v[4:5], v[14:15], v[6:7], v[4:5] op_sel_hi:[0,1,1]
	v_mul_f32_e32 v1, 0xbfb8aa3b, v4
	v_exp_f32_e32 v1, v1
	v_pk_mul_f32 v[6:7], v[10:11], v[6:7] op_sel_hi:[0,1]
	v_pk_fma_f32 v[6:7], v[8:9], v[66:67], v[6:7] op_sel_hi:[0,1,1]
	v_pk_fma_f32 v[6:7], v[12:13], v[64:65], v[6:7] op_sel_hi:[0,1,1]
	v_add_f32_e32 v1, 1.0, v1
	v_rcp_f32_e32 v166, v1
	v_mul_f32_e32 v1, 0xbfb8aa3b, v5
	v_exp_f32_e32 v1, v1
	s_nop 0
	v_add_f32_e32 v1, 1.0, v1
	v_rcp_f32_e32 v167, v1
	s_nop 0
	v_pk_mul_f32 v[166:167], v[4:5], v[166:167]
	v_pk_mov_b32 v[4:5], v[64:65], v[62:63] op_sel:[1,0]
	s_nop 0
	v_pk_fma_f32 v[6:7], v[14:15], v[4:5], v[6:7] op_sel_hi:[0,1,1]
	v_mul_f32_e32 v1, 0xbfb8aa3b, v6
	v_exp_f32_e32 v1, v1
	v_pk_mul_f32 v[4:5], v[10:11], v[4:5] op_sel_hi:[0,1]
	v_pk_fma_f32 v[4:5], v[8:9], v[64:65], v[4:5] op_sel_hi:[0,1,1]
	v_pk_fma_f32 v[4:5], v[12:13], v[62:63], v[4:5] op_sel_hi:[0,1,1]
	v_add_f32_e32 v1, 1.0, v1
	v_rcp_f32_e32 v66, v1
	v_mul_f32_e32 v1, 0xbfb8aa3b, v7
	v_exp_f32_e32 v1, v1
	s_nop 0
	v_add_f32_e32 v1, 1.0, v1
	v_rcp_f32_e32 v67, v1
	s_nop 0
	v_pk_mul_f32 v[168:169], v[6:7], v[66:67]
	v_pk_mov_b32 v[6:7], v[62:63], v[60:61] op_sel:[1,0]
	s_nop 0
	v_pk_fma_f32 v[4:5], v[14:15], v[6:7], v[4:5] op_sel_hi:[0,1,1]
	v_mul_f32_e32 v1, 0xbfb8aa3b, v4
	v_exp_f32_e32 v1, v1
	v_pk_mul_f32 v[6:7], v[10:11], v[6:7] op_sel_hi:[0,1]
	v_pk_fma_f32 v[6:7], v[8:9], v[62:63], v[6:7] op_sel_hi:[0,1,1]
	v_pk_fma_f32 v[6:7], v[12:13], v[60:61], v[6:7] op_sel_hi:[0,1,1]
	v_add_f32_e32 v1, 1.0, v1
	v_rcp_f32_e32 v64, v1
	v_mul_f32_e32 v1, 0xbfb8aa3b, v5
	v_exp_f32_e32 v1, v1
	s_nop 0
	v_add_f32_e32 v1, 1.0, v1
	v_rcp_f32_e32 v65, v1
	s_nop 0
	v_pk_mul_f32 v[170:171], v[4:5], v[64:65]
	v_pk_mov_b32 v[4:5], v[60:61], v[58:59] op_sel:[1,0]
	s_nop 0
	v_pk_fma_f32 v[6:7], v[14:15], v[4:5], v[6:7] op_sel_hi:[0,1,1]
	v_mul_f32_e32 v1, 0xbfb8aa3b, v6
	v_exp_f32_e32 v1, v1
	v_pk_mul_f32 v[4:5], v[10:11], v[4:5] op_sel_hi:[0,1]
	v_pk_fma_f32 v[4:5], v[8:9], v[60:61], v[4:5] op_sel_hi:[0,1,1]
	v_pk_fma_f32 v[4:5], v[12:13], v[58:59], v[4:5] op_sel_hi:[0,1,1]
	v_add_f32_e32 v1, 1.0, v1
	v_rcp_f32_e32 v62, v1
	v_mul_f32_e32 v1, 0xbfb8aa3b, v7
	v_exp_f32_e32 v1, v1
	s_nop 0
	v_add_f32_e32 v1, 1.0, v1
	v_rcp_f32_e32 v63, v1
	s_nop 0
	v_pk_mul_f32 v[174:175], v[6:7], v[62:63]
	v_pk_mov_b32 v[6:7], v[58:59], v[56:57] op_sel:[1,0]
	s_nop 0
	v_pk_fma_f32 v[4:5], v[14:15], v[6:7], v[4:5] op_sel_hi:[0,1,1]
	v_mul_f32_e32 v1, 0xbfb8aa3b, v4
	v_exp_f32_e32 v1, v1
	v_pk_mul_f32 v[6:7], v[10:11], v[6:7] op_sel_hi:[0,1]
	v_pk_fma_f32 v[6:7], v[8:9], v[58:59], v[6:7] op_sel_hi:[0,1,1]
	v_pk_fma_f32 v[6:7], v[12:13], v[56:57], v[6:7] op_sel_hi:[0,1,1]
	v_add_f32_e32 v1, 1.0, v1
	v_rcp_f32_e32 v60, v1
	v_mul_f32_e32 v1, 0xbfb8aa3b, v5
	v_exp_f32_e32 v1, v1
	s_nop 0
	v_add_f32_e32 v1, 1.0, v1
	v_rcp_f32_e32 v61, v1
	s_nop 0
	v_pk_mul_f32 v[176:177], v[4:5], v[60:61]
	v_pk_mov_b32 v[4:5], v[56:57], v[54:55] op_sel:[1,0]
	s_nop 0
	v_pk_fma_f32 v[6:7], v[14:15], v[4:5], v[6:7] op_sel_hi:[0,1,1]
	v_mul_f32_e32 v1, 0xbfb8aa3b, v6
	v_exp_f32_e32 v1, v1
	v_pk_mul_f32 v[4:5], v[10:11], v[4:5] op_sel_hi:[0,1]
	v_pk_fma_f32 v[4:5], v[8:9], v[56:57], v[4:5] op_sel_hi:[0,1,1]
	v_pk_fma_f32 v[4:5], v[12:13], v[54:55], v[4:5] op_sel_hi:[0,1,1]
	v_add_f32_e32 v1, 1.0, v1
	v_rcp_f32_e32 v58, v1
	v_mul_f32_e32 v1, 0xbfb8aa3b, v7
	v_exp_f32_e32 v1, v1
	s_nop 0
	v_add_f32_e32 v1, 1.0, v1
	v_rcp_f32_e32 v59, v1
	s_nop 0
	v_pk_mul_f32 v[184:185], v[6:7], v[58:59]
	v_pk_mov_b32 v[6:7], v[54:55], v[52:53] op_sel:[1,0]
	s_nop 0
	v_pk_fma_f32 v[4:5], v[14:15], v[6:7], v[4:5] op_sel_hi:[0,1,1]
	v_mul_f32_e32 v1, 0xbfb8aa3b, v4
	v_exp_f32_e32 v1, v1
	v_pk_mul_f32 v[6:7], v[10:11], v[6:7] op_sel_hi:[0,1]
	v_pk_fma_f32 v[6:7], v[8:9], v[54:55], v[6:7] op_sel_hi:[0,1,1]
	v_pk_fma_f32 v[6:7], v[12:13], v[52:53], v[6:7] op_sel_hi:[0,1,1]
; DI float bf2f(bf16_t b) { return __uint_as_float(((unsigned)b) << 16); }
; DI float silu_fast(float x) { return x * __builtin_amdgcn_rcpf(1.f + __expf(-x)); }
; DI void gdn_prep_phase(const int tid, LAS unsigned char* lds, const P& p, int G, int c) {
;     ...
;             { const float w0 = convw[colkv], w1 = convw[2304 + colkv], w2 = convw[4608 + colkv], w3 = convw[6912 + colkv];
; #pragma unroll
;               for (int e = 0; e < 64; ++e) { const float y = w0 * bf2f(kvraw[e]) + w1 * bf2f(kvraw[e + 1]) + w2 * bf2f(kvraw[e + 2]) + w3 * bf2f(kvraw[e + 3]); xs[e] = silu_fast(y); }
	v_add_f32_e32 v1, 1.0, v1
	v_rcp_f32_e32 v56, v1
	v_mul_f32_e32 v1, 0xbfb8aa3b, v5
	v_exp_f32_e32 v1, v1
	s_nop 0
	v_add_f32_e32 v1, 1.0, v1
	v_rcp_f32_e32 v57, v1
	s_nop 0
	v_pk_mul_f32 v[186:187], v[4:5], v[56:57]
	v_pk_mov_b32 v[4:5], v[52:53], v[50:51] op_sel:[1,0]
	s_nop 0
	v_pk_fma_f32 v[6:7], v[14:15], v[4:5], v[6:7] op_sel_hi:[0,1,1]
	v_mul_f32_e32 v1, 0xbfb8aa3b, v6
	v_exp_f32_e32 v1, v1
	v_pk_mul_f32 v[4:5], v[10:11], v[4:5] op_sel_hi:[0,1]
	v_pk_fma_f32 v[4:5], v[8:9], v[52:53], v[4:5] op_sel_hi:[0,1,1]
	v_pk_fma_f32 v[4:5], v[12:13], v[50:51], v[4:5] op_sel_hi:[0,1,1]
	v_add_f32_e32 v1, 1.0, v1
	v_rcp_f32_e32 v54, v1
	v_mul_f32_e32 v1, 0xbfb8aa3b, v7
	v_exp_f32_e32 v1, v1
	s_nop 0
	v_add_f32_e32 v1, 1.0, v1
	v_rcp_f32_e32 v55, v1
	s_nop 0
	v_pk_mul_f32 v[190:191], v[6:7], v[54:55]
	v_pk_mov_b32 v[6:7], v[50:51], v[48:49] op_sel:[1,0]
	s_nop 0
	v_pk_fma_f32 v[4:5], v[14:15], v[6:7], v[4:5] op_sel_hi:[0,1,1]
	v_mul_f32_e32 v1, 0xbfb8aa3b, v4
	v_exp_f32_e32 v1, v1
	v_pk_mul_f32 v[6:7], v[10:11], v[6:7] op_sel_hi:[0,1]
	v_pk_fma_f32 v[6:7], v[8:9], v[50:51], v[6:7] op_sel_hi:[0,1,1]
	v_pk_fma_f32 v[6:7], v[12:13], v[48:49], v[6:7] op_sel_hi:[0,1,1]
	v_add_f32_e32 v1, 1.0, v1
	v_rcp_f32_e32 v52, v1
	v_mul_f32_e32 v1, 0xbfb8aa3b, v5
	v_exp_f32_e32 v1, v1
	s_nop 0
	v_add_f32_e32 v1, 1.0, v1
	v_rcp_f32_e32 v53, v1
	s_nop 0
	v_pk_mul_f32 v[192:193], v[4:5], v[52:53]
	v_pk_mov_b32 v[4:5], v[48:49], v[46:47] op_sel:[1,0]
	s_nop 0
	v_pk_fma_f32 v[6:7], v[14:15], v[4:5], v[6:7] op_sel_hi:[0,1,1]
	v_mul_f32_e32 v1, 0xbfb8aa3b, v6
	v_exp_f32_e32 v1, v1
	v_pk_mul_f32 v[4:5], v[10:11], v[4:5] op_sel_hi:[0,1]
	v_pk_fma_f32 v[4:5], v[8:9], v[48:49], v[4:5] op_sel_hi:[0,1,1]
	v_pk_fma_f32 v[4:5], v[12:13], v[46:47], v[4:5] op_sel_hi:[0,1,1]
	v_add_f32_e32 v1, 1.0, v1
	v_rcp_f32_e32 v50, v1
	v_mul_f32_e32 v1, 0xbfb8aa3b, v7
	v_exp_f32_e32 v1, v1
	s_nop 0
	v_add_f32_e32 v1, 1.0, v1
	v_rcp_f32_e32 v51, v1
	s_nop 0
	v_pk_mul_f32 v[194:195], v[6:7], v[50:51]
	v_pk_mov_b32 v[6:7], v[46:47], v[44:45] op_sel:[1,0]
	s_nop 0
	v_pk_fma_f32 v[4:5], v[14:15], v[6:7], v[4:5] op_sel_hi:[0,1,1]
	v_mul_f32_e32 v1, 0xbfb8aa3b, v4
	v_exp_f32_e32 v1, v1
	v_pk_mul_f32 v[6:7], v[10:11], v[6:7] op_sel_hi:[0,1]
	v_pk_fma_f32 v[6:7], v[8:9], v[46:47], v[6:7] op_sel_hi:[0,1,1]
	v_pk_fma_f32 v[6:7], v[12:13], v[44:45], v[6:7] op_sel_hi:[0,1,1]
	v_add_f32_e32 v1, 1.0, v1
	v_rcp_f32_e32 v48, v1
	v_mul_f32_e32 v1, 0xbfb8aa3b, v5
	v_exp_f32_e32 v1, v1
	s_nop 0
	v_add_f32_e32 v1, 1.0, v1
	v_rcp_f32_e32 v49, v1
	s_nop 0
	v_pk_mul_f32 v[196:197], v[4:5], v[48:49]
	v_pk_mov_b32 v[4:5], v[44:45], v[42:43] op_sel:[1,0]
	s_nop 0
	v_pk_fma_f32 v[6:7], v[14:15], v[4:5], v[6:7] op_sel_hi:[0,1,1]
	v_mul_f32_e32 v1, 0xbfb8aa3b, v6
	v_exp_f32_e32 v1, v1
	v_pk_mul_f32 v[4:5], v[10:11], v[4:5] op_sel_hi:[0,1]
	v_pk_fma_f32 v[4:5], v[8:9], v[44:45], v[4:5] op_sel_hi:[0,1,1]
	v_pk_fma_f32 v[4:5], v[12:13], v[42:43], v[4:5] op_sel_hi:[0,1,1]
	v_add_f32_e32 v1, 1.0, v1
	v_rcp_f32_e32 v46, v1
	v_mul_f32_e32 v1, 0xbfb8aa3b, v7
	v_exp_f32_e32 v1, v1
	s_nop 0
	v_add_f32_e32 v1, 1.0, v1
	v_rcp_f32_e32 v47, v1
	s_nop 0
	v_pk_mul_f32 v[198:199], v[6:7], v[46:47]
	v_pk_mov_b32 v[6:7], v[42:43], v[40:41] op_sel:[1,0]
	s_nop 0
	v_pk_fma_f32 v[4:5], v[14:15], v[6:7], v[4:5] op_sel_hi:[0,1,1]
	v_mul_f32_e32 v1, 0xbfb8aa3b, v4
	v_exp_f32_e32 v1, v1
	v_pk_mul_f32 v[6:7], v[10:11], v[6:7] op_sel_hi:[0,1]
	v_pk_fma_f32 v[6:7], v[8:9], v[42:43], v[6:7] op_sel_hi:[0,1,1]
	v_pk_fma_f32 v[6:7], v[12:13], v[40:41], v[6:7] op_sel_hi:[0,1,1]
	v_add_f32_e32 v1, 1.0, v1
	v_rcp_f32_e32 v44, v1
	v_mul_f32_e32 v1, 0xbfb8aa3b, v5
	v_exp_f32_e32 v1, v1
	s_nop 0
	v_add_f32_e32 v1, 1.0, v1
	v_rcp_f32_e32 v45, v1
	s_nop 0
	v_pk_mul_f32 v[200:201], v[4:5], v[44:45]
	v_pk_mov_b32 v[4:5], v[40:41], v[38:39] op_sel:[1,0]
	s_nop 0
	v_pk_fma_f32 v[6:7], v[14:15], v[4:5], v[6:7] op_sel_hi:[0,1,1]
	v_mul_f32_e32 v1, 0xbfb8aa3b, v6
	v_exp_f32_e32 v1, v1
	v_pk_mul_f32 v[4:5], v[10:11], v[4:5] op_sel_hi:[0,1]
	v_pk_fma_f32 v[4:5], v[8:9], v[40:41], v[4:5] op_sel_hi:[0,1,1]
	v_pk_fma_f32 v[4:5], v[12:13], v[38:39], v[4:5] op_sel_hi:[0,1,1]
	v_add_f32_e32 v1, 1.0, v1
	v_rcp_f32_e32 v42, v1
	v_mul_f32_e32 v1, 0xbfb8aa3b, v7
	v_exp_f32_e32 v1, v1
	s_nop 0
	v_add_f32_e32 v1, 1.0, v1
	v_rcp_f32_e32 v43, v1
	s_nop 0
	v_pk_mul_f32 v[202:203], v[6:7], v[42:43]
	v_pk_mov_b32 v[6:7], v[38:39], v[36:37] op_sel:[1,0]
	s_nop 0
	v_pk_fma_f32 v[4:5], v[14:15], v[6:7], v[4:5] op_sel_hi:[0,1,1]
	v_mul_f32_e32 v1, 0xbfb8aa3b, v4
	v_exp_f32_e32 v1, v1
	v_pk_mul_f32 v[6:7], v[10:11], v[6:7] op_sel_hi:[0,1]
	v_pk_fma_f32 v[6:7], v[8:9], v[38:39], v[6:7] op_sel_hi:[0,1,1]
	v_pk_fma_f32 v[6:7], v[12:13], v[36:37], v[6:7] op_sel_hi:[0,1,1]
	v_add_f32_e32 v1, 1.0, v1
	v_rcp_f32_e32 v40, v1
	v_mul_f32_e32 v1, 0xbfb8aa3b, v5
	v_exp_f32_e32 v1, v1
	s_nop 0
	v_add_f32_e32 v1, 1.0, v1
	v_rcp_f32_e32 v41, v1
	s_nop 0
	v_pk_mul_f32 v[204:205], v[4:5], v[40:41]
	v_pk_mov_b32 v[4:5], v[36:37], v[34:35] op_sel:[1,0]
	s_nop 0
	v_pk_fma_f32 v[6:7], v[14:15], v[4:5], v[6:7] op_sel_hi:[0,1,1]
	v_mul_f32_e32 v1, 0xbfb8aa3b, v6
	v_exp_f32_e32 v1, v1
	v_pk_mul_f32 v[4:5], v[10:11], v[4:5] op_sel_hi:[0,1]
	v_pk_fma_f32 v[4:5], v[8:9], v[36:37], v[4:5] op_sel_hi:[0,1,1]
	v_pk_fma_f32 v[4:5], v[12:13], v[34:35], v[4:5] op_sel_hi:[0,1,1]
	v_add_f32_e32 v1, 1.0, v1
	v_rcp_f32_e32 v38, v1
	v_mul_f32_e32 v1, 0xbfb8aa3b, v7
	v_exp_f32_e32 v1, v1
	s_nop 0
	v_add_f32_e32 v1, 1.0, v1
	v_rcp_f32_e32 v39, v1
	s_nop 0
	v_pk_mul_f32 v[206:207], v[6:7], v[38:39]
	v_pk_mov_b32 v[6:7], v[34:35], v[32:33] op_sel:[1,0]
	s_nop 0
	v_pk_fma_f32 v[4:5], v[14:15], v[6:7], v[4:5] op_sel_hi:[0,1,1]
; DI float bf2f(bf16_t b) { return __uint_as_float(((unsigned)b) << 16); }
; DI float silu_fast(float x) { return x * __builtin_amdgcn_rcpf(1.f + __expf(-x)); }
; DI void gdn_prep_phase(const int tid, LAS unsigned char* lds, const P& p, int G, int c) {
;     ...
;             { const float w0 = convw[colkv], w1 = convw[2304 + colkv], w2 = convw[4608 + colkv], w3 = convw[6912 + colkv];
; #pragma unroll
;               for (int e = 0; e < 64; ++e) { const float y = w0 * bf2f(kvraw[e]) + w1 * bf2f(kvraw[e + 1]) + w2 * bf2f(kvraw[e + 2]) + w3 * bf2f(kvraw[e + 3]); xs[e] = silu_fast(y); }
;               if (!isv) {
	v_mul_f32_e32 v1, 0xbfb8aa3b, v4
	v_exp_f32_e32 v1, v1
	v_pk_mul_f32 v[6:7], v[10:11], v[6:7] op_sel_hi:[0,1]
	v_pk_fma_f32 v[6:7], v[8:9], v[34:35], v[6:7] op_sel_hi:[0,1,1]
	v_pk_fma_f32 v[6:7], v[12:13], v[32:33], v[6:7] op_sel_hi:[0,1,1]
	v_add_f32_e32 v1, 1.0, v1
	v_rcp_f32_e32 v36, v1
	v_mul_f32_e32 v1, 0xbfb8aa3b, v5
	v_exp_f32_e32 v1, v1
	s_nop 0
	v_add_f32_e32 v1, 1.0, v1
	v_rcp_f32_e32 v37, v1
	s_nop 0
	v_pk_mul_f32 v[208:209], v[4:5], v[36:37]
	v_pk_mov_b32 v[4:5], v[32:33], v[30:31] op_sel:[1,0]
	s_nop 0
	v_pk_fma_f32 v[6:7], v[14:15], v[4:5], v[6:7] op_sel_hi:[0,1,1]
	v_mul_f32_e32 v1, 0xbfb8aa3b, v6
	v_exp_f32_e32 v1, v1
	v_pk_mul_f32 v[4:5], v[10:11], v[4:5] op_sel_hi:[0,1]
	v_pk_fma_f32 v[4:5], v[8:9], v[32:33], v[4:5] op_sel_hi:[0,1,1]
	v_pk_fma_f32 v[4:5], v[12:13], v[30:31], v[4:5] op_sel_hi:[0,1,1]
	v_add_f32_e32 v1, 1.0, v1
	v_rcp_f32_e32 v34, v1
	v_mul_f32_e32 v1, 0xbfb8aa3b, v7
	v_exp_f32_e32 v1, v1
	s_nop 0
	v_add_f32_e32 v1, 1.0, v1
	v_rcp_f32_e32 v35, v1
	s_nop 0
	v_pk_mul_f32 v[210:211], v[6:7], v[34:35]
	v_pk_mov_b32 v[6:7], v[30:31], v[28:29] op_sel:[1,0]
	s_nop 0
	v_pk_fma_f32 v[4:5], v[14:15], v[6:7], v[4:5] op_sel_hi:[0,1,1]
	v_mul_f32_e32 v1, 0xbfb8aa3b, v4
	v_exp_f32_e32 v1, v1
	v_pk_mul_f32 v[6:7], v[10:11], v[6:7] op_sel_hi:[0,1]
	v_pk_fma_f32 v[6:7], v[8:9], v[30:31], v[6:7] op_sel_hi:[0,1,1]
	v_pk_fma_f32 v[6:7], v[12:13], v[28:29], v[6:7] op_sel_hi:[0,1,1]
	v_add_f32_e32 v1, 1.0, v1
	v_rcp_f32_e32 v32, v1
	v_mul_f32_e32 v1, 0xbfb8aa3b, v5
	v_exp_f32_e32 v1, v1
	s_nop 0
	v_add_f32_e32 v1, 1.0, v1
	v_rcp_f32_e32 v33, v1
	s_nop 0
	v_pk_mul_f32 v[212:213], v[4:5], v[32:33]
	v_pk_mov_b32 v[4:5], v[28:29], v[26:27] op_sel:[1,0]
	s_nop 0
	v_pk_fma_f32 v[6:7], v[14:15], v[4:5], v[6:7] op_sel_hi:[0,1,1]
	v_mul_f32_e32 v1, 0xbfb8aa3b, v6
	v_exp_f32_e32 v1, v1
	v_pk_mul_f32 v[4:5], v[10:11], v[4:5] op_sel_hi:[0,1]
	v_pk_fma_f32 v[4:5], v[8:9], v[28:29], v[4:5] op_sel_hi:[0,1,1]
	v_pk_fma_f32 v[4:5], v[12:13], v[26:27], v[4:5] op_sel_hi:[0,1,1]
	v_add_f32_e32 v1, 1.0, v1
	v_rcp_f32_e32 v30, v1
	v_mul_f32_e32 v1, 0xbfb8aa3b, v7
	v_exp_f32_e32 v1, v1
	s_nop 0
	v_add_f32_e32 v1, 1.0, v1
	v_rcp_f32_e32 v31, v1
	s_nop 0
	v_pk_mul_f32 v[214:215], v[6:7], v[30:31]
	v_pk_mov_b32 v[6:7], v[26:27], v[24:25] op_sel:[1,0]
	s_nop 0
	v_pk_fma_f32 v[4:5], v[14:15], v[6:7], v[4:5] op_sel_hi:[0,1,1]
	v_mul_f32_e32 v1, 0xbfb8aa3b, v4
	v_exp_f32_e32 v1, v1
	v_pk_mul_f32 v[6:7], v[10:11], v[6:7] op_sel_hi:[0,1]
	v_pk_fma_f32 v[6:7], v[8:9], v[26:27], v[6:7] op_sel_hi:[0,1,1]
	v_pk_fma_f32 v[6:7], v[12:13], v[24:25], v[6:7] op_sel_hi:[0,1,1]
	v_add_f32_e32 v1, 1.0, v1
	v_rcp_f32_e32 v28, v1
	v_mul_f32_e32 v1, 0xbfb8aa3b, v5
	v_exp_f32_e32 v1, v1
	s_nop 0
	v_add_f32_e32 v1, 1.0, v1
	v_rcp_f32_e32 v29, v1
	s_nop 0
	v_pk_mul_f32 v[216:217], v[4:5], v[28:29]
	v_pk_mov_b32 v[4:5], v[24:25], v[22:23] op_sel:[1,0]
	s_nop 0
	v_pk_fma_f32 v[6:7], v[14:15], v[4:5], v[6:7] op_sel_hi:[0,1,1]
	v_mul_f32_e32 v1, 0xbfb8aa3b, v6
	v_exp_f32_e32 v1, v1
	v_pk_mul_f32 v[4:5], v[10:11], v[4:5] op_sel_hi:[0,1]
	v_pk_fma_f32 v[4:5], v[8:9], v[24:25], v[4:5] op_sel_hi:[0,1,1]
	v_pk_fma_f32 v[4:5], v[12:13], v[22:23], v[4:5] op_sel_hi:[0,1,1]
	v_add_f32_e32 v1, 1.0, v1
	v_rcp_f32_e32 v26, v1
	v_mul_f32_e32 v1, 0xbfb8aa3b, v7
	v_exp_f32_e32 v1, v1
	s_nop 0
	v_add_f32_e32 v1, 1.0, v1
	v_rcp_f32_e32 v27, v1
	s_nop 0
	v_pk_mul_f32 v[218:219], v[6:7], v[26:27]
	v_pk_mov_b32 v[6:7], v[22:23], v[16:17] op_sel:[1,0]
	s_nop 0
	v_pk_fma_f32 v[4:5], v[14:15], v[6:7], v[4:5] op_sel_hi:[0,1,1]
	v_mul_f32_e32 v1, 0xbfb8aa3b, v4
	v_exp_f32_e32 v1, v1
	s_nop 0
	v_add_f32_e32 v1, 1.0, v1
	v_rcp_f32_e32 v24, v1
	v_mul_f32_e32 v1, 0xbfb8aa3b, v5
	v_exp_f32_e32 v1, v1
	s_nop 0
	v_add_f32_e32 v1, 1.0, v1
	v_rcp_f32_e32 v25, v1
	s_nop 0
	v_pk_mul_f32 v[220:221], v[4:5], v[24:25]
	v_pk_mul_f32 v[4:5], v[10:11], v[6:7] op_sel_hi:[0,1]
	v_pk_fma_f32 v[4:5], v[8:9], v[22:23], v[4:5] op_sel_hi:[0,1,1]
	v_pk_fma_f32 v[4:5], v[12:13], v[16:17], v[4:5] op_sel_hi:[0,1,1]
	v_pk_fma_f32 v[4:5], v[14:15], v[20:21], v[4:5] op_sel_hi:[0,1,1]
	v_mul_f32_e32 v1, 0xbfb8aa3b, v4
	v_exp_f32_e32 v1, v1
	s_nop 0
	v_add_f32_e32 v1, 1.0, v1
	v_rcp_f32_e32 v6, v1
	v_mul_f32_e32 v1, 0xbfb8aa3b, v5
	v_exp_f32_e32 v1, v1
	s_nop 0
	v_add_f32_e32 v1, 1.0, v1
	v_rcp_f32_e32 v7, v1
	s_nop 0
	v_pk_mul_f32 v[222:223], v[4:5], v[6:7]
	v_pk_mul_f32 v[4:5], v[10:11], v[20:21] op_sel_hi:[0,1]
	v_pk_fma_f32 v[4:5], v[8:9], v[16:17], v[4:5] op_sel_hi:[0,1,1]
	v_mov_b32_e32 v8, v19
	v_pk_fma_f32 v[4:5], v[12:13], v[18:19], v[4:5] op_sel_hi:[0,1,1]
	v_pk_fma_f32 v[4:5], v[14:15], v[8:9], v[4:5] op_sel_hi:[0,1,1]
	v_mul_f32_e32 v1, 0xbfb8aa3b, v4
	v_exp_f32_e32 v1, v1
	s_nop 0
	v_add_f32_e32 v1, 1.0, v1
	v_rcp_f32_e32 v6, v1
	v_mul_f32_e32 v1, 0xbfb8aa3b, v5
	v_exp_f32_e32 v1, v1
	s_nop 0
	v_add_f32_e32 v1, 1.0, v1
	v_rcp_f32_e32 v7, v1
	s_nop 0
	v_pk_mul_f32 v[224:225], v[4:5], v[6:7]
	s_mov_b64 s[0:1], exec
	v_readlane_b32 s26, v254, 54
	v_readlane_b32 s27, v254, 55
	s_and_b64 s[26:27], s[0:1], s[26:27]
	s_mov_b64 exec, s[26:27]
	s_cbranch_execz .LBB0_608
; DI void gdn_prep_phase(const int tid, LAS unsigned char* lds, const P& p, int G, int c) {
;     ...
;               if (!isv) {
; #pragma unroll
;                   for (int tt = 0; tt < 64; ++tt) Ks[tt * 136 + ch] = f2bf(xs[tt]); } }
	v_cvt_pk_bf16_f32 v1, v158, s0
	ds_write_b16 v75, v1 offset:17408
	v_cvt_pk_bf16_f32 v1, v159, s0
	ds_write_b16 v75, v1 offset:17680
	v_cvt_pk_bf16_f32 v1, v188, s0
	ds_write_b16 v75, v1 offset:17952
	v_cvt_pk_bf16_f32 v1, v189, s0
	ds_write_b16 v75, v1 offset:18224
	v_cvt_pk_bf16_f32 v1, v160, s0
	ds_write_b16 v75, v1 offset:18496
	v_cvt_pk_bf16_f32 v1, v161, s0
	ds_write_b16 v75, v1 offset:18768
	v_cvt_pk_bf16_f32 v1, v162, s0
	ds_write_b16 v75, v1 offset:19040
	v_cvt_pk_bf16_f32 v1, v163, s0
	ds_write_b16 v75, v1 offset:19312
	v_cvt_pk_bf16_f32 v1, v178, s0
	ds_write_b16 v75, v1 offset:19584
	v_cvt_pk_bf16_f32 v1, v179, s0
	ds_write_b16 v75, v1 offset:19856
	v_cvt_pk_bf16_f32 v1, v172, s0
	ds_write_b16 v75, v1 offset:20128
	v_cvt_pk_bf16_f32 v1, v173, s0
	ds_write_b16 v75, v1 offset:20400
	v_cvt_pk_bf16_f32 v1, v164, s0
	ds_write_b16 v75, v1 offset:20672
	v_cvt_pk_bf16_f32 v1, v165, s0
	ds_write_b16 v75, v1 offset:20944
	v_cvt_pk_bf16_f32 v1, v166, s0
	ds_write_b16 v75, v1 offset:21216
	v_cvt_pk_bf16_f32 v1, v167, s0
	ds_write_b16 v75, v1 offset:21488
	v_cvt_pk_bf16_f32 v1, v168, s0
	ds_write_b16 v75, v1 offset:21760
	v_cvt_pk_bf16_f32 v1, v169, s0
	ds_write_b16 v75, v1 offset:22032
	v_cvt_pk_bf16_f32 v1, v170, s0
	ds_write_b16 v75, v1 offset:22304
	v_cvt_pk_bf16_f32 v1, v171, s0
	ds_write_b16 v75, v1 offset:22576
	v_cvt_pk_bf16_f32 v1, v174, s0
	ds_write_b16 v75, v1 offset:22848
	v_cvt_pk_bf16_f32 v1, v175, s0
	ds_write_b16 v75, v1 offset:23120
	v_cvt_pk_bf16_f32 v1, v176, s0
	ds_write_b16 v75, v1 offset:23392
	v_cvt_pk_bf16_f32 v1, v177, s0
	ds_write_b16 v75, v1 offset:23664
	v_cvt_pk_bf16_f32 v1, v184, s0
	ds_write_b16 v75, v1 offset:23936
	v_cvt_pk_bf16_f32 v1, v185, s0
	ds_write_b16 v75, v1 offset:24208
	v_cvt_pk_bf16_f32 v1, v186, s0
	ds_write_b16 v75, v1 offset:24480
	v_cvt_pk_bf16_f32 v1, v187, s0
	ds_write_b16 v75, v1 offset:24752
	v_cvt_pk_bf16_f32 v1, v190, s0
	ds_write_b16 v75, v1 offset:25024
	v_cvt_pk_bf16_f32 v1, v191, s0
	ds_write_b16 v75, v1 offset:25296
	v_cvt_pk_bf16_f32 v1, v192, s0
	ds_write_b16 v75, v1 offset:25568
	v_cvt_pk_bf16_f32 v1, v193, s0
	ds_write_b16 v75, v1 offset:25840
	v_cvt_pk_bf16_f32 v1, v194, s0
	ds_write_b16 v75, v1 offset:26112
	v_cvt_pk_bf16_f32 v1, v195, s0
	ds_write_b16 v75, v1 offset:26384
	v_cvt_pk_bf16_f32 v1, v196, s0
	ds_write_b16 v75, v1 offset:26656
	v_cvt_pk_bf16_f32 v1, v197, s0
	ds_write_b16 v75, v1 offset:26928
	v_cvt_pk_bf16_f32 v1, v198, s0
	ds_write_b16 v75, v1 offset:27200
	v_cvt_pk_bf16_f32 v1, v199, s0
	ds_write_b16 v75, v1 offset:27472
	v_cvt_pk_bf16_f32 v1, v200, s0
	ds_write_b16 v75, v1 offset:27744
	v_cvt_pk_bf16_f32 v1, v201, s0
	ds_write_b16 v75, v1 offset:28016
	v_cvt_pk_bf16_f32 v1, v202, s0
	ds_write_b16 v75, v1 offset:28288
	v_cvt_pk_bf16_f32 v1, v203, s0
	ds_write_b16 v75, v1 offset:28560
	v_cvt_pk_bf16_f32 v1, v204, s0
	ds_write_b16 v75, v1 offset:28832
	v_cvt_pk_bf16_f32 v1, v205, s0
	ds_write_b16 v75, v1 offset:29104
	v_cvt_pk_bf16_f32 v1, v206, s0
	ds_write_b16 v75, v1 offset:29376
	v_cvt_pk_bf16_f32 v1, v207, s0
	ds_write_b16 v75, v1 offset:29648
	v_cvt_pk_bf16_f32 v1, v208, s0
	ds_write_b16 v75, v1 offset:29920
	v_cvt_pk_bf16_f32 v1, v209, s0
	ds_write_b16 v75, v1 offset:30192
	v_cvt_pk_bf16_f32 v1, v210, s0
	ds_write_b16 v75, v1 offset:30464
	v_cvt_pk_bf16_f32 v1, v211, s0
	ds_write_b16 v75, v1 offset:30736
	v_cvt_pk_bf16_f32 v1, v212, s0
	ds_write_b16 v75, v1 offset:31008
	v_cvt_pk_bf16_f32 v1, v213, s0
	ds_write_b16 v75, v1 offset:31280
	v_cvt_pk_bf16_f32 v1, v214, s0
	ds_write_b16 v75, v1 offset:31552
	v_cvt_pk_bf16_f32 v1, v215, s0
	ds_write_b16 v75, v1 offset:31824
	v_cvt_pk_bf16_f32 v1, v216, s0
	ds_write_b16 v75, v1 offset:32096
	v_cvt_pk_bf16_f32 v1, v217, s0
	ds_write_b16 v75, v1 offset:32368
	v_cvt_pk_bf16_f32 v1, v218, s0
	ds_write_b16 v75, v1 offset:32640
	v_cvt_pk_bf16_f32 v1, v219, s0
	ds_write_b16 v75, v1 offset:32912
	v_cvt_pk_bf16_f32 v1, v220, s0
	ds_write_b16 v75, v1 offset:33184
	v_cvt_pk_bf16_f32 v1, v221, s0
	ds_write_b16 v75, v1 offset:33456
	v_cvt_pk_bf16_f32 v1, v222, s0
	ds_write_b16 v75, v1 offset:33728
	v_cvt_pk_bf16_f32 v1, v223, s0
	ds_write_b16 v75, v1 offset:34000
	v_cvt_pk_bf16_f32 v1, v224, s0
	ds_write_b16 v75, v1 offset:34272
	v_cvt_pk_bf16_f32 v1, v225, s0
	ds_write_b16 v75, v1 offset:34544

; #define LAS __attribute__((address_space(3)))
; DI void gdn_prep_phase(const int tid, LAS unsigned char* lds, const P& p, int G, int c) {
;     ...
; #pragma unroll
;           for (int kb = 0; kb < 8; ++kb) {
; #pragma unroll
;               for (int pp = 0; pp < 4; ++pp) { const int pr = 4 * kb + pp;
;                   f32x2 s = (f32x2){xs[2 * pr], xs[2 * pr + 1]};
; #pragma unroll
;                   for (int j = 8 * kb; j < 2 * pr; j += 2) { const f32x4 l = *(const LAS f32x4*)(Ls + pr * 136 + j * 2);
;                       s -= (f32x2){l[0], l[1]} * (f32x2){xs[j], xs[j]}; s -= (f32x2){l[2], l[3]} * (f32x2){xs[j + 1], xs[j + 1]}; }
;                   xs[2 * pr] = s[0];
;                   xs[2 * pr + 1] = s[1] - Ls[pr * 136 + 4 * pr + 1] * s[0]; }
; #pragma unroll
;               for (int pr = 4 * kb + 4; pr < 32; ++pr) {
;                   f32x2 s0 = (f32x2){xs[2 * pr], xs[2 * pr + 1]}, s1 = (f32x2){0.f, 0.f};
; #pragma unroll
;                   for (int q = 0; q < 4; ++q) { const int j = 8 * kb + 2 * q; const f32x4 l = *(const LAS f32x4*)(Ls + pr * 136 + j * 2);
;                       s0 -= (f32x2){l[0], l[1]} * (f32x2){xs[j], xs[j]}; s1 -= (f32x2){l[2], l[3]} * (f32x2){xs[j + 1], xs[j + 1]}; }
;                   const f32x2 s = s0 + s1; xs[2 * pr] = s[0]; xs[2 * pr + 1] = s[1]; }
.LBB0_630:
	s_or_b64 exec, exec, s[0:1]
	ds_read_b128 v[112:115], v69 offset:35360
	v_add_u32_e32 v141, 0x8800, v69
	ds_read2_b32 v[116:117], v141 offset0:1 offset1:141
	ds_read_b128 v[120:123], v69 offset:35904
	ds_read_b128 v[124:127], v69 offset:35920
	ds_read_b128 v[128:131], v69 offset:36448
	v_add_u32_e32 v183, 0x8c00, v69
	ds_read2_b32 v[132:133], v183 offset0:25 offset1:165
	ds_read_b128 v[136:139], v69 offset:36464
	ds_read_b128 v[238:241], v69 offset:36480
	ds_read_b128 v[242:245], v69 offset:36992
	ds_read_b128 v[246:249], v69 offset:37008
	s_waitcnt lgkmcnt(15)
	v_pk_mul_f32 v[66:67], v[158:159], v[60:61]
	s_waitcnt lgkmcnt(9)
	v_pk_mul_f32 v[60:61], v[66:67], v[112:113] op_sel_hi:[0,1]
	s_waitcnt lgkmcnt(8)
	v_fma_f32 v158, -v66, v116, v67
	v_pk_fma_f32 v[60:61], v[188:189], v[62:63], v[60:61] neg_lo:[0,0,1] neg_hi:[0,0,1]
	s_nop 0
	v_pk_fma_f32 v[60:61], v[114:115], v[158:159], v[60:61] op_sel_hi:[1,0,1] neg_lo:[1,0,0] neg_hi:[1,0,0]
	ds_read_b128 v[112:115], v69 offset:37024
	v_fma_f32 v62, -v117, v60, v61
	ds_read_b128 v[116:119], v69 offset:37040
	s_waitcnt lgkmcnt(9)
	v_pk_mul_f32 v[188:189], v[66:67], v[120:121] op_sel_hi:[0,1]
	v_pk_fma_f32 v[56:57], v[160:161], v[56:57], v[188:189] neg_lo:[0,0,1] neg_hi:[0,0,1]
	s_nop 0
	v_pk_fma_f32 v[56:57], v[122:123], v[158:159], v[56:57] op_sel_hi:[1,0,1] neg_lo:[1,0,0] neg_hi:[1,0,0]
	ds_read_b128 v[120:123], v69 offset:37536
	s_waitcnt lgkmcnt(9)
	v_pk_fma_f32 v[56:57], v[124:125], v[60:61], v[56:57] op_sel_hi:[1,0,1] neg_lo:[1,0,0] neg_hi:[1,0,0]
	s_nop 0
	v_pk_fma_f32 v[56:57], v[126:127], v[62:63], v[56:57] op_sel_hi:[1,0,1] neg_lo:[1,0,0] neg_hi:[1,0,0]
	ds_read_b128 v[124:127], v69 offset:37552
	s_waitcnt lgkmcnt(9)
	v_pk_mul_f32 v[188:189], v[66:67], v[128:129] op_sel_hi:[0,1]
	v_pk_fma_f32 v[58:59], v[162:163], v[58:59], v[188:189] neg_lo:[0,0,1] neg_hi:[0,0,1]
	s_waitcnt lgkmcnt(8)
	v_fma_f32 v160, -v132, v56, v57
	v_pk_fma_f32 v[58:59], v[158:159], v[130:131], v[58:59] op_sel_hi:[0,1,1] neg_lo:[1,0,0] neg_hi:[1,0,0]
	ds_read_b128 v[128:131], v69 offset:37568
	s_waitcnt lgkmcnt(8)
	v_pk_fma_f32 v[58:59], v[60:61], v[136:137], v[58:59] op_sel_hi:[0,1,1] neg_lo:[1,0,0] neg_hi:[1,0,0]
	v_pk_fma_f32 v[58:59], v[138:139], v[62:63], v[58:59] op_sel_hi:[1,0,1] neg_lo:[1,0,0] neg_hi:[1,0,0]
	ds_read_b128 v[136:139], v69 offset:37584
	s_waitcnt lgkmcnt(8)
	v_pk_fma_f32 v[58:59], v[238:239], v[56:57], v[58:59] op_sel_hi:[1,0,1] neg_lo:[1,0,0] neg_hi:[1,0,0]
	s_nop 0
	v_pk_fma_f32 v[58:59], v[240:241], v[160:161], v[58:59] op_sel_hi:[1,0,1] neg_lo:[1,0,0] neg_hi:[1,0,0]
	ds_read_b128 v[238:241], v69 offset:38080
	v_fma_f32 v162, -v133, v58, v59
	ds_read_b128 v[132:135], v69 offset:38096
	s_waitcnt lgkmcnt(9)
	v_pk_mul_f32 v[188:189], v[66:67], v[242:243] op_sel_hi:[0,1]
	v_pk_fma_f32 v[48:49], v[178:179], v[48:49], v[188:189] neg_lo:[0,0,1] neg_hi:[0,0,1]
	v_pk_fma_f32 v[178:179], v[158:159], v[244:245], 0 op_sel_hi:[0,1,0] neg_lo:[1,0,0] neg_hi:[1,0,0]
	ds_read_b128 v[242:245], v69 offset:38112
	s_waitcnt lgkmcnt(9)
	v_pk_fma_f32 v[48:49], v[60:61], v[246:247], v[48:49] op_sel_hi:[0,1,1] neg_lo:[1,0,0] neg_hi:[1,0,0]
	v_pk_fma_f32 v[178:179], v[62:63], v[248:249], v[178:179] op_sel_hi:[0,1,1] neg_lo:[1,0,0] neg_hi:[1,0,0]
	ds_read_b128 v[246:249], v69 offset:38128
	s_waitcnt lgkmcnt(9)
	v_pk_fma_f32 v[48:49], v[112:113], v[56:57], v[48:49] op_sel_hi:[1,0,1] neg_lo:[1,0,0] neg_hi:[1,0,0]
	v_pk_fma_f32 v[178:179], v[114:115], v[160:161], v[178:179] op_sel_hi:[1,0,1] neg_lo:[1,0,0] neg_hi:[1,0,0]
	ds_read_b128 v[112:115], v69 offset:38624
	s_waitcnt lgkmcnt(9)
	v_pk_fma_f32 v[48:49], v[116:117], v[58:59], v[48:49] op_sel_hi:[1,0,1] neg_lo:[1,0,0] neg_hi:[1,0,0]
	v_pk_fma_f32 v[178:179], v[118:119], v[162:163], v[178:179] op_sel_hi:[1,0,1] neg_lo:[1,0,0] neg_hi:[1,0,0]
	ds_read_b128 v[116:119], v69 offset:38640
	v_pk_add_f32 v[48:49], v[48:49], v[178:179]
	s_waitcnt lgkmcnt(9)
	v_pk_mul_f32 v[178:179], v[66:67], v[120:121] op_sel_hi:[0,1]
	v_pk_fma_f32 v[50:51], v[172:173], v[50:51], v[178:179] neg_lo:[0,0,1] neg_hi:[0,0,1]
	v_pk_fma_f32 v[172:173], v[158:159], v[122:123], 0 op_sel_hi:[0,1,0] neg_lo:[1,0,0] neg_hi:[1,0,0]
	ds_read_b128 v[120:123], v69 offset:38656
	s_waitcnt lgkmcnt(9)
	v_pk_fma_f32 v[50:51], v[60:61], v[124:125], v[50:51] op_sel_hi:[0,1,1] neg_lo:[1,0,0] neg_hi:[1,0,0]
	v_pk_fma_f32 v[172:173], v[62:63], v[126:127], v[172:173] op_sel_hi:[0,1,1] neg_lo:[1,0,0] neg_hi:[1,0,0]
	ds_read_b128 v[124:127], v69 offset:38672
	s_waitcnt lgkmcnt(9)
	v_pk_fma_f32 v[50:51], v[56:57], v[128:129], v[50:51] op_sel_hi:[0,1,1] neg_lo:[1,0,0] neg_hi:[1,0,0]
	v_pk_fma_f32 v[172:173], v[130:131], v[160:161], v[172:173] op_sel_hi:[1,0,1] neg_lo:[1,0,0] neg_hi:[1,0,0]
	ds_read_b128 v[128:131], v69 offset:39168
	s_waitcnt lgkmcnt(9)
	v_pk_fma_f32 v[50:51], v[136:137], v[58:59], v[50:51] op_sel_hi:[1,0,1] neg_lo:[1,0,0] neg_hi:[1,0,0]
	v_pk_fma_f32 v[172:173], v[138:139], v[162:163], v[172:173] op_sel_hi:[1,0,1] neg_lo:[1,0,0] neg_hi:[1,0,0]
	ds_read_b128 v[136:139], v69 offset:39184
	v_pk_add_f32 v[178:179], v[50:51], v[172:173]
	s_waitcnt lgkmcnt(9)
	v_pk_mul_f32 v[50:51], v[66:67], v[238:239] op_sel_hi:[0,1]
	v_pk_fma_f32 v[4:5], v[164:165], v[4:5], v[50:51] neg_lo:[0,0,1] neg_hi:[0,0,1]
	v_pk_fma_f32 v[50:51], v[158:159], v[240:241], 0 op_sel_hi:[0,1,0] neg_lo:[1,0,0] neg_hi:[1,0,0]
	ds_read_b128 v[238:241], v69 offset:39200
	s_waitcnt lgkmcnt(9)
	v_pk_fma_f32 v[4:5], v[60:61], v[132:133], v[4:5] op_sel_hi:[0,1,1] neg_lo:[1,0,0] neg_hi:[1,0,0]
	v_pk_fma_f32 v[50:51], v[62:63], v[134:135], v[50:51] op_sel_hi:[0,1,1] neg_lo:[1,0,0] neg_hi:[1,0,0]
	ds_read_b128 v[132:135], v69 offset:39216
	s_waitcnt lgkmcnt(9)
; #define LAS __attribute__((address_space(3)))
; DI void gdn_prep_phase(const int tid, LAS unsigned char* lds, const P& p, int G, int c) {
;     ...
;               for (int pr = 4 * kb + 4; pr < 32; ++pr) {
;                   f32x2 s0 = (f32x2){xs[2 * pr], xs[2 * pr + 1]}, s1 = (f32x2){0.f, 0.f};
; #pragma unroll
;                   for (int q = 0; q < 4; ++q) { const int j = 8 * kb + 2 * q; const f32x4 l = *(const LAS f32x4*)(Ls + pr * 136 + j * 2);
;                       s0 -= (f32x2){l[0], l[1]} * (f32x2){xs[j], xs[j]}; s1 -= (f32x2){l[2], l[3]} * (f32x2){xs[j + 1], xs[j + 1]}; }
;                   const f32x2 s = s0 + s1; xs[2 * pr] = s[0]; xs[2 * pr + 1] = s[1]; }
	v_pk_fma_f32 v[4:5], v[56:57], v[242:243], v[4:5] op_sel_hi:[0,1,1] neg_lo:[1,0,0] neg_hi:[1,0,0]
	v_pk_fma_f32 v[50:51], v[160:161], v[244:245], v[50:51] op_sel_hi:[0,1,1] neg_lo:[1,0,0] neg_hi:[1,0,0]
	ds_read_b128 v[242:245], v69 offset:39712
	s_waitcnt lgkmcnt(9)
	v_pk_fma_f32 v[4:5], v[58:59], v[246:247], v[4:5] op_sel_hi:[0,1,1] neg_lo:[1,0,0] neg_hi:[1,0,0]
	v_pk_fma_f32 v[50:51], v[248:249], v[162:163], v[50:51] op_sel_hi:[1,0,1] neg_lo:[1,0,0] neg_hi:[1,0,0]
	ds_read_b128 v[246:249], v69 offset:39728
	v_pk_add_f32 v[188:189], v[4:5], v[50:51]
	s_waitcnt lgkmcnt(9)
	v_pk_mul_f32 v[4:5], v[66:67], v[112:113] op_sel_hi:[0,1]
	v_pk_fma_f32 v[50:51], v[166:167], v[6:7], v[4:5] neg_lo:[0,0,1] neg_hi:[0,0,1]
	v_pk_fma_f32 v[164:165], v[158:159], v[114:115], 0 op_sel_hi:[0,1,0] neg_lo:[1,0,0] neg_hi:[1,0,0]
	ds_read_b128 v[112:115], v69 offset:39744
	s_waitcnt lgkmcnt(9)
	v_pk_fma_f32 v[50:51], v[60:61], v[116:117], v[50:51] op_sel_hi:[0,1,1] neg_lo:[1,0,0] neg_hi:[1,0,0]
	v_pk_fma_f32 v[164:165], v[62:63], v[118:119], v[164:165] op_sel_hi:[0,1,1] neg_lo:[1,0,0] neg_hi:[1,0,0]
	ds_read_b128 v[116:119], v69 offset:39760
	s_waitcnt lgkmcnt(9)
	v_pk_fma_f32 v[50:51], v[56:57], v[120:121], v[50:51] op_sel_hi:[0,1,1] neg_lo:[1,0,0] neg_hi:[1,0,0]
	v_pk_fma_f32 v[164:165], v[160:161], v[122:123], v[164:165] op_sel_hi:[0,1,1] neg_lo:[1,0,0] neg_hi:[1,0,0]
	ds_read_b128 v[120:123], v69 offset:40256
	s_waitcnt lgkmcnt(9)
	v_pk_fma_f32 v[4:5], v[58:59], v[124:125], v[50:51] op_sel_hi:[0,1,1] neg_lo:[1,0,0] neg_hi:[1,0,0]
	v_pk_fma_f32 v[6:7], v[162:163], v[126:127], v[164:165] op_sel_hi:[0,1,1] neg_lo:[1,0,0] neg_hi:[1,0,0]
	ds_read_b128 v[124:127], v69 offset:40272
	v_pk_add_f32 v[50:51], v[4:5], v[6:7]
	s_waitcnt lgkmcnt(9)
	v_pk_mul_f32 v[4:5], v[66:67], v[128:129] op_sel_hi:[0,1]
	v_pk_fma_f32 v[8:9], v[168:169], v[8:9], v[4:5] neg_lo:[0,0,1] neg_hi:[0,0,1]
	v_pk_fma_f32 v[164:165], v[158:159], v[130:131], 0 op_sel_hi:[0,1,0] neg_lo:[1,0,0] neg_hi:[1,0,0]
	ds_read_b128 v[128:131], v69 offset:40288
	s_waitcnt lgkmcnt(9)
	v_pk_fma_f32 v[8:9], v[60:61], v[136:137], v[8:9] op_sel_hi:[0,1,1] neg_lo:[1,0,0] neg_hi:[1,0,0]
	v_pk_fma_f32 v[164:165], v[62:63], v[138:139], v[164:165] op_sel_hi:[0,1,1] neg_lo:[1,0,0] neg_hi:[1,0,0]
	ds_read_b128 v[136:139], v69 offset:40304
	s_waitcnt lgkmcnt(9)
	v_pk_fma_f32 v[8:9], v[56:57], v[238:239], v[8:9] op_sel_hi:[0,1,1] neg_lo:[1,0,0] neg_hi:[1,0,0]
	v_pk_fma_f32 v[164:165], v[160:161], v[240:241], v[164:165] op_sel_hi:[0,1,1] neg_lo:[1,0,0] neg_hi:[1,0,0]
	ds_read_b128 v[238:241], v69 offset:40800
	s_waitcnt lgkmcnt(9)
	v_pk_fma_f32 v[4:5], v[58:59], v[132:133], v[8:9] op_sel_hi:[0,1,1] neg_lo:[1,0,0] neg_hi:[1,0,0]
	v_pk_fma_f32 v[6:7], v[162:163], v[134:135], v[164:165] op_sel_hi:[0,1,1] neg_lo:[1,0,0] neg_hi:[1,0,0]
	ds_read_b128 v[132:135], v69 offset:40816
	v_pk_add_f32 v[164:165], v[4:5], v[6:7]
	s_waitcnt lgkmcnt(9)
	v_pk_mul_f32 v[4:5], v[66:67], v[242:243] op_sel_hi:[0,1]
	v_pk_fma_f32 v[8:9], v[170:171], v[10:11], v[4:5] neg_lo:[0,0,1] neg_hi:[0,0,1]
	v_pk_fma_f32 v[10:11], v[158:159], v[244:245], 0 op_sel_hi:[0,1,0] neg_lo:[1,0,0] neg_hi:[1,0,0]
	ds_read_b128 v[242:245], v69 offset:40832
	s_waitcnt lgkmcnt(9)
	v_pk_fma_f32 v[8:9], v[60:61], v[246:247], v[8:9] op_sel_hi:[0,1,1] neg_lo:[1,0,0] neg_hi:[1,0,0]
	v_pk_fma_f32 v[10:11], v[62:63], v[248:249], v[10:11] op_sel_hi:[0,1,1] neg_lo:[1,0,0] neg_hi:[1,0,0]
	ds_read_b128 v[246:249], v69 offset:40848
	s_waitcnt lgkmcnt(9)
	v_pk_fma_f32 v[8:9], v[56:57], v[112:113], v[8:9] op_sel_hi:[0,1,1] neg_lo:[1,0,0] neg_hi:[1,0,0]
	v_pk_fma_f32 v[10:11], v[160:161], v[114:115], v[10:11] op_sel_hi:[0,1,1] neg_lo:[1,0,0] neg_hi:[1,0,0]
	ds_read_b128 v[112:115], v69 offset:41344
	s_waitcnt lgkmcnt(9)
	v_pk_fma_f32 v[4:5], v[58:59], v[116:117], v[8:9] op_sel_hi:[0,1,1] neg_lo:[1,0,0] neg_hi:[1,0,0]
	v_pk_fma_f32 v[6:7], v[162:163], v[118:119], v[10:11] op_sel_hi:[0,1,1] neg_lo:[1,0,0] neg_hi:[1,0,0]
	ds_read_b128 v[116:119], v69 offset:41360
	v_pk_add_f32 v[166:167], v[4:5], v[6:7]
	s_waitcnt lgkmcnt(9)
	v_pk_mul_f32 v[4:5], v[66:67], v[120:121] op_sel_hi:[0,1]
	v_pk_fma_f32 v[0:1], v[174:175], v[0:1], v[4:5] neg_lo:[0,0,1] neg_hi:[0,0,1]
	v_pk_fma_f32 v[8:9], v[158:159], v[122:123], 0 op_sel_hi:[0,1,0] neg_lo:[1,0,0] neg_hi:[1,0,0]
	ds_read_b128 v[120:123], v69 offset:41376
	s_waitcnt lgkmcnt(9)
	v_pk_fma_f32 v[0:1], v[60:61], v[124:125], v[0:1] op_sel_hi:[0,1,1] neg_lo:[1,0,0] neg_hi:[1,0,0]
	v_pk_fma_f32 v[8:9], v[62:63], v[126:127], v[8:9] op_sel_hi:[0,1,1] neg_lo:[1,0,0] neg_hi:[1,0,0]
	ds_read_b128 v[124:127], v69 offset:41392
	s_waitcnt lgkmcnt(9)
	v_pk_fma_f32 v[0:1], v[56:57], v[128:129], v[0:1] op_sel_hi:[0,1,1] neg_lo:[1,0,0] neg_hi:[1,0,0]
	v_pk_fma_f32 v[8:9], v[160:161], v[130:131], v[8:9] op_sel_hi:[0,1,1] neg_lo:[1,0,0] neg_hi:[1,0,0]
	ds_read_b128 v[128:131], v69 offset:41888
	s_waitcnt lgkmcnt(9)
	v_pk_fma_f32 v[0:1], v[58:59], v[136:137], v[0:1] op_sel_hi:[0,1,1] neg_lo:[1,0,0] neg_hi:[1,0,0]
	v_pk_fma_f32 v[4:5], v[162:163], v[138:139], v[8:9] op_sel_hi:[0,1,1] neg_lo:[1,0,0] neg_hi:[1,0,0]
	ds_read_b128 v[136:139], v69 offset:41904
	v_pk_add_f32 v[168:169], v[0:1], v[4:5]
	s_waitcnt lgkmcnt(9)
	v_pk_mul_f32 v[0:1], v[66:67], v[238:239] op_sel_hi:[0,1]
	v_pk_fma_f32 v[4:5], v[176:177], v[2:3], v[0:1] neg_lo:[0,0,1] neg_hi:[0,0,1]
	v_pk_fma_f32 v[6:7], v[158:159], v[240:241], 0 op_sel_hi:[0,1,0] neg_lo:[1,0,0] neg_hi:[1,0,0]
	ds_read_b128 v[238:241], v69 offset:41920
	s_waitcnt lgkmcnt(9)
	v_pk_fma_f32 v[4:5], v[60:61], v[132:133], v[4:5] op_sel_hi:[0,1,1] neg_lo:[1,0,0] neg_hi:[1,0,0]
	v_pk_fma_f32 v[6:7], v[62:63], v[134:135], v[6:7] op_sel_hi:[0,1,1] neg_lo:[1,0,0] neg_hi:[1,0,0]
	ds_read_b128 v[132:135], v69 offset:41936
	s_waitcnt lgkmcnt(9)
; #define LAS __attribute__((address_space(3)))
; DI void gdn_prep_phase(const int tid, LAS unsigned char* lds, const P& p, int G, int c) {
;     ...
;               for (int pr = 4 * kb + 4; pr < 32; ++pr) {
;                   f32x2 s0 = (f32x2){xs[2 * pr], xs[2 * pr + 1]}, s1 = (f32x2){0.f, 0.f};
; #pragma unroll
;                   for (int q = 0; q < 4; ++q) { const int j = 8 * kb + 2 * q; const f32x4 l = *(const LAS f32x4*)(Ls + pr * 136 + j * 2);
;                       s0 -= (f32x2){l[0], l[1]} * (f32x2){xs[j], xs[j]}; s1 -= (f32x2){l[2], l[3]} * (f32x2){xs[j + 1], xs[j + 1]}; }
;                   const f32x2 s = s0 + s1; xs[2 * pr] = s[0]; xs[2 * pr + 1] = s[1]; }
	v_pk_fma_f32 v[4:5], v[56:57], v[242:243], v[4:5] op_sel_hi:[0,1,1] neg_lo:[1,0,0] neg_hi:[1,0,0]
	v_pk_fma_f32 v[6:7], v[160:161], v[244:245], v[6:7] op_sel_hi:[0,1,1] neg_lo:[1,0,0] neg_hi:[1,0,0]
	ds_read_b128 v[242:245], v69 offset:42432
	s_waitcnt lgkmcnt(9)
	v_pk_fma_f32 v[0:1], v[58:59], v[246:247], v[4:5] op_sel_hi:[0,1,1] neg_lo:[1,0,0] neg_hi:[1,0,0]
	v_pk_fma_f32 v[2:3], v[162:163], v[248:249], v[6:7] op_sel_hi:[0,1,1] neg_lo:[1,0,0] neg_hi:[1,0,0]
	ds_read_b128 v[246:249], v69 offset:42448
	v_pk_add_f32 v[170:171], v[0:1], v[2:3]
	s_waitcnt lgkmcnt(9)
	v_pk_mul_f32 v[0:1], v[66:67], v[112:113] op_sel_hi:[0,1]
	v_pk_fma_f32 v[4:5], v[184:185], v[16:17], v[0:1] neg_lo:[0,0,1] neg_hi:[0,0,1]
	v_pk_fma_f32 v[6:7], v[158:159], v[114:115], 0 op_sel_hi:[0,1,0] neg_lo:[1,0,0] neg_hi:[1,0,0]
	ds_read_b128 v[112:115], v69 offset:42464
	s_waitcnt lgkmcnt(9)
	v_pk_fma_f32 v[4:5], v[60:61], v[116:117], v[4:5] op_sel_hi:[0,1,1] neg_lo:[1,0,0] neg_hi:[1,0,0]
	v_pk_fma_f32 v[6:7], v[62:63], v[118:119], v[6:7] op_sel_hi:[0,1,1] neg_lo:[1,0,0] neg_hi:[1,0,0]
	ds_read_b128 v[116:119], v69 offset:42480
	s_waitcnt lgkmcnt(9)
	v_pk_fma_f32 v[4:5], v[56:57], v[120:121], v[4:5] op_sel_hi:[0,1,1] neg_lo:[1,0,0] neg_hi:[1,0,0]
	v_pk_fma_f32 v[6:7], v[160:161], v[122:123], v[6:7] op_sel_hi:[0,1,1] neg_lo:[1,0,0] neg_hi:[1,0,0]
	ds_read_b128 v[120:123], v69 offset:42976
	s_waitcnt lgkmcnt(9)
	v_pk_fma_f32 v[0:1], v[58:59], v[124:125], v[4:5] op_sel_hi:[0,1,1] neg_lo:[1,0,0] neg_hi:[1,0,0]
	v_pk_fma_f32 v[2:3], v[162:163], v[126:127], v[6:7] op_sel_hi:[0,1,1] neg_lo:[1,0,0] neg_hi:[1,0,0]
	ds_read_b128 v[124:127], v69 offset:42992
	v_pk_add_f32 v[16:17], v[0:1], v[2:3]
	s_waitcnt lgkmcnt(9)
	v_pk_mul_f32 v[0:1], v[66:67], v[128:129] op_sel_hi:[0,1]
	v_pk_fma_f32 v[4:5], v[186:187], v[18:19], v[0:1] neg_lo:[0,0,1] neg_hi:[0,0,1]
	v_pk_fma_f32 v[6:7], v[158:159], v[130:131], 0 op_sel_hi:[0,1,0] neg_lo:[1,0,0] neg_hi:[1,0,0]
	ds_read_b128 v[128:131], v69 offset:43008
	s_waitcnt lgkmcnt(9)
	v_pk_fma_f32 v[4:5], v[60:61], v[136:137], v[4:5] op_sel_hi:[0,1,1] neg_lo:[1,0,0] neg_hi:[1,0,0]
	v_pk_fma_f32 v[6:7], v[62:63], v[138:139], v[6:7] op_sel_hi:[0,1,1] neg_lo:[1,0,0] neg_hi:[1,0,0]
	ds_read_b128 v[136:139], v69 offset:43024
	s_waitcnt lgkmcnt(9)
	v_pk_fma_f32 v[4:5], v[56:57], v[238:239], v[4:5] op_sel_hi:[0,1,1] neg_lo:[1,0,0] neg_hi:[1,0,0]
	v_pk_fma_f32 v[6:7], v[160:161], v[240:241], v[6:7] op_sel_hi:[0,1,1] neg_lo:[1,0,0] neg_hi:[1,0,0]
	ds_read_b128 v[238:241], v69 offset:43520
	s_waitcnt lgkmcnt(9)
	v_pk_fma_f32 v[0:1], v[58:59], v[132:133], v[4:5] op_sel_hi:[0,1,1] neg_lo:[1,0,0] neg_hi:[1,0,0]
	v_pk_fma_f32 v[2:3], v[162:163], v[134:135], v[6:7] op_sel_hi:[0,1,1] neg_lo:[1,0,0] neg_hi:[1,0,0]
	ds_read_b128 v[132:135], v69 offset:43536
	v_pk_add_f32 v[18:19], v[0:1], v[2:3]
	s_waitcnt lgkmcnt(9)
	v_pk_mul_f32 v[0:1], v[66:67], v[242:243] op_sel_hi:[0,1]
	v_pk_fma_f32 v[4:5], v[190:191], v[12:13], v[0:1] neg_lo:[0,0,1] neg_hi:[0,0,1]
	v_pk_fma_f32 v[6:7], v[158:159], v[244:245], 0 op_sel_hi:[0,1,0] neg_lo:[1,0,0] neg_hi:[1,0,0]
	ds_read_b128 v[242:245], v69 offset:43552
	s_waitcnt lgkmcnt(9)
	v_pk_fma_f32 v[4:5], v[60:61], v[246:247], v[4:5] op_sel_hi:[0,1,1] neg_lo:[1,0,0] neg_hi:[1,0,0]
	v_pk_fma_f32 v[6:7], v[62:63], v[248:249], v[6:7] op_sel_hi:[0,1,1] neg_lo:[1,0,0] neg_hi:[1,0,0]
	ds_read_b128 v[246:249], v69 offset:43568
	s_waitcnt lgkmcnt(9)
	v_pk_fma_f32 v[4:5], v[56:57], v[112:113], v[4:5] op_sel_hi:[0,1,1] neg_lo:[1,0,0] neg_hi:[1,0,0]
	v_pk_fma_f32 v[6:7], v[160:161], v[114:115], v[6:7] op_sel_hi:[0,1,1] neg_lo:[1,0,0] neg_hi:[1,0,0]
	ds_read_b128 v[112:115], v69 offset:44064
	s_waitcnt lgkmcnt(9)
	v_pk_fma_f32 v[0:1], v[58:59], v[116:117], v[4:5] op_sel_hi:[0,1,1] neg_lo:[1,0,0] neg_hi:[1,0,0]
	v_pk_fma_f32 v[2:3], v[162:163], v[118:119], v[6:7] op_sel_hi:[0,1,1] neg_lo:[1,0,0] neg_hi:[1,0,0]
	ds_read_b128 v[116:119], v69 offset:44080
	v_pk_add_f32 v[172:173], v[0:1], v[2:3]
	s_waitcnt lgkmcnt(9)
	v_pk_mul_f32 v[0:1], v[66:67], v[120:121] op_sel_hi:[0,1]
	v_pk_fma_f32 v[4:5], v[192:193], v[14:15], v[0:1] neg_lo:[0,0,1] neg_hi:[0,0,1]
	v_pk_fma_f32 v[6:7], v[158:159], v[122:123], 0 op_sel_hi:[0,1,0] neg_lo:[1,0,0] neg_hi:[1,0,0]
	ds_read_b128 v[120:123], v69 offset:44096
	s_waitcnt lgkmcnt(9)
	v_pk_fma_f32 v[4:5], v[60:61], v[124:125], v[4:5] op_sel_hi:[0,1,1] neg_lo:[1,0,0] neg_hi:[1,0,0]
	v_pk_fma_f32 v[6:7], v[62:63], v[126:127], v[6:7] op_sel_hi:[0,1,1] neg_lo:[1,0,0] neg_hi:[1,0,0]
	ds_read_b128 v[124:127], v69 offset:44112
	s_waitcnt lgkmcnt(9)
	v_pk_fma_f32 v[4:5], v[56:57], v[128:129], v[4:5] op_sel_hi:[0,1,1] neg_lo:[1,0,0] neg_hi:[1,0,0]
	v_pk_fma_f32 v[6:7], v[160:161], v[130:131], v[6:7] op_sel_hi:[0,1,1] neg_lo:[1,0,0] neg_hi:[1,0,0]
	ds_read_b128 v[128:131], v69 offset:44608
	s_waitcnt lgkmcnt(9)
	v_pk_fma_f32 v[0:1], v[58:59], v[136:137], v[4:5] op_sel_hi:[0,1,1] neg_lo:[1,0,0] neg_hi:[1,0,0]
	v_pk_fma_f32 v[2:3], v[162:163], v[138:139], v[6:7] op_sel_hi:[0,1,1] neg_lo:[1,0,0] neg_hi:[1,0,0]
	ds_read_b128 v[136:139], v69 offset:44624
	v_pk_add_f32 v[174:175], v[0:1], v[2:3]
	s_waitcnt lgkmcnt(9)
	v_pk_mul_f32 v[0:1], v[66:67], v[238:239] op_sel_hi:[0,1]
	v_pk_fma_f32 v[4:5], v[194:195], v[36:37], v[0:1] neg_lo:[0,0,1] neg_hi:[0,0,1]
	v_pk_fma_f32 v[6:7], v[158:159], v[240:241], 0 op_sel_hi:[0,1,0] neg_lo:[1,0,0] neg_hi:[1,0,0]
	ds_read_b128 v[238:241], v69 offset:44640
	s_waitcnt lgkmcnt(9)
	v_pk_fma_f32 v[4:5], v[60:61], v[132:133], v[4:5] op_sel_hi:[0,1,1] neg_lo:[1,0,0] neg_hi:[1,0,0]
	v_pk_fma_f32 v[6:7], v[62:63], v[134:135], v[6:7] op_sel_hi:[0,1,1] neg_lo:[1,0,0] neg_hi:[1,0,0]
	ds_read_b128 v[132:135], v69 offset:44656
	s_waitcnt lgkmcnt(9)
; #define LAS __attribute__((address_space(3)))
; DI void gdn_prep_phase(const int tid, LAS unsigned char* lds, const P& p, int G, int c) {
;     ...
;               for (int pr = 4 * kb + 4; pr < 32; ++pr) {
;                   f32x2 s0 = (f32x2){xs[2 * pr], xs[2 * pr + 1]}, s1 = (f32x2){0.f, 0.f};
; #pragma unroll
;                   for (int q = 0; q < 4; ++q) { const int j = 8 * kb + 2 * q; const f32x4 l = *(const LAS f32x4*)(Ls + pr * 136 + j * 2);
;                       s0 -= (f32x2){l[0], l[1]} * (f32x2){xs[j], xs[j]}; s1 -= (f32x2){l[2], l[3]} * (f32x2){xs[j + 1], xs[j + 1]}; }
;                   const f32x2 s = s0 + s1; xs[2 * pr] = s[0]; xs[2 * pr + 1] = s[1]; }
	v_pk_fma_f32 v[4:5], v[56:57], v[242:243], v[4:5] op_sel_hi:[0,1,1] neg_lo:[1,0,0] neg_hi:[1,0,0]
	v_pk_fma_f32 v[6:7], v[160:161], v[244:245], v[6:7] op_sel_hi:[0,1,1] neg_lo:[1,0,0] neg_hi:[1,0,0]
	ds_read_b128 v[242:245], v69 offset:45152
	s_waitcnt lgkmcnt(9)
	v_pk_fma_f32 v[0:1], v[58:59], v[246:247], v[4:5] op_sel_hi:[0,1,1] neg_lo:[1,0,0] neg_hi:[1,0,0]
	v_pk_fma_f32 v[2:3], v[162:163], v[248:249], v[6:7] op_sel_hi:[0,1,1] neg_lo:[1,0,0] neg_hi:[1,0,0]
	ds_read_b128 v[246:249], v69 offset:45168
	v_pk_add_f32 v[36:37], v[0:1], v[2:3]
	s_waitcnt lgkmcnt(9)
	v_pk_mul_f32 v[0:1], v[66:67], v[112:113] op_sel_hi:[0,1]
	v_pk_fma_f32 v[4:5], v[196:197], v[38:39], v[0:1] neg_lo:[0,0,1] neg_hi:[0,0,1]
	v_pk_fma_f32 v[6:7], v[158:159], v[114:115], 0 op_sel_hi:[0,1,0] neg_lo:[1,0,0] neg_hi:[1,0,0]
	ds_read_b128 v[112:115], v69 offset:45184
	s_waitcnt lgkmcnt(9)
	v_pk_fma_f32 v[4:5], v[60:61], v[116:117], v[4:5] op_sel_hi:[0,1,1] neg_lo:[1,0,0] neg_hi:[1,0,0]
	v_pk_fma_f32 v[6:7], v[62:63], v[118:119], v[6:7] op_sel_hi:[0,1,1] neg_lo:[1,0,0] neg_hi:[1,0,0]
	ds_read_b128 v[116:119], v69 offset:45200
	s_waitcnt lgkmcnt(9)
	v_pk_fma_f32 v[4:5], v[56:57], v[120:121], v[4:5] op_sel_hi:[0,1,1] neg_lo:[1,0,0] neg_hi:[1,0,0]
	v_pk_fma_f32 v[6:7], v[160:161], v[122:123], v[6:7] op_sel_hi:[0,1,1] neg_lo:[1,0,0] neg_hi:[1,0,0]
	ds_read_b128 v[120:123], v69 offset:45696
	s_waitcnt lgkmcnt(9)
	v_pk_fma_f32 v[0:1], v[58:59], v[124:125], v[4:5] op_sel_hi:[0,1,1] neg_lo:[1,0,0] neg_hi:[1,0,0]
	v_pk_fma_f32 v[2:3], v[162:163], v[126:127], v[6:7] op_sel_hi:[0,1,1] neg_lo:[1,0,0] neg_hi:[1,0,0]
	ds_read_b128 v[124:127], v69 offset:45712
	v_pk_add_f32 v[38:39], v[0:1], v[2:3]
	s_waitcnt lgkmcnt(9)
	v_pk_mul_f32 v[0:1], v[66:67], v[128:129] op_sel_hi:[0,1]
	v_pk_fma_f32 v[4:5], v[198:199], v[24:25], v[0:1] neg_lo:[0,0,1] neg_hi:[0,0,1]
	v_pk_fma_f32 v[6:7], v[158:159], v[130:131], 0 op_sel_hi:[0,1,0] neg_lo:[1,0,0] neg_hi:[1,0,0]
	ds_read_b128 v[128:131], v69 offset:45728
	s_waitcnt lgkmcnt(9)
	v_pk_fma_f32 v[4:5], v[60:61], v[136:137], v[4:5] op_sel_hi:[0,1,1] neg_lo:[1,0,0] neg_hi:[1,0,0]
	v_pk_fma_f32 v[6:7], v[62:63], v[138:139], v[6:7] op_sel_hi:[0,1,1] neg_lo:[1,0,0] neg_hi:[1,0,0]
	ds_read_b128 v[136:139], v69 offset:45744
	s_waitcnt lgkmcnt(9)
	v_pk_fma_f32 v[4:5], v[56:57], v[238:239], v[4:5] op_sel_hi:[0,1,1] neg_lo:[1,0,0] neg_hi:[1,0,0]
	v_pk_fma_f32 v[6:7], v[160:161], v[240:241], v[6:7] op_sel_hi:[0,1,1] neg_lo:[1,0,0] neg_hi:[1,0,0]
	ds_read_b128 v[238:241], v69 offset:46240
	s_waitcnt lgkmcnt(9)
	v_pk_fma_f32 v[0:1], v[58:59], v[132:133], v[4:5] op_sel_hi:[0,1,1] neg_lo:[1,0,0] neg_hi:[1,0,0]
	v_pk_fma_f32 v[2:3], v[162:163], v[134:135], v[6:7] op_sel_hi:[0,1,1] neg_lo:[1,0,0] neg_hi:[1,0,0]
	ds_read_b128 v[132:135], v69 offset:46256
	v_pk_add_f32 v[24:25], v[0:1], v[2:3]
	s_waitcnt lgkmcnt(9)
	v_pk_mul_f32 v[0:1], v[66:67], v[242:243] op_sel_hi:[0,1]
	v_pk_fma_f32 v[4:5], v[200:201], v[26:27], v[0:1] neg_lo:[0,0,1] neg_hi:[0,0,1]
	v_pk_fma_f32 v[6:7], v[158:159], v[244:245], 0 op_sel_hi:[0,1,0] neg_lo:[1,0,0] neg_hi:[1,0,0]
	ds_read_b128 v[242:245], v69 offset:46272
	s_waitcnt lgkmcnt(9)
	v_pk_fma_f32 v[4:5], v[60:61], v[246:247], v[4:5] op_sel_hi:[0,1,1] neg_lo:[1,0,0] neg_hi:[1,0,0]
	v_pk_fma_f32 v[6:7], v[62:63], v[248:249], v[6:7] op_sel_hi:[0,1,1] neg_lo:[1,0,0] neg_hi:[1,0,0]
	ds_read_b128 v[246:249], v69 offset:46288
	s_waitcnt lgkmcnt(9)
	v_pk_fma_f32 v[4:5], v[56:57], v[112:113], v[4:5] op_sel_hi:[0,1,1] neg_lo:[1,0,0] neg_hi:[1,0,0]
	v_pk_fma_f32 v[6:7], v[160:161], v[114:115], v[6:7] op_sel_hi:[0,1,1] neg_lo:[1,0,0] neg_hi:[1,0,0]
	ds_read_b128 v[112:115], v69 offset:46784
	s_waitcnt lgkmcnt(9)
	v_pk_fma_f32 v[0:1], v[58:59], v[116:117], v[4:5] op_sel_hi:[0,1,1] neg_lo:[1,0,0] neg_hi:[1,0,0]
	v_pk_fma_f32 v[2:3], v[162:163], v[118:119], v[6:7] op_sel_hi:[0,1,1] neg_lo:[1,0,0] neg_hi:[1,0,0]
	ds_read_b128 v[116:119], v69 offset:46800
	v_pk_add_f32 v[26:27], v[0:1], v[2:3]
	s_waitcnt lgkmcnt(9)
	v_pk_mul_f32 v[0:1], v[66:67], v[120:121] op_sel_hi:[0,1]
	v_pk_fma_f32 v[4:5], v[202:203], v[40:41], v[0:1] neg_lo:[0,0,1] neg_hi:[0,0,1]
	v_pk_fma_f32 v[6:7], v[158:159], v[122:123], 0 op_sel_hi:[0,1,0] neg_lo:[1,0,0] neg_hi:[1,0,0]
	ds_read_b128 v[120:123], v69 offset:46816
	s_waitcnt lgkmcnt(9)
	v_pk_fma_f32 v[4:5], v[60:61], v[124:125], v[4:5] op_sel_hi:[0,1,1] neg_lo:[1,0,0] neg_hi:[1,0,0]
	v_pk_fma_f32 v[6:7], v[62:63], v[126:127], v[6:7] op_sel_hi:[0,1,1] neg_lo:[1,0,0] neg_hi:[1,0,0]
	ds_read_b128 v[124:127], v69 offset:46832
	s_waitcnt lgkmcnt(9)
	v_pk_fma_f32 v[4:5], v[56:57], v[128:129], v[4:5] op_sel_hi:[0,1,1] neg_lo:[1,0,0] neg_hi:[1,0,0]
	v_pk_fma_f32 v[6:7], v[160:161], v[130:131], v[6:7] op_sel_hi:[0,1,1] neg_lo:[1,0,0] neg_hi:[1,0,0]
	ds_read_b128 v[128:131], v69 offset:47328
	s_waitcnt lgkmcnt(9)
	v_pk_fma_f32 v[0:1], v[58:59], v[136:137], v[4:5] op_sel_hi:[0,1,1] neg_lo:[1,0,0] neg_hi:[1,0,0]
	v_pk_fma_f32 v[2:3], v[162:163], v[138:139], v[6:7] op_sel_hi:[0,1,1] neg_lo:[1,0,0] neg_hi:[1,0,0]
	ds_read_b128 v[136:139], v69 offset:47344
	v_pk_add_f32 v[40:41], v[0:1], v[2:3]
	s_waitcnt lgkmcnt(9)
	v_pk_mul_f32 v[0:1], v[66:67], v[238:239] op_sel_hi:[0,1]
	v_pk_fma_f32 v[4:5], v[204:205], v[42:43], v[0:1] neg_lo:[0,0,1] neg_hi:[0,0,1]
	v_pk_fma_f32 v[6:7], v[158:159], v[240:241], 0 op_sel_hi:[0,1,0] neg_lo:[1,0,0] neg_hi:[1,0,0]
	ds_read_b128 v[238:241], v69 offset:47360
	s_waitcnt lgkmcnt(9)
	v_pk_fma_f32 v[4:5], v[60:61], v[132:133], v[4:5] op_sel_hi:[0,1,1] neg_lo:[1,0,0] neg_hi:[1,0,0]
	v_pk_fma_f32 v[6:7], v[62:63], v[134:135], v[6:7] op_sel_hi:[0,1,1] neg_lo:[1,0,0] neg_hi:[1,0,0]
	ds_read_b128 v[132:135], v69 offset:47376
	s_waitcnt lgkmcnt(9)
; #define LAS __attribute__((address_space(3)))
; DI void gdn_prep_phase(const int tid, LAS unsigned char* lds, const P& p, int G, int c) {
;     ...
;               for (int pr = 4 * kb + 4; pr < 32; ++pr) {
;                   f32x2 s0 = (f32x2){xs[2 * pr], xs[2 * pr + 1]}, s1 = (f32x2){0.f, 0.f};
; #pragma unroll
;                   for (int q = 0; q < 4; ++q) { const int j = 8 * kb + 2 * q; const f32x4 l = *(const LAS f32x4*)(Ls + pr * 136 + j * 2);
;                       s0 -= (f32x2){l[0], l[1]} * (f32x2){xs[j], xs[j]}; s1 -= (f32x2){l[2], l[3]} * (f32x2){xs[j + 1], xs[j + 1]}; }
;                   const f32x2 s = s0 + s1; xs[2 * pr] = s[0]; xs[2 * pr + 1] = s[1]; }
	v_pk_fma_f32 v[4:5], v[56:57], v[242:243], v[4:5] op_sel_hi:[0,1,1] neg_lo:[1,0,0] neg_hi:[1,0,0]
	v_pk_fma_f32 v[6:7], v[160:161], v[244:245], v[6:7] op_sel_hi:[0,1,1] neg_lo:[1,0,0] neg_hi:[1,0,0]
	ds_read_b128 v[242:245], v69 offset:47872
	s_waitcnt lgkmcnt(9)
	v_pk_fma_f32 v[0:1], v[58:59], v[246:247], v[4:5] op_sel_hi:[0,1,1] neg_lo:[1,0,0] neg_hi:[1,0,0]
	v_pk_fma_f32 v[2:3], v[162:163], v[248:249], v[6:7] op_sel_hi:[0,1,1] neg_lo:[1,0,0] neg_hi:[1,0,0]
	ds_read_b128 v[246:249], v69 offset:47888
	v_pk_add_f32 v[42:43], v[0:1], v[2:3]
	s_waitcnt lgkmcnt(9)
	v_pk_mul_f32 v[0:1], v[66:67], v[112:113] op_sel_hi:[0,1]
	v_pk_fma_f32 v[4:5], v[206:207], v[32:33], v[0:1] neg_lo:[0,0,1] neg_hi:[0,0,1]
	v_pk_fma_f32 v[6:7], v[158:159], v[114:115], 0 op_sel_hi:[0,1,0] neg_lo:[1,0,0] neg_hi:[1,0,0]
	ds_read_b128 v[112:115], v69 offset:47904
	s_waitcnt lgkmcnt(9)
	v_pk_fma_f32 v[4:5], v[60:61], v[116:117], v[4:5] op_sel_hi:[0,1,1] neg_lo:[1,0,0] neg_hi:[1,0,0]
	v_pk_fma_f32 v[6:7], v[62:63], v[118:119], v[6:7] op_sel_hi:[0,1,1] neg_lo:[1,0,0] neg_hi:[1,0,0]
	ds_read_b128 v[116:119], v69 offset:47920
	s_waitcnt lgkmcnt(9)
	v_pk_fma_f32 v[4:5], v[56:57], v[120:121], v[4:5] op_sel_hi:[0,1,1] neg_lo:[1,0,0] neg_hi:[1,0,0]
	v_pk_fma_f32 v[6:7], v[160:161], v[122:123], v[6:7] op_sel_hi:[0,1,1] neg_lo:[1,0,0] neg_hi:[1,0,0]
	ds_read_b128 v[120:123], v69 offset:48416
	s_waitcnt lgkmcnt(9)
	v_pk_fma_f32 v[0:1], v[58:59], v[124:125], v[4:5] op_sel_hi:[0,1,1] neg_lo:[1,0,0] neg_hi:[1,0,0]
	v_pk_fma_f32 v[2:3], v[162:163], v[126:127], v[6:7] op_sel_hi:[0,1,1] neg_lo:[1,0,0] neg_hi:[1,0,0]
	ds_read_b128 v[124:127], v69 offset:48432
	v_pk_add_f32 v[32:33], v[0:1], v[2:3]
	s_waitcnt lgkmcnt(9)
	v_pk_mul_f32 v[0:1], v[66:67], v[128:129] op_sel_hi:[0,1]
	v_pk_fma_f32 v[4:5], v[208:209], v[34:35], v[0:1] neg_lo:[0,0,1] neg_hi:[0,0,1]
	v_pk_fma_f32 v[6:7], v[158:159], v[130:131], 0 op_sel_hi:[0,1,0] neg_lo:[1,0,0] neg_hi:[1,0,0]
	ds_read_b128 v[128:131], v69 offset:48448
	s_waitcnt lgkmcnt(9)
	v_pk_fma_f32 v[4:5], v[60:61], v[136:137], v[4:5] op_sel_hi:[0,1,1] neg_lo:[1,0,0] neg_hi:[1,0,0]
	v_pk_fma_f32 v[6:7], v[62:63], v[138:139], v[6:7] op_sel_hi:[0,1,1] neg_lo:[1,0,0] neg_hi:[1,0,0]
	ds_read_b128 v[136:139], v69 offset:48464
	s_waitcnt lgkmcnt(9)
	v_pk_fma_f32 v[4:5], v[56:57], v[238:239], v[4:5] op_sel_hi:[0,1,1] neg_lo:[1,0,0] neg_hi:[1,0,0]
	v_pk_fma_f32 v[6:7], v[160:161], v[240:241], v[6:7] op_sel_hi:[0,1,1] neg_lo:[1,0,0] neg_hi:[1,0,0]
	ds_read_b128 v[238:241], v69 offset:48960
	s_waitcnt lgkmcnt(9)
	v_pk_fma_f32 v[0:1], v[58:59], v[132:133], v[4:5] op_sel_hi:[0,1,1] neg_lo:[1,0,0] neg_hi:[1,0,0]
	v_pk_fma_f32 v[2:3], v[162:163], v[134:135], v[6:7] op_sel_hi:[0,1,1] neg_lo:[1,0,0] neg_hi:[1,0,0]
	ds_read_b128 v[132:135], v69 offset:48976
	v_pk_add_f32 v[34:35], v[0:1], v[2:3]
	s_waitcnt lgkmcnt(9)
	v_pk_mul_f32 v[0:1], v[66:67], v[242:243] op_sel_hi:[0,1]
	v_pk_fma_f32 v[4:5], v[210:211], v[28:29], v[0:1] neg_lo:[0,0,1] neg_hi:[0,0,1]
	v_pk_fma_f32 v[6:7], v[158:159], v[244:245], 0 op_sel_hi:[0,1,0] neg_lo:[1,0,0] neg_hi:[1,0,0]
	ds_read_b128 v[242:245], v69 offset:48992
	s_waitcnt lgkmcnt(9)
	v_pk_fma_f32 v[4:5], v[60:61], v[246:247], v[4:5] op_sel_hi:[0,1,1] neg_lo:[1,0,0] neg_hi:[1,0,0]
	v_pk_fma_f32 v[6:7], v[62:63], v[248:249], v[6:7] op_sel_hi:[0,1,1] neg_lo:[1,0,0] neg_hi:[1,0,0]
	ds_read_b128 v[246:249], v69 offset:49008
	s_waitcnt lgkmcnt(9)
	v_pk_fma_f32 v[4:5], v[56:57], v[112:113], v[4:5] op_sel_hi:[0,1,1] neg_lo:[1,0,0] neg_hi:[1,0,0]
	v_pk_fma_f32 v[6:7], v[160:161], v[114:115], v[6:7] op_sel_hi:[0,1,1] neg_lo:[1,0,0] neg_hi:[1,0,0]
	ds_read_b128 v[112:115], v69 offset:49504
	s_waitcnt lgkmcnt(9)
	v_pk_fma_f32 v[0:1], v[58:59], v[116:117], v[4:5] op_sel_hi:[0,1,1] neg_lo:[1,0,0] neg_hi:[1,0,0]
	v_pk_fma_f32 v[2:3], v[162:163], v[118:119], v[6:7] op_sel_hi:[0,1,1] neg_lo:[1,0,0] neg_hi:[1,0,0]
	ds_read_b128 v[116:119], v69 offset:49520
	v_pk_add_f32 v[28:29], v[0:1], v[2:3]
	s_waitcnt lgkmcnt(9)
	v_pk_mul_f32 v[0:1], v[66:67], v[120:121] op_sel_hi:[0,1]
	v_pk_fma_f32 v[4:5], v[212:213], v[30:31], v[0:1] neg_lo:[0,0,1] neg_hi:[0,0,1]
	v_pk_fma_f32 v[6:7], v[158:159], v[122:123], 0 op_sel_hi:[0,1,0] neg_lo:[1,0,0] neg_hi:[1,0,0]
	ds_read_b128 v[120:123], v69 offset:49536
	s_waitcnt lgkmcnt(9)
	v_pk_fma_f32 v[4:5], v[60:61], v[124:125], v[4:5] op_sel_hi:[0,1,1] neg_lo:[1,0,0] neg_hi:[1,0,0]
	v_pk_fma_f32 v[6:7], v[62:63], v[126:127], v[6:7] op_sel_hi:[0,1,1] neg_lo:[1,0,0] neg_hi:[1,0,0]
	ds_read_b128 v[124:127], v69 offset:49552
	s_waitcnt lgkmcnt(9)
	v_pk_fma_f32 v[4:5], v[56:57], v[128:129], v[4:5] op_sel_hi:[0,1,1] neg_lo:[1,0,0] neg_hi:[1,0,0]
	v_pk_fma_f32 v[6:7], v[160:161], v[130:131], v[6:7] op_sel_hi:[0,1,1] neg_lo:[1,0,0] neg_hi:[1,0,0]
	ds_read_b128 v[128:131], v69 offset:50048
	s_waitcnt lgkmcnt(9)
	v_pk_fma_f32 v[0:1], v[58:59], v[136:137], v[4:5] op_sel_hi:[0,1,1] neg_lo:[1,0,0] neg_hi:[1,0,0]
	v_pk_fma_f32 v[2:3], v[162:163], v[138:139], v[6:7] op_sel_hi:[0,1,1] neg_lo:[1,0,0] neg_hi:[1,0,0]
	ds_read_b128 v[136:139], v69 offset:50064
	v_pk_add_f32 v[30:31], v[0:1], v[2:3]
	s_waitcnt lgkmcnt(9)
	v_pk_mul_f32 v[0:1], v[66:67], v[238:239] op_sel_hi:[0,1]
	v_pk_fma_f32 v[4:5], v[214:215], v[20:21], v[0:1] neg_lo:[0,0,1] neg_hi:[0,0,1]
	v_pk_fma_f32 v[6:7], v[158:159], v[240:241], 0 op_sel_hi:[0,1,0] neg_lo:[1,0,0] neg_hi:[1,0,0]
	ds_read_b128 v[238:241], v69 offset:50080
	s_waitcnt lgkmcnt(9)
	v_pk_fma_f32 v[4:5], v[60:61], v[132:133], v[4:5] op_sel_hi:[0,1,1] neg_lo:[1,0,0] neg_hi:[1,0,0]
	v_pk_fma_f32 v[6:7], v[62:63], v[134:135], v[6:7] op_sel_hi:[0,1,1] neg_lo:[1,0,0] neg_hi:[1,0,0]
	ds_read_b128 v[132:135], v69 offset:50096
	s_waitcnt lgkmcnt(9)
; #define LAS __attribute__((address_space(3)))
; DI void gdn_prep_phase(const int tid, LAS unsigned char* lds, const P& p, int G, int c) {
;     ...
;                   xs[2 * pr + 1] = s[1] - Ls[pr * 136 + 4 * pr + 1] * s[0]; }
; #pragma unroll
;               for (int pr = 4 * kb + 4; pr < 32; ++pr) {
;                   f32x2 s0 = (f32x2){xs[2 * pr], xs[2 * pr + 1]}, s1 = (f32x2){0.f, 0.f};
; #pragma unroll
;                   for (int q = 0; q < 4; ++q) { const int j = 8 * kb + 2 * q; const f32x4 l = *(const LAS f32x4*)(Ls + pr * 136 + j * 2);
;                       s0 -= (f32x2){l[0], l[1]} * (f32x2){xs[j], xs[j]}; s1 -= (f32x2){l[2], l[3]} * (f32x2){xs[j + 1], xs[j + 1]}; }
;                   const f32x2 s = s0 + s1; xs[2 * pr] = s[0]; xs[2 * pr + 1] = s[1]; }
	v_pk_fma_f32 v[4:5], v[56:57], v[242:243], v[4:5] op_sel_hi:[0,1,1] neg_lo:[1,0,0] neg_hi:[1,0,0]
	v_pk_fma_f32 v[6:7], v[160:161], v[244:245], v[6:7] op_sel_hi:[0,1,1] neg_lo:[1,0,0] neg_hi:[1,0,0]
	ds_read_b128 v[242:245], v69 offset:50592
	s_waitcnt lgkmcnt(9)
	v_pk_fma_f32 v[0:1], v[58:59], v[246:247], v[4:5] op_sel_hi:[0,1,1] neg_lo:[1,0,0] neg_hi:[1,0,0]
	v_pk_fma_f32 v[2:3], v[162:163], v[248:249], v[6:7] op_sel_hi:[0,1,1] neg_lo:[1,0,0] neg_hi:[1,0,0]
	ds_read_b128 v[246:249], v69 offset:50608
	v_pk_add_f32 v[20:21], v[0:1], v[2:3]
	s_waitcnt lgkmcnt(9)
	v_pk_mul_f32 v[0:1], v[66:67], v[112:113] op_sel_hi:[0,1]
	v_pk_fma_f32 v[4:5], v[216:217], v[22:23], v[0:1] neg_lo:[0,0,1] neg_hi:[0,0,1]
	v_pk_fma_f32 v[6:7], v[158:159], v[114:115], 0 op_sel_hi:[0,1,0] neg_lo:[1,0,0] neg_hi:[1,0,0]
	ds_read_b128 v[112:115], v69 offset:50624
	s_waitcnt lgkmcnt(9)
	v_pk_fma_f32 v[4:5], v[60:61], v[116:117], v[4:5] op_sel_hi:[0,1,1] neg_lo:[1,0,0] neg_hi:[1,0,0]
	v_pk_fma_f32 v[6:7], v[62:63], v[118:119], v[6:7] op_sel_hi:[0,1,1] neg_lo:[1,0,0] neg_hi:[1,0,0]
	ds_read_b128 v[116:119], v69 offset:50640
	s_waitcnt lgkmcnt(9)
	v_pk_fma_f32 v[4:5], v[56:57], v[120:121], v[4:5] op_sel_hi:[0,1,1] neg_lo:[1,0,0] neg_hi:[1,0,0]
	v_pk_fma_f32 v[6:7], v[160:161], v[122:123], v[6:7] op_sel_hi:[0,1,1] neg_lo:[1,0,0] neg_hi:[1,0,0]
	ds_read_b128 v[120:123], v69 offset:51136
	s_waitcnt lgkmcnt(9)
	v_pk_fma_f32 v[0:1], v[58:59], v[124:125], v[4:5] op_sel_hi:[0,1,1] neg_lo:[1,0,0] neg_hi:[1,0,0]
	v_pk_fma_f32 v[2:3], v[162:163], v[126:127], v[6:7] op_sel_hi:[0,1,1] neg_lo:[1,0,0] neg_hi:[1,0,0]
	ds_read_b128 v[124:127], v69 offset:51152
	v_pk_add_f32 v[22:23], v[0:1], v[2:3]
	s_waitcnt lgkmcnt(9)
	v_pk_mul_f32 v[0:1], v[66:67], v[128:129] op_sel_hi:[0,1]
	v_pk_fma_f32 v[4:5], v[218:219], v[52:53], v[0:1] neg_lo:[0,0,1] neg_hi:[0,0,1]
	v_pk_fma_f32 v[6:7], v[158:159], v[130:131], 0 op_sel_hi:[0,1,0] neg_lo:[1,0,0] neg_hi:[1,0,0]
	ds_read_b128 v[128:131], v69 offset:51168
	s_waitcnt lgkmcnt(9)
	v_pk_fma_f32 v[4:5], v[60:61], v[136:137], v[4:5] op_sel_hi:[0,1,1] neg_lo:[1,0,0] neg_hi:[1,0,0]
	v_pk_fma_f32 v[6:7], v[62:63], v[138:139], v[6:7] op_sel_hi:[0,1,1] neg_lo:[1,0,0] neg_hi:[1,0,0]
	ds_read_b128 v[136:139], v69 offset:51184
	s_waitcnt lgkmcnt(9)
	v_pk_fma_f32 v[4:5], v[56:57], v[238:239], v[4:5] op_sel_hi:[0,1,1] neg_lo:[1,0,0] neg_hi:[1,0,0]
	v_pk_fma_f32 v[6:7], v[160:161], v[240:241], v[6:7] op_sel_hi:[0,1,1] neg_lo:[1,0,0] neg_hi:[1,0,0]
	ds_read_b128 v[238:241], v69 offset:51680
	s_waitcnt lgkmcnt(9)
	v_pk_fma_f32 v[0:1], v[58:59], v[132:133], v[4:5] op_sel_hi:[0,1,1] neg_lo:[1,0,0] neg_hi:[1,0,0]
	v_pk_fma_f32 v[2:3], v[162:163], v[134:135], v[6:7] op_sel_hi:[0,1,1] neg_lo:[1,0,0] neg_hi:[1,0,0]
	ds_read_b128 v[132:135], v69 offset:51696
	v_pk_add_f32 v[52:53], v[0:1], v[2:3]
	s_waitcnt lgkmcnt(9)
	v_pk_mul_f32 v[0:1], v[66:67], v[242:243] op_sel_hi:[0,1]
	v_pk_fma_f32 v[4:5], v[220:221], v[54:55], v[0:1] neg_lo:[0,0,1] neg_hi:[0,0,1]
	v_pk_fma_f32 v[6:7], v[158:159], v[244:245], 0 op_sel_hi:[0,1,0] neg_lo:[1,0,0] neg_hi:[1,0,0]
	ds_read_b128 v[242:245], v69 offset:51712
	s_waitcnt lgkmcnt(9)
	v_pk_fma_f32 v[4:5], v[60:61], v[246:247], v[4:5] op_sel_hi:[0,1,1] neg_lo:[1,0,0] neg_hi:[1,0,0]
	v_pk_fma_f32 v[6:7], v[62:63], v[248:249], v[6:7] op_sel_hi:[0,1,1] neg_lo:[1,0,0] neg_hi:[1,0,0]
	ds_read_b128 v[246:249], v69 offset:51728
	s_waitcnt lgkmcnt(9)
	v_pk_fma_f32 v[4:5], v[56:57], v[112:113], v[4:5] op_sel_hi:[0,1,1] neg_lo:[1,0,0] neg_hi:[1,0,0]
	v_pk_fma_f32 v[6:7], v[160:161], v[114:115], v[6:7] op_sel_hi:[0,1,1] neg_lo:[1,0,0] neg_hi:[1,0,0]
	v_add_u32_e32 v232, 0x9000, v69
	ds_read2_b32 v[112:113], v232 offset0:49 offset1:189
	s_waitcnt lgkmcnt(9)
	v_pk_fma_f32 v[0:1], v[58:59], v[116:117], v[4:5] op_sel_hi:[0,1,1] neg_lo:[1,0,0] neg_hi:[1,0,0]
	v_pk_fma_f32 v[2:3], v[162:163], v[118:119], v[6:7] op_sel_hi:[0,1,1] neg_lo:[1,0,0] neg_hi:[1,0,0]
	ds_read_b128 v[116:119], v69 offset:37600
	v_pk_add_f32 v[54:55], v[0:1], v[2:3]
	s_waitcnt lgkmcnt(9)
	v_pk_mul_f32 v[0:1], v[66:67], v[120:121] op_sel_hi:[0,1]
	v_pk_fma_f32 v[4:5], v[222:223], v[44:45], v[0:1] neg_lo:[0,0,1] neg_hi:[0,0,1]
	v_pk_fma_f32 v[6:7], v[158:159], v[122:123], 0 op_sel_hi:[0,1,0] neg_lo:[1,0,0] neg_hi:[1,0,0]
	ds_read_b128 v[120:123], v69 offset:38144
	s_waitcnt lgkmcnt(9)
	v_pk_fma_f32 v[4:5], v[60:61], v[124:125], v[4:5] op_sel_hi:[0,1,1] neg_lo:[1,0,0] neg_hi:[1,0,0]
	v_pk_fma_f32 v[6:7], v[62:63], v[126:127], v[6:7] op_sel_hi:[0,1,1] neg_lo:[1,0,0] neg_hi:[1,0,0]
	ds_read_b128 v[124:127], v69 offset:38160
	s_waitcnt lgkmcnt(9)
	v_pk_fma_f32 v[4:5], v[56:57], v[128:129], v[4:5] op_sel_hi:[0,1,1] neg_lo:[1,0,0] neg_hi:[1,0,0]
	v_pk_fma_f32 v[6:7], v[160:161], v[130:131], v[6:7] op_sel_hi:[0,1,1] neg_lo:[1,0,0] neg_hi:[1,0,0]
	ds_read_b128 v[128:131], v69 offset:38688
	s_waitcnt lgkmcnt(9)
	v_pk_fma_f32 v[0:1], v[58:59], v[136:137], v[4:5] op_sel_hi:[0,1,1] neg_lo:[1,0,0] neg_hi:[1,0,0]
	v_pk_fma_f32 v[2:3], v[162:163], v[138:139], v[6:7] op_sel_hi:[0,1,1] neg_lo:[1,0,0] neg_hi:[1,0,0]
	ds_read_b128 v[136:139], v69 offset:39232
	v_pk_add_f32 v[44:45], v[0:1], v[2:3]
	s_waitcnt lgkmcnt(9)
	v_pk_mul_f32 v[0:1], v[66:67], v[238:239] op_sel_hi:[0,1]
	v_pk_fma_f32 v[4:5], v[224:225], v[46:47], v[0:1] neg_lo:[0,0,1] neg_hi:[0,0,1]
	v_pk_fma_f32 v[6:7], v[158:159], v[240:241], 0 op_sel_hi:[0,1,0] neg_lo:[1,0,0] neg_hi:[1,0,0]
	v_add_u32_e32 v233, 0x9400, v69
	ds_read2_b32 v[238:239], v233 offset0:73 offset1:213
	s_waitcnt lgkmcnt(9)
	v_pk_fma_f32 v[4:5], v[60:61], v[132:133], v[4:5] op_sel_hi:[0,1,1] neg_lo:[1,0,0] neg_hi:[1,0,0]
	v_pk_fma_f32 v[6:7], v[62:63], v[134:135], v[6:7] op_sel_hi:[0,1,1] neg_lo:[1,0,0] neg_hi:[1,0,0]
	ds_read_b128 v[132:135], v69 offset:38704
	s_waitcnt lgkmcnt(9)
; #define LAS __attribute__((address_space(3)))
; DI void gdn_prep_phase(const int tid, LAS unsigned char* lds, const P& p, int G, int c) {
;     ...
;           for (int kb = 0; kb < 8; ++kb) {
; #pragma unroll
;               for (int pp = 0; pp < 4; ++pp) { const int pr = 4 * kb + pp;
;                   f32x2 s = (f32x2){xs[2 * pr], xs[2 * pr + 1]};
; #pragma unroll
;                   for (int j = 8 * kb; j < 2 * pr; j += 2) { const f32x4 l = *(const LAS f32x4*)(Ls + pr * 136 + j * 2);
;                       s -= (f32x2){l[0], l[1]} * (f32x2){xs[j], xs[j]}; s -= (f32x2){l[2], l[3]} * (f32x2){xs[j + 1], xs[j + 1]}; }
;                   xs[2 * pr] = s[0];
;                   xs[2 * pr + 1] = s[1] - Ls[pr * 136 + 4 * pr + 1] * s[0]; }
; #pragma unroll
;               for (int pr = 4 * kb + 4; pr < 32; ++pr) {
;                   f32x2 s0 = (f32x2){xs[2 * pr], xs[2 * pr + 1]}, s1 = (f32x2){0.f, 0.f};
; #pragma unroll
;                   for (int q = 0; q < 4; ++q) { const int j = 8 * kb + 2 * q; const f32x4 l = *(const LAS f32x4*)(Ls + pr * 136 + j * 2);
;                       s0 -= (f32x2){l[0], l[1]} * (f32x2){xs[j], xs[j]}; s1 -= (f32x2){l[2], l[3]} * (f32x2){xs[j + 1], xs[j + 1]}; }
;                   const f32x2 s = s0 + s1; xs[2 * pr] = s[0]; xs[2 * pr + 1] = s[1]; }
	v_pk_fma_f32 v[4:5], v[56:57], v[242:243], v[4:5] op_sel_hi:[0,1,1] neg_lo:[1,0,0] neg_hi:[1,0,0]
	v_pk_fma_f32 v[6:7], v[160:161], v[244:245], v[6:7] op_sel_hi:[0,1,1] neg_lo:[1,0,0] neg_hi:[1,0,0]
	ds_read_b128 v[242:245], v69 offset:38720
	s_waitcnt lgkmcnt(9)
	v_pk_fma_f32 v[0:1], v[58:59], v[246:247], v[4:5] op_sel_hi:[0,1,1] neg_lo:[1,0,0] neg_hi:[1,0,0]
	v_pk_fma_f32 v[2:3], v[162:163], v[248:249], v[6:7] op_sel_hi:[0,1,1] neg_lo:[1,0,0] neg_hi:[1,0,0]
	ds_read_b128 v[246:249], v69 offset:39248
	v_pk_add_f32 v[46:47], v[0:1], v[2:3]
	s_waitcnt lgkmcnt(9)
	v_fma_f32 v0, -v48, v112, v49
	s_waitcnt lgkmcnt(8)
	v_pk_fma_f32 v[2:3], v[48:49], v[116:117], v[178:179] op_sel_hi:[0,1,1] neg_lo:[1,0,0] neg_hi:[1,0,0]
	s_waitcnt lgkmcnt(7)
	v_pk_fma_f32 v[6:7], v[48:49], v[120:121], v[188:189] op_sel_hi:[0,1,1] neg_lo:[1,0,0] neg_hi:[1,0,0]
	v_pk_fma_f32 v[10:11], v[122:123], v[0:1], v[6:7] op_sel_hi:[1,0,1] neg_lo:[1,0,0] neg_hi:[1,0,0]
	ds_read_b128 v[120:123], v69 offset:39264
	v_pk_fma_f32 v[4:5], v[118:119], v[0:1], v[2:3] op_sel_hi:[1,0,1] neg_lo:[1,0,0] neg_hi:[1,0,0]
	ds_read_b128 v[116:119], v69 offset:39280
	v_fma_f32 v2, -v113, v4, v5
	ds_read_b128 v[112:115], v69 offset:39776
	s_waitcnt lgkmcnt(9)
	v_pk_fma_f32 v[6:7], v[124:125], v[4:5], v[10:11] op_sel_hi:[1,0,1] neg_lo:[1,0,0] neg_hi:[1,0,0]
	s_nop 0
	v_pk_fma_f32 v[8:9], v[126:127], v[2:3], v[6:7] op_sel_hi:[1,0,1] neg_lo:[1,0,0] neg_hi:[1,0,0]
	ds_read_b128 v[124:127], v69 offset:39792
	s_waitcnt lgkmcnt(9)
	v_pk_fma_f32 v[10:11], v[48:49], v[128:129], v[50:51] op_sel_hi:[0,1,1] neg_lo:[1,0,0] neg_hi:[1,0,0]
	v_pk_fma_f32 v[14:15], v[0:1], v[130:131], v[10:11] op_sel_hi:[0,1,1] neg_lo:[1,0,0] neg_hi:[1,0,0]
	ds_read_b128 v[128:131], v69 offset:39808
	s_waitcnt lgkmcnt(9)
	v_pk_fma_f32 v[50:51], v[0:1], v[138:139], 0 op_sel_hi:[0,1,0] neg_lo:[1,0,0] neg_hi:[1,0,0]
	s_waitcnt lgkmcnt(8)
	v_fma_f32 v6, -v238, v8, v9
	s_waitcnt lgkmcnt(7)
	v_pk_fma_f32 v[10:11], v[4:5], v[132:133], v[14:15] op_sel_hi:[0,1,1] neg_lo:[1,0,0] neg_hi:[1,0,0]
	v_pk_fma_f32 v[14:15], v[134:135], v[2:3], v[10:11] op_sel_hi:[1,0,1] neg_lo:[1,0,0] neg_hi:[1,0,0]
	ds_read_b128 v[132:135], v69 offset:39824
	s_waitcnt lgkmcnt(7)
	v_pk_fma_f32 v[10:11], v[242:243], v[8:9], v[14:15] op_sel_hi:[1,0,1] neg_lo:[1,0,0] neg_hi:[1,0,0]
	v_pk_fma_f32 v[14:15], v[48:49], v[136:137], v[164:165] op_sel_hi:[0,1,1] neg_lo:[1,0,0] neg_hi:[1,0,0]
	ds_read_b128 v[136:139], v69 offset:40320
	v_pk_fma_f32 v[12:13], v[244:245], v[6:7], v[10:11] op_sel_hi:[1,0,1] neg_lo:[1,0,0] neg_hi:[1,0,0]
	ds_read_b128 v[242:245], v69 offset:40336
	s_waitcnt lgkmcnt(8)
	v_pk_fma_f32 v[14:15], v[4:5], v[246:247], v[14:15] op_sel_hi:[0,1,1] neg_lo:[1,0,0] neg_hi:[1,0,0]
	v_pk_fma_f32 v[50:51], v[2:3], v[248:249], v[50:51] op_sel_hi:[0,1,1] neg_lo:[1,0,0] neg_hi:[1,0,0]
	ds_read_b128 v[246:249], v69 offset:40352
	v_fma_f32 v10, -v239, v12, v13
	ds_read_b128 v[238:241], v69 offset:40368
	s_waitcnt lgkmcnt(9)
	v_pk_fma_f32 v[14:15], v[120:121], v[8:9], v[14:15] op_sel_hi:[1,0,1] neg_lo:[1,0,0] neg_hi:[1,0,0]
	v_pk_fma_f32 v[50:51], v[122:123], v[6:7], v[50:51] op_sel_hi:[1,0,1] neg_lo:[1,0,0] neg_hi:[1,0,0]
	ds_read_b128 v[120:123], v69 offset:40864
	s_waitcnt lgkmcnt(9)
	v_pk_fma_f32 v[14:15], v[116:117], v[12:13], v[14:15] op_sel_hi:[1,0,1] neg_lo:[1,0,0] neg_hi:[1,0,0]
	v_pk_fma_f32 v[50:51], v[118:119], v[10:11], v[50:51] op_sel_hi:[1,0,1] neg_lo:[1,0,0] neg_hi:[1,0,0]
	ds_read_b128 v[116:119], v69 offset:40880
	v_pk_add_f32 v[14:15], v[14:15], v[50:51]
	s_waitcnt lgkmcnt(9)
	v_pk_fma_f32 v[50:51], v[48:49], v[112:113], v[166:167] op_sel_hi:[0,1,1] neg_lo:[1,0,0] neg_hi:[1,0,0]
	v_pk_fma_f32 v[176:177], v[0:1], v[114:115], 0 op_sel_hi:[0,1,0] neg_lo:[1,0,0] neg_hi:[1,0,0]
	ds_read_b128 v[112:115], v69 offset:40896
	s_waitcnt lgkmcnt(9)
	v_pk_fma_f32 v[50:51], v[4:5], v[124:125], v[50:51] op_sel_hi:[0,1,1] neg_lo:[1,0,0] neg_hi:[1,0,0]
	v_pk_fma_f32 v[176:177], v[2:3], v[126:127], v[176:177] op_sel_hi:[0,1,1] neg_lo:[1,0,0] neg_hi:[1,0,0]
	ds_read_b128 v[124:127], v69 offset:40912
	s_waitcnt lgkmcnt(9)
	v_pk_fma_f32 v[50:51], v[8:9], v[128:129], v[50:51] op_sel_hi:[0,1,1] neg_lo:[1,0,0] neg_hi:[1,0,0]
	v_pk_fma_f32 v[176:177], v[130:131], v[6:7], v[176:177] op_sel_hi:[1,0,1] neg_lo:[1,0,0] neg_hi:[1,0,0]
	ds_read_b128 v[128:131], v69 offset:41408
	s_waitcnt lgkmcnt(9)
	v_pk_fma_f32 v[50:51], v[132:133], v[12:13], v[50:51] op_sel_hi:[1,0,1] neg_lo:[1,0,0] neg_hi:[1,0,0]
	v_pk_fma_f32 v[164:165], v[134:135], v[10:11], v[176:177] op_sel_hi:[1,0,1] neg_lo:[1,0,0] neg_hi:[1,0,0]
	ds_read_b128 v[132:135], v69 offset:41424
	v_pk_add_f32 v[188:189], v[50:51], v[164:165]
	s_waitcnt lgkmcnt(9)
	v_pk_fma_f32 v[50:51], v[48:49], v[136:137], v[168:169] op_sel_hi:[0,1,1] neg_lo:[1,0,0] neg_hi:[1,0,0]
	v_pk_fma_f32 v[168:169], v[0:1], v[138:139], 0 op_sel_hi:[0,1,0] neg_lo:[1,0,0] neg_hi:[1,0,0]
	ds_read_b128 v[136:139], v69 offset:41440
	s_waitcnt lgkmcnt(9)
	v_pk_fma_f32 v[50:51], v[4:5], v[242:243], v[50:51] op_sel_hi:[0,1,1] neg_lo:[1,0,0] neg_hi:[1,0,0]
	v_pk_fma_f32 v[168:169], v[2:3], v[244:245], v[168:169] op_sel_hi:[0,1,1] neg_lo:[1,0,0] neg_hi:[1,0,0]
	ds_read_b128 v[242:245], v69 offset:41456
	s_waitcnt lgkmcnt(9)
	v_pk_fma_f32 v[50:51], v[8:9], v[246:247], v[50:51] op_sel_hi:[0,1,1] neg_lo:[1,0,0] neg_hi:[1,0,0]
	v_pk_fma_f32 v[168:169], v[6:7], v[248:249], v[168:169] op_sel_hi:[0,1,1] neg_lo:[1,0,0] neg_hi:[1,0,0]
	ds_read_b128 v[246:249], v69 offset:41952
	s_waitcnt lgkmcnt(9)
	v_pk_fma_f32 v[50:51], v[12:13], v[238:239], v[50:51] op_sel_hi:[0,1,1] neg_lo:[1,0,0] neg_hi:[1,0,0]
	v_pk_fma_f32 v[164:165], v[240:241], v[10:11], v[168:169] op_sel_hi:[1,0,1] neg_lo:[1,0,0] neg_hi:[1,0,0]
	ds_read_b128 v[238:241], v69 offset:41968
	v_pk_add_f32 v[190:191], v[50:51], v[164:165]
	s_waitcnt lgkmcnt(9)
; #define LAS __attribute__((address_space(3)))
; DI void gdn_prep_phase(const int tid, LAS unsigned char* lds, const P& p, int G, int c) {
;     ...
;               for (int pr = 4 * kb + 4; pr < 32; ++pr) {
;                   f32x2 s0 = (f32x2){xs[2 * pr], xs[2 * pr + 1]}, s1 = (f32x2){0.f, 0.f};
; #pragma unroll
;                   for (int q = 0; q < 4; ++q) { const int j = 8 * kb + 2 * q; const f32x4 l = *(const LAS f32x4*)(Ls + pr * 136 + j * 2);
;                       s0 -= (f32x2){l[0], l[1]} * (f32x2){xs[j], xs[j]}; s1 -= (f32x2){l[2], l[3]} * (f32x2){xs[j + 1], xs[j + 1]}; }
;                   const f32x2 s = s0 + s1; xs[2 * pr] = s[0]; xs[2 * pr + 1] = s[1]; }
	v_pk_fma_f32 v[50:51], v[48:49], v[120:121], v[170:171] op_sel_hi:[0,1,1] neg_lo:[1,0,0] neg_hi:[1,0,0]
	v_pk_fma_f32 v[168:169], v[0:1], v[122:123], 0 op_sel_hi:[0,1,0] neg_lo:[1,0,0] neg_hi:[1,0,0]
	ds_read_b128 v[120:123], v69 offset:41984
	s_waitcnt lgkmcnt(9)
	v_pk_fma_f32 v[50:51], v[4:5], v[116:117], v[50:51] op_sel_hi:[0,1,1] neg_lo:[1,0,0] neg_hi:[1,0,0]
	v_pk_fma_f32 v[168:169], v[2:3], v[118:119], v[168:169] op_sel_hi:[0,1,1] neg_lo:[1,0,0] neg_hi:[1,0,0]
	ds_read_b128 v[116:119], v69 offset:42000
	s_waitcnt lgkmcnt(9)
	v_pk_fma_f32 v[50:51], v[8:9], v[112:113], v[50:51] op_sel_hi:[0,1,1] neg_lo:[1,0,0] neg_hi:[1,0,0]
	v_pk_fma_f32 v[168:169], v[6:7], v[114:115], v[168:169] op_sel_hi:[0,1,1] neg_lo:[1,0,0] neg_hi:[1,0,0]
	ds_read_b128 v[112:115], v69 offset:42496
	s_waitcnt lgkmcnt(9)
	v_pk_fma_f32 v[50:51], v[12:13], v[124:125], v[50:51] op_sel_hi:[0,1,1] neg_lo:[1,0,0] neg_hi:[1,0,0]
	v_pk_fma_f32 v[164:165], v[10:11], v[126:127], v[168:169] op_sel_hi:[0,1,1] neg_lo:[1,0,0] neg_hi:[1,0,0]
	ds_read_b128 v[124:127], v69 offset:42512
	v_pk_add_f32 v[50:51], v[50:51], v[164:165]
	s_waitcnt lgkmcnt(9)
	v_pk_fma_f32 v[16:17], v[48:49], v[128:129], v[16:17] op_sel_hi:[0,1,1] neg_lo:[1,0,0] neg_hi:[1,0,0]
	v_pk_fma_f32 v[168:169], v[0:1], v[130:131], 0 op_sel_hi:[0,1,0] neg_lo:[1,0,0] neg_hi:[1,0,0]
	ds_read_b128 v[128:131], v69 offset:42528
	s_waitcnt lgkmcnt(9)
	v_pk_fma_f32 v[16:17], v[4:5], v[132:133], v[16:17] op_sel_hi:[0,1,1] neg_lo:[1,0,0] neg_hi:[1,0,0]
	v_pk_fma_f32 v[168:169], v[2:3], v[134:135], v[168:169] op_sel_hi:[0,1,1] neg_lo:[1,0,0] neg_hi:[1,0,0]
	ds_read_b128 v[132:135], v69 offset:42544
	s_waitcnt lgkmcnt(9)
	v_pk_fma_f32 v[16:17], v[8:9], v[136:137], v[16:17] op_sel_hi:[0,1,1] neg_lo:[1,0,0] neg_hi:[1,0,0]
	v_pk_fma_f32 v[168:169], v[6:7], v[138:139], v[168:169] op_sel_hi:[0,1,1] neg_lo:[1,0,0] neg_hi:[1,0,0]
	ds_read_b128 v[136:139], v69 offset:43040
	s_waitcnt lgkmcnt(9)
	v_pk_fma_f32 v[16:17], v[12:13], v[242:243], v[16:17] op_sel_hi:[0,1,1] neg_lo:[1,0,0] neg_hi:[1,0,0]
	v_pk_fma_f32 v[164:165], v[10:11], v[244:245], v[168:169] op_sel_hi:[0,1,1] neg_lo:[1,0,0] neg_hi:[1,0,0]
	ds_read_b128 v[242:245], v69 offset:43056
	v_pk_add_f32 v[164:165], v[16:17], v[164:165]
	s_waitcnt lgkmcnt(9)
	v_pk_fma_f32 v[166:167], v[48:49], v[246:247], v[18:19] op_sel_hi:[0,1,1] neg_lo:[1,0,0] neg_hi:[1,0,0]
	v_pk_fma_f32 v[168:169], v[0:1], v[248:249], 0 op_sel_hi:[0,1,0] neg_lo:[1,0,0] neg_hi:[1,0,0]
	ds_read_b128 v[246:249], v69 offset:43072
	s_waitcnt lgkmcnt(9)
	v_pk_fma_f32 v[166:167], v[4:5], v[238:239], v[166:167] op_sel_hi:[0,1,1] neg_lo:[1,0,0] neg_hi:[1,0,0]
	v_pk_fma_f32 v[168:169], v[2:3], v[240:241], v[168:169] op_sel_hi:[0,1,1] neg_lo:[1,0,0] neg_hi:[1,0,0]
	ds_read_b128 v[238:241], v69 offset:43088
	s_waitcnt lgkmcnt(9)
	v_pk_fma_f32 v[166:167], v[8:9], v[120:121], v[166:167] op_sel_hi:[0,1,1] neg_lo:[1,0,0] neg_hi:[1,0,0]
	v_pk_fma_f32 v[168:169], v[6:7], v[122:123], v[168:169] op_sel_hi:[0,1,1] neg_lo:[1,0,0] neg_hi:[1,0,0]
	ds_read_b128 v[120:123], v69 offset:43584
	s_waitcnt lgkmcnt(9)
	v_pk_fma_f32 v[16:17], v[12:13], v[116:117], v[166:167] op_sel_hi:[0,1,1] neg_lo:[1,0,0] neg_hi:[1,0,0]
	v_pk_fma_f32 v[18:19], v[10:11], v[118:119], v[168:169] op_sel_hi:[0,1,1] neg_lo:[1,0,0] neg_hi:[1,0,0]
	ds_read_b128 v[116:119], v69 offset:43600
	v_pk_add_f32 v[166:167], v[16:17], v[18:19]
	s_waitcnt lgkmcnt(9)
	v_pk_fma_f32 v[168:169], v[48:49], v[112:113], v[172:173] op_sel_hi:[0,1,1] neg_lo:[1,0,0] neg_hi:[1,0,0]
	v_pk_fma_f32 v[170:171], v[0:1], v[114:115], 0 op_sel_hi:[0,1,0] neg_lo:[1,0,0] neg_hi:[1,0,0]
	ds_read_b128 v[112:115], v69 offset:43616
	s_waitcnt lgkmcnt(9)
	v_pk_fma_f32 v[168:169], v[4:5], v[124:125], v[168:169] op_sel_hi:[0,1,1] neg_lo:[1,0,0] neg_hi:[1,0,0]
	v_pk_fma_f32 v[170:171], v[2:3], v[126:127], v[170:171] op_sel_hi:[0,1,1] neg_lo:[1,0,0] neg_hi:[1,0,0]
	ds_read_b128 v[124:127], v69 offset:43632
	s_waitcnt lgkmcnt(9)
	v_pk_fma_f32 v[168:169], v[8:9], v[128:129], v[168:169] op_sel_hi:[0,1,1] neg_lo:[1,0,0] neg_hi:[1,0,0]
	v_pk_fma_f32 v[170:171], v[6:7], v[130:131], v[170:171] op_sel_hi:[0,1,1] neg_lo:[1,0,0] neg_hi:[1,0,0]
	ds_read_b128 v[128:131], v69 offset:44128
	s_waitcnt lgkmcnt(9)
	v_pk_fma_f32 v[16:17], v[12:13], v[132:133], v[168:169] op_sel_hi:[0,1,1] neg_lo:[1,0,0] neg_hi:[1,0,0]
	v_pk_fma_f32 v[18:19], v[10:11], v[134:135], v[170:171] op_sel_hi:[0,1,1] neg_lo:[1,0,0] neg_hi:[1,0,0]
	ds_read_b128 v[132:135], v69 offset:44144
	v_pk_add_f32 v[168:169], v[16:17], v[18:19]
	s_waitcnt lgkmcnt(9)
	v_pk_fma_f32 v[170:171], v[48:49], v[136:137], v[174:175] op_sel_hi:[0,1,1] neg_lo:[1,0,0] neg_hi:[1,0,0]
	v_pk_fma_f32 v[172:173], v[0:1], v[138:139], 0 op_sel_hi:[0,1,0] neg_lo:[1,0,0] neg_hi:[1,0,0]
	ds_read_b128 v[136:139], v69 offset:44160
	s_waitcnt lgkmcnt(9)
	v_pk_fma_f32 v[170:171], v[4:5], v[242:243], v[170:171] op_sel_hi:[0,1,1] neg_lo:[1,0,0] neg_hi:[1,0,0]
	v_pk_fma_f32 v[172:173], v[2:3], v[244:245], v[172:173] op_sel_hi:[0,1,1] neg_lo:[1,0,0] neg_hi:[1,0,0]
	ds_read_b128 v[242:245], v69 offset:44176
	s_waitcnt lgkmcnt(9)
	v_pk_fma_f32 v[170:171], v[8:9], v[246:247], v[170:171] op_sel_hi:[0,1,1] neg_lo:[1,0,0] neg_hi:[1,0,0]
	v_pk_fma_f32 v[172:173], v[6:7], v[248:249], v[172:173] op_sel_hi:[0,1,1] neg_lo:[1,0,0] neg_hi:[1,0,0]
	ds_read_b128 v[246:249], v69 offset:44672
	s_waitcnt lgkmcnt(9)
	v_pk_fma_f32 v[16:17], v[12:13], v[238:239], v[170:171] op_sel_hi:[0,1,1] neg_lo:[1,0,0] neg_hi:[1,0,0]
	v_pk_fma_f32 v[18:19], v[10:11], v[240:241], v[172:173] op_sel_hi:[0,1,1] neg_lo:[1,0,0] neg_hi:[1,0,0]
	ds_read_b128 v[238:241], v69 offset:44688
	v_pk_add_f32 v[170:171], v[16:17], v[18:19]
	s_waitcnt lgkmcnt(9)
; #define LAS __attribute__((address_space(3)))
; DI void gdn_prep_phase(const int tid, LAS unsigned char* lds, const P& p, int G, int c) {
;     ...
;               for (int pr = 4 * kb + 4; pr < 32; ++pr) {
;                   f32x2 s0 = (f32x2){xs[2 * pr], xs[2 * pr + 1]}, s1 = (f32x2){0.f, 0.f};
; #pragma unroll
;                   for (int q = 0; q < 4; ++q) { const int j = 8 * kb + 2 * q; const f32x4 l = *(const LAS f32x4*)(Ls + pr * 136 + j * 2);
;                       s0 -= (f32x2){l[0], l[1]} * (f32x2){xs[j], xs[j]}; s1 -= (f32x2){l[2], l[3]} * (f32x2){xs[j + 1], xs[j + 1]}; }
;                   const f32x2 s = s0 + s1; xs[2 * pr] = s[0]; xs[2 * pr + 1] = s[1]; }
	v_pk_fma_f32 v[36:37], v[48:49], v[120:121], v[36:37] op_sel_hi:[0,1,1] neg_lo:[1,0,0] neg_hi:[1,0,0]
	v_pk_fma_f32 v[172:173], v[0:1], v[122:123], 0 op_sel_hi:[0,1,0] neg_lo:[1,0,0] neg_hi:[1,0,0]
	ds_read_b128 v[120:123], v69 offset:44704
	s_waitcnt lgkmcnt(9)
	v_pk_fma_f32 v[36:37], v[4:5], v[116:117], v[36:37] op_sel_hi:[0,1,1] neg_lo:[1,0,0] neg_hi:[1,0,0]
	v_pk_fma_f32 v[172:173], v[2:3], v[118:119], v[172:173] op_sel_hi:[0,1,1] neg_lo:[1,0,0] neg_hi:[1,0,0]
	ds_read_b128 v[116:119], v69 offset:44720
	s_waitcnt lgkmcnt(9)
	v_pk_fma_f32 v[36:37], v[8:9], v[112:113], v[36:37] op_sel_hi:[0,1,1] neg_lo:[1,0,0] neg_hi:[1,0,0]
	v_pk_fma_f32 v[172:173], v[6:7], v[114:115], v[172:173] op_sel_hi:[0,1,1] neg_lo:[1,0,0] neg_hi:[1,0,0]
	ds_read_b128 v[112:115], v69 offset:45216
	s_waitcnt lgkmcnt(9)
	v_pk_fma_f32 v[16:17], v[12:13], v[124:125], v[36:37] op_sel_hi:[0,1,1] neg_lo:[1,0,0] neg_hi:[1,0,0]
	v_pk_fma_f32 v[18:19], v[10:11], v[126:127], v[172:173] op_sel_hi:[0,1,1] neg_lo:[1,0,0] neg_hi:[1,0,0]
	ds_read_b128 v[124:127], v69 offset:45232
	v_pk_add_f32 v[36:37], v[16:17], v[18:19]
	s_waitcnt lgkmcnt(9)
	v_pk_fma_f32 v[38:39], v[48:49], v[128:129], v[38:39] op_sel_hi:[0,1,1] neg_lo:[1,0,0] neg_hi:[1,0,0]
	v_pk_fma_f32 v[172:173], v[0:1], v[130:131], 0 op_sel_hi:[0,1,0] neg_lo:[1,0,0] neg_hi:[1,0,0]
	ds_read_b128 v[128:131], v69 offset:45248
	s_waitcnt lgkmcnt(9)
	v_pk_fma_f32 v[38:39], v[4:5], v[132:133], v[38:39] op_sel_hi:[0,1,1] neg_lo:[1,0,0] neg_hi:[1,0,0]
	v_pk_fma_f32 v[172:173], v[2:3], v[134:135], v[172:173] op_sel_hi:[0,1,1] neg_lo:[1,0,0] neg_hi:[1,0,0]
	ds_read_b128 v[132:135], v69 offset:45264
	s_waitcnt lgkmcnt(9)
	v_pk_fma_f32 v[38:39], v[8:9], v[136:137], v[38:39] op_sel_hi:[0,1,1] neg_lo:[1,0,0] neg_hi:[1,0,0]
	v_pk_fma_f32 v[172:173], v[6:7], v[138:139], v[172:173] op_sel_hi:[0,1,1] neg_lo:[1,0,0] neg_hi:[1,0,0]
	ds_read_b128 v[136:139], v69 offset:45760
	s_waitcnt lgkmcnt(9)
	v_pk_fma_f32 v[16:17], v[12:13], v[242:243], v[38:39] op_sel_hi:[0,1,1] neg_lo:[1,0,0] neg_hi:[1,0,0]
	v_pk_fma_f32 v[18:19], v[10:11], v[244:245], v[172:173] op_sel_hi:[0,1,1] neg_lo:[1,0,0] neg_hi:[1,0,0]
	ds_read_b128 v[242:245], v69 offset:45776
	v_pk_add_f32 v[38:39], v[16:17], v[18:19]
	s_waitcnt lgkmcnt(9)
	v_pk_fma_f32 v[24:25], v[48:49], v[246:247], v[24:25] op_sel_hi:[0,1,1] neg_lo:[1,0,0] neg_hi:[1,0,0]
	v_pk_fma_f32 v[172:173], v[0:1], v[248:249], 0 op_sel_hi:[0,1,0] neg_lo:[1,0,0] neg_hi:[1,0,0]
	ds_read_b128 v[246:249], v69 offset:45792
	s_waitcnt lgkmcnt(9)
	v_pk_fma_f32 v[24:25], v[4:5], v[238:239], v[24:25] op_sel_hi:[0,1,1] neg_lo:[1,0,0] neg_hi:[1,0,0]
	v_pk_fma_f32 v[172:173], v[2:3], v[240:241], v[172:173] op_sel_hi:[0,1,1] neg_lo:[1,0,0] neg_hi:[1,0,0]
	ds_read_b128 v[238:241], v69 offset:45808
	s_waitcnt lgkmcnt(9)
	v_pk_fma_f32 v[24:25], v[8:9], v[120:121], v[24:25] op_sel_hi:[0,1,1] neg_lo:[1,0,0] neg_hi:[1,0,0]
	v_pk_fma_f32 v[172:173], v[6:7], v[122:123], v[172:173] op_sel_hi:[0,1,1] neg_lo:[1,0,0] neg_hi:[1,0,0]
	ds_read_b128 v[120:123], v69 offset:46304
	s_waitcnt lgkmcnt(9)
	v_pk_fma_f32 v[16:17], v[12:13], v[116:117], v[24:25] op_sel_hi:[0,1,1] neg_lo:[1,0,0] neg_hi:[1,0,0]
	v_pk_fma_f32 v[18:19], v[10:11], v[118:119], v[172:173] op_sel_hi:[0,1,1] neg_lo:[1,0,0] neg_hi:[1,0,0]
	ds_read_b128 v[116:119], v69 offset:46320
	v_pk_add_f32 v[172:173], v[16:17], v[18:19]
	s_waitcnt lgkmcnt(9)
	v_pk_fma_f32 v[24:25], v[48:49], v[112:113], v[26:27] op_sel_hi:[0,1,1] neg_lo:[1,0,0] neg_hi:[1,0,0]
	v_pk_fma_f32 v[26:27], v[0:1], v[114:115], 0 op_sel_hi:[0,1,0] neg_lo:[1,0,0] neg_hi:[1,0,0]
	ds_read_b128 v[112:115], v69 offset:46336
	s_waitcnt lgkmcnt(9)
	v_pk_fma_f32 v[24:25], v[4:5], v[124:125], v[24:25] op_sel_hi:[0,1,1] neg_lo:[1,0,0] neg_hi:[1,0,0]
	v_pk_fma_f32 v[26:27], v[2:3], v[126:127], v[26:27] op_sel_hi:[0,1,1] neg_lo:[1,0,0] neg_hi:[1,0,0]
	ds_read_b128 v[124:127], v69 offset:46352
	s_waitcnt lgkmcnt(9)
	v_pk_fma_f32 v[24:25], v[8:9], v[128:129], v[24:25] op_sel_hi:[0,1,1] neg_lo:[1,0,0] neg_hi:[1,0,0]
	v_pk_fma_f32 v[26:27], v[6:7], v[130:131], v[26:27] op_sel_hi:[0,1,1] neg_lo:[1,0,0] neg_hi:[1,0,0]
	ds_read_b128 v[128:131], v69 offset:46848
	s_waitcnt lgkmcnt(9)
	v_pk_fma_f32 v[16:17], v[12:13], v[132:133], v[24:25] op_sel_hi:[0,1,1] neg_lo:[1,0,0] neg_hi:[1,0,0]
	v_pk_fma_f32 v[18:19], v[10:11], v[134:135], v[26:27] op_sel_hi:[0,1,1] neg_lo:[1,0,0] neg_hi:[1,0,0]
	ds_read_b128 v[132:135], v69 offset:46864
	v_pk_add_f32 v[174:175], v[16:17], v[18:19]
	s_waitcnt lgkmcnt(9)
	v_pk_fma_f32 v[24:25], v[48:49], v[136:137], v[40:41] op_sel_hi:[0,1,1] neg_lo:[1,0,0] neg_hi:[1,0,0]
	v_pk_fma_f32 v[26:27], v[0:1], v[138:139], 0 op_sel_hi:[0,1,0] neg_lo:[1,0,0] neg_hi:[1,0,0]
	ds_read_b128 v[136:139], v69 offset:46880
	s_waitcnt lgkmcnt(9)
	v_pk_fma_f32 v[24:25], v[4:5], v[242:243], v[24:25] op_sel_hi:[0,1,1] neg_lo:[1,0,0] neg_hi:[1,0,0]
	v_pk_fma_f32 v[26:27], v[2:3], v[244:245], v[26:27] op_sel_hi:[0,1,1] neg_lo:[1,0,0] neg_hi:[1,0,0]
	ds_read_b128 v[242:245], v69 offset:46896
	s_waitcnt lgkmcnt(9)
	v_pk_fma_f32 v[24:25], v[8:9], v[246:247], v[24:25] op_sel_hi:[0,1,1] neg_lo:[1,0,0] neg_hi:[1,0,0]
	v_pk_fma_f32 v[26:27], v[6:7], v[248:249], v[26:27] op_sel_hi:[0,1,1] neg_lo:[1,0,0] neg_hi:[1,0,0]
	ds_read_b128 v[246:249], v69 offset:47392
	s_waitcnt lgkmcnt(9)
	v_pk_fma_f32 v[16:17], v[12:13], v[238:239], v[24:25] op_sel_hi:[0,1,1] neg_lo:[1,0,0] neg_hi:[1,0,0]
	v_pk_fma_f32 v[18:19], v[10:11], v[240:241], v[26:27] op_sel_hi:[0,1,1] neg_lo:[1,0,0] neg_hi:[1,0,0]
	ds_read_b128 v[238:241], v69 offset:47408
	v_pk_add_f32 v[40:41], v[16:17], v[18:19]
	s_waitcnt lgkmcnt(9)
; #define LAS __attribute__((address_space(3)))
; DI void gdn_prep_phase(const int tid, LAS unsigned char* lds, const P& p, int G, int c) {
;     ...
;               for (int pr = 4 * kb + 4; pr < 32; ++pr) {
;                   f32x2 s0 = (f32x2){xs[2 * pr], xs[2 * pr + 1]}, s1 = (f32x2){0.f, 0.f};
; #pragma unroll
;                   for (int q = 0; q < 4; ++q) { const int j = 8 * kb + 2 * q; const f32x4 l = *(const LAS f32x4*)(Ls + pr * 136 + j * 2);
;                       s0 -= (f32x2){l[0], l[1]} * (f32x2){xs[j], xs[j]}; s1 -= (f32x2){l[2], l[3]} * (f32x2){xs[j + 1], xs[j + 1]}; }
;                   const f32x2 s = s0 + s1; xs[2 * pr] = s[0]; xs[2 * pr + 1] = s[1]; }
	v_pk_fma_f32 v[24:25], v[48:49], v[120:121], v[42:43] op_sel_hi:[0,1,1] neg_lo:[1,0,0] neg_hi:[1,0,0]
	v_pk_fma_f32 v[26:27], v[0:1], v[122:123], 0 op_sel_hi:[0,1,0] neg_lo:[1,0,0] neg_hi:[1,0,0]
	ds_read_b128 v[120:123], v69 offset:47424
	s_waitcnt lgkmcnt(9)
	v_pk_fma_f32 v[24:25], v[4:5], v[116:117], v[24:25] op_sel_hi:[0,1,1] neg_lo:[1,0,0] neg_hi:[1,0,0]
	v_pk_fma_f32 v[26:27], v[2:3], v[118:119], v[26:27] op_sel_hi:[0,1,1] neg_lo:[1,0,0] neg_hi:[1,0,0]
	ds_read_b128 v[116:119], v69 offset:47440
	s_waitcnt lgkmcnt(9)
	v_pk_fma_f32 v[24:25], v[8:9], v[112:113], v[24:25] op_sel_hi:[0,1,1] neg_lo:[1,0,0] neg_hi:[1,0,0]
	v_pk_fma_f32 v[26:27], v[6:7], v[114:115], v[26:27] op_sel_hi:[0,1,1] neg_lo:[1,0,0] neg_hi:[1,0,0]
	ds_read_b128 v[112:115], v69 offset:47936
	s_waitcnt lgkmcnt(9)
	v_pk_fma_f32 v[16:17], v[12:13], v[124:125], v[24:25] op_sel_hi:[0,1,1] neg_lo:[1,0,0] neg_hi:[1,0,0]
	v_pk_fma_f32 v[18:19], v[10:11], v[126:127], v[26:27] op_sel_hi:[0,1,1] neg_lo:[1,0,0] neg_hi:[1,0,0]
	ds_read_b128 v[124:127], v69 offset:47952
	v_pk_add_f32 v[42:43], v[16:17], v[18:19]
	s_waitcnt lgkmcnt(9)
	v_pk_fma_f32 v[24:25], v[48:49], v[128:129], v[32:33] op_sel_hi:[0,1,1] neg_lo:[1,0,0] neg_hi:[1,0,0]
	v_pk_fma_f32 v[26:27], v[0:1], v[130:131], 0 op_sel_hi:[0,1,0] neg_lo:[1,0,0] neg_hi:[1,0,0]
	ds_read_b128 v[128:131], v69 offset:47968
	s_waitcnt lgkmcnt(9)
	v_pk_fma_f32 v[24:25], v[4:5], v[132:133], v[24:25] op_sel_hi:[0,1,1] neg_lo:[1,0,0] neg_hi:[1,0,0]
	v_pk_fma_f32 v[26:27], v[2:3], v[134:135], v[26:27] op_sel_hi:[0,1,1] neg_lo:[1,0,0] neg_hi:[1,0,0]
	ds_read_b128 v[132:135], v69 offset:47984
	s_waitcnt lgkmcnt(9)
	v_pk_fma_f32 v[24:25], v[8:9], v[136:137], v[24:25] op_sel_hi:[0,1,1] neg_lo:[1,0,0] neg_hi:[1,0,0]
	v_pk_fma_f32 v[26:27], v[6:7], v[138:139], v[26:27] op_sel_hi:[0,1,1] neg_lo:[1,0,0] neg_hi:[1,0,0]
	ds_read_b128 v[136:139], v69 offset:48480
	s_waitcnt lgkmcnt(9)
	v_pk_fma_f32 v[16:17], v[12:13], v[242:243], v[24:25] op_sel_hi:[0,1,1] neg_lo:[1,0,0] neg_hi:[1,0,0]
	v_pk_fma_f32 v[18:19], v[10:11], v[244:245], v[26:27] op_sel_hi:[0,1,1] neg_lo:[1,0,0] neg_hi:[1,0,0]
	ds_read_b128 v[242:245], v69 offset:48496
	v_pk_add_f32 v[32:33], v[16:17], v[18:19]
	s_waitcnt lgkmcnt(9)
	v_pk_fma_f32 v[24:25], v[48:49], v[246:247], v[34:35] op_sel_hi:[0,1,1] neg_lo:[1,0,0] neg_hi:[1,0,0]
	v_pk_fma_f32 v[26:27], v[0:1], v[248:249], 0 op_sel_hi:[0,1,0] neg_lo:[1,0,0] neg_hi:[1,0,0]
	ds_read_b128 v[246:249], v69 offset:48512
	s_waitcnt lgkmcnt(9)
	v_pk_fma_f32 v[24:25], v[4:5], v[238:239], v[24:25] op_sel_hi:[0,1,1] neg_lo:[1,0,0] neg_hi:[1,0,0]
	v_pk_fma_f32 v[26:27], v[2:3], v[240:241], v[26:27] op_sel_hi:[0,1,1] neg_lo:[1,0,0] neg_hi:[1,0,0]
	ds_read_b128 v[238:241], v69 offset:48528
	s_waitcnt lgkmcnt(9)
	v_pk_fma_f32 v[24:25], v[8:9], v[120:121], v[24:25] op_sel_hi:[0,1,1] neg_lo:[1,0,0] neg_hi:[1,0,0]
	v_pk_fma_f32 v[26:27], v[6:7], v[122:123], v[26:27] op_sel_hi:[0,1,1] neg_lo:[1,0,0] neg_hi:[1,0,0]
	ds_read_b128 v[120:123], v69 offset:49024
	s_waitcnt lgkmcnt(9)
	v_pk_fma_f32 v[16:17], v[12:13], v[116:117], v[24:25] op_sel_hi:[0,1,1] neg_lo:[1,0,0] neg_hi:[1,0,0]
	v_pk_fma_f32 v[18:19], v[10:11], v[118:119], v[26:27] op_sel_hi:[0,1,1] neg_lo:[1,0,0] neg_hi:[1,0,0]
	ds_read_b128 v[116:119], v69 offset:49040
	v_pk_add_f32 v[34:35], v[16:17], v[18:19]
	s_waitcnt lgkmcnt(9)
	v_pk_fma_f32 v[24:25], v[48:49], v[112:113], v[28:29] op_sel_hi:[0,1,1] neg_lo:[1,0,0] neg_hi:[1,0,0]
	v_pk_fma_f32 v[26:27], v[0:1], v[114:115], 0 op_sel_hi:[0,1,0] neg_lo:[1,0,0] neg_hi:[1,0,0]
	ds_read_b128 v[112:115], v69 offset:49056
	s_waitcnt lgkmcnt(9)
	v_pk_fma_f32 v[24:25], v[4:5], v[124:125], v[24:25] op_sel_hi:[0,1,1] neg_lo:[1,0,0] neg_hi:[1,0,0]
	v_pk_fma_f32 v[26:27], v[2:3], v[126:127], v[26:27] op_sel_hi:[0,1,1] neg_lo:[1,0,0] neg_hi:[1,0,0]
	ds_read_b128 v[124:127], v69 offset:49072
	s_waitcnt lgkmcnt(9)
	v_pk_fma_f32 v[24:25], v[8:9], v[128:129], v[24:25] op_sel_hi:[0,1,1] neg_lo:[1,0,0] neg_hi:[1,0,0]
	v_pk_fma_f32 v[26:27], v[6:7], v[130:131], v[26:27] op_sel_hi:[0,1,1] neg_lo:[1,0,0] neg_hi:[1,0,0]
	ds_read_b128 v[128:131], v69 offset:49568
	s_waitcnt lgkmcnt(9)
	v_pk_fma_f32 v[16:17], v[12:13], v[132:133], v[24:25] op_sel_hi:[0,1,1] neg_lo:[1,0,0] neg_hi:[1,0,0]
	v_pk_fma_f32 v[18:19], v[10:11], v[134:135], v[26:27] op_sel_hi:[0,1,1] neg_lo:[1,0,0] neg_hi:[1,0,0]
	ds_read_b128 v[132:135], v69 offset:49584
	v_pk_add_f32 v[176:177], v[16:17], v[18:19]
	s_waitcnt lgkmcnt(9)
	v_pk_fma_f32 v[24:25], v[48:49], v[136:137], v[30:31] op_sel_hi:[0,1,1] neg_lo:[1,0,0] neg_hi:[1,0,0]
	v_pk_fma_f32 v[26:27], v[0:1], v[138:139], 0 op_sel_hi:[0,1,0] neg_lo:[1,0,0] neg_hi:[1,0,0]
	ds_read_b128 v[136:139], v69 offset:49600
	s_waitcnt lgkmcnt(9)
	v_pk_fma_f32 v[24:25], v[4:5], v[242:243], v[24:25] op_sel_hi:[0,1,1] neg_lo:[1,0,0] neg_hi:[1,0,0]
	v_pk_fma_f32 v[26:27], v[2:3], v[244:245], v[26:27] op_sel_hi:[0,1,1] neg_lo:[1,0,0] neg_hi:[1,0,0]
	ds_read_b128 v[242:245], v69 offset:49616
	s_waitcnt lgkmcnt(9)
	v_pk_fma_f32 v[24:25], v[8:9], v[246:247], v[24:25] op_sel_hi:[0,1,1] neg_lo:[1,0,0] neg_hi:[1,0,0]
	v_pk_fma_f32 v[26:27], v[6:7], v[248:249], v[26:27] op_sel_hi:[0,1,1] neg_lo:[1,0,0] neg_hi:[1,0,0]
	ds_read_b128 v[246:249], v69 offset:50112
	s_waitcnt lgkmcnt(9)
	v_pk_fma_f32 v[16:17], v[12:13], v[238:239], v[24:25] op_sel_hi:[0,1,1] neg_lo:[1,0,0] neg_hi:[1,0,0]
	v_pk_fma_f32 v[18:19], v[10:11], v[240:241], v[26:27] op_sel_hi:[0,1,1] neg_lo:[1,0,0] neg_hi:[1,0,0]
	ds_read_b128 v[238:241], v69 offset:50128
	v_pk_add_f32 v[178:179], v[16:17], v[18:19]
	s_waitcnt lgkmcnt(9)
; #define LAS __attribute__((address_space(3)))
; DI void gdn_prep_phase(const int tid, LAS unsigned char* lds, const P& p, int G, int c) {
;     ...
;                   xs[2 * pr + 1] = s[1] - Ls[pr * 136 + 4 * pr + 1] * s[0]; }
; #pragma unroll
;               for (int pr = 4 * kb + 4; pr < 32; ++pr) {
;                   f32x2 s0 = (f32x2){xs[2 * pr], xs[2 * pr + 1]}, s1 = (f32x2){0.f, 0.f};
; #pragma unroll
;                   for (int q = 0; q < 4; ++q) { const int j = 8 * kb + 2 * q; const f32x4 l = *(const LAS f32x4*)(Ls + pr * 136 + j * 2);
;                       s0 -= (f32x2){l[0], l[1]} * (f32x2){xs[j], xs[j]}; s1 -= (f32x2){l[2], l[3]} * (f32x2){xs[j + 1], xs[j + 1]}; }
;                   const f32x2 s = s0 + s1; xs[2 * pr] = s[0]; xs[2 * pr + 1] = s[1]; }
	v_pk_fma_f32 v[20:21], v[48:49], v[120:121], v[20:21] op_sel_hi:[0,1,1] neg_lo:[1,0,0] neg_hi:[1,0,0]
	v_pk_fma_f32 v[24:25], v[0:1], v[122:123], 0 op_sel_hi:[0,1,0] neg_lo:[1,0,0] neg_hi:[1,0,0]
	ds_read_b128 v[120:123], v69 offset:50144
	s_waitcnt lgkmcnt(9)
	v_pk_fma_f32 v[20:21], v[4:5], v[116:117], v[20:21] op_sel_hi:[0,1,1] neg_lo:[1,0,0] neg_hi:[1,0,0]
	v_pk_fma_f32 v[24:25], v[2:3], v[118:119], v[24:25] op_sel_hi:[0,1,1] neg_lo:[1,0,0] neg_hi:[1,0,0]
	ds_read_b128 v[116:119], v69 offset:50160
	s_waitcnt lgkmcnt(9)
	v_pk_fma_f32 v[20:21], v[8:9], v[112:113], v[20:21] op_sel_hi:[0,1,1] neg_lo:[1,0,0] neg_hi:[1,0,0]
	v_pk_fma_f32 v[24:25], v[6:7], v[114:115], v[24:25] op_sel_hi:[0,1,1] neg_lo:[1,0,0] neg_hi:[1,0,0]
	ds_read_b128 v[112:115], v69 offset:50656
	s_waitcnt lgkmcnt(9)
	v_pk_fma_f32 v[16:17], v[12:13], v[124:125], v[20:21] op_sel_hi:[0,1,1] neg_lo:[1,0,0] neg_hi:[1,0,0]
	v_pk_fma_f32 v[18:19], v[10:11], v[126:127], v[24:25] op_sel_hi:[0,1,1] neg_lo:[1,0,0] neg_hi:[1,0,0]
	ds_read_b128 v[124:127], v69 offset:50672
	v_pk_add_f32 v[184:185], v[16:17], v[18:19]
	s_waitcnt lgkmcnt(9)
	v_pk_fma_f32 v[20:21], v[48:49], v[128:129], v[22:23] op_sel_hi:[0,1,1] neg_lo:[1,0,0] neg_hi:[1,0,0]
	v_pk_fma_f32 v[22:23], v[0:1], v[130:131], 0 op_sel_hi:[0,1,0] neg_lo:[1,0,0] neg_hi:[1,0,0]
	ds_read_b128 v[128:131], v69 offset:50688
	s_waitcnt lgkmcnt(9)
	v_pk_fma_f32 v[20:21], v[4:5], v[132:133], v[20:21] op_sel_hi:[0,1,1] neg_lo:[1,0,0] neg_hi:[1,0,0]
	v_pk_fma_f32 v[22:23], v[2:3], v[134:135], v[22:23] op_sel_hi:[0,1,1] neg_lo:[1,0,0] neg_hi:[1,0,0]
	ds_read_b128 v[132:135], v69 offset:50704
	s_waitcnt lgkmcnt(9)
	v_pk_fma_f32 v[20:21], v[8:9], v[136:137], v[20:21] op_sel_hi:[0,1,1] neg_lo:[1,0,0] neg_hi:[1,0,0]
	v_pk_fma_f32 v[22:23], v[6:7], v[138:139], v[22:23] op_sel_hi:[0,1,1] neg_lo:[1,0,0] neg_hi:[1,0,0]
	ds_read_b128 v[136:139], v69 offset:51200
	s_waitcnt lgkmcnt(9)
	v_pk_fma_f32 v[16:17], v[12:13], v[242:243], v[20:21] op_sel_hi:[0,1,1] neg_lo:[1,0,0] neg_hi:[1,0,0]
	v_pk_fma_f32 v[18:19], v[10:11], v[244:245], v[22:23] op_sel_hi:[0,1,1] neg_lo:[1,0,0] neg_hi:[1,0,0]
	ds_read_b128 v[242:245], v69 offset:51216
	v_pk_add_f32 v[186:187], v[16:17], v[18:19]
	s_waitcnt lgkmcnt(9)
	v_pk_fma_f32 v[20:21], v[48:49], v[246:247], v[52:53] op_sel_hi:[0,1,1] neg_lo:[1,0,0] neg_hi:[1,0,0]
	v_pk_fma_f32 v[22:23], v[0:1], v[248:249], 0 op_sel_hi:[0,1,0] neg_lo:[1,0,0] neg_hi:[1,0,0]
	ds_read_b128 v[246:249], v69 offset:51232
	s_waitcnt lgkmcnt(9)
	v_pk_fma_f32 v[20:21], v[4:5], v[238:239], v[20:21] op_sel_hi:[0,1,1] neg_lo:[1,0,0] neg_hi:[1,0,0]
	v_pk_fma_f32 v[22:23], v[2:3], v[240:241], v[22:23] op_sel_hi:[0,1,1] neg_lo:[1,0,0] neg_hi:[1,0,0]
	ds_read_b128 v[238:241], v69 offset:51248
	s_waitcnt lgkmcnt(9)
	v_pk_fma_f32 v[20:21], v[8:9], v[120:121], v[20:21] op_sel_hi:[0,1,1] neg_lo:[1,0,0] neg_hi:[1,0,0]
	v_pk_fma_f32 v[22:23], v[6:7], v[122:123], v[22:23] op_sel_hi:[0,1,1] neg_lo:[1,0,0] neg_hi:[1,0,0]
	ds_read_b128 v[120:123], v69 offset:51744
	s_waitcnt lgkmcnt(9)
	v_pk_fma_f32 v[16:17], v[12:13], v[116:117], v[20:21] op_sel_hi:[0,1,1] neg_lo:[1,0,0] neg_hi:[1,0,0]
	v_pk_fma_f32 v[18:19], v[10:11], v[118:119], v[22:23] op_sel_hi:[0,1,1] neg_lo:[1,0,0] neg_hi:[1,0,0]
	ds_read_b128 v[116:119], v69 offset:51760
	v_pk_add_f32 v[52:53], v[16:17], v[18:19]
	s_waitcnt lgkmcnt(9)
	v_pk_fma_f32 v[20:21], v[48:49], v[112:113], v[54:55] op_sel_hi:[0,1,1] neg_lo:[1,0,0] neg_hi:[1,0,0]
	v_pk_fma_f32 v[22:23], v[0:1], v[114:115], 0 op_sel_hi:[0,1,0] neg_lo:[1,0,0] neg_hi:[1,0,0]
	ds_read_b128 v[112:115], v69 offset:51776
	s_waitcnt lgkmcnt(9)
	v_pk_fma_f32 v[20:21], v[4:5], v[124:125], v[20:21] op_sel_hi:[0,1,1] neg_lo:[1,0,0] neg_hi:[1,0,0]
	v_pk_fma_f32 v[22:23], v[2:3], v[126:127], v[22:23] op_sel_hi:[0,1,1] neg_lo:[1,0,0] neg_hi:[1,0,0]
	ds_read_b128 v[124:127], v69 offset:51792
	s_waitcnt lgkmcnt(9)
	v_pk_fma_f32 v[20:21], v[8:9], v[128:129], v[20:21] op_sel_hi:[0,1,1] neg_lo:[1,0,0] neg_hi:[1,0,0]
	v_pk_fma_f32 v[22:23], v[6:7], v[130:131], v[22:23] op_sel_hi:[0,1,1] neg_lo:[1,0,0] neg_hi:[1,0,0]
	v_add_u32_e32 v141, 0x9800, v69
	ds_read2_b32 v[128:129], v141 offset0:97 offset1:237
	s_waitcnt lgkmcnt(9)
	v_pk_fma_f32 v[16:17], v[12:13], v[132:133], v[20:21] op_sel_hi:[0,1,1] neg_lo:[1,0,0] neg_hi:[1,0,0]
	v_pk_fma_f32 v[18:19], v[10:11], v[134:135], v[22:23] op_sel_hi:[0,1,1] neg_lo:[1,0,0] neg_hi:[1,0,0]
	ds_read_b128 v[132:135], v69 offset:39840
	v_pk_add_f32 v[54:55], v[16:17], v[18:19]
	s_waitcnt lgkmcnt(9)
	v_pk_fma_f32 v[20:21], v[48:49], v[136:137], v[44:45] op_sel_hi:[0,1,1] neg_lo:[1,0,0] neg_hi:[1,0,0]
	v_pk_fma_f32 v[22:23], v[0:1], v[138:139], 0 op_sel_hi:[0,1,0] neg_lo:[1,0,0] neg_hi:[1,0,0]
	ds_read_b128 v[136:139], v69 offset:40384
	s_waitcnt lgkmcnt(9)
	v_pk_fma_f32 v[20:21], v[4:5], v[242:243], v[20:21] op_sel_hi:[0,1,1] neg_lo:[1,0,0] neg_hi:[1,0,0]
	v_pk_fma_f32 v[22:23], v[2:3], v[244:245], v[22:23] op_sel_hi:[0,1,1] neg_lo:[1,0,0] neg_hi:[1,0,0]
	ds_read_b128 v[242:245], v69 offset:40400
	s_waitcnt lgkmcnt(9)
	v_pk_fma_f32 v[20:21], v[8:9], v[246:247], v[20:21] op_sel_hi:[0,1,1] neg_lo:[1,0,0] neg_hi:[1,0,0]
	v_pk_fma_f32 v[22:23], v[6:7], v[248:249], v[22:23] op_sel_hi:[0,1,1] neg_lo:[1,0,0] neg_hi:[1,0,0]
	ds_read_b128 v[246:249], v69 offset:40928
	s_waitcnt lgkmcnt(9)
	v_pk_fma_f32 v[16:17], v[12:13], v[238:239], v[20:21] op_sel_hi:[0,1,1] neg_lo:[1,0,0] neg_hi:[1,0,0]
	v_pk_fma_f32 v[18:19], v[10:11], v[240:241], v[22:23] op_sel_hi:[0,1,1] neg_lo:[1,0,0] neg_hi:[1,0,0]
	ds_read_b128 v[238:241], v69 offset:41472
	v_pk_add_f32 v[44:45], v[16:17], v[18:19]
	s_waitcnt lgkmcnt(9)
; #define LAS __attribute__((address_space(3)))
; DI void gdn_prep_phase(const int tid, LAS unsigned char* lds, const P& p, int G, int c) {
;     ...
;           for (int kb = 0; kb < 8; ++kb) {
; #pragma unroll
;               for (int pp = 0; pp < 4; ++pp) { const int pr = 4 * kb + pp;
;                   f32x2 s = (f32x2){xs[2 * pr], xs[2 * pr + 1]};
; #pragma unroll
;                   for (int j = 8 * kb; j < 2 * pr; j += 2) { const f32x4 l = *(const LAS f32x4*)(Ls + pr * 136 + j * 2);
;                       s -= (f32x2){l[0], l[1]} * (f32x2){xs[j], xs[j]}; s -= (f32x2){l[2], l[3]} * (f32x2){xs[j + 1], xs[j + 1]}; }
;                   xs[2 * pr] = s[0];
;                   xs[2 * pr + 1] = s[1] - Ls[pr * 136 + 4 * pr + 1] * s[0]; }
; #pragma unroll
;               for (int pr = 4 * kb + 4; pr < 32; ++pr) {
;                   f32x2 s0 = (f32x2){xs[2 * pr], xs[2 * pr + 1]}, s1 = (f32x2){0.f, 0.f};
; #pragma unroll
;                   for (int q = 0; q < 4; ++q) { const int j = 8 * kb + 2 * q; const f32x4 l = *(const LAS f32x4*)(Ls + pr * 136 + j * 2);
;                       s0 -= (f32x2){l[0], l[1]} * (f32x2){xs[j], xs[j]}; s1 -= (f32x2){l[2], l[3]} * (f32x2){xs[j + 1], xs[j + 1]}; }
;                   const f32x2 s = s0 + s1; xs[2 * pr] = s[0]; xs[2 * pr + 1] = s[1]; }
;           }
;           if (isv) {
; #pragma unroll
;               for (int i8 = 0; i8 < 8; ++i8) { u32x4 w; w.x = pk2(xs[i8 * 8], xs[i8 * 8 + 1]); w.y = pk2(xs[i8 * 8 + 2], xs[i8 * 8 + 3]); w.z = pk2(xs[i8 * 8 + 4], xs[i8 * 8 + 5]); w.w = pk2(xs[i8 * 8 + 6], xs[i8 * 8 + 7]);
	v_pk_fma_f32 v[20:21], v[48:49], v[120:121], v[46:47] op_sel_hi:[0,1,1] neg_lo:[1,0,0] neg_hi:[1,0,0]
	v_pk_fma_f32 v[22:23], v[0:1], v[122:123], 0 op_sel_hi:[0,1,0] neg_lo:[1,0,0] neg_hi:[1,0,0]
	ds_read_b128 v[120:123], v69 offset:40944
	s_waitcnt lgkmcnt(9)
	v_pk_fma_f32 v[20:21], v[4:5], v[116:117], v[20:21] op_sel_hi:[0,1,1] neg_lo:[1,0,0] neg_hi:[1,0,0]
	v_pk_fma_f32 v[22:23], v[2:3], v[118:119], v[22:23] op_sel_hi:[0,1,1] neg_lo:[1,0,0] neg_hi:[1,0,0]
	v_add_u32_e32 v183, 0x9d00, v69
	ds_read2_b32 v[116:117], v183 offset0:57 offset1:197
	v_cvt_pk_bf16_f32 v3, v162, s0
	s_waitcnt lgkmcnt(9)
	v_pk_fma_f32 v[20:21], v[8:9], v[112:113], v[20:21] op_sel_hi:[0,1,1] neg_lo:[1,0,0] neg_hi:[1,0,0]
	v_pk_fma_f32 v[22:23], v[6:7], v[114:115], v[22:23] op_sel_hi:[0,1,1] neg_lo:[1,0,0] neg_hi:[1,0,0]
	ds_read_b128 v[112:115], v69 offset:40960
	v_cvt_pk_bf16_f32 v7, v160, s0
	s_waitcnt lgkmcnt(9)
	v_pk_fma_f32 v[16:17], v[12:13], v[124:125], v[20:21] op_sel_hi:[0,1,1] neg_lo:[1,0,0] neg_hi:[1,0,0]
	v_pk_fma_f32 v[18:19], v[10:11], v[126:127], v[22:23] op_sel_hi:[0,1,1] neg_lo:[1,0,0] neg_hi:[1,0,0]
	ds_read_b128 v[124:127], v69 offset:41488
	v_pk_add_f32 v[46:47], v[16:17], v[18:19]
	v_cvt_pk_bf16_f32 v11, v62, s0
	s_waitcnt lgkmcnt(9)
	v_fma_f32 v16, -v14, v128, v15
	s_waitcnt lgkmcnt(8)
	v_pk_fma_f32 v[18:19], v[14:15], v[132:133], v[188:189] op_sel_hi:[0,1,1] neg_lo:[1,0,0] neg_hi:[1,0,0]
	s_waitcnt lgkmcnt(7)
	v_pk_fma_f32 v[22:23], v[14:15], v[136:137], v[190:191] op_sel_hi:[0,1,1] neg_lo:[1,0,0] neg_hi:[1,0,0]
	v_pk_fma_f32 v[26:27], v[138:139], v[16:17], v[22:23] op_sel_hi:[1,0,1] neg_lo:[1,0,0] neg_hi:[1,0,0]
	ds_read_b128 v[136:139], v69 offset:41504
	v_pk_fma_f32 v[20:21], v[134:135], v[16:17], v[18:19] op_sel_hi:[1,0,1] neg_lo:[1,0,0] neg_hi:[1,0,0]
	ds_read_b128 v[132:135], v69 offset:41520
	v_fma_f32 v18, -v129, v20, v21
	ds_read_b128 v[128:131], v69 offset:42016
	s_waitcnt lgkmcnt(9)
	v_pk_fma_f32 v[22:23], v[242:243], v[20:21], v[26:27] op_sel_hi:[1,0,1] neg_lo:[1,0,0] neg_hi:[1,0,0]
	s_nop 0
	v_pk_fma_f32 v[26:27], v[244:245], v[18:19], v[22:23] op_sel_hi:[1,0,1] neg_lo:[1,0,0] neg_hi:[1,0,0]
	ds_read_b128 v[242:245], v69 offset:42032
	s_waitcnt lgkmcnt(9)
	v_pk_fma_f32 v[24:25], v[14:15], v[246:247], v[50:51] op_sel_hi:[0,1,1] neg_lo:[1,0,0] neg_hi:[1,0,0]
	v_pk_fma_f32 v[24:25], v[16:17], v[248:249], v[24:25] op_sel_hi:[0,1,1] neg_lo:[1,0,0] neg_hi:[1,0,0]
	ds_read_b128 v[246:249], v69 offset:42048
	s_waitcnt lgkmcnt(9)
	v_pk_fma_f32 v[50:51], v[16:17], v[240:241], 0 op_sel_hi:[0,1,0] neg_lo:[1,0,0] neg_hi:[1,0,0]
	s_waitcnt lgkmcnt(8)
	v_pk_fma_f32 v[24:25], v[20:21], v[120:121], v[24:25] op_sel_hi:[0,1,1] neg_lo:[1,0,0] neg_hi:[1,0,0]
	v_pk_fma_f32 v[24:25], v[122:123], v[18:19], v[24:25] op_sel_hi:[1,0,1] neg_lo:[1,0,0] neg_hi:[1,0,0]
	ds_read_b128 v[120:123], v69 offset:42064
	s_waitcnt lgkmcnt(8)
	v_fma_f32 v22, -v116, v26, v27
	s_waitcnt lgkmcnt(7)
	v_pk_fma_f32 v[24:25], v[112:113], v[26:27], v[24:25] op_sel_hi:[1,0,1] neg_lo:[1,0,0] neg_hi:[1,0,0]
	s_nop 0
	v_pk_fma_f32 v[28:29], v[114:115], v[22:23], v[24:25] op_sel_hi:[1,0,1] neg_lo:[1,0,0] neg_hi:[1,0,0]
	ds_read_b128 v[112:115], v69 offset:42560
	v_pk_fma_f32 v[30:31], v[14:15], v[238:239], v[164:165] op_sel_hi:[0,1,1] neg_lo:[1,0,0] neg_hi:[1,0,0]
	ds_read_b128 v[238:241], v69 offset:42576
	v_fma_f32 v24, -v117, v28, v29
	ds_read_b128 v[116:119], v69 offset:42592
	s_waitcnt lgkmcnt(9)
	v_pk_fma_f32 v[30:31], v[20:21], v[124:125], v[30:31] op_sel_hi:[0,1,1] neg_lo:[1,0,0] neg_hi:[1,0,0]
	v_pk_fma_f32 v[50:51], v[18:19], v[126:127], v[50:51] op_sel_hi:[0,1,1] neg_lo:[1,0,0] neg_hi:[1,0,0]
	ds_read_b128 v[124:127], v69 offset:42608
	s_waitcnt lgkmcnt(9)
	v_pk_fma_f32 v[30:31], v[136:137], v[26:27], v[30:31] op_sel_hi:[1,0,1] neg_lo:[1,0,0] neg_hi:[1,0,0]
	v_pk_fma_f32 v[50:51], v[138:139], v[22:23], v[50:51] op_sel_hi:[1,0,1] neg_lo:[1,0,0] neg_hi:[1,0,0]
	ds_read_b128 v[136:139], v69 offset:43104
	s_waitcnt lgkmcnt(9)
	v_pk_fma_f32 v[30:31], v[132:133], v[28:29], v[30:31] op_sel_hi:[1,0,1] neg_lo:[1,0,0] neg_hi:[1,0,0]
	v_pk_fma_f32 v[50:51], v[134:135], v[24:25], v[50:51] op_sel_hi:[1,0,1] neg_lo:[1,0,0] neg_hi:[1,0,0]
	ds_read_b128 v[132:135], v69 offset:43120
	v_pk_add_f32 v[30:31], v[30:31], v[50:51]
	s_waitcnt lgkmcnt(9)
	v_pk_fma_f32 v[50:51], v[14:15], v[128:129], v[166:167] op_sel_hi:[0,1,1] neg_lo:[1,0,0] neg_hi:[1,0,0]
	v_pk_fma_f32 v[188:189], v[16:17], v[130:131], 0 op_sel_hi:[0,1,0] neg_lo:[1,0,0] neg_hi:[1,0,0]
	ds_read_b128 v[128:131], v69 offset:43136
	s_waitcnt lgkmcnt(9)
	v_pk_fma_f32 v[50:51], v[20:21], v[242:243], v[50:51] op_sel_hi:[0,1,1] neg_lo:[1,0,0] neg_hi:[1,0,0]
	v_pk_fma_f32 v[188:189], v[18:19], v[244:245], v[188:189] op_sel_hi:[0,1,1] neg_lo:[1,0,0] neg_hi:[1,0,0]
	ds_read_b128 v[242:245], v69 offset:43152
	s_waitcnt lgkmcnt(9)
	v_pk_fma_f32 v[50:51], v[26:27], v[246:247], v[50:51] op_sel_hi:[0,1,1] neg_lo:[1,0,0] neg_hi:[1,0,0]
	v_pk_fma_f32 v[188:189], v[248:249], v[22:23], v[188:189] op_sel_hi:[1,0,1] neg_lo:[1,0,0] neg_hi:[1,0,0]
	ds_read_b128 v[246:249], v69 offset:43648
	s_waitcnt lgkmcnt(9)
	v_pk_fma_f32 v[50:51], v[120:121], v[28:29], v[50:51] op_sel_hi:[1,0,1] neg_lo:[1,0,0] neg_hi:[1,0,0]
	v_pk_fma_f32 v[164:165], v[122:123], v[24:25], v[188:189] op_sel_hi:[1,0,1] neg_lo:[1,0,0] neg_hi:[1,0,0]
	ds_read_b128 v[120:123], v69 offset:43664
	v_pk_add_f32 v[196:197], v[50:51], v[164:165]
	s_waitcnt lgkmcnt(9)
	v_pk_fma_f32 v[50:51], v[14:15], v[112:113], v[168:169] op_sel_hi:[0,1,1] neg_lo:[1,0,0] neg_hi:[1,0,0]
	v_pk_fma_f32 v[168:169], v[16:17], v[114:115], 0 op_sel_hi:[0,1,0] neg_lo:[1,0,0] neg_hi:[1,0,0]
	ds_read_b128 v[112:115], v69 offset:43680
	s_waitcnt lgkmcnt(9)
; #define LAS __attribute__((address_space(3)))
; DI void gdn_prep_phase(const int tid, LAS unsigned char* lds, const P& p, int G, int c) {
;     ...
;               for (int pr = 4 * kb + 4; pr < 32; ++pr) {
;                   f32x2 s0 = (f32x2){xs[2 * pr], xs[2 * pr + 1]}, s1 = (f32x2){0.f, 0.f};
; #pragma unroll
;                   for (int q = 0; q < 4; ++q) { const int j = 8 * kb + 2 * q; const f32x4 l = *(const LAS f32x4*)(Ls + pr * 136 + j * 2);
;                       s0 -= (f32x2){l[0], l[1]} * (f32x2){xs[j], xs[j]}; s1 -= (f32x2){l[2], l[3]} * (f32x2){xs[j + 1], xs[j + 1]}; }
;                   const f32x2 s = s0 + s1; xs[2 * pr] = s[0]; xs[2 * pr + 1] = s[1]; }
	v_pk_fma_f32 v[50:51], v[20:21], v[238:239], v[50:51] op_sel_hi:[0,1,1] neg_lo:[1,0,0] neg_hi:[1,0,0]
	v_pk_fma_f32 v[168:169], v[18:19], v[240:241], v[168:169] op_sel_hi:[0,1,1] neg_lo:[1,0,0] neg_hi:[1,0,0]
	ds_read_b128 v[238:241], v69 offset:43696
	s_waitcnt lgkmcnt(9)
	v_pk_fma_f32 v[50:51], v[26:27], v[116:117], v[50:51] op_sel_hi:[0,1,1] neg_lo:[1,0,0] neg_hi:[1,0,0]
	v_pk_fma_f32 v[168:169], v[22:23], v[118:119], v[168:169] op_sel_hi:[0,1,1] neg_lo:[1,0,0] neg_hi:[1,0,0]
	ds_read_b128 v[116:119], v69 offset:44192
	s_waitcnt lgkmcnt(9)
	v_pk_fma_f32 v[50:51], v[28:29], v[124:125], v[50:51] op_sel_hi:[0,1,1] neg_lo:[1,0,0] neg_hi:[1,0,0]
	v_pk_fma_f32 v[164:165], v[126:127], v[24:25], v[168:169] op_sel_hi:[1,0,1] neg_lo:[1,0,0] neg_hi:[1,0,0]
	ds_read_b128 v[124:127], v69 offset:44208
	v_pk_add_f32 v[198:199], v[50:51], v[164:165]
	s_waitcnt lgkmcnt(9)
	v_pk_fma_f32 v[50:51], v[14:15], v[136:137], v[170:171] op_sel_hi:[0,1,1] neg_lo:[1,0,0] neg_hi:[1,0,0]
	v_pk_fma_f32 v[168:169], v[16:17], v[138:139], 0 op_sel_hi:[0,1,0] neg_lo:[1,0,0] neg_hi:[1,0,0]
	ds_read_b128 v[136:139], v69 offset:44224
	s_waitcnt lgkmcnt(9)
	v_pk_fma_f32 v[50:51], v[20:21], v[132:133], v[50:51] op_sel_hi:[0,1,1] neg_lo:[1,0,0] neg_hi:[1,0,0]
	v_pk_fma_f32 v[168:169], v[18:19], v[134:135], v[168:169] op_sel_hi:[0,1,1] neg_lo:[1,0,0] neg_hi:[1,0,0]
	ds_read_b128 v[132:135], v69 offset:44240
	s_waitcnt lgkmcnt(9)
	v_pk_fma_f32 v[50:51], v[26:27], v[128:129], v[50:51] op_sel_hi:[0,1,1] neg_lo:[1,0,0] neg_hi:[1,0,0]
	v_pk_fma_f32 v[168:169], v[22:23], v[130:131], v[168:169] op_sel_hi:[0,1,1] neg_lo:[1,0,0] neg_hi:[1,0,0]
	ds_read_b128 v[128:131], v69 offset:44736
	s_waitcnt lgkmcnt(9)
	v_pk_fma_f32 v[50:51], v[28:29], v[242:243], v[50:51] op_sel_hi:[0,1,1] neg_lo:[1,0,0] neg_hi:[1,0,0]
	v_pk_fma_f32 v[164:165], v[24:25], v[244:245], v[168:169] op_sel_hi:[0,1,1] neg_lo:[1,0,0] neg_hi:[1,0,0]
	ds_read_b128 v[242:245], v69 offset:44752
	v_pk_add_f32 v[50:51], v[50:51], v[164:165]
	s_waitcnt lgkmcnt(9)
	v_pk_fma_f32 v[36:37], v[14:15], v[246:247], v[36:37] op_sel_hi:[0,1,1] neg_lo:[1,0,0] neg_hi:[1,0,0]
	v_pk_fma_f32 v[168:169], v[16:17], v[248:249], 0 op_sel_hi:[0,1,0] neg_lo:[1,0,0] neg_hi:[1,0,0]
	ds_read_b128 v[246:249], v69 offset:44768
	s_waitcnt lgkmcnt(9)
	v_pk_fma_f32 v[36:37], v[20:21], v[120:121], v[36:37] op_sel_hi:[0,1,1] neg_lo:[1,0,0] neg_hi:[1,0,0]
	v_pk_fma_f32 v[168:169], v[18:19], v[122:123], v[168:169] op_sel_hi:[0,1,1] neg_lo:[1,0,0] neg_hi:[1,0,0]
	ds_read_b128 v[120:123], v69 offset:44784
	s_waitcnt lgkmcnt(9)
	v_pk_fma_f32 v[36:37], v[26:27], v[112:113], v[36:37] op_sel_hi:[0,1,1] neg_lo:[1,0,0] neg_hi:[1,0,0]
	v_pk_fma_f32 v[168:169], v[22:23], v[114:115], v[168:169] op_sel_hi:[0,1,1] neg_lo:[1,0,0] neg_hi:[1,0,0]
	ds_read_b128 v[112:115], v69 offset:45280
	s_waitcnt lgkmcnt(9)
	v_pk_fma_f32 v[36:37], v[28:29], v[238:239], v[36:37] op_sel_hi:[0,1,1] neg_lo:[1,0,0] neg_hi:[1,0,0]
	v_pk_fma_f32 v[164:165], v[24:25], v[240:241], v[168:169] op_sel_hi:[0,1,1] neg_lo:[1,0,0] neg_hi:[1,0,0]
	ds_read_b128 v[238:241], v69 offset:45296
	v_pk_add_f32 v[164:165], v[36:37], v[164:165]
	s_waitcnt lgkmcnt(9)
	v_pk_fma_f32 v[166:167], v[14:15], v[116:117], v[38:39] op_sel_hi:[0,1,1] neg_lo:[1,0,0] neg_hi:[1,0,0]
	v_pk_fma_f32 v[168:169], v[16:17], v[118:119], 0 op_sel_hi:[0,1,0] neg_lo:[1,0,0] neg_hi:[1,0,0]
	ds_read_b128 v[116:119], v69 offset:45312
	s_waitcnt lgkmcnt(9)
	v_pk_fma_f32 v[166:167], v[20:21], v[124:125], v[166:167] op_sel_hi:[0,1,1] neg_lo:[1,0,0] neg_hi:[1,0,0]
	v_pk_fma_f32 v[168:169], v[18:19], v[126:127], v[168:169] op_sel_hi:[0,1,1] neg_lo:[1,0,0] neg_hi:[1,0,0]
	ds_read_b128 v[124:127], v69 offset:45328
	s_waitcnt lgkmcnt(9)
	v_pk_fma_f32 v[166:167], v[26:27], v[136:137], v[166:167] op_sel_hi:[0,1,1] neg_lo:[1,0,0] neg_hi:[1,0,0]
	v_pk_fma_f32 v[168:169], v[22:23], v[138:139], v[168:169] op_sel_hi:[0,1,1] neg_lo:[1,0,0] neg_hi:[1,0,0]
	ds_read_b128 v[136:139], v69 offset:45824
	s_waitcnt lgkmcnt(9)
	v_pk_fma_f32 v[36:37], v[28:29], v[132:133], v[166:167] op_sel_hi:[0,1,1] neg_lo:[1,0,0] neg_hi:[1,0,0]
	v_pk_fma_f32 v[38:39], v[24:25], v[134:135], v[168:169] op_sel_hi:[0,1,1] neg_lo:[1,0,0] neg_hi:[1,0,0]
	ds_read_b128 v[132:135], v69 offset:45840
	v_pk_add_f32 v[166:167], v[36:37], v[38:39]
	s_waitcnt lgkmcnt(9)
	v_pk_fma_f32 v[168:169], v[14:15], v[128:129], v[172:173] op_sel_hi:[0,1,1] neg_lo:[1,0,0] neg_hi:[1,0,0]
	v_pk_fma_f32 v[170:171], v[16:17], v[130:131], 0 op_sel_hi:[0,1,0] neg_lo:[1,0,0] neg_hi:[1,0,0]
	ds_read_b128 v[128:131], v69 offset:45856
	s_waitcnt lgkmcnt(9)
	v_pk_fma_f32 v[168:169], v[20:21], v[242:243], v[168:169] op_sel_hi:[0,1,1] neg_lo:[1,0,0] neg_hi:[1,0,0]
	v_pk_fma_f32 v[170:171], v[18:19], v[244:245], v[170:171] op_sel_hi:[0,1,1] neg_lo:[1,0,0] neg_hi:[1,0,0]
	ds_read_b128 v[242:245], v69 offset:45872
	s_waitcnt lgkmcnt(9)
	v_pk_fma_f32 v[168:169], v[26:27], v[246:247], v[168:169] op_sel_hi:[0,1,1] neg_lo:[1,0,0] neg_hi:[1,0,0]
	v_pk_fma_f32 v[170:171], v[22:23], v[248:249], v[170:171] op_sel_hi:[0,1,1] neg_lo:[1,0,0] neg_hi:[1,0,0]
	ds_read_b128 v[246:249], v69 offset:46368
	s_waitcnt lgkmcnt(9)
	v_pk_fma_f32 v[36:37], v[28:29], v[120:121], v[168:169] op_sel_hi:[0,1,1] neg_lo:[1,0,0] neg_hi:[1,0,0]
	v_pk_fma_f32 v[38:39], v[24:25], v[122:123], v[170:171] op_sel_hi:[0,1,1] neg_lo:[1,0,0] neg_hi:[1,0,0]
	ds_read_b128 v[120:123], v69 offset:46384
	v_pk_add_f32 v[168:169], v[36:37], v[38:39]
	s_waitcnt lgkmcnt(9)
	v_pk_fma_f32 v[170:171], v[14:15], v[112:113], v[174:175] op_sel_hi:[0,1,1] neg_lo:[1,0,0] neg_hi:[1,0,0]
	v_pk_fma_f32 v[172:173], v[16:17], v[114:115], 0 op_sel_hi:[0,1,0] neg_lo:[1,0,0] neg_hi:[1,0,0]
	ds_read_b128 v[112:115], v69 offset:46400
	s_waitcnt lgkmcnt(9)
; #define LAS __attribute__((address_space(3)))
; DI void gdn_prep_phase(const int tid, LAS unsigned char* lds, const P& p, int G, int c) {
;     ...
;               for (int pr = 4 * kb + 4; pr < 32; ++pr) {
;                   f32x2 s0 = (f32x2){xs[2 * pr], xs[2 * pr + 1]}, s1 = (f32x2){0.f, 0.f};
; #pragma unroll
;                   for (int q = 0; q < 4; ++q) { const int j = 8 * kb + 2 * q; const f32x4 l = *(const LAS f32x4*)(Ls + pr * 136 + j * 2);
;                       s0 -= (f32x2){l[0], l[1]} * (f32x2){xs[j], xs[j]}; s1 -= (f32x2){l[2], l[3]} * (f32x2){xs[j + 1], xs[j + 1]}; }
;                   const f32x2 s = s0 + s1; xs[2 * pr] = s[0]; xs[2 * pr + 1] = s[1]; }
	v_pk_fma_f32 v[170:171], v[20:21], v[238:239], v[170:171] op_sel_hi:[0,1,1] neg_lo:[1,0,0] neg_hi:[1,0,0]
	v_pk_fma_f32 v[172:173], v[18:19], v[240:241], v[172:173] op_sel_hi:[0,1,1] neg_lo:[1,0,0] neg_hi:[1,0,0]
	ds_read_b128 v[238:241], v69 offset:46416
	s_waitcnt lgkmcnt(9)
	v_pk_fma_f32 v[170:171], v[26:27], v[116:117], v[170:171] op_sel_hi:[0,1,1] neg_lo:[1,0,0] neg_hi:[1,0,0]
	v_pk_fma_f32 v[172:173], v[22:23], v[118:119], v[172:173] op_sel_hi:[0,1,1] neg_lo:[1,0,0] neg_hi:[1,0,0]
	ds_read_b128 v[116:119], v69 offset:46912
	s_waitcnt lgkmcnt(9)
	v_pk_fma_f32 v[36:37], v[28:29], v[124:125], v[170:171] op_sel_hi:[0,1,1] neg_lo:[1,0,0] neg_hi:[1,0,0]
	v_pk_fma_f32 v[38:39], v[24:25], v[126:127], v[172:173] op_sel_hi:[0,1,1] neg_lo:[1,0,0] neg_hi:[1,0,0]
	ds_read_b128 v[124:127], v69 offset:46928
	v_pk_add_f32 v[170:171], v[36:37], v[38:39]
	s_waitcnt lgkmcnt(9)
	v_pk_fma_f32 v[40:41], v[14:15], v[136:137], v[40:41] op_sel_hi:[0,1,1] neg_lo:[1,0,0] neg_hi:[1,0,0]
	v_pk_fma_f32 v[172:173], v[16:17], v[138:139], 0 op_sel_hi:[0,1,0] neg_lo:[1,0,0] neg_hi:[1,0,0]
	ds_read_b128 v[136:139], v69 offset:46944
	s_waitcnt lgkmcnt(9)
	v_pk_fma_f32 v[40:41], v[20:21], v[132:133], v[40:41] op_sel_hi:[0,1,1] neg_lo:[1,0,0] neg_hi:[1,0,0]
	v_pk_fma_f32 v[172:173], v[18:19], v[134:135], v[172:173] op_sel_hi:[0,1,1] neg_lo:[1,0,0] neg_hi:[1,0,0]
	ds_read_b128 v[132:135], v69 offset:46960
	s_waitcnt lgkmcnt(9)
	v_pk_fma_f32 v[40:41], v[26:27], v[128:129], v[40:41] op_sel_hi:[0,1,1] neg_lo:[1,0,0] neg_hi:[1,0,0]
	v_pk_fma_f32 v[172:173], v[22:23], v[130:131], v[172:173] op_sel_hi:[0,1,1] neg_lo:[1,0,0] neg_hi:[1,0,0]
	ds_read_b128 v[128:131], v69 offset:47456
	s_waitcnt lgkmcnt(9)
	v_pk_fma_f32 v[36:37], v[28:29], v[242:243], v[40:41] op_sel_hi:[0,1,1] neg_lo:[1,0,0] neg_hi:[1,0,0]
	v_pk_fma_f32 v[38:39], v[24:25], v[244:245], v[172:173] op_sel_hi:[0,1,1] neg_lo:[1,0,0] neg_hi:[1,0,0]
	ds_read_b128 v[242:245], v69 offset:47472
	v_pk_add_f32 v[172:173], v[36:37], v[38:39]
	s_waitcnt lgkmcnt(9)
	v_pk_fma_f32 v[40:41], v[14:15], v[246:247], v[42:43] op_sel_hi:[0,1,1] neg_lo:[1,0,0] neg_hi:[1,0,0]
	v_pk_fma_f32 v[42:43], v[16:17], v[248:249], 0 op_sel_hi:[0,1,0] neg_lo:[1,0,0] neg_hi:[1,0,0]
	ds_read_b128 v[246:249], v69 offset:47488
	s_waitcnt lgkmcnt(9)
	v_pk_fma_f32 v[40:41], v[20:21], v[120:121], v[40:41] op_sel_hi:[0,1,1] neg_lo:[1,0,0] neg_hi:[1,0,0]
	v_pk_fma_f32 v[42:43], v[18:19], v[122:123], v[42:43] op_sel_hi:[0,1,1] neg_lo:[1,0,0] neg_hi:[1,0,0]
	ds_read_b128 v[120:123], v69 offset:47504
	s_waitcnt lgkmcnt(9)
	v_pk_fma_f32 v[40:41], v[26:27], v[112:113], v[40:41] op_sel_hi:[0,1,1] neg_lo:[1,0,0] neg_hi:[1,0,0]
	v_pk_fma_f32 v[42:43], v[22:23], v[114:115], v[42:43] op_sel_hi:[0,1,1] neg_lo:[1,0,0] neg_hi:[1,0,0]
	ds_read_b128 v[112:115], v69 offset:48000
	s_waitcnt lgkmcnt(9)
	v_pk_fma_f32 v[36:37], v[28:29], v[238:239], v[40:41] op_sel_hi:[0,1,1] neg_lo:[1,0,0] neg_hi:[1,0,0]
	v_pk_fma_f32 v[38:39], v[24:25], v[240:241], v[42:43] op_sel_hi:[0,1,1] neg_lo:[1,0,0] neg_hi:[1,0,0]
	ds_read_b128 v[238:241], v69 offset:48016
	v_pk_add_f32 v[174:175], v[36:37], v[38:39]
	s_waitcnt lgkmcnt(9)
	v_pk_fma_f32 v[32:33], v[14:15], v[116:117], v[32:33] op_sel_hi:[0,1,1] neg_lo:[1,0,0] neg_hi:[1,0,0]
	v_pk_fma_f32 v[40:41], v[16:17], v[118:119], 0 op_sel_hi:[0,1,0] neg_lo:[1,0,0] neg_hi:[1,0,0]
	ds_read_b128 v[116:119], v69 offset:48032
	s_waitcnt lgkmcnt(9)
	v_pk_fma_f32 v[32:33], v[20:21], v[124:125], v[32:33] op_sel_hi:[0,1,1] neg_lo:[1,0,0] neg_hi:[1,0,0]
	v_pk_fma_f32 v[40:41], v[18:19], v[126:127], v[40:41] op_sel_hi:[0,1,1] neg_lo:[1,0,0] neg_hi:[1,0,0]
	ds_read_b128 v[124:127], v69 offset:48048
	s_waitcnt lgkmcnt(9)
	v_pk_fma_f32 v[32:33], v[26:27], v[136:137], v[32:33] op_sel_hi:[0,1,1] neg_lo:[1,0,0] neg_hi:[1,0,0]
	v_pk_fma_f32 v[40:41], v[22:23], v[138:139], v[40:41] op_sel_hi:[0,1,1] neg_lo:[1,0,0] neg_hi:[1,0,0]
	ds_read_b128 v[136:139], v69 offset:48544
	s_waitcnt lgkmcnt(9)
	v_pk_fma_f32 v[32:33], v[28:29], v[132:133], v[32:33] op_sel_hi:[0,1,1] neg_lo:[1,0,0] neg_hi:[1,0,0]
	v_pk_fma_f32 v[36:37], v[24:25], v[134:135], v[40:41] op_sel_hi:[0,1,1] neg_lo:[1,0,0] neg_hi:[1,0,0]
	ds_read_b128 v[132:135], v69 offset:48560
	v_pk_add_f32 v[188:189], v[32:33], v[36:37]
	s_waitcnt lgkmcnt(9)
	v_pk_fma_f32 v[36:37], v[14:15], v[128:129], v[34:35] op_sel_hi:[0,1,1] neg_lo:[1,0,0] neg_hi:[1,0,0]
	v_pk_fma_f32 v[38:39], v[16:17], v[130:131], 0 op_sel_hi:[0,1,0] neg_lo:[1,0,0] neg_hi:[1,0,0]
	ds_read_b128 v[128:131], v69 offset:48576
	s_waitcnt lgkmcnt(9)
	v_pk_fma_f32 v[36:37], v[20:21], v[242:243], v[36:37] op_sel_hi:[0,1,1] neg_lo:[1,0,0] neg_hi:[1,0,0]
	v_pk_fma_f32 v[38:39], v[18:19], v[244:245], v[38:39] op_sel_hi:[0,1,1] neg_lo:[1,0,0] neg_hi:[1,0,0]
	ds_read_b128 v[242:245], v69 offset:48592
	s_waitcnt lgkmcnt(9)
	v_pk_fma_f32 v[36:37], v[26:27], v[246:247], v[36:37] op_sel_hi:[0,1,1] neg_lo:[1,0,0] neg_hi:[1,0,0]
	v_pk_fma_f32 v[38:39], v[22:23], v[248:249], v[38:39] op_sel_hi:[0,1,1] neg_lo:[1,0,0] neg_hi:[1,0,0]
	ds_read_b128 v[246:249], v69 offset:49088
	s_waitcnt lgkmcnt(9)
	v_pk_fma_f32 v[32:33], v[28:29], v[120:121], v[36:37] op_sel_hi:[0,1,1] neg_lo:[1,0,0] neg_hi:[1,0,0]
	v_pk_fma_f32 v[34:35], v[24:25], v[122:123], v[38:39] op_sel_hi:[0,1,1] neg_lo:[1,0,0] neg_hi:[1,0,0]
	ds_read_b128 v[120:123], v69 offset:49104
	v_pk_add_f32 v[190:191], v[32:33], v[34:35]
	s_waitcnt lgkmcnt(9)
	v_pk_fma_f32 v[36:37], v[14:15], v[112:113], v[176:177] op_sel_hi:[0,1,1] neg_lo:[1,0,0] neg_hi:[1,0,0]
	v_pk_fma_f32 v[38:39], v[16:17], v[114:115], 0 op_sel_hi:[0,1,0] neg_lo:[1,0,0] neg_hi:[1,0,0]
	ds_read_b128 v[112:115], v69 offset:49120
	s_waitcnt lgkmcnt(9)
; #define LAS __attribute__((address_space(3)))
; DI void gdn_prep_phase(const int tid, LAS unsigned char* lds, const P& p, int G, int c) {
;     ...
;               for (int pr = 4 * kb + 4; pr < 32; ++pr) {
;                   f32x2 s0 = (f32x2){xs[2 * pr], xs[2 * pr + 1]}, s1 = (f32x2){0.f, 0.f};
; #pragma unroll
;                   for (int q = 0; q < 4; ++q) { const int j = 8 * kb + 2 * q; const f32x4 l = *(const LAS f32x4*)(Ls + pr * 136 + j * 2);
;                       s0 -= (f32x2){l[0], l[1]} * (f32x2){xs[j], xs[j]}; s1 -= (f32x2){l[2], l[3]} * (f32x2){xs[j + 1], xs[j + 1]}; }
;                   const f32x2 s = s0 + s1; xs[2 * pr] = s[0]; xs[2 * pr + 1] = s[1]; }
	v_pk_fma_f32 v[36:37], v[20:21], v[238:239], v[36:37] op_sel_hi:[0,1,1] neg_lo:[1,0,0] neg_hi:[1,0,0]
	v_pk_fma_f32 v[38:39], v[18:19], v[240:241], v[38:39] op_sel_hi:[0,1,1] neg_lo:[1,0,0] neg_hi:[1,0,0]
	ds_read_b128 v[238:241], v69 offset:49136
	s_waitcnt lgkmcnt(9)
	v_pk_fma_f32 v[36:37], v[26:27], v[116:117], v[36:37] op_sel_hi:[0,1,1] neg_lo:[1,0,0] neg_hi:[1,0,0]
	v_pk_fma_f32 v[38:39], v[22:23], v[118:119], v[38:39] op_sel_hi:[0,1,1] neg_lo:[1,0,0] neg_hi:[1,0,0]
	ds_read_b128 v[116:119], v69 offset:49632
	s_waitcnt lgkmcnt(9)
	v_pk_fma_f32 v[32:33], v[28:29], v[124:125], v[36:37] op_sel_hi:[0,1,1] neg_lo:[1,0,0] neg_hi:[1,0,0]
	v_pk_fma_f32 v[34:35], v[24:25], v[126:127], v[38:39] op_sel_hi:[0,1,1] neg_lo:[1,0,0] neg_hi:[1,0,0]
	ds_read_b128 v[124:127], v69 offset:49648
	v_pk_add_f32 v[176:177], v[32:33], v[34:35]
	s_waitcnt lgkmcnt(9)
	v_pk_fma_f32 v[36:37], v[14:15], v[136:137], v[178:179] op_sel_hi:[0,1,1] neg_lo:[1,0,0] neg_hi:[1,0,0]
	v_pk_fma_f32 v[38:39], v[16:17], v[138:139], 0 op_sel_hi:[0,1,0] neg_lo:[1,0,0] neg_hi:[1,0,0]
	ds_read_b128 v[136:139], v69 offset:49664
	s_waitcnt lgkmcnt(9)
	v_pk_fma_f32 v[36:37], v[20:21], v[132:133], v[36:37] op_sel_hi:[0,1,1] neg_lo:[1,0,0] neg_hi:[1,0,0]
	v_pk_fma_f32 v[38:39], v[18:19], v[134:135], v[38:39] op_sel_hi:[0,1,1] neg_lo:[1,0,0] neg_hi:[1,0,0]
	ds_read_b128 v[132:135], v69 offset:49680
	s_waitcnt lgkmcnt(9)
	v_pk_fma_f32 v[36:37], v[26:27], v[128:129], v[36:37] op_sel_hi:[0,1,1] neg_lo:[1,0,0] neg_hi:[1,0,0]
	v_pk_fma_f32 v[38:39], v[22:23], v[130:131], v[38:39] op_sel_hi:[0,1,1] neg_lo:[1,0,0] neg_hi:[1,0,0]
	ds_read_b128 v[128:131], v69 offset:50176
	s_waitcnt lgkmcnt(9)
	v_pk_fma_f32 v[32:33], v[28:29], v[242:243], v[36:37] op_sel_hi:[0,1,1] neg_lo:[1,0,0] neg_hi:[1,0,0]
	v_pk_fma_f32 v[34:35], v[24:25], v[244:245], v[38:39] op_sel_hi:[0,1,1] neg_lo:[1,0,0] neg_hi:[1,0,0]
	ds_read_b128 v[242:245], v69 offset:50192
	v_pk_add_f32 v[178:179], v[32:33], v[34:35]
	s_waitcnt lgkmcnt(9)
	v_pk_fma_f32 v[36:37], v[14:15], v[246:247], v[184:185] op_sel_hi:[0,1,1] neg_lo:[1,0,0] neg_hi:[1,0,0]
	v_pk_fma_f32 v[38:39], v[16:17], v[248:249], 0 op_sel_hi:[0,1,0] neg_lo:[1,0,0] neg_hi:[1,0,0]
	ds_read_b128 v[246:249], v69 offset:50208
	s_waitcnt lgkmcnt(9)
	v_pk_fma_f32 v[36:37], v[20:21], v[120:121], v[36:37] op_sel_hi:[0,1,1] neg_lo:[1,0,0] neg_hi:[1,0,0]
	v_pk_fma_f32 v[38:39], v[18:19], v[122:123], v[38:39] op_sel_hi:[0,1,1] neg_lo:[1,0,0] neg_hi:[1,0,0]
	ds_read_b128 v[120:123], v69 offset:50224
	s_waitcnt lgkmcnt(9)
	v_pk_fma_f32 v[36:37], v[26:27], v[112:113], v[36:37] op_sel_hi:[0,1,1] neg_lo:[1,0,0] neg_hi:[1,0,0]
	v_pk_fma_f32 v[38:39], v[22:23], v[114:115], v[38:39] op_sel_hi:[0,1,1] neg_lo:[1,0,0] neg_hi:[1,0,0]
	ds_read_b128 v[112:115], v69 offset:50720
	s_waitcnt lgkmcnt(9)
	v_pk_fma_f32 v[32:33], v[28:29], v[238:239], v[36:37] op_sel_hi:[0,1,1] neg_lo:[1,0,0] neg_hi:[1,0,0]
	v_pk_fma_f32 v[34:35], v[24:25], v[240:241], v[38:39] op_sel_hi:[0,1,1] neg_lo:[1,0,0] neg_hi:[1,0,0]
	ds_read_b128 v[238:241], v69 offset:50736
	v_pk_add_f32 v[184:185], v[32:33], v[34:35]
	s_waitcnt lgkmcnt(9)
	v_pk_fma_f32 v[36:37], v[14:15], v[116:117], v[186:187] op_sel_hi:[0,1,1] neg_lo:[1,0,0] neg_hi:[1,0,0]
	v_pk_fma_f32 v[38:39], v[16:17], v[118:119], 0 op_sel_hi:[0,1,0] neg_lo:[1,0,0] neg_hi:[1,0,0]
	ds_read_b128 v[116:119], v69 offset:50752
	s_waitcnt lgkmcnt(9)
	v_pk_fma_f32 v[36:37], v[20:21], v[124:125], v[36:37] op_sel_hi:[0,1,1] neg_lo:[1,0,0] neg_hi:[1,0,0]
	v_pk_fma_f32 v[38:39], v[18:19], v[126:127], v[38:39] op_sel_hi:[0,1,1] neg_lo:[1,0,0] neg_hi:[1,0,0]
	ds_read_b128 v[124:127], v69 offset:50768
	s_waitcnt lgkmcnt(9)
	v_pk_fma_f32 v[36:37], v[26:27], v[136:137], v[36:37] op_sel_hi:[0,1,1] neg_lo:[1,0,0] neg_hi:[1,0,0]
	v_pk_fma_f32 v[38:39], v[22:23], v[138:139], v[38:39] op_sel_hi:[0,1,1] neg_lo:[1,0,0] neg_hi:[1,0,0]
	ds_read_b128 v[136:139], v69 offset:51264
	s_waitcnt lgkmcnt(9)
	v_pk_fma_f32 v[32:33], v[28:29], v[132:133], v[36:37] op_sel_hi:[0,1,1] neg_lo:[1,0,0] neg_hi:[1,0,0]
	v_pk_fma_f32 v[34:35], v[24:25], v[134:135], v[38:39] op_sel_hi:[0,1,1] neg_lo:[1,0,0] neg_hi:[1,0,0]
	ds_read_b128 v[132:135], v69 offset:51280
	v_pk_add_f32 v[186:187], v[32:33], v[34:35]
	s_waitcnt lgkmcnt(9)
	v_pk_fma_f32 v[36:37], v[14:15], v[128:129], v[52:53] op_sel_hi:[0,1,1] neg_lo:[1,0,0] neg_hi:[1,0,0]
	v_pk_fma_f32 v[38:39], v[16:17], v[130:131], 0 op_sel_hi:[0,1,0] neg_lo:[1,0,0] neg_hi:[1,0,0]
	ds_read_b128 v[128:131], v69 offset:51296
	s_waitcnt lgkmcnt(9)
	v_pk_fma_f32 v[36:37], v[20:21], v[242:243], v[36:37] op_sel_hi:[0,1,1] neg_lo:[1,0,0] neg_hi:[1,0,0]
	v_pk_fma_f32 v[38:39], v[18:19], v[244:245], v[38:39] op_sel_hi:[0,1,1] neg_lo:[1,0,0] neg_hi:[1,0,0]
	ds_read_b128 v[242:245], v69 offset:51312
	s_waitcnt lgkmcnt(9)
	v_pk_fma_f32 v[36:37], v[26:27], v[246:247], v[36:37] op_sel_hi:[0,1,1] neg_lo:[1,0,0] neg_hi:[1,0,0]
	v_pk_fma_f32 v[38:39], v[22:23], v[248:249], v[38:39] op_sel_hi:[0,1,1] neg_lo:[1,0,0] neg_hi:[1,0,0]
	ds_read_b128 v[246:249], v69 offset:51808
	s_waitcnt lgkmcnt(9)
	v_pk_fma_f32 v[32:33], v[28:29], v[120:121], v[36:37] op_sel_hi:[0,1,1] neg_lo:[1,0,0] neg_hi:[1,0,0]
	v_pk_fma_f32 v[34:35], v[24:25], v[122:123], v[38:39] op_sel_hi:[0,1,1] neg_lo:[1,0,0] neg_hi:[1,0,0]
	ds_read_b128 v[120:123], v69 offset:51824
	v_pk_add_f32 v[52:53], v[32:33], v[34:35]
	s_waitcnt lgkmcnt(9)
	v_pk_fma_f32 v[36:37], v[14:15], v[112:113], v[54:55] op_sel_hi:[0,1,1] neg_lo:[1,0,0] neg_hi:[1,0,0]
	v_pk_fma_f32 v[38:39], v[16:17], v[114:115], 0 op_sel_hi:[0,1,0] neg_lo:[1,0,0] neg_hi:[1,0,0]
	ds_read_b128 v[112:115], v69 offset:51840
	s_waitcnt lgkmcnt(9)
; #define LAS __attribute__((address_space(3)))
; DI void gdn_prep_phase(const int tid, LAS unsigned char* lds, const P& p, int G, int c) {
;     ...
;           for (int kb = 0; kb < 8; ++kb) {
; #pragma unroll
;               for (int pp = 0; pp < 4; ++pp) { const int pr = 4 * kb + pp;
;                   f32x2 s = (f32x2){xs[2 * pr], xs[2 * pr + 1]};
; #pragma unroll
;                   for (int j = 8 * kb; j < 2 * pr; j += 2) { const f32x4 l = *(const LAS f32x4*)(Ls + pr * 136 + j * 2);
;                       s -= (f32x2){l[0], l[1]} * (f32x2){xs[j], xs[j]}; s -= (f32x2){l[2], l[3]} * (f32x2){xs[j + 1], xs[j + 1]}; }
;                   xs[2 * pr] = s[0];
;                   xs[2 * pr + 1] = s[1] - Ls[pr * 136 + 4 * pr + 1] * s[0]; }
; #pragma unroll
;               for (int pr = 4 * kb + 4; pr < 32; ++pr) {
;                   f32x2 s0 = (f32x2){xs[2 * pr], xs[2 * pr + 1]}, s1 = (f32x2){0.f, 0.f};
; #pragma unroll
;                   for (int q = 0; q < 4; ++q) { const int j = 8 * kb + 2 * q; const f32x4 l = *(const LAS f32x4*)(Ls + pr * 136 + j * 2);
;                       s0 -= (f32x2){l[0], l[1]} * (f32x2){xs[j], xs[j]}; s1 -= (f32x2){l[2], l[3]} * (f32x2){xs[j + 1], xs[j + 1]}; }
;                   const f32x2 s = s0 + s1; xs[2 * pr] = s[0]; xs[2 * pr + 1] = s[1]; }
;           }
;           if (isv) {
; #pragma unroll
;               for (int i8 = 0; i8 < 8; ++i8) { u32x4 w; w.x = pk2(xs[i8 * 8], xs[i8 * 8 + 1]); w.y = pk2(xs[i8 * 8 + 2], xs[i8 * 8 + 3]); w.z = pk2(xs[i8 * 8 + 4], xs[i8 * 8 + 5]); w.w = pk2(xs[i8 * 8 + 6], xs[i8 * 8 + 7]);
	v_pk_fma_f32 v[36:37], v[20:21], v[238:239], v[36:37] op_sel_hi:[0,1,1] neg_lo:[1,0,0] neg_hi:[1,0,0]
	v_pk_fma_f32 v[38:39], v[18:19], v[240:241], v[38:39] op_sel_hi:[0,1,1] neg_lo:[1,0,0] neg_hi:[1,0,0]
	ds_read_b128 v[238:241], v69 offset:51856
	s_waitcnt lgkmcnt(9)
	v_pk_fma_f32 v[36:37], v[26:27], v[116:117], v[36:37] op_sel_hi:[0,1,1] neg_lo:[1,0,0] neg_hi:[1,0,0]
	v_pk_fma_f32 v[38:39], v[22:23], v[118:119], v[38:39] op_sel_hi:[0,1,1] neg_lo:[1,0,0] neg_hi:[1,0,0]
	v_add_u32_e32 v232, 0xa200, v69
	ds_read2_b32 v[116:117], v232 offset0:17 offset1:157
	s_waitcnt lgkmcnt(9)
	v_pk_fma_f32 v[32:33], v[28:29], v[124:125], v[36:37] op_sel_hi:[0,1,1] neg_lo:[1,0,0] neg_hi:[1,0,0]
	v_pk_fma_f32 v[34:35], v[24:25], v[126:127], v[38:39] op_sel_hi:[0,1,1] neg_lo:[1,0,0] neg_hi:[1,0,0]
	ds_read_b128 v[124:127], v69 offset:42080
	v_pk_add_f32 v[54:55], v[32:33], v[34:35]
	s_waitcnt lgkmcnt(9)
	v_pk_fma_f32 v[36:37], v[14:15], v[136:137], v[44:45] op_sel_hi:[0,1,1] neg_lo:[1,0,0] neg_hi:[1,0,0]
	v_pk_fma_f32 v[38:39], v[16:17], v[138:139], 0 op_sel_hi:[0,1,0] neg_lo:[1,0,0] neg_hi:[1,0,0]
	ds_read_b128 v[136:139], v69 offset:42624
	s_waitcnt lgkmcnt(9)
	v_pk_fma_f32 v[36:37], v[20:21], v[132:133], v[36:37] op_sel_hi:[0,1,1] neg_lo:[1,0,0] neg_hi:[1,0,0]
	v_pk_fma_f32 v[38:39], v[18:19], v[134:135], v[38:39] op_sel_hi:[0,1,1] neg_lo:[1,0,0] neg_hi:[1,0,0]
	ds_read_b128 v[132:135], v69 offset:42640
	s_waitcnt lgkmcnt(9)
	v_pk_fma_f32 v[36:37], v[26:27], v[128:129], v[36:37] op_sel_hi:[0,1,1] neg_lo:[1,0,0] neg_hi:[1,0,0]
	v_pk_fma_f32 v[38:39], v[22:23], v[130:131], v[38:39] op_sel_hi:[0,1,1] neg_lo:[1,0,0] neg_hi:[1,0,0]
	ds_read_b128 v[128:131], v69 offset:43168
	s_waitcnt lgkmcnt(9)
	v_pk_fma_f32 v[32:33], v[28:29], v[242:243], v[36:37] op_sel_hi:[0,1,1] neg_lo:[1,0,0] neg_hi:[1,0,0]
	v_pk_fma_f32 v[34:35], v[24:25], v[244:245], v[38:39] op_sel_hi:[0,1,1] neg_lo:[1,0,0] neg_hi:[1,0,0]
	ds_read_b128 v[242:245], v69 offset:43712
	v_pk_add_f32 v[192:193], v[32:33], v[34:35]
	s_waitcnt lgkmcnt(9)
	v_pk_fma_f32 v[36:37], v[14:15], v[246:247], v[46:47] op_sel_hi:[0,1,1] neg_lo:[1,0,0] neg_hi:[1,0,0]
	v_pk_fma_f32 v[38:39], v[16:17], v[248:249], 0 op_sel_hi:[0,1,0] neg_lo:[1,0,0] neg_hi:[1,0,0]
	ds_read_b128 v[246:249], v69 offset:43184
	v_cvt_pk_bf16_f32 v17, v66, s0
	s_waitcnt lgkmcnt(9)
	v_pk_fma_f32 v[36:37], v[20:21], v[120:121], v[36:37] op_sel_hi:[0,1,1] neg_lo:[1,0,0] neg_hi:[1,0,0]
	v_pk_fma_f32 v[38:39], v[18:19], v[122:123], v[38:39] op_sel_hi:[0,1,1] neg_lo:[1,0,0] neg_hi:[1,0,0]
	v_add_u32_e32 v233, 0xa600, v69
	ds_read2_b32 v[120:121], v233 offset0:41 offset1:181
	v_cvt_pk_bf16_f32 v19, v158, s0
	s_waitcnt lgkmcnt(9)
	v_pk_fma_f32 v[36:37], v[26:27], v[112:113], v[36:37] op_sel_hi:[0,1,1] neg_lo:[1,0,0] neg_hi:[1,0,0]
	v_pk_fma_f32 v[38:39], v[22:23], v[114:115], v[38:39] op_sel_hi:[0,1,1] neg_lo:[1,0,0] neg_hi:[1,0,0]
	ds_read_b128 v[112:115], v69 offset:43200
	s_waitcnt lgkmcnt(9)
	v_pk_fma_f32 v[32:33], v[28:29], v[238:239], v[36:37] op_sel_hi:[0,1,1] neg_lo:[1,0,0] neg_hi:[1,0,0]
	v_pk_fma_f32 v[34:35], v[24:25], v[240:241], v[38:39] op_sel_hi:[0,1,1] neg_lo:[1,0,0] neg_hi:[1,0,0]
	ds_read_b128 v[238:241], v69 offset:43728
	v_pk_add_f32 v[194:195], v[32:33], v[34:35]
	s_waitcnt lgkmcnt(9)
	v_fma_f32 v32, -v30, v116, v31
	s_waitcnt lgkmcnt(8)
	v_pk_fma_f32 v[34:35], v[30:31], v[124:125], v[196:197] op_sel_hi:[0,1,1] neg_lo:[1,0,0] neg_hi:[1,0,0]
	s_waitcnt lgkmcnt(7)
	v_pk_fma_f32 v[38:39], v[30:31], v[136:137], v[198:199] op_sel_hi:[0,1,1] neg_lo:[1,0,0] neg_hi:[1,0,0]
	v_pk_fma_f32 v[42:43], v[138:139], v[32:33], v[38:39] op_sel_hi:[1,0,1] neg_lo:[1,0,0] neg_hi:[1,0,0]
	ds_read_b128 v[136:139], v69 offset:43744
	v_pk_fma_f32 v[36:37], v[126:127], v[32:33], v[34:35] op_sel_hi:[1,0,1] neg_lo:[1,0,0] neg_hi:[1,0,0]
	ds_read_b128 v[124:127], v69 offset:43760
	v_fma_f32 v34, -v117, v36, v37
	ds_read_b128 v[116:119], v69 offset:44256
	s_waitcnt lgkmcnt(9)
	v_pk_fma_f32 v[38:39], v[132:133], v[36:37], v[42:43] op_sel_hi:[1,0,1] neg_lo:[1,0,0] neg_hi:[1,0,0]
	s_nop 0
	v_pk_fma_f32 v[42:43], v[134:135], v[34:35], v[38:39] op_sel_hi:[1,0,1] neg_lo:[1,0,0] neg_hi:[1,0,0]
	ds_read_b128 v[132:135], v69 offset:44272
	s_waitcnt lgkmcnt(9)
	v_pk_fma_f32 v[40:41], v[30:31], v[128:129], v[50:51] op_sel_hi:[0,1,1] neg_lo:[1,0,0] neg_hi:[1,0,0]
	v_pk_fma_f32 v[40:41], v[32:33], v[130:131], v[40:41] op_sel_hi:[0,1,1] neg_lo:[1,0,0] neg_hi:[1,0,0]
	ds_read_b128 v[128:131], v69 offset:44288
	s_waitcnt lgkmcnt(9)
	v_pk_fma_f32 v[50:51], v[32:33], v[244:245], 0 op_sel_hi:[0,1,0] neg_lo:[1,0,0] neg_hi:[1,0,0]
	s_waitcnt lgkmcnt(8)
	v_pk_fma_f32 v[40:41], v[36:37], v[246:247], v[40:41] op_sel_hi:[0,1,1] neg_lo:[1,0,0] neg_hi:[1,0,0]
	v_pk_fma_f32 v[40:41], v[248:249], v[34:35], v[40:41] op_sel_hi:[1,0,1] neg_lo:[1,0,0] neg_hi:[1,0,0]
	ds_read_b128 v[246:249], v69 offset:44304
	s_waitcnt lgkmcnt(8)
	v_fma_f32 v38, -v120, v42, v43
	s_waitcnt lgkmcnt(7)
	v_pk_fma_f32 v[40:41], v[112:113], v[42:43], v[40:41] op_sel_hi:[1,0,1] neg_lo:[1,0,0] neg_hi:[1,0,0]
	s_nop 0
	v_pk_fma_f32 v[44:45], v[114:115], v[38:39], v[40:41] op_sel_hi:[1,0,1] neg_lo:[1,0,0] neg_hi:[1,0,0]
	ds_read_b128 v[112:115], v69 offset:44800
	v_pk_fma_f32 v[46:47], v[30:31], v[242:243], v[164:165] op_sel_hi:[0,1,1] neg_lo:[1,0,0] neg_hi:[1,0,0]
	ds_read_b128 v[242:245], v69 offset:44816
	v_fma_f32 v40, -v121, v44, v45
	ds_read_b128 v[120:123], v69 offset:44832
	s_waitcnt lgkmcnt(9)
	v_pk_fma_f32 v[46:47], v[36:37], v[238:239], v[46:47] op_sel_hi:[0,1,1] neg_lo:[1,0,0] neg_hi:[1,0,0]
	v_pk_fma_f32 v[50:51], v[34:35], v[240:241], v[50:51] op_sel_hi:[0,1,1] neg_lo:[1,0,0] neg_hi:[1,0,0]
	ds_read_b128 v[238:241], v69 offset:44848
	s_waitcnt lgkmcnt(9)
; #define LAS __attribute__((address_space(3)))
; DI void gdn_prep_phase(const int tid, LAS unsigned char* lds, const P& p, int G, int c) {
;     ...
;               for (int pr = 4 * kb + 4; pr < 32; ++pr) {
;                   f32x2 s0 = (f32x2){xs[2 * pr], xs[2 * pr + 1]}, s1 = (f32x2){0.f, 0.f};
; #pragma unroll
;                   for (int q = 0; q < 4; ++q) { const int j = 8 * kb + 2 * q; const f32x4 l = *(const LAS f32x4*)(Ls + pr * 136 + j * 2);
;                       s0 -= (f32x2){l[0], l[1]} * (f32x2){xs[j], xs[j]}; s1 -= (f32x2){l[2], l[3]} * (f32x2){xs[j + 1], xs[j + 1]}; }
;                   const f32x2 s = s0 + s1; xs[2 * pr] = s[0]; xs[2 * pr + 1] = s[1]; }
	v_pk_fma_f32 v[46:47], v[136:137], v[42:43], v[46:47] op_sel_hi:[1,0,1] neg_lo:[1,0,0] neg_hi:[1,0,0]
	v_pk_fma_f32 v[50:51], v[138:139], v[38:39], v[50:51] op_sel_hi:[1,0,1] neg_lo:[1,0,0] neg_hi:[1,0,0]
	ds_read_b128 v[136:139], v69 offset:45344
	s_waitcnt lgkmcnt(9)
	v_pk_fma_f32 v[46:47], v[124:125], v[44:45], v[46:47] op_sel_hi:[1,0,1] neg_lo:[1,0,0] neg_hi:[1,0,0]
	v_pk_fma_f32 v[50:51], v[126:127], v[40:41], v[50:51] op_sel_hi:[1,0,1] neg_lo:[1,0,0] neg_hi:[1,0,0]
	ds_read_b128 v[124:127], v69 offset:45360
	v_pk_add_f32 v[46:47], v[46:47], v[50:51]
	s_waitcnt lgkmcnt(9)
	v_pk_fma_f32 v[50:51], v[30:31], v[116:117], v[166:167] op_sel_hi:[0,1,1] neg_lo:[1,0,0] neg_hi:[1,0,0]
	v_pk_fma_f32 v[196:197], v[32:33], v[118:119], 0 op_sel_hi:[0,1,0] neg_lo:[1,0,0] neg_hi:[1,0,0]
	ds_read_b128 v[116:119], v69 offset:45376
	s_waitcnt lgkmcnt(9)
	v_pk_fma_f32 v[50:51], v[36:37], v[132:133], v[50:51] op_sel_hi:[0,1,1] neg_lo:[1,0,0] neg_hi:[1,0,0]
	v_pk_fma_f32 v[196:197], v[34:35], v[134:135], v[196:197] op_sel_hi:[0,1,1] neg_lo:[1,0,0] neg_hi:[1,0,0]
	ds_read_b128 v[132:135], v69 offset:45392
	s_waitcnt lgkmcnt(9)
	v_pk_fma_f32 v[50:51], v[42:43], v[128:129], v[50:51] op_sel_hi:[0,1,1] neg_lo:[1,0,0] neg_hi:[1,0,0]
	v_pk_fma_f32 v[196:197], v[130:131], v[38:39], v[196:197] op_sel_hi:[1,0,1] neg_lo:[1,0,0] neg_hi:[1,0,0]
	ds_read_b128 v[128:131], v69 offset:45888
	s_waitcnt lgkmcnt(9)
	v_pk_fma_f32 v[50:51], v[246:247], v[44:45], v[50:51] op_sel_hi:[1,0,1] neg_lo:[1,0,0] neg_hi:[1,0,0]
	v_pk_fma_f32 v[164:165], v[248:249], v[40:41], v[196:197] op_sel_hi:[1,0,1] neg_lo:[1,0,0] neg_hi:[1,0,0]
	ds_read_b128 v[246:249], v69 offset:45904
	v_pk_add_f32 v[164:165], v[50:51], v[164:165]
	s_waitcnt lgkmcnt(9)
	v_pk_fma_f32 v[50:51], v[30:31], v[112:113], v[168:169] op_sel_hi:[0,1,1] neg_lo:[1,0,0] neg_hi:[1,0,0]
	v_pk_fma_f32 v[196:197], v[32:33], v[114:115], 0 op_sel_hi:[0,1,0] neg_lo:[1,0,0] neg_hi:[1,0,0]
	ds_read_b128 v[112:115], v69 offset:45920
	s_waitcnt lgkmcnt(9)
	v_pk_fma_f32 v[50:51], v[36:37], v[242:243], v[50:51] op_sel_hi:[0,1,1] neg_lo:[1,0,0] neg_hi:[1,0,0]
	v_pk_fma_f32 v[196:197], v[34:35], v[244:245], v[196:197] op_sel_hi:[0,1,1] neg_lo:[1,0,0] neg_hi:[1,0,0]
	ds_read_b128 v[242:245], v69 offset:45936
	s_waitcnt lgkmcnt(9)
	v_pk_fma_f32 v[50:51], v[42:43], v[120:121], v[50:51] op_sel_hi:[0,1,1] neg_lo:[1,0,0] neg_hi:[1,0,0]
	v_pk_fma_f32 v[196:197], v[38:39], v[122:123], v[196:197] op_sel_hi:[0,1,1] neg_lo:[1,0,0] neg_hi:[1,0,0]
	ds_read_b128 v[120:123], v69 offset:46432
	s_waitcnt lgkmcnt(9)
	v_pk_fma_f32 v[50:51], v[44:45], v[238:239], v[50:51] op_sel_hi:[0,1,1] neg_lo:[1,0,0] neg_hi:[1,0,0]
	v_pk_fma_f32 v[166:167], v[240:241], v[40:41], v[196:197] op_sel_hi:[1,0,1] neg_lo:[1,0,0] neg_hi:[1,0,0]
	ds_read_b128 v[238:241], v69 offset:46448
	v_pk_add_f32 v[168:169], v[50:51], v[166:167]
	s_waitcnt lgkmcnt(9)
	v_pk_fma_f32 v[50:51], v[30:31], v[136:137], v[170:171] op_sel_hi:[0,1,1] neg_lo:[1,0,0] neg_hi:[1,0,0]
	v_pk_fma_f32 v[166:167], v[32:33], v[138:139], 0 op_sel_hi:[0,1,0] neg_lo:[1,0,0] neg_hi:[1,0,0]
	ds_read_b128 v[136:139], v69 offset:46464
	s_waitcnt lgkmcnt(9)
	v_pk_fma_f32 v[50:51], v[36:37], v[124:125], v[50:51] op_sel_hi:[0,1,1] neg_lo:[1,0,0] neg_hi:[1,0,0]
	v_pk_fma_f32 v[166:167], v[34:35], v[126:127], v[166:167] op_sel_hi:[0,1,1] neg_lo:[1,0,0] neg_hi:[1,0,0]
	ds_read_b128 v[124:127], v69 offset:46480
	s_waitcnt lgkmcnt(9)
	v_pk_fma_f32 v[50:51], v[42:43], v[116:117], v[50:51] op_sel_hi:[0,1,1] neg_lo:[1,0,0] neg_hi:[1,0,0]
	v_pk_fma_f32 v[166:167], v[38:39], v[118:119], v[166:167] op_sel_hi:[0,1,1] neg_lo:[1,0,0] neg_hi:[1,0,0]
	ds_read_b128 v[116:119], v69 offset:46976
	s_waitcnt lgkmcnt(9)
	v_pk_fma_f32 v[50:51], v[44:45], v[132:133], v[50:51] op_sel_hi:[0,1,1] neg_lo:[1,0,0] neg_hi:[1,0,0]
	v_pk_fma_f32 v[166:167], v[40:41], v[134:135], v[166:167] op_sel_hi:[0,1,1] neg_lo:[1,0,0] neg_hi:[1,0,0]
	ds_read_b128 v[132:135], v69 offset:46992
	v_pk_add_f32 v[166:167], v[50:51], v[166:167]
	s_waitcnt lgkmcnt(9)
	v_pk_fma_f32 v[50:51], v[30:31], v[128:129], v[172:173] op_sel_hi:[0,1,1] neg_lo:[1,0,0] neg_hi:[1,0,0]
	v_pk_fma_f32 v[196:197], v[32:33], v[130:131], 0 op_sel_hi:[0,1,0] neg_lo:[1,0,0] neg_hi:[1,0,0]
	ds_read_b128 v[128:131], v69 offset:47008
	s_waitcnt lgkmcnt(9)
	v_pk_fma_f32 v[50:51], v[36:37], v[246:247], v[50:51] op_sel_hi:[0,1,1] neg_lo:[1,0,0] neg_hi:[1,0,0]
	v_pk_fma_f32 v[196:197], v[34:35], v[248:249], v[196:197] op_sel_hi:[0,1,1] neg_lo:[1,0,0] neg_hi:[1,0,0]
	ds_read_b128 v[246:249], v69 offset:47024
	s_waitcnt lgkmcnt(9)
	v_pk_fma_f32 v[50:51], v[42:43], v[112:113], v[50:51] op_sel_hi:[0,1,1] neg_lo:[1,0,0] neg_hi:[1,0,0]
	v_pk_fma_f32 v[196:197], v[38:39], v[114:115], v[196:197] op_sel_hi:[0,1,1] neg_lo:[1,0,0] neg_hi:[1,0,0]
	ds_read_b128 v[112:115], v69 offset:47520
	s_waitcnt lgkmcnt(9)
	v_pk_fma_f32 v[50:51], v[44:45], v[242:243], v[50:51] op_sel_hi:[0,1,1] neg_lo:[1,0,0] neg_hi:[1,0,0]
	v_pk_fma_f32 v[170:171], v[40:41], v[244:245], v[196:197] op_sel_hi:[0,1,1] neg_lo:[1,0,0] neg_hi:[1,0,0]
	ds_read_b128 v[242:245], v69 offset:47536
	v_pk_add_f32 v[172:173], v[50:51], v[170:171]
	s_waitcnt lgkmcnt(9)
	v_pk_fma_f32 v[50:51], v[30:31], v[120:121], v[174:175] op_sel_hi:[0,1,1] neg_lo:[1,0,0] neg_hi:[1,0,0]
	v_pk_fma_f32 v[170:171], v[32:33], v[122:123], 0 op_sel_hi:[0,1,0] neg_lo:[1,0,0] neg_hi:[1,0,0]
	ds_read_b128 v[120:123], v69 offset:47552
	s_waitcnt lgkmcnt(9)
	v_pk_fma_f32 v[50:51], v[36:37], v[238:239], v[50:51] op_sel_hi:[0,1,1] neg_lo:[1,0,0] neg_hi:[1,0,0]
	v_pk_fma_f32 v[170:171], v[34:35], v[240:241], v[170:171] op_sel_hi:[0,1,1] neg_lo:[1,0,0] neg_hi:[1,0,0]
	ds_read_b128 v[238:241], v69 offset:47568
	s_waitcnt lgkmcnt(9)
; #define LAS __attribute__((address_space(3)))
; DI void gdn_prep_phase(const int tid, LAS unsigned char* lds, const P& p, int G, int c) {
;     ...
;               for (int pr = 4 * kb + 4; pr < 32; ++pr) {
;                   f32x2 s0 = (f32x2){xs[2 * pr], xs[2 * pr + 1]}, s1 = (f32x2){0.f, 0.f};
; #pragma unroll
;                   for (int q = 0; q < 4; ++q) { const int j = 8 * kb + 2 * q; const f32x4 l = *(const LAS f32x4*)(Ls + pr * 136 + j * 2);
;                       s0 -= (f32x2){l[0], l[1]} * (f32x2){xs[j], xs[j]}; s1 -= (f32x2){l[2], l[3]} * (f32x2){xs[j + 1], xs[j + 1]}; }
;                   const f32x2 s = s0 + s1; xs[2 * pr] = s[0]; xs[2 * pr + 1] = s[1]; }
	v_pk_fma_f32 v[50:51], v[42:43], v[136:137], v[50:51] op_sel_hi:[0,1,1] neg_lo:[1,0,0] neg_hi:[1,0,0]
	v_pk_fma_f32 v[170:171], v[38:39], v[138:139], v[170:171] op_sel_hi:[0,1,1] neg_lo:[1,0,0] neg_hi:[1,0,0]
	ds_read_b128 v[136:139], v69 offset:48064
	s_waitcnt lgkmcnt(9)
	v_pk_fma_f32 v[50:51], v[44:45], v[124:125], v[50:51] op_sel_hi:[0,1,1] neg_lo:[1,0,0] neg_hi:[1,0,0]
	v_pk_fma_f32 v[170:171], v[40:41], v[126:127], v[170:171] op_sel_hi:[0,1,1] neg_lo:[1,0,0] neg_hi:[1,0,0]
	ds_read_b128 v[124:127], v69 offset:48080
	v_pk_add_f32 v[174:175], v[50:51], v[170:171]
	s_waitcnt lgkmcnt(9)
	v_pk_fma_f32 v[50:51], v[30:31], v[116:117], v[188:189] op_sel_hi:[0,1,1] neg_lo:[1,0,0] neg_hi:[1,0,0]
	v_pk_fma_f32 v[170:171], v[32:33], v[118:119], 0 op_sel_hi:[0,1,0] neg_lo:[1,0,0] neg_hi:[1,0,0]
	ds_read_b128 v[116:119], v69 offset:48096
	s_waitcnt lgkmcnt(9)
	v_pk_fma_f32 v[50:51], v[36:37], v[132:133], v[50:51] op_sel_hi:[0,1,1] neg_lo:[1,0,0] neg_hi:[1,0,0]
	v_pk_fma_f32 v[170:171], v[34:35], v[134:135], v[170:171] op_sel_hi:[0,1,1] neg_lo:[1,0,0] neg_hi:[1,0,0]
	ds_read_b128 v[132:135], v69 offset:48112
	s_waitcnt lgkmcnt(9)
	v_pk_fma_f32 v[50:51], v[42:43], v[128:129], v[50:51] op_sel_hi:[0,1,1] neg_lo:[1,0,0] neg_hi:[1,0,0]
	v_pk_fma_f32 v[170:171], v[38:39], v[130:131], v[170:171] op_sel_hi:[0,1,1] neg_lo:[1,0,0] neg_hi:[1,0,0]
	ds_read_b128 v[128:131], v69 offset:48608
	s_waitcnt lgkmcnt(9)
	v_pk_fma_f32 v[50:51], v[44:45], v[246:247], v[50:51] op_sel_hi:[0,1,1] neg_lo:[1,0,0] neg_hi:[1,0,0]
	v_pk_fma_f32 v[170:171], v[40:41], v[248:249], v[170:171] op_sel_hi:[0,1,1] neg_lo:[1,0,0] neg_hi:[1,0,0]
	ds_read_b128 v[246:249], v69 offset:48624
	v_pk_add_f32 v[188:189], v[50:51], v[170:171]
	s_waitcnt lgkmcnt(9)
	v_pk_fma_f32 v[50:51], v[30:31], v[112:113], v[190:191] op_sel_hi:[0,1,1] neg_lo:[1,0,0] neg_hi:[1,0,0]
	v_pk_fma_f32 v[170:171], v[32:33], v[114:115], 0 op_sel_hi:[0,1,0] neg_lo:[1,0,0] neg_hi:[1,0,0]
	ds_read_b128 v[112:115], v69 offset:48640
	s_waitcnt lgkmcnt(9)
	v_pk_fma_f32 v[50:51], v[36:37], v[242:243], v[50:51] op_sel_hi:[0,1,1] neg_lo:[1,0,0] neg_hi:[1,0,0]
	v_pk_fma_f32 v[170:171], v[34:35], v[244:245], v[170:171] op_sel_hi:[0,1,1] neg_lo:[1,0,0] neg_hi:[1,0,0]
	ds_read_b128 v[242:245], v69 offset:48656
	s_waitcnt lgkmcnt(9)
	v_pk_fma_f32 v[50:51], v[42:43], v[120:121], v[50:51] op_sel_hi:[0,1,1] neg_lo:[1,0,0] neg_hi:[1,0,0]
	v_pk_fma_f32 v[170:171], v[38:39], v[122:123], v[170:171] op_sel_hi:[0,1,1] neg_lo:[1,0,0] neg_hi:[1,0,0]
	ds_read_b128 v[120:123], v69 offset:49152
	s_waitcnt lgkmcnt(9)
	v_pk_fma_f32 v[50:51], v[44:45], v[238:239], v[50:51] op_sel_hi:[0,1,1] neg_lo:[1,0,0] neg_hi:[1,0,0]
	v_pk_fma_f32 v[170:171], v[40:41], v[240:241], v[170:171] op_sel_hi:[0,1,1] neg_lo:[1,0,0] neg_hi:[1,0,0]
	ds_read_b128 v[238:241], v69 offset:49168
	v_pk_add_f32 v[190:191], v[50:51], v[170:171]
	s_waitcnt lgkmcnt(9)
	v_pk_fma_f32 v[50:51], v[30:31], v[136:137], v[176:177] op_sel_hi:[0,1,1] neg_lo:[1,0,0] neg_hi:[1,0,0]
	v_pk_fma_f32 v[170:171], v[32:33], v[138:139], 0 op_sel_hi:[0,1,0] neg_lo:[1,0,0] neg_hi:[1,0,0]
	ds_read_b128 v[136:139], v69 offset:49184
	s_waitcnt lgkmcnt(9)
	v_pk_fma_f32 v[50:51], v[36:37], v[124:125], v[50:51] op_sel_hi:[0,1,1] neg_lo:[1,0,0] neg_hi:[1,0,0]
	v_pk_fma_f32 v[170:171], v[34:35], v[126:127], v[170:171] op_sel_hi:[0,1,1] neg_lo:[1,0,0] neg_hi:[1,0,0]
	ds_read_b128 v[124:127], v69 offset:49200
	s_waitcnt lgkmcnt(9)
	v_pk_fma_f32 v[50:51], v[42:43], v[116:117], v[50:51] op_sel_hi:[0,1,1] neg_lo:[1,0,0] neg_hi:[1,0,0]
	v_pk_fma_f32 v[170:171], v[38:39], v[118:119], v[170:171] op_sel_hi:[0,1,1] neg_lo:[1,0,0] neg_hi:[1,0,0]
	ds_read_b128 v[116:119], v69 offset:49696
	s_waitcnt lgkmcnt(9)
	v_pk_fma_f32 v[50:51], v[44:45], v[132:133], v[50:51] op_sel_hi:[0,1,1] neg_lo:[1,0,0] neg_hi:[1,0,0]
	v_pk_fma_f32 v[170:171], v[40:41], v[134:135], v[170:171] op_sel_hi:[0,1,1] neg_lo:[1,0,0] neg_hi:[1,0,0]
	ds_read_b128 v[132:135], v69 offset:49712
	v_pk_add_f32 v[176:177], v[50:51], v[170:171]
	s_waitcnt lgkmcnt(9)
	v_pk_fma_f32 v[50:51], v[30:31], v[128:129], v[178:179] op_sel_hi:[0,1,1] neg_lo:[1,0,0] neg_hi:[1,0,0]
	v_pk_fma_f32 v[170:171], v[32:33], v[130:131], 0 op_sel_hi:[0,1,0] neg_lo:[1,0,0] neg_hi:[1,0,0]
	ds_read_b128 v[128:131], v69 offset:49728
	s_waitcnt lgkmcnt(9)
	v_pk_fma_f32 v[50:51], v[36:37], v[246:247], v[50:51] op_sel_hi:[0,1,1] neg_lo:[1,0,0] neg_hi:[1,0,0]
	v_pk_fma_f32 v[170:171], v[34:35], v[248:249], v[170:171] op_sel_hi:[0,1,1] neg_lo:[1,0,0] neg_hi:[1,0,0]
	ds_read_b128 v[246:249], v69 offset:49744
	s_waitcnt lgkmcnt(9)
	v_pk_fma_f32 v[50:51], v[42:43], v[112:113], v[50:51] op_sel_hi:[0,1,1] neg_lo:[1,0,0] neg_hi:[1,0,0]
	v_pk_fma_f32 v[170:171], v[38:39], v[114:115], v[170:171] op_sel_hi:[0,1,1] neg_lo:[1,0,0] neg_hi:[1,0,0]
	ds_read_b128 v[112:115], v69 offset:50240
	s_waitcnt lgkmcnt(9)
	v_pk_fma_f32 v[50:51], v[44:45], v[242:243], v[50:51] op_sel_hi:[0,1,1] neg_lo:[1,0,0] neg_hi:[1,0,0]
	v_pk_fma_f32 v[170:171], v[40:41], v[244:245], v[170:171] op_sel_hi:[0,1,1] neg_lo:[1,0,0] neg_hi:[1,0,0]
	ds_read_b128 v[242:245], v69 offset:50256
	v_pk_add_f32 v[178:179], v[50:51], v[170:171]
	s_waitcnt lgkmcnt(9)
	v_pk_fma_f32 v[50:51], v[30:31], v[120:121], v[184:185] op_sel_hi:[0,1,1] neg_lo:[1,0,0] neg_hi:[1,0,0]
	v_pk_fma_f32 v[170:171], v[32:33], v[122:123], 0 op_sel_hi:[0,1,0] neg_lo:[1,0,0] neg_hi:[1,0,0]
	ds_read_b128 v[120:123], v69 offset:50272
	s_waitcnt lgkmcnt(9)
	v_pk_fma_f32 v[50:51], v[36:37], v[238:239], v[50:51] op_sel_hi:[0,1,1] neg_lo:[1,0,0] neg_hi:[1,0,0]
	v_pk_fma_f32 v[170:171], v[34:35], v[240:241], v[170:171] op_sel_hi:[0,1,1] neg_lo:[1,0,0] neg_hi:[1,0,0]
	ds_read_b128 v[238:241], v69 offset:50288
	s_waitcnt lgkmcnt(9)
; #define LAS __attribute__((address_space(3)))
; DI void gdn_prep_phase(const int tid, LAS unsigned char* lds, const P& p, int G, int c) {
;     ...
;                   xs[2 * pr + 1] = s[1] - Ls[pr * 136 + 4 * pr + 1] * s[0]; }
; #pragma unroll
;               for (int pr = 4 * kb + 4; pr < 32; ++pr) {
;                   f32x2 s0 = (f32x2){xs[2 * pr], xs[2 * pr + 1]}, s1 = (f32x2){0.f, 0.f};
; #pragma unroll
;                   for (int q = 0; q < 4; ++q) { const int j = 8 * kb + 2 * q; const f32x4 l = *(const LAS f32x4*)(Ls + pr * 136 + j * 2);
;                       s0 -= (f32x2){l[0], l[1]} * (f32x2){xs[j], xs[j]}; s1 -= (f32x2){l[2], l[3]} * (f32x2){xs[j + 1], xs[j + 1]}; }
;                   const f32x2 s = s0 + s1; xs[2 * pr] = s[0]; xs[2 * pr + 1] = s[1]; }
	v_pk_fma_f32 v[50:51], v[42:43], v[136:137], v[50:51] op_sel_hi:[0,1,1] neg_lo:[1,0,0] neg_hi:[1,0,0]
	v_pk_fma_f32 v[170:171], v[38:39], v[138:139], v[170:171] op_sel_hi:[0,1,1] neg_lo:[1,0,0] neg_hi:[1,0,0]
	ds_read_b128 v[136:139], v69 offset:50784
	s_waitcnt lgkmcnt(9)
	v_pk_fma_f32 v[50:51], v[44:45], v[124:125], v[50:51] op_sel_hi:[0,1,1] neg_lo:[1,0,0] neg_hi:[1,0,0]
	v_pk_fma_f32 v[170:171], v[40:41], v[126:127], v[170:171] op_sel_hi:[0,1,1] neg_lo:[1,0,0] neg_hi:[1,0,0]
	ds_read_b128 v[124:127], v69 offset:50800
	v_pk_add_f32 v[184:185], v[50:51], v[170:171]
	s_waitcnt lgkmcnt(9)
	v_pk_fma_f32 v[50:51], v[30:31], v[116:117], v[186:187] op_sel_hi:[0,1,1] neg_lo:[1,0,0] neg_hi:[1,0,0]
	v_pk_fma_f32 v[170:171], v[32:33], v[118:119], 0 op_sel_hi:[0,1,0] neg_lo:[1,0,0] neg_hi:[1,0,0]
	ds_read_b128 v[116:119], v69 offset:50816
	s_waitcnt lgkmcnt(9)
	v_pk_fma_f32 v[50:51], v[36:37], v[132:133], v[50:51] op_sel_hi:[0,1,1] neg_lo:[1,0,0] neg_hi:[1,0,0]
	v_pk_fma_f32 v[170:171], v[34:35], v[134:135], v[170:171] op_sel_hi:[0,1,1] neg_lo:[1,0,0] neg_hi:[1,0,0]
	ds_read_b128 v[132:135], v69 offset:50832
	s_waitcnt lgkmcnt(9)
	v_pk_fma_f32 v[50:51], v[42:43], v[128:129], v[50:51] op_sel_hi:[0,1,1] neg_lo:[1,0,0] neg_hi:[1,0,0]
	v_pk_fma_f32 v[170:171], v[38:39], v[130:131], v[170:171] op_sel_hi:[0,1,1] neg_lo:[1,0,0] neg_hi:[1,0,0]
	ds_read_b128 v[128:131], v69 offset:51328
	s_waitcnt lgkmcnt(9)
	v_pk_fma_f32 v[50:51], v[44:45], v[246:247], v[50:51] op_sel_hi:[0,1,1] neg_lo:[1,0,0] neg_hi:[1,0,0]
	v_pk_fma_f32 v[170:171], v[40:41], v[248:249], v[170:171] op_sel_hi:[0,1,1] neg_lo:[1,0,0] neg_hi:[1,0,0]
	ds_read_b128 v[246:249], v69 offset:51344
	v_pk_add_f32 v[186:187], v[50:51], v[170:171]
	s_waitcnt lgkmcnt(9)
	v_pk_fma_f32 v[170:171], v[30:31], v[112:113], v[52:53] op_sel_hi:[0,1,1] neg_lo:[1,0,0] neg_hi:[1,0,0]
	v_pk_fma_f32 v[196:197], v[32:33], v[114:115], 0 op_sel_hi:[0,1,0] neg_lo:[1,0,0] neg_hi:[1,0,0]
	ds_read_b128 v[112:115], v69 offset:51360
	s_waitcnt lgkmcnt(9)
	v_pk_fma_f32 v[170:171], v[36:37], v[242:243], v[170:171] op_sel_hi:[0,1,1] neg_lo:[1,0,0] neg_hi:[1,0,0]
	v_pk_fma_f32 v[196:197], v[34:35], v[244:245], v[196:197] op_sel_hi:[0,1,1] neg_lo:[1,0,0] neg_hi:[1,0,0]
	ds_read_b128 v[242:245], v69 offset:51376
	s_waitcnt lgkmcnt(9)
	v_pk_fma_f32 v[170:171], v[42:43], v[120:121], v[170:171] op_sel_hi:[0,1,1] neg_lo:[1,0,0] neg_hi:[1,0,0]
	v_pk_fma_f32 v[196:197], v[38:39], v[122:123], v[196:197] op_sel_hi:[0,1,1] neg_lo:[1,0,0] neg_hi:[1,0,0]
	ds_read_b128 v[120:123], v69 offset:51872
	s_waitcnt lgkmcnt(9)
	v_pk_fma_f32 v[50:51], v[44:45], v[238:239], v[170:171] op_sel_hi:[0,1,1] neg_lo:[1,0,0] neg_hi:[1,0,0]
	v_pk_fma_f32 v[52:53], v[40:41], v[240:241], v[196:197] op_sel_hi:[0,1,1] neg_lo:[1,0,0] neg_hi:[1,0,0]
	ds_read_b128 v[238:241], v69 offset:51888
	v_pk_add_f32 v[196:197], v[50:51], v[52:53]
	s_waitcnt lgkmcnt(9)
	v_pk_fma_f32 v[54:55], v[30:31], v[136:137], v[54:55] op_sel_hi:[0,1,1] neg_lo:[1,0,0] neg_hi:[1,0,0]
	v_pk_fma_f32 v[170:171], v[32:33], v[138:139], 0 op_sel_hi:[0,1,0] neg_lo:[1,0,0] neg_hi:[1,0,0]
	ds_read_b128 v[136:139], v69 offset:51904
	s_waitcnt lgkmcnt(9)
	v_pk_fma_f32 v[54:55], v[36:37], v[124:125], v[54:55] op_sel_hi:[0,1,1] neg_lo:[1,0,0] neg_hi:[1,0,0]
	v_pk_fma_f32 v[170:171], v[34:35], v[126:127], v[170:171] op_sel_hi:[0,1,1] neg_lo:[1,0,0] neg_hi:[1,0,0]
	ds_read_b128 v[124:127], v69 offset:51920
	s_waitcnt lgkmcnt(9)
	v_pk_fma_f32 v[54:55], v[42:43], v[116:117], v[54:55] op_sel_hi:[0,1,1] neg_lo:[1,0,0] neg_hi:[1,0,0]
	v_pk_fma_f32 v[170:171], v[38:39], v[118:119], v[170:171] op_sel_hi:[0,1,1] neg_lo:[1,0,0] neg_hi:[1,0,0]
	v_add_u32_e32 v141, 0xaa00, v69
	ds_read2_b32 v[116:117], v141 offset0:65 offset1:205
	s_waitcnt lgkmcnt(9)
	v_pk_fma_f32 v[50:51], v[44:45], v[132:133], v[54:55] op_sel_hi:[0,1,1] neg_lo:[1,0,0] neg_hi:[1,0,0]
	v_pk_fma_f32 v[52:53], v[40:41], v[134:135], v[170:171] op_sel_hi:[0,1,1] neg_lo:[1,0,0] neg_hi:[1,0,0]
	ds_read_b128 v[132:135], v69 offset:44320
	v_pk_add_f32 v[198:199], v[50:51], v[52:53]
	s_waitcnt lgkmcnt(9)
	v_pk_fma_f32 v[54:55], v[30:31], v[128:129], v[192:193] op_sel_hi:[0,1,1] neg_lo:[1,0,0] neg_hi:[1,0,0]
	v_pk_fma_f32 v[170:171], v[32:33], v[130:131], 0 op_sel_hi:[0,1,0] neg_lo:[1,0,0] neg_hi:[1,0,0]
	ds_read_b128 v[128:131], v69 offset:44864
	s_waitcnt lgkmcnt(9)
	v_pk_fma_f32 v[54:55], v[36:37], v[246:247], v[54:55] op_sel_hi:[0,1,1] neg_lo:[1,0,0] neg_hi:[1,0,0]
	v_pk_fma_f32 v[170:171], v[34:35], v[248:249], v[170:171] op_sel_hi:[0,1,1] neg_lo:[1,0,0] neg_hi:[1,0,0]
	ds_read_b128 v[246:249], v69 offset:45408
	s_waitcnt lgkmcnt(9)
	v_pk_fma_f32 v[54:55], v[42:43], v[112:113], v[54:55] op_sel_hi:[0,1,1] neg_lo:[1,0,0] neg_hi:[1,0,0]
	v_pk_fma_f32 v[170:171], v[38:39], v[114:115], v[170:171] op_sel_hi:[0,1,1] neg_lo:[1,0,0] neg_hi:[1,0,0]
	ds_read_b128 v[112:115], v69 offset:44880
	s_waitcnt lgkmcnt(9)
	v_pk_fma_f32 v[50:51], v[44:45], v[242:243], v[54:55] op_sel_hi:[0,1,1] neg_lo:[1,0,0] neg_hi:[1,0,0]
	v_pk_fma_f32 v[52:53], v[40:41], v[244:245], v[170:171] op_sel_hi:[0,1,1] neg_lo:[1,0,0] neg_hi:[1,0,0]
	ds_read_b128 v[242:245], v69 offset:45424
	v_pk_add_f32 v[192:193], v[50:51], v[52:53]
	s_waitcnt lgkmcnt(9)
	v_pk_fma_f32 v[54:55], v[30:31], v[120:121], v[194:195] op_sel_hi:[0,1,1] neg_lo:[1,0,0] neg_hi:[1,0,0]
	v_pk_fma_f32 v[170:171], v[32:33], v[122:123], 0 op_sel_hi:[0,1,0] neg_lo:[1,0,0] neg_hi:[1,0,0]
	v_add_u32_e32 v183, 0xae00, v69
	ds_read2_b32 v[120:121], v183 offset0:89 offset1:229
	s_waitcnt lgkmcnt(9)
; #define LAS __attribute__((address_space(3)))
; DI void gdn_prep_phase(const int tid, LAS unsigned char* lds, const P& p, int G, int c) {
;     ...
;           for (int kb = 0; kb < 8; ++kb) {
; #pragma unroll
;               for (int pp = 0; pp < 4; ++pp) { const int pr = 4 * kb + pp;
;                   f32x2 s = (f32x2){xs[2 * pr], xs[2 * pr + 1]};
; #pragma unroll
;                   for (int j = 8 * kb; j < 2 * pr; j += 2) { const f32x4 l = *(const LAS f32x4*)(Ls + pr * 136 + j * 2);
;                       s -= (f32x2){l[0], l[1]} * (f32x2){xs[j], xs[j]}; s -= (f32x2){l[2], l[3]} * (f32x2){xs[j + 1], xs[j + 1]}; }
;                   xs[2 * pr] = s[0];
;                   xs[2 * pr + 1] = s[1] - Ls[pr * 136 + 4 * pr + 1] * s[0]; }
; #pragma unroll
;               for (int pr = 4 * kb + 4; pr < 32; ++pr) {
;                   f32x2 s0 = (f32x2){xs[2 * pr], xs[2 * pr + 1]}, s1 = (f32x2){0.f, 0.f};
; #pragma unroll
;                   for (int q = 0; q < 4; ++q) { const int j = 8 * kb + 2 * q; const f32x4 l = *(const LAS f32x4*)(Ls + pr * 136 + j * 2);
;                       s0 -= (f32x2){l[0], l[1]} * (f32x2){xs[j], xs[j]}; s1 -= (f32x2){l[2], l[3]} * (f32x2){xs[j + 1], xs[j + 1]}; }
;                   const f32x2 s = s0 + s1; xs[2 * pr] = s[0]; xs[2 * pr + 1] = s[1]; }
	v_pk_fma_f32 v[54:55], v[36:37], v[238:239], v[54:55] op_sel_hi:[0,1,1] neg_lo:[1,0,0] neg_hi:[1,0,0]
	v_pk_fma_f32 v[170:171], v[34:35], v[240:241], v[170:171] op_sel_hi:[0,1,1] neg_lo:[1,0,0] neg_hi:[1,0,0]
	ds_read_b128 v[238:241], v69 offset:45440
	s_waitcnt lgkmcnt(9)
	v_pk_fma_f32 v[54:55], v[42:43], v[136:137], v[54:55] op_sel_hi:[0,1,1] neg_lo:[1,0,0] neg_hi:[1,0,0]
	v_pk_fma_f32 v[170:171], v[38:39], v[138:139], v[170:171] op_sel_hi:[0,1,1] neg_lo:[1,0,0] neg_hi:[1,0,0]
	ds_read_b128 v[136:139], v69 offset:45952
	s_waitcnt lgkmcnt(9)
	v_pk_fma_f32 v[50:51], v[44:45], v[124:125], v[54:55] op_sel_hi:[0,1,1] neg_lo:[1,0,0] neg_hi:[1,0,0]
	v_pk_fma_f32 v[52:53], v[40:41], v[126:127], v[170:171] op_sel_hi:[0,1,1] neg_lo:[1,0,0] neg_hi:[1,0,0]
	ds_read_b128 v[124:127], v69 offset:45968
	v_pk_add_f32 v[194:195], v[50:51], v[52:53]
	s_waitcnt lgkmcnt(9)
	v_fma_f32 v50, -v46, v116, v47
	s_waitcnt lgkmcnt(8)
	v_pk_fma_f32 v[52:53], v[46:47], v[132:133], v[164:165] op_sel_hi:[0,1,1] neg_lo:[1,0,0] neg_hi:[1,0,0]
	s_waitcnt lgkmcnt(7)
	v_pk_fma_f32 v[164:165], v[46:47], v[128:129], v[168:169] op_sel_hi:[0,1,1] neg_lo:[1,0,0] neg_hi:[1,0,0]
	v_pk_fma_f32 v[164:165], v[130:131], v[50:51], v[164:165] op_sel_hi:[1,0,1] neg_lo:[1,0,0] neg_hi:[1,0,0]
	ds_read_b128 v[128:131], v69 offset:45984
	v_pk_fma_f32 v[54:55], v[134:135], v[50:51], v[52:53] op_sel_hi:[1,0,1] neg_lo:[1,0,0] neg_hi:[1,0,0]
	ds_read_b128 v[132:135], v69 offset:46000
	s_waitcnt lgkmcnt(8)
	v_pk_fma_f32 v[166:167], v[46:47], v[246:247], v[166:167] op_sel_hi:[0,1,1] neg_lo:[1,0,0] neg_hi:[1,0,0]
	v_pk_fma_f32 v[166:167], v[50:51], v[248:249], v[166:167] op_sel_hi:[0,1,1] neg_lo:[1,0,0] neg_hi:[1,0,0]
	ds_read_b128 v[246:249], v69 offset:46496
	v_fma_f32 v52, -v117, v54, v55
	ds_read_b128 v[116:119], v69 offset:46512
	s_waitcnt lgkmcnt(9)
	v_pk_fma_f32 v[164:165], v[112:113], v[54:55], v[164:165] op_sel_hi:[1,0,1] neg_lo:[1,0,0] neg_hi:[1,0,0]
	s_waitcnt lgkmcnt(8)
	v_pk_fma_f32 v[166:167], v[54:55], v[242:243], v[166:167] op_sel_hi:[0,1,1] neg_lo:[1,0,0] neg_hi:[1,0,0]
	v_pk_fma_f32 v[168:169], v[114:115], v[52:53], v[164:165] op_sel_hi:[1,0,1] neg_lo:[1,0,0] neg_hi:[1,0,0]
	ds_read_b128 v[112:115], v69 offset:46528
	v_pk_fma_f32 v[166:167], v[244:245], v[52:53], v[166:167] op_sel_hi:[1,0,1] neg_lo:[1,0,0] neg_hi:[1,0,0]
	ds_read_b128 v[242:245], v69 offset:46544
	s_waitcnt lgkmcnt(9)
	v_fma_f32 v164, -v120, v168, v169
	s_waitcnt lgkmcnt(8)
	v_pk_fma_f32 v[166:167], v[238:239], v[168:169], v[166:167] op_sel_hi:[1,0,1] neg_lo:[1,0,0] neg_hi:[1,0,0]
	s_nop 0
	v_pk_fma_f32 v[170:171], v[240:241], v[164:165], v[166:167] op_sel_hi:[1,0,1] neg_lo:[1,0,0] neg_hi:[1,0,0]
	ds_read_b128 v[238:241], v69 offset:47040
	v_fma_f32 v166, -v121, v170, v171
	ds_read_b128 v[120:123], v69 offset:47056
	s_waitcnt lgkmcnt(9)
	v_pk_fma_f32 v[172:173], v[46:47], v[136:137], v[172:173] op_sel_hi:[0,1,1] neg_lo:[1,0,0] neg_hi:[1,0,0]
	v_pk_fma_f32 v[204:205], v[50:51], v[138:139], 0 op_sel_hi:[0,1,0] neg_lo:[1,0,0] neg_hi:[1,0,0]
	ds_read_b128 v[136:139], v69 offset:47072
	s_waitcnt lgkmcnt(9)
	v_pk_fma_f32 v[172:173], v[54:55], v[124:125], v[172:173] op_sel_hi:[0,1,1] neg_lo:[1,0,0] neg_hi:[1,0,0]
	v_pk_fma_f32 v[204:205], v[52:53], v[126:127], v[204:205] op_sel_hi:[0,1,1] neg_lo:[1,0,0] neg_hi:[1,0,0]
	ds_read_b128 v[124:127], v69 offset:47088
	s_waitcnt lgkmcnt(9)
	v_pk_fma_f32 v[172:173], v[128:129], v[168:169], v[172:173] op_sel_hi:[1,0,1] neg_lo:[1,0,0] neg_hi:[1,0,0]
	v_pk_fma_f32 v[204:205], v[130:131], v[164:165], v[204:205] op_sel_hi:[1,0,1] neg_lo:[1,0,0] neg_hi:[1,0,0]
	ds_read_b128 v[128:131], v69 offset:47584
	s_waitcnt lgkmcnt(9)
	v_pk_fma_f32 v[172:173], v[132:133], v[170:171], v[172:173] op_sel_hi:[1,0,1] neg_lo:[1,0,0] neg_hi:[1,0,0]
	v_pk_fma_f32 v[200:201], v[134:135], v[166:167], v[204:205] op_sel_hi:[1,0,1] neg_lo:[1,0,0] neg_hi:[1,0,0]
	ds_read_b128 v[132:135], v69 offset:47600
	v_pk_add_f32 v[172:173], v[172:173], v[200:201]
	s_waitcnt lgkmcnt(9)
	v_pk_fma_f32 v[174:175], v[46:47], v[246:247], v[174:175] op_sel_hi:[0,1,1] neg_lo:[1,0,0] neg_hi:[1,0,0]
	v_pk_fma_f32 v[204:205], v[50:51], v[248:249], 0 op_sel_hi:[0,1,0] neg_lo:[1,0,0] neg_hi:[1,0,0]
	ds_read_b128 v[246:249], v69 offset:47616
	s_waitcnt lgkmcnt(9)
	v_pk_fma_f32 v[174:175], v[54:55], v[116:117], v[174:175] op_sel_hi:[0,1,1] neg_lo:[1,0,0] neg_hi:[1,0,0]
	v_pk_fma_f32 v[204:205], v[52:53], v[118:119], v[204:205] op_sel_hi:[0,1,1] neg_lo:[1,0,0] neg_hi:[1,0,0]
	ds_read_b128 v[116:119], v69 offset:47632
	s_waitcnt lgkmcnt(9)
	v_pk_fma_f32 v[174:175], v[168:169], v[112:113], v[174:175] op_sel_hi:[0,1,1] neg_lo:[1,0,0] neg_hi:[1,0,0]
	v_pk_fma_f32 v[204:205], v[114:115], v[164:165], v[204:205] op_sel_hi:[1,0,1] neg_lo:[1,0,0] neg_hi:[1,0,0]
	ds_read_b128 v[112:115], v69 offset:48128
	s_waitcnt lgkmcnt(9)
	v_pk_fma_f32 v[174:175], v[242:243], v[170:171], v[174:175] op_sel_hi:[1,0,1] neg_lo:[1,0,0] neg_hi:[1,0,0]
	v_pk_fma_f32 v[200:201], v[244:245], v[166:167], v[204:205] op_sel_hi:[1,0,1] neg_lo:[1,0,0] neg_hi:[1,0,0]
	ds_read_b128 v[242:245], v69 offset:48144
	v_pk_add_f32 v[206:207], v[174:175], v[200:201]
	s_waitcnt lgkmcnt(9)
	v_pk_fma_f32 v[174:175], v[46:47], v[238:239], v[188:189] op_sel_hi:[0,1,1] neg_lo:[1,0,0] neg_hi:[1,0,0]
	v_pk_fma_f32 v[188:189], v[50:51], v[240:241], 0 op_sel_hi:[0,1,0] neg_lo:[1,0,0] neg_hi:[1,0,0]
	ds_read_b128 v[238:241], v69 offset:48160
	s_waitcnt lgkmcnt(9)
	v_pk_fma_f32 v[174:175], v[54:55], v[120:121], v[174:175] op_sel_hi:[0,1,1] neg_lo:[1,0,0] neg_hi:[1,0,0]
	v_pk_fma_f32 v[188:189], v[52:53], v[122:123], v[188:189] op_sel_hi:[0,1,1] neg_lo:[1,0,0] neg_hi:[1,0,0]
	ds_read_b128 v[120:123], v69 offset:48176
	s_waitcnt lgkmcnt(9)
; #define LAS __attribute__((address_space(3)))
; DI void gdn_prep_phase(const int tid, LAS unsigned char* lds, const P& p, int G, int c) {
;     ...
;               for (int pr = 4 * kb + 4; pr < 32; ++pr) {
;                   f32x2 s0 = (f32x2){xs[2 * pr], xs[2 * pr + 1]}, s1 = (f32x2){0.f, 0.f};
; #pragma unroll
;                   for (int q = 0; q < 4; ++q) { const int j = 8 * kb + 2 * q; const f32x4 l = *(const LAS f32x4*)(Ls + pr * 136 + j * 2);
;                       s0 -= (f32x2){l[0], l[1]} * (f32x2){xs[j], xs[j]}; s1 -= (f32x2){l[2], l[3]} * (f32x2){xs[j + 1], xs[j + 1]}; }
;                   const f32x2 s = s0 + s1; xs[2 * pr] = s[0]; xs[2 * pr + 1] = s[1]; }
	v_pk_fma_f32 v[174:175], v[168:169], v[136:137], v[174:175] op_sel_hi:[0,1,1] neg_lo:[1,0,0] neg_hi:[1,0,0]
	v_pk_fma_f32 v[188:189], v[164:165], v[138:139], v[188:189] op_sel_hi:[0,1,1] neg_lo:[1,0,0] neg_hi:[1,0,0]
	ds_read_b128 v[136:139], v69 offset:48672
	s_waitcnt lgkmcnt(9)
	v_pk_fma_f32 v[174:175], v[170:171], v[124:125], v[174:175] op_sel_hi:[0,1,1] neg_lo:[1,0,0] neg_hi:[1,0,0]
	v_pk_fma_f32 v[188:189], v[126:127], v[166:167], v[188:189] op_sel_hi:[1,0,1] neg_lo:[1,0,0] neg_hi:[1,0,0]
	ds_read_b128 v[124:127], v69 offset:48688
	v_pk_add_f32 v[208:209], v[174:175], v[188:189]
	s_waitcnt lgkmcnt(9)
	v_pk_fma_f32 v[174:175], v[46:47], v[128:129], v[190:191] op_sel_hi:[0,1,1] neg_lo:[1,0,0] neg_hi:[1,0,0]
	v_pk_fma_f32 v[200:201], v[50:51], v[130:131], 0 op_sel_hi:[0,1,0] neg_lo:[1,0,0] neg_hi:[1,0,0]
	ds_read_b128 v[128:131], v69 offset:48704
	s_waitcnt lgkmcnt(9)
	v_pk_fma_f32 v[174:175], v[54:55], v[132:133], v[174:175] op_sel_hi:[0,1,1] neg_lo:[1,0,0] neg_hi:[1,0,0]
	v_pk_fma_f32 v[200:201], v[52:53], v[134:135], v[200:201] op_sel_hi:[0,1,1] neg_lo:[1,0,0] neg_hi:[1,0,0]
	ds_read_b128 v[132:135], v69 offset:48720
	s_waitcnt lgkmcnt(9)
	v_pk_fma_f32 v[174:175], v[168:169], v[246:247], v[174:175] op_sel_hi:[0,1,1] neg_lo:[1,0,0] neg_hi:[1,0,0]
	v_pk_fma_f32 v[200:201], v[164:165], v[248:249], v[200:201] op_sel_hi:[0,1,1] neg_lo:[1,0,0] neg_hi:[1,0,0]
	ds_read_b128 v[246:249], v69 offset:49216
	s_waitcnt lgkmcnt(9)
	v_pk_fma_f32 v[174:175], v[170:171], v[116:117], v[174:175] op_sel_hi:[0,1,1] neg_lo:[1,0,0] neg_hi:[1,0,0]
	v_pk_fma_f32 v[188:189], v[166:167], v[118:119], v[200:201] op_sel_hi:[0,1,1] neg_lo:[1,0,0] neg_hi:[1,0,0]
	ds_read_b128 v[116:119], v69 offset:49232
	v_pk_add_f32 v[188:189], v[174:175], v[188:189]
	s_waitcnt lgkmcnt(9)
	v_pk_fma_f32 v[190:191], v[46:47], v[112:113], v[176:177] op_sel_hi:[0,1,1] neg_lo:[1,0,0] neg_hi:[1,0,0]
	v_pk_fma_f32 v[200:201], v[50:51], v[114:115], 0 op_sel_hi:[0,1,0] neg_lo:[1,0,0] neg_hi:[1,0,0]
	ds_read_b128 v[112:115], v69 offset:49248
	s_waitcnt lgkmcnt(9)
	v_pk_fma_f32 v[190:191], v[54:55], v[242:243], v[190:191] op_sel_hi:[0,1,1] neg_lo:[1,0,0] neg_hi:[1,0,0]
	v_pk_fma_f32 v[200:201], v[52:53], v[244:245], v[200:201] op_sel_hi:[0,1,1] neg_lo:[1,0,0] neg_hi:[1,0,0]
	ds_read_b128 v[242:245], v69 offset:49264
	s_waitcnt lgkmcnt(9)
	v_pk_fma_f32 v[190:191], v[168:169], v[238:239], v[190:191] op_sel_hi:[0,1,1] neg_lo:[1,0,0] neg_hi:[1,0,0]
	v_pk_fma_f32 v[200:201], v[164:165], v[240:241], v[200:201] op_sel_hi:[0,1,1] neg_lo:[1,0,0] neg_hi:[1,0,0]
	ds_read_b128 v[238:241], v69 offset:49760
	s_waitcnt lgkmcnt(9)
	v_pk_fma_f32 v[174:175], v[170:171], v[120:121], v[190:191] op_sel_hi:[0,1,1] neg_lo:[1,0,0] neg_hi:[1,0,0]
	v_pk_fma_f32 v[176:177], v[166:167], v[122:123], v[200:201] op_sel_hi:[0,1,1] neg_lo:[1,0,0] neg_hi:[1,0,0]
	ds_read_b128 v[120:123], v69 offset:49776
	v_pk_add_f32 v[190:191], v[174:175], v[176:177]
	s_waitcnt lgkmcnt(9)
	v_pk_fma_f32 v[178:179], v[46:47], v[136:137], v[178:179] op_sel_hi:[0,1,1] neg_lo:[1,0,0] neg_hi:[1,0,0]
	v_pk_fma_f32 v[200:201], v[50:51], v[138:139], 0 op_sel_hi:[0,1,0] neg_lo:[1,0,0] neg_hi:[1,0,0]
	ds_read_b128 v[136:139], v69 offset:49792
	s_waitcnt lgkmcnt(9)
	v_pk_fma_f32 v[178:179], v[54:55], v[124:125], v[178:179] op_sel_hi:[0,1,1] neg_lo:[1,0,0] neg_hi:[1,0,0]
	v_pk_fma_f32 v[200:201], v[52:53], v[126:127], v[200:201] op_sel_hi:[0,1,1] neg_lo:[1,0,0] neg_hi:[1,0,0]
	ds_read_b128 v[124:127], v69 offset:49808
	s_waitcnt lgkmcnt(9)
	v_pk_fma_f32 v[178:179], v[168:169], v[128:129], v[178:179] op_sel_hi:[0,1,1] neg_lo:[1,0,0] neg_hi:[1,0,0]
	v_pk_fma_f32 v[200:201], v[164:165], v[130:131], v[200:201] op_sel_hi:[0,1,1] neg_lo:[1,0,0] neg_hi:[1,0,0]
	ds_read_b128 v[128:131], v69 offset:50304
	s_waitcnt lgkmcnt(9)
	v_pk_fma_f32 v[174:175], v[170:171], v[132:133], v[178:179] op_sel_hi:[0,1,1] neg_lo:[1,0,0] neg_hi:[1,0,0]
	v_pk_fma_f32 v[176:177], v[166:167], v[134:135], v[200:201] op_sel_hi:[0,1,1] neg_lo:[1,0,0] neg_hi:[1,0,0]
	ds_read_b128 v[132:135], v69 offset:50320
	v_pk_add_f32 v[200:201], v[174:175], v[176:177]
	s_waitcnt lgkmcnt(9)
	v_pk_fma_f32 v[178:179], v[46:47], v[246:247], v[184:185] op_sel_hi:[0,1,1] neg_lo:[1,0,0] neg_hi:[1,0,0]
	v_pk_fma_f32 v[184:185], v[50:51], v[248:249], 0 op_sel_hi:[0,1,0] neg_lo:[1,0,0] neg_hi:[1,0,0]
	ds_read_b128 v[246:249], v69 offset:50336
	s_waitcnt lgkmcnt(9)
	v_pk_fma_f32 v[178:179], v[54:55], v[116:117], v[178:179] op_sel_hi:[0,1,1] neg_lo:[1,0,0] neg_hi:[1,0,0]
	v_pk_fma_f32 v[184:185], v[52:53], v[118:119], v[184:185] op_sel_hi:[0,1,1] neg_lo:[1,0,0] neg_hi:[1,0,0]
	ds_read_b128 v[116:119], v69 offset:50352
	s_waitcnt lgkmcnt(9)
	v_pk_fma_f32 v[178:179], v[168:169], v[112:113], v[178:179] op_sel_hi:[0,1,1] neg_lo:[1,0,0] neg_hi:[1,0,0]
	v_pk_fma_f32 v[184:185], v[164:165], v[114:115], v[184:185] op_sel_hi:[0,1,1] neg_lo:[1,0,0] neg_hi:[1,0,0]
	ds_read_b128 v[112:115], v69 offset:50848
	s_waitcnt lgkmcnt(9)
	v_pk_fma_f32 v[174:175], v[170:171], v[242:243], v[178:179] op_sel_hi:[0,1,1] neg_lo:[1,0,0] neg_hi:[1,0,0]
	v_pk_fma_f32 v[176:177], v[166:167], v[244:245], v[184:185] op_sel_hi:[0,1,1] neg_lo:[1,0,0] neg_hi:[1,0,0]
	ds_read_b128 v[242:245], v69 offset:50864
	v_pk_add_f32 v[202:203], v[174:175], v[176:177]
	s_waitcnt lgkmcnt(9)
	v_pk_fma_f32 v[178:179], v[46:47], v[238:239], v[186:187] op_sel_hi:[0,1,1] neg_lo:[1,0,0] neg_hi:[1,0,0]
	v_pk_fma_f32 v[184:185], v[50:51], v[240:241], 0 op_sel_hi:[0,1,0] neg_lo:[1,0,0] neg_hi:[1,0,0]
	ds_read_b128 v[238:241], v69 offset:50880
	s_waitcnt lgkmcnt(9)
; #define LAS __attribute__((address_space(3)))
; DI void gdn_prep_phase(const int tid, LAS unsigned char* lds, const P& p, int G, int c) {
;     ...
;                   xs[2 * pr + 1] = s[1] - Ls[pr * 136 + 4 * pr + 1] * s[0]; }
; #pragma unroll
;               for (int pr = 4 * kb + 4; pr < 32; ++pr) {
;                   f32x2 s0 = (f32x2){xs[2 * pr], xs[2 * pr + 1]}, s1 = (f32x2){0.f, 0.f};
; #pragma unroll
;                   for (int q = 0; q < 4; ++q) { const int j = 8 * kb + 2 * q; const f32x4 l = *(const LAS f32x4*)(Ls + pr * 136 + j * 2);
;                       s0 -= (f32x2){l[0], l[1]} * (f32x2){xs[j], xs[j]}; s1 -= (f32x2){l[2], l[3]} * (f32x2){xs[j + 1], xs[j + 1]}; }
;                   const f32x2 s = s0 + s1; xs[2 * pr] = s[0]; xs[2 * pr + 1] = s[1]; }
	v_pk_fma_f32 v[178:179], v[54:55], v[120:121], v[178:179] op_sel_hi:[0,1,1] neg_lo:[1,0,0] neg_hi:[1,0,0]
	v_pk_fma_f32 v[184:185], v[52:53], v[122:123], v[184:185] op_sel_hi:[0,1,1] neg_lo:[1,0,0] neg_hi:[1,0,0]
	ds_read_b128 v[120:123], v69 offset:50896
	s_waitcnt lgkmcnt(9)
	v_pk_fma_f32 v[178:179], v[168:169], v[136:137], v[178:179] op_sel_hi:[0,1,1] neg_lo:[1,0,0] neg_hi:[1,0,0]
	v_pk_fma_f32 v[184:185], v[164:165], v[138:139], v[184:185] op_sel_hi:[0,1,1] neg_lo:[1,0,0] neg_hi:[1,0,0]
	ds_read_b128 v[136:139], v69 offset:51392
	s_waitcnt lgkmcnt(9)
	v_pk_fma_f32 v[174:175], v[170:171], v[124:125], v[178:179] op_sel_hi:[0,1,1] neg_lo:[1,0,0] neg_hi:[1,0,0]
	v_pk_fma_f32 v[176:177], v[166:167], v[126:127], v[184:185] op_sel_hi:[0,1,1] neg_lo:[1,0,0] neg_hi:[1,0,0]
	ds_read_b128 v[124:127], v69 offset:51408
	v_pk_add_f32 v[204:205], v[174:175], v[176:177]
	s_waitcnt lgkmcnt(9)
	v_pk_fma_f32 v[178:179], v[46:47], v[128:129], v[196:197] op_sel_hi:[0,1,1] neg_lo:[1,0,0] neg_hi:[1,0,0]
	v_pk_fma_f32 v[184:185], v[50:51], v[130:131], 0 op_sel_hi:[0,1,0] neg_lo:[1,0,0] neg_hi:[1,0,0]
	ds_read_b128 v[128:131], v69 offset:51424
	s_waitcnt lgkmcnt(9)
	v_pk_fma_f32 v[178:179], v[54:55], v[132:133], v[178:179] op_sel_hi:[0,1,1] neg_lo:[1,0,0] neg_hi:[1,0,0]
	v_pk_fma_f32 v[184:185], v[52:53], v[134:135], v[184:185] op_sel_hi:[0,1,1] neg_lo:[1,0,0] neg_hi:[1,0,0]
	ds_read_b128 v[132:135], v69 offset:51440
	s_waitcnt lgkmcnt(9)
	v_pk_fma_f32 v[178:179], v[168:169], v[246:247], v[178:179] op_sel_hi:[0,1,1] neg_lo:[1,0,0] neg_hi:[1,0,0]
	v_pk_fma_f32 v[184:185], v[164:165], v[248:249], v[184:185] op_sel_hi:[0,1,1] neg_lo:[1,0,0] neg_hi:[1,0,0]
	ds_read_b128 v[246:249], v69 offset:51936
	s_waitcnt lgkmcnt(9)
	v_pk_fma_f32 v[174:175], v[170:171], v[116:117], v[178:179] op_sel_hi:[0,1,1] neg_lo:[1,0,0] neg_hi:[1,0,0]
	v_pk_fma_f32 v[176:177], v[166:167], v[118:119], v[184:185] op_sel_hi:[0,1,1] neg_lo:[1,0,0] neg_hi:[1,0,0]
	ds_read_b128 v[116:119], v69 offset:51952
	v_pk_add_f32 v[196:197], v[174:175], v[176:177]
	s_waitcnt lgkmcnt(9)
	v_pk_fma_f32 v[178:179], v[46:47], v[112:113], v[198:199] op_sel_hi:[0,1,1] neg_lo:[1,0,0] neg_hi:[1,0,0]
	v_pk_fma_f32 v[184:185], v[50:51], v[114:115], 0 op_sel_hi:[0,1,0] neg_lo:[1,0,0] neg_hi:[1,0,0]
	ds_read_b128 v[112:115], v69 offset:51968
	s_waitcnt lgkmcnt(9)
	v_pk_fma_f32 v[178:179], v[54:55], v[242:243], v[178:179] op_sel_hi:[0,1,1] neg_lo:[1,0,0] neg_hi:[1,0,0]
	v_pk_fma_f32 v[184:185], v[52:53], v[244:245], v[184:185] op_sel_hi:[0,1,1] neg_lo:[1,0,0] neg_hi:[1,0,0]
	ds_read_b128 v[242:245], v69 offset:51984
	s_waitcnt lgkmcnt(9)
	v_pk_fma_f32 v[178:179], v[168:169], v[238:239], v[178:179] op_sel_hi:[0,1,1] neg_lo:[1,0,0] neg_hi:[1,0,0]
	v_pk_fma_f32 v[184:185], v[164:165], v[240:241], v[184:185] op_sel_hi:[0,1,1] neg_lo:[1,0,0] neg_hi:[1,0,0]
	v_add_u32_e32 v232, 0xb200, v69
	ds_read2_b32 v[238:239], v232 offset0:113 offset1:253
	s_waitcnt lgkmcnt(9)
	v_pk_fma_f32 v[174:175], v[170:171], v[120:121], v[178:179] op_sel_hi:[0,1,1] neg_lo:[1,0,0] neg_hi:[1,0,0]
	v_pk_fma_f32 v[176:177], v[166:167], v[122:123], v[184:185] op_sel_hi:[0,1,1] neg_lo:[1,0,0] neg_hi:[1,0,0]
	ds_read_b128 v[120:123], v69 offset:46560
	v_pk_add_f32 v[198:199], v[174:175], v[176:177]
	s_waitcnt lgkmcnt(9)
	v_pk_fma_f32 v[178:179], v[46:47], v[136:137], v[192:193] op_sel_hi:[0,1,1] neg_lo:[1,0,0] neg_hi:[1,0,0]
	v_pk_fma_f32 v[184:185], v[50:51], v[138:139], 0 op_sel_hi:[0,1,0] neg_lo:[1,0,0] neg_hi:[1,0,0]
	ds_read_b128 v[136:139], v69 offset:47104
	s_waitcnt lgkmcnt(9)
	v_pk_fma_f32 v[178:179], v[54:55], v[124:125], v[178:179] op_sel_hi:[0,1,1] neg_lo:[1,0,0] neg_hi:[1,0,0]
	v_pk_fma_f32 v[184:185], v[52:53], v[126:127], v[184:185] op_sel_hi:[0,1,1] neg_lo:[1,0,0] neg_hi:[1,0,0]
	ds_read_b128 v[124:127], v69 offset:47120
	s_waitcnt lgkmcnt(9)
	v_pk_fma_f32 v[178:179], v[168:169], v[128:129], v[178:179] op_sel_hi:[0,1,1] neg_lo:[1,0,0] neg_hi:[1,0,0]
	v_pk_fma_f32 v[184:185], v[164:165], v[130:131], v[184:185] op_sel_hi:[0,1,1] neg_lo:[1,0,0] neg_hi:[1,0,0]
	ds_read_b128 v[128:131], v69 offset:47648
	s_waitcnt lgkmcnt(9)
	v_pk_fma_f32 v[174:175], v[170:171], v[132:133], v[178:179] op_sel_hi:[0,1,1] neg_lo:[1,0,0] neg_hi:[1,0,0]
	v_pk_fma_f32 v[176:177], v[166:167], v[134:135], v[184:185] op_sel_hi:[0,1,1] neg_lo:[1,0,0] neg_hi:[1,0,0]
	v_add_u32_e32 v233, 0xb800, v69
	ds_read2_b32 v[132:133], v233 offset0:9 offset1:149
	v_pk_add_f32 v[192:193], v[174:175], v[176:177]
	s_waitcnt lgkmcnt(9)
	v_pk_fma_f32 v[178:179], v[46:47], v[246:247], v[194:195] op_sel_hi:[0,1,1] neg_lo:[1,0,0] neg_hi:[1,0,0]
	v_pk_fma_f32 v[184:185], v[50:51], v[248:249], 0 op_sel_hi:[0,1,0] neg_lo:[1,0,0] neg_hi:[1,0,0]
	ds_read_b128 v[246:249], v69 offset:47664
	s_waitcnt lgkmcnt(9)
	v_pk_fma_f32 v[178:179], v[54:55], v[116:117], v[178:179] op_sel_hi:[0,1,1] neg_lo:[1,0,0] neg_hi:[1,0,0]
	v_pk_fma_f32 v[184:185], v[52:53], v[118:119], v[184:185] op_sel_hi:[0,1,1] neg_lo:[1,0,0] neg_hi:[1,0,0]
	ds_read_b128 v[116:119], v69 offset:47680
	s_waitcnt lgkmcnt(9)
	v_pk_fma_f32 v[178:179], v[168:169], v[112:113], v[178:179] op_sel_hi:[0,1,1] neg_lo:[1,0,0] neg_hi:[1,0,0]
	v_pk_fma_f32 v[184:185], v[164:165], v[114:115], v[184:185] op_sel_hi:[0,1,1] neg_lo:[1,0,0] neg_hi:[1,0,0]
	ds_read_b128 v[112:115], v69 offset:48192
	s_waitcnt lgkmcnt(9)
	v_pk_fma_f32 v[174:175], v[170:171], v[242:243], v[178:179] op_sel_hi:[0,1,1] neg_lo:[1,0,0] neg_hi:[1,0,0]
	v_pk_fma_f32 v[176:177], v[166:167], v[244:245], v[184:185] op_sel_hi:[0,1,1] neg_lo:[1,0,0] neg_hi:[1,0,0]
	ds_read_b128 v[242:245], v69 offset:48208
	v_pk_add_f32 v[194:195], v[174:175], v[176:177]
	s_waitcnt lgkmcnt(9)
; #define LAS __attribute__((address_space(3)))
; DI void gdn_prep_phase(const int tid, LAS unsigned char* lds, const P& p, int G, int c) {
;     ...
;           for (int kb = 0; kb < 8; ++kb) {
; #pragma unroll
;               for (int pp = 0; pp < 4; ++pp) { const int pr = 4 * kb + pp;
;                   f32x2 s = (f32x2){xs[2 * pr], xs[2 * pr + 1]};
; #pragma unroll
;                   for (int j = 8 * kb; j < 2 * pr; j += 2) { const f32x4 l = *(const LAS f32x4*)(Ls + pr * 136 + j * 2);
;                       s -= (f32x2){l[0], l[1]} * (f32x2){xs[j], xs[j]}; s -= (f32x2){l[2], l[3]} * (f32x2){xs[j + 1], xs[j + 1]}; }
;                   xs[2 * pr] = s[0];
;                   xs[2 * pr + 1] = s[1] - Ls[pr * 136 + 4 * pr + 1] * s[0]; }
; #pragma unroll
;               for (int pr = 4 * kb + 4; pr < 32; ++pr) {
;                   f32x2 s0 = (f32x2){xs[2 * pr], xs[2 * pr + 1]}, s1 = (f32x2){0.f, 0.f};
; #pragma unroll
;                   for (int q = 0; q < 4; ++q) { const int j = 8 * kb + 2 * q; const f32x4 l = *(const LAS f32x4*)(Ls + pr * 136 + j * 2);
;                       s0 -= (f32x2){l[0], l[1]} * (f32x2){xs[j], xs[j]}; s1 -= (f32x2){l[2], l[3]} * (f32x2){xs[j + 1], xs[j + 1]}; }
;                   const f32x2 s = s0 + s1; xs[2 * pr] = s[0]; xs[2 * pr + 1] = s[1]; }
	v_fma_f32 v174, -v172, v238, v173
	s_waitcnt lgkmcnt(8)
	v_pk_fma_f32 v[176:177], v[172:173], v[120:121], v[206:207] op_sel_hi:[0,1,1] neg_lo:[1,0,0] neg_hi:[1,0,0]
	s_waitcnt lgkmcnt(7)
	v_pk_fma_f32 v[184:185], v[172:173], v[136:137], v[208:209] op_sel_hi:[0,1,1] neg_lo:[1,0,0] neg_hi:[1,0,0]
	v_pk_fma_f32 v[206:207], v[138:139], v[174:175], v[184:185] op_sel_hi:[1,0,1] neg_lo:[1,0,0] neg_hi:[1,0,0]
	ds_read_b128 v[136:139], v69 offset:48224
	v_pk_fma_f32 v[178:179], v[122:123], v[174:175], v[176:177] op_sel_hi:[1,0,1] neg_lo:[1,0,0] neg_hi:[1,0,0]
	ds_read_b128 v[120:123], v69 offset:48240
	v_fma_f32 v176, -v239, v178, v179
	ds_read_b128 v[238:241], v69 offset:48736
	s_waitcnt lgkmcnt(9)
	v_pk_fma_f32 v[184:185], v[124:125], v[178:179], v[206:207] op_sel_hi:[1,0,1] neg_lo:[1,0,0] neg_hi:[1,0,0]
	s_nop 0
	v_pk_fma_f32 v[186:187], v[126:127], v[176:177], v[184:185] op_sel_hi:[1,0,1] neg_lo:[1,0,0] neg_hi:[1,0,0]
	ds_read_b128 v[124:127], v69 offset:48752
	s_waitcnt lgkmcnt(9)
	v_pk_fma_f32 v[188:189], v[172:173], v[128:129], v[188:189] op_sel_hi:[0,1,1] neg_lo:[1,0,0] neg_hi:[1,0,0]
	v_pk_fma_f32 v[188:189], v[174:175], v[130:131], v[188:189] op_sel_hi:[0,1,1] neg_lo:[1,0,0] neg_hi:[1,0,0]
	ds_read_b128 v[128:131], v69 offset:48768
	s_waitcnt lgkmcnt(9)
	v_fma_f32 v180, -v132, v186, v187
	s_waitcnt lgkmcnt(8)
	v_pk_fma_f32 v[188:189], v[178:179], v[246:247], v[188:189] op_sel_hi:[0,1,1] neg_lo:[1,0,0] neg_hi:[1,0,0]
	v_pk_fma_f32 v[188:189], v[248:249], v[176:177], v[188:189] op_sel_hi:[1,0,1] neg_lo:[1,0,0] neg_hi:[1,0,0]
	ds_read_b128 v[246:249], v69 offset:48784
	s_waitcnt lgkmcnt(8)
	v_pk_fma_f32 v[188:189], v[116:117], v[186:187], v[188:189] op_sel_hi:[1,0,1] neg_lo:[1,0,0] neg_hi:[1,0,0]
	s_nop 0
	v_pk_fma_f32 v[188:189], v[118:119], v[180:181], v[188:189] op_sel_hi:[1,0,1] neg_lo:[1,0,0] neg_hi:[1,0,0]
	ds_read_b128 v[116:119], v69 offset:49280
	v_fma_f32 v184, -v133, v188, v189
	ds_read_b128 v[132:135], v69 offset:49296
	s_waitcnt lgkmcnt(9)
	v_pk_fma_f32 v[190:191], v[172:173], v[112:113], v[190:191] op_sel_hi:[0,1,1] neg_lo:[1,0,0] neg_hi:[1,0,0]
	v_pk_fma_f32 v[210:211], v[174:175], v[114:115], 0 op_sel_hi:[0,1,0] neg_lo:[1,0,0] neg_hi:[1,0,0]
	ds_read_b128 v[112:115], v69 offset:49312
	s_waitcnt lgkmcnt(9)
	v_pk_fma_f32 v[190:191], v[178:179], v[242:243], v[190:191] op_sel_hi:[0,1,1] neg_lo:[1,0,0] neg_hi:[1,0,0]
	v_pk_fma_f32 v[210:211], v[176:177], v[244:245], v[210:211] op_sel_hi:[0,1,1] neg_lo:[1,0,0] neg_hi:[1,0,0]
	ds_read_b128 v[242:245], v69 offset:49328
	s_waitcnt lgkmcnt(9)
	v_pk_fma_f32 v[190:191], v[136:137], v[186:187], v[190:191] op_sel_hi:[1,0,1] neg_lo:[1,0,0] neg_hi:[1,0,0]
	v_pk_fma_f32 v[210:211], v[138:139], v[180:181], v[210:211] op_sel_hi:[1,0,1] neg_lo:[1,0,0] neg_hi:[1,0,0]
	ds_read_b128 v[136:139], v69 offset:49824
	s_waitcnt lgkmcnt(9)
	v_pk_fma_f32 v[190:191], v[120:121], v[188:189], v[190:191] op_sel_hi:[1,0,1] neg_lo:[1,0,0] neg_hi:[1,0,0]
	v_pk_fma_f32 v[206:207], v[122:123], v[184:185], v[210:211] op_sel_hi:[1,0,1] neg_lo:[1,0,0] neg_hi:[1,0,0]
	ds_read_b128 v[120:123], v69 offset:49840
	v_pk_add_f32 v[190:191], v[190:191], v[206:207]
	s_waitcnt lgkmcnt(9)
	v_pk_fma_f32 v[200:201], v[172:173], v[238:239], v[200:201] op_sel_hi:[0,1,1] neg_lo:[1,0,0] neg_hi:[1,0,0]
	v_pk_fma_f32 v[210:211], v[174:175], v[240:241], 0 op_sel_hi:[0,1,0] neg_lo:[1,0,0] neg_hi:[1,0,0]
	ds_read_b128 v[238:241], v69 offset:49856
	s_waitcnt lgkmcnt(9)
	v_pk_fma_f32 v[200:201], v[178:179], v[124:125], v[200:201] op_sel_hi:[0,1,1] neg_lo:[1,0,0] neg_hi:[1,0,0]
	v_pk_fma_f32 v[210:211], v[176:177], v[126:127], v[210:211] op_sel_hi:[0,1,1] neg_lo:[1,0,0] neg_hi:[1,0,0]
	ds_read_b128 v[124:127], v69 offset:49872
	s_waitcnt lgkmcnt(9)
	v_pk_fma_f32 v[200:201], v[186:187], v[128:129], v[200:201] op_sel_hi:[0,1,1] neg_lo:[1,0,0] neg_hi:[1,0,0]
	v_pk_fma_f32 v[210:211], v[130:131], v[180:181], v[210:211] op_sel_hi:[1,0,1] neg_lo:[1,0,0] neg_hi:[1,0,0]
	ds_read_b128 v[128:131], v69 offset:50368
	s_waitcnt lgkmcnt(9)
	v_pk_fma_f32 v[200:201], v[246:247], v[188:189], v[200:201] op_sel_hi:[1,0,1] neg_lo:[1,0,0] neg_hi:[1,0,0]
	v_pk_fma_f32 v[206:207], v[248:249], v[184:185], v[210:211] op_sel_hi:[1,0,1] neg_lo:[1,0,0] neg_hi:[1,0,0]
	ds_read_b128 v[246:249], v69 offset:50384
	v_pk_add_f32 v[214:215], v[200:201], v[206:207]
	s_waitcnt lgkmcnt(9)
	v_pk_fma_f32 v[206:207], v[172:173], v[116:117], v[202:203] op_sel_hi:[0,1,1] neg_lo:[1,0,0] neg_hi:[1,0,0]
	v_pk_fma_f32 v[208:209], v[174:175], v[118:119], 0 op_sel_hi:[0,1,0] neg_lo:[1,0,0] neg_hi:[1,0,0]
	ds_read_b128 v[116:119], v69 offset:50400
	s_waitcnt lgkmcnt(9)
	v_pk_fma_f32 v[206:207], v[178:179], v[132:133], v[206:207] op_sel_hi:[0,1,1] neg_lo:[1,0,0] neg_hi:[1,0,0]
	v_pk_fma_f32 v[208:209], v[176:177], v[134:135], v[208:209] op_sel_hi:[0,1,1] neg_lo:[1,0,0] neg_hi:[1,0,0]
	ds_read_b128 v[132:135], v69 offset:50416
	s_waitcnt lgkmcnt(9)
	v_pk_fma_f32 v[206:207], v[186:187], v[112:113], v[206:207] op_sel_hi:[0,1,1] neg_lo:[1,0,0] neg_hi:[1,0,0]
	v_pk_fma_f32 v[208:209], v[180:181], v[114:115], v[208:209] op_sel_hi:[0,1,1] neg_lo:[1,0,0] neg_hi:[1,0,0]
	ds_read_b128 v[112:115], v69 offset:50912
	s_waitcnt lgkmcnt(9)
	v_pk_fma_f32 v[200:201], v[188:189], v[242:243], v[206:207] op_sel_hi:[0,1,1] neg_lo:[1,0,0] neg_hi:[1,0,0]
	v_pk_fma_f32 v[202:203], v[244:245], v[184:185], v[208:209] op_sel_hi:[1,0,1] neg_lo:[1,0,0] neg_hi:[1,0,0]
	ds_read_b128 v[242:245], v69 offset:50928
	v_pk_add_f32 v[202:203], v[200:201], v[202:203]
	s_waitcnt lgkmcnt(9)
	v_pk_fma_f32 v[200:201], v[172:173], v[136:137], v[204:205] op_sel_hi:[0,1,1] neg_lo:[1,0,0] neg_hi:[1,0,0]
	v_pk_fma_f32 v[208:209], v[174:175], v[138:139], 0 op_sel_hi:[0,1,0] neg_lo:[1,0,0] neg_hi:[1,0,0]
	ds_read_b128 v[136:139], v69 offset:50944
	s_waitcnt lgkmcnt(9)
; #define LAS __attribute__((address_space(3)))
; DI void gdn_prep_phase(const int tid, LAS unsigned char* lds, const P& p, int G, int c) {
;     ...
;                   xs[2 * pr + 1] = s[1] - Ls[pr * 136 + 4 * pr + 1] * s[0]; }
; #pragma unroll
;               for (int pr = 4 * kb + 4; pr < 32; ++pr) {
;                   f32x2 s0 = (f32x2){xs[2 * pr], xs[2 * pr + 1]}, s1 = (f32x2){0.f, 0.f};
; #pragma unroll
;                   for (int q = 0; q < 4; ++q) { const int j = 8 * kb + 2 * q; const f32x4 l = *(const LAS f32x4*)(Ls + pr * 136 + j * 2);
;                       s0 -= (f32x2){l[0], l[1]} * (f32x2){xs[j], xs[j]}; s1 -= (f32x2){l[2], l[3]} * (f32x2){xs[j + 1], xs[j + 1]}; }
;                   const f32x2 s = s0 + s1; xs[2 * pr] = s[0]; xs[2 * pr + 1] = s[1]; }
	v_pk_fma_f32 v[200:201], v[178:179], v[120:121], v[200:201] op_sel_hi:[0,1,1] neg_lo:[1,0,0] neg_hi:[1,0,0]
	v_pk_fma_f32 v[208:209], v[176:177], v[122:123], v[208:209] op_sel_hi:[0,1,1] neg_lo:[1,0,0] neg_hi:[1,0,0]
	ds_read_b128 v[120:123], v69 offset:50960
	s_waitcnt lgkmcnt(9)
	v_pk_fma_f32 v[200:201], v[186:187], v[238:239], v[200:201] op_sel_hi:[0,1,1] neg_lo:[1,0,0] neg_hi:[1,0,0]
	v_pk_fma_f32 v[208:209], v[180:181], v[240:241], v[208:209] op_sel_hi:[0,1,1] neg_lo:[1,0,0] neg_hi:[1,0,0]
	ds_read_b128 v[238:241], v69 offset:51456
	s_waitcnt lgkmcnt(9)
	v_pk_fma_f32 v[200:201], v[188:189], v[124:125], v[200:201] op_sel_hi:[0,1,1] neg_lo:[1,0,0] neg_hi:[1,0,0]
	v_pk_fma_f32 v[204:205], v[184:185], v[126:127], v[208:209] op_sel_hi:[0,1,1] neg_lo:[1,0,0] neg_hi:[1,0,0]
	ds_read_b128 v[124:127], v69 offset:51472
	v_pk_add_f32 v[200:201], v[200:201], v[204:205]
	s_waitcnt lgkmcnt(9)
	v_pk_fma_f32 v[196:197], v[172:173], v[128:129], v[196:197] op_sel_hi:[0,1,1] neg_lo:[1,0,0] neg_hi:[1,0,0]
	v_pk_fma_f32 v[208:209], v[174:175], v[130:131], 0 op_sel_hi:[0,1,0] neg_lo:[1,0,0] neg_hi:[1,0,0]
	ds_read_b128 v[128:131], v69 offset:51488
	s_waitcnt lgkmcnt(9)
	v_pk_fma_f32 v[196:197], v[178:179], v[246:247], v[196:197] op_sel_hi:[0,1,1] neg_lo:[1,0,0] neg_hi:[1,0,0]
	v_pk_fma_f32 v[208:209], v[176:177], v[248:249], v[208:209] op_sel_hi:[0,1,1] neg_lo:[1,0,0] neg_hi:[1,0,0]
	ds_read_b128 v[246:249], v69 offset:51504
	s_waitcnt lgkmcnt(9)
	v_pk_fma_f32 v[196:197], v[186:187], v[116:117], v[196:197] op_sel_hi:[0,1,1] neg_lo:[1,0,0] neg_hi:[1,0,0]
	v_pk_fma_f32 v[208:209], v[180:181], v[118:119], v[208:209] op_sel_hi:[0,1,1] neg_lo:[1,0,0] neg_hi:[1,0,0]
	ds_read_b128 v[116:119], v69 offset:52000
	s_waitcnt lgkmcnt(9)
	v_pk_fma_f32 v[196:197], v[188:189], v[132:133], v[196:197] op_sel_hi:[0,1,1] neg_lo:[1,0,0] neg_hi:[1,0,0]
	v_pk_fma_f32 v[204:205], v[184:185], v[134:135], v[208:209] op_sel_hi:[0,1,1] neg_lo:[1,0,0] neg_hi:[1,0,0]
	ds_read_b128 v[132:135], v69 offset:52016
	v_pk_add_f32 v[206:207], v[196:197], v[204:205]
	s_waitcnt lgkmcnt(9)
	v_pk_fma_f32 v[204:205], v[172:173], v[112:113], v[198:199] op_sel_hi:[0,1,1] neg_lo:[1,0,0] neg_hi:[1,0,0]
	v_pk_fma_f32 v[208:209], v[174:175], v[114:115], 0 op_sel_hi:[0,1,0] neg_lo:[1,0,0] neg_hi:[1,0,0]
	ds_read_b128 v[112:115], v69 offset:52032
	s_waitcnt lgkmcnt(9)
	v_pk_fma_f32 v[204:205], v[178:179], v[242:243], v[204:205] op_sel_hi:[0,1,1] neg_lo:[1,0,0] neg_hi:[1,0,0]
	v_pk_fma_f32 v[208:209], v[176:177], v[244:245], v[208:209] op_sel_hi:[0,1,1] neg_lo:[1,0,0] neg_hi:[1,0,0]
	ds_read_b128 v[242:245], v69 offset:52048
	s_waitcnt lgkmcnt(9)
	v_pk_fma_f32 v[204:205], v[186:187], v[136:137], v[204:205] op_sel_hi:[0,1,1] neg_lo:[1,0,0] neg_hi:[1,0,0]
	v_pk_fma_f32 v[208:209], v[180:181], v[138:139], v[208:209] op_sel_hi:[0,1,1] neg_lo:[1,0,0] neg_hi:[1,0,0]
	ds_read_b128 v[136:139], v69 offset:48800
	s_waitcnt lgkmcnt(9)
	v_pk_fma_f32 v[196:197], v[188:189], v[120:121], v[204:205] op_sel_hi:[0,1,1] neg_lo:[1,0,0] neg_hi:[1,0,0]
	v_pk_fma_f32 v[198:199], v[184:185], v[122:123], v[208:209] op_sel_hi:[0,1,1] neg_lo:[1,0,0] neg_hi:[1,0,0]
	v_add_u32_e32 v141, 0xbc00, v69
	ds_read2_b32 v[120:121], v141 offset0:33 offset1:173
	v_pk_add_f32 v[208:209], v[196:197], v[198:199]
	s_waitcnt lgkmcnt(9)
	v_pk_fma_f32 v[192:193], v[172:173], v[238:239], v[192:193] op_sel_hi:[0,1,1] neg_lo:[1,0,0] neg_hi:[1,0,0]
	v_pk_fma_f32 v[204:205], v[174:175], v[240:241], 0 op_sel_hi:[0,1,0] neg_lo:[1,0,0] neg_hi:[1,0,0]
	ds_read_b128 v[238:241], v69 offset:49344
	s_waitcnt lgkmcnt(9)
	v_pk_fma_f32 v[192:193], v[178:179], v[124:125], v[192:193] op_sel_hi:[0,1,1] neg_lo:[1,0,0] neg_hi:[1,0,0]
	v_pk_fma_f32 v[204:205], v[176:177], v[126:127], v[204:205] op_sel_hi:[0,1,1] neg_lo:[1,0,0] neg_hi:[1,0,0]
	ds_read_b128 v[124:127], v69 offset:49360
	s_waitcnt lgkmcnt(9)
	v_pk_fma_f32 v[192:193], v[186:187], v[128:129], v[192:193] op_sel_hi:[0,1,1] neg_lo:[1,0,0] neg_hi:[1,0,0]
	v_pk_fma_f32 v[204:205], v[180:181], v[130:131], v[204:205] op_sel_hi:[0,1,1] neg_lo:[1,0,0] neg_hi:[1,0,0]
	ds_read_b128 v[128:131], v69 offset:49888
	s_waitcnt lgkmcnt(9)
	v_pk_fma_f32 v[192:193], v[188:189], v[246:247], v[192:193] op_sel_hi:[0,1,1] neg_lo:[1,0,0] neg_hi:[1,0,0]
	v_pk_fma_f32 v[196:197], v[184:185], v[248:249], v[204:205] op_sel_hi:[0,1,1] neg_lo:[1,0,0] neg_hi:[1,0,0]
	ds_read_b128 v[246:249], v69 offset:49904
	v_pk_add_f32 v[210:211], v[192:193], v[196:197]
	s_waitcnt lgkmcnt(9)
	v_pk_fma_f32 v[196:197], v[172:173], v[116:117], v[194:195] op_sel_hi:[0,1,1] neg_lo:[1,0,0] neg_hi:[1,0,0]
	v_pk_fma_f32 v[198:199], v[174:175], v[118:119], 0 op_sel_hi:[0,1,0] neg_lo:[1,0,0] neg_hi:[1,0,0]
	v_add_u32_e32 v183, 0xc000, v69
	ds_read2_b32 v[116:117], v183 offset0:57 offset1:197
	s_waitcnt lgkmcnt(9)
	v_pk_fma_f32 v[196:197], v[178:179], v[132:133], v[196:197] op_sel_hi:[0,1,1] neg_lo:[1,0,0] neg_hi:[1,0,0]
	v_pk_fma_f32 v[198:199], v[176:177], v[134:135], v[198:199] op_sel_hi:[0,1,1] neg_lo:[1,0,0] neg_hi:[1,0,0]
	ds_read_b128 v[132:135], v69 offset:49920
	s_waitcnt lgkmcnt(9)
	v_pk_fma_f32 v[196:197], v[186:187], v[112:113], v[196:197] op_sel_hi:[0,1,1] neg_lo:[1,0,0] neg_hi:[1,0,0]
	v_pk_fma_f32 v[198:199], v[180:181], v[114:115], v[198:199] op_sel_hi:[0,1,1] neg_lo:[1,0,0] neg_hi:[1,0,0]
	ds_read_b128 v[112:115], v69 offset:50432
	s_waitcnt lgkmcnt(9)
	v_pk_fma_f32 v[192:193], v[188:189], v[242:243], v[196:197] op_sel_hi:[0,1,1] neg_lo:[1,0,0] neg_hi:[1,0,0]
	v_pk_fma_f32 v[194:195], v[184:185], v[244:245], v[198:199] op_sel_hi:[0,1,1] neg_lo:[1,0,0] neg_hi:[1,0,0]
	ds_read_b128 v[242:245], v69 offset:50448
	v_pk_add_f32 v[212:213], v[192:193], v[194:195]
	s_waitcnt lgkmcnt(9)
; #define LAS __attribute__((address_space(3)))
; DI void gdn_prep_phase(const int tid, LAS unsigned char* lds, const P& p, int G, int c) {
;     ...
;           for (int kb = 0; kb < 8; ++kb) {
; #pragma unroll
;               for (int pp = 0; pp < 4; ++pp) { const int pr = 4 * kb + pp;
;                   f32x2 s = (f32x2){xs[2 * pr], xs[2 * pr + 1]};
; #pragma unroll
;                   for (int j = 8 * kb; j < 2 * pr; j += 2) { const f32x4 l = *(const LAS f32x4*)(Ls + pr * 136 + j * 2);
;                       s -= (f32x2){l[0], l[1]} * (f32x2){xs[j], xs[j]}; s -= (f32x2){l[2], l[3]} * (f32x2){xs[j + 1], xs[j + 1]}; }
;                   xs[2 * pr] = s[0];
;                   xs[2 * pr + 1] = s[1] - Ls[pr * 136 + 4 * pr + 1] * s[0]; }
; #pragma unroll
;               for (int pr = 4 * kb + 4; pr < 32; ++pr) {
;                   f32x2 s0 = (f32x2){xs[2 * pr], xs[2 * pr + 1]}, s1 = (f32x2){0.f, 0.f};
; #pragma unroll
;                   for (int q = 0; q < 4; ++q) { const int j = 8 * kb + 2 * q; const f32x4 l = *(const LAS f32x4*)(Ls + pr * 136 + j * 2);
;                       s0 -= (f32x2){l[0], l[1]} * (f32x2){xs[j], xs[j]}; s1 -= (f32x2){l[2], l[3]} * (f32x2){xs[j + 1], xs[j + 1]}; }
;                   const f32x2 s = s0 + s1; xs[2 * pr] = s[0]; xs[2 * pr + 1] = s[1]; }
	v_pk_fma_f32 v[194:195], v[190:191], v[136:137], v[214:215] op_sel_hi:[0,1,1] neg_lo:[1,0,0] neg_hi:[1,0,0]
	s_waitcnt lgkmcnt(8)
	v_fma_f32 v192, -v190, v120, v191
	v_pk_fma_f32 v[196:197], v[138:139], v[192:193], v[194:195] op_sel_hi:[1,0,1] neg_lo:[1,0,0] neg_hi:[1,0,0]
	ds_read_b128 v[136:139], v69 offset:50464
	s_waitcnt lgkmcnt(8)
	v_pk_fma_f32 v[198:199], v[190:191], v[238:239], v[202:203] op_sel_hi:[0,1,1] neg_lo:[1,0,0] neg_hi:[1,0,0]
	v_pk_fma_f32 v[198:199], v[240:241], v[192:193], v[198:199] op_sel_hi:[1,0,1] neg_lo:[1,0,0] neg_hi:[1,0,0]
	ds_read_b128 v[238:241], v69 offset:50480
	v_fma_f32 v194, -v121, v196, v197
	ds_read_b128 v[120:123], v69 offset:50976
	s_waitcnt lgkmcnt(9)
	v_pk_fma_f32 v[198:199], v[124:125], v[196:197], v[198:199] op_sel_hi:[1,0,1] neg_lo:[1,0,0] neg_hi:[1,0,0]
	s_waitcnt lgkmcnt(8)
	v_pk_fma_f32 v[200:201], v[190:191], v[128:129], v[200:201] op_sel_hi:[0,1,1] neg_lo:[1,0,0] neg_hi:[1,0,0]
	v_pk_fma_f32 v[200:201], v[192:193], v[130:131], v[200:201] op_sel_hi:[0,1,1] neg_lo:[1,0,0] neg_hi:[1,0,0]
	ds_read_b128 v[128:131], v69 offset:50992
	v_pk_fma_f32 v[202:203], v[126:127], v[194:195], v[198:199] op_sel_hi:[1,0,1] neg_lo:[1,0,0] neg_hi:[1,0,0]
	ds_read_b128 v[124:127], v69 offset:51008
	s_waitcnt lgkmcnt(9)
	v_pk_fma_f32 v[200:201], v[196:197], v[246:247], v[200:201] op_sel_hi:[0,1,1] neg_lo:[1,0,0] neg_hi:[1,0,0]
	v_pk_fma_f32 v[200:201], v[248:249], v[194:195], v[200:201] op_sel_hi:[1,0,1] neg_lo:[1,0,0] neg_hi:[1,0,0]
	ds_read_b128 v[246:249], v69 offset:51024
	s_waitcnt lgkmcnt(9)
	v_fma_f32 v198, -v116, v202, v203
	s_waitcnt lgkmcnt(8)
	v_pk_fma_f32 v[200:201], v[132:133], v[202:203], v[200:201] op_sel_hi:[1,0,1] neg_lo:[1,0,0] neg_hi:[1,0,0]
	s_nop 0
	v_pk_fma_f32 v[204:205], v[134:135], v[198:199], v[200:201] op_sel_hi:[1,0,1] neg_lo:[1,0,0] neg_hi:[1,0,0]
	ds_read_b128 v[132:135], v69 offset:51520
	v_fma_f32 v200, -v117, v204, v205
	ds_read_b128 v[116:119], v69 offset:51536
	s_waitcnt lgkmcnt(9)
	v_pk_fma_f32 v[206:207], v[190:191], v[112:113], v[206:207] op_sel_hi:[0,1,1] neg_lo:[1,0,0] neg_hi:[1,0,0]
	v_pk_fma_f32 v[218:219], v[192:193], v[114:115], 0 op_sel_hi:[0,1,0] neg_lo:[1,0,0] neg_hi:[1,0,0]
	ds_read_b128 v[112:115], v69 offset:51552
	s_waitcnt lgkmcnt(9)
	v_pk_fma_f32 v[206:207], v[196:197], v[242:243], v[206:207] op_sel_hi:[0,1,1] neg_lo:[1,0,0] neg_hi:[1,0,0]
	v_pk_fma_f32 v[218:219], v[194:195], v[244:245], v[218:219] op_sel_hi:[0,1,1] neg_lo:[1,0,0] neg_hi:[1,0,0]
	ds_read_b128 v[242:245], v69 offset:51568
	s_waitcnt lgkmcnt(9)
	v_pk_fma_f32 v[206:207], v[136:137], v[202:203], v[206:207] op_sel_hi:[1,0,1] neg_lo:[1,0,0] neg_hi:[1,0,0]
	v_pk_fma_f32 v[218:219], v[138:139], v[198:199], v[218:219] op_sel_hi:[1,0,1] neg_lo:[1,0,0] neg_hi:[1,0,0]
	ds_read_b128 v[136:139], v69 offset:52064
	s_waitcnt lgkmcnt(9)
	v_pk_fma_f32 v[206:207], v[238:239], v[204:205], v[206:207] op_sel_hi:[1,0,1] neg_lo:[1,0,0] neg_hi:[1,0,0]
	v_pk_fma_f32 v[214:215], v[240:241], v[200:201], v[218:219] op_sel_hi:[1,0,1] neg_lo:[1,0,0] neg_hi:[1,0,0]
	ds_read_b128 v[238:241], v69 offset:52080
	v_pk_add_f32 v[206:207], v[206:207], v[214:215]
	s_waitcnt lgkmcnt(9)
	v_pk_fma_f32 v[208:209], v[190:191], v[120:121], v[208:209] op_sel_hi:[0,1,1] neg_lo:[1,0,0] neg_hi:[1,0,0]
	v_pk_fma_f32 v[218:219], v[192:193], v[122:123], 0 op_sel_hi:[0,1,0] neg_lo:[1,0,0] neg_hi:[1,0,0]
	ds_read_b128 v[120:123], v69 offset:52096
	s_waitcnt lgkmcnt(9)
	v_pk_fma_f32 v[208:209], v[196:197], v[128:129], v[208:209] op_sel_hi:[0,1,1] neg_lo:[1,0,0] neg_hi:[1,0,0]
	v_pk_fma_f32 v[218:219], v[194:195], v[130:131], v[218:219] op_sel_hi:[0,1,1] neg_lo:[1,0,0] neg_hi:[1,0,0]
	ds_read_b128 v[128:131], v69 offset:52112
	s_waitcnt lgkmcnt(9)
	v_pk_fma_f32 v[208:209], v[202:203], v[124:125], v[208:209] op_sel_hi:[0,1,1] neg_lo:[1,0,0] neg_hi:[1,0,0]
	v_pk_fma_f32 v[218:219], v[126:127], v[198:199], v[218:219] op_sel_hi:[1,0,1] neg_lo:[1,0,0] neg_hi:[1,0,0]
	v_add_u32_e32 v232, 0xc400, v69
	ds_read2_b32 v[124:125], v232 offset0:81 offset1:221
	s_waitcnt lgkmcnt(9)
	v_pk_fma_f32 v[208:209], v[246:247], v[204:205], v[208:209] op_sel_hi:[1,0,1] neg_lo:[1,0,0] neg_hi:[1,0,0]
	v_pk_fma_f32 v[214:215], v[248:249], v[200:201], v[218:219] op_sel_hi:[1,0,1] neg_lo:[1,0,0] neg_hi:[1,0,0]
	ds_read_b128 v[246:249], v69 offset:51040
	v_pk_add_f32 v[214:215], v[208:209], v[214:215]
	s_waitcnt lgkmcnt(9)
	v_pk_fma_f32 v[216:217], v[190:191], v[132:133], v[210:211] op_sel_hi:[0,1,1] neg_lo:[1,0,0] neg_hi:[1,0,0]
	v_pk_fma_f32 v[218:219], v[192:193], v[134:135], 0 op_sel_hi:[0,1,0] neg_lo:[1,0,0] neg_hi:[1,0,0]
	ds_read_b128 v[132:135], v69 offset:51584
	s_waitcnt lgkmcnt(9)
	v_pk_fma_f32 v[216:217], v[196:197], v[116:117], v[216:217] op_sel_hi:[0,1,1] neg_lo:[1,0,0] neg_hi:[1,0,0]
	v_pk_fma_f32 v[218:219], v[194:195], v[118:119], v[218:219] op_sel_hi:[0,1,1] neg_lo:[1,0,0] neg_hi:[1,0,0]
	ds_read_b128 v[116:119], v69 offset:51600
	s_waitcnt lgkmcnt(9)
; #define LAS __attribute__((address_space(3)))
; DI void gdn_prep_phase(const int tid, LAS unsigned char* lds, const P& p, int G, int c) {
;     ...
; #pragma unroll
;           for (int kb = 0; kb < 8; ++kb) {
; #pragma unroll
;               for (int pp = 0; pp < 4; ++pp) { const int pr = 4 * kb + pp;
;                   f32x2 s = (f32x2){xs[2 * pr], xs[2 * pr + 1]};
; #pragma unroll
;                   for (int j = 8 * kb; j < 2 * pr; j += 2) { const f32x4 l = *(const LAS f32x4*)(Ls + pr * 136 + j * 2);
;                       s -= (f32x2){l[0], l[1]} * (f32x2){xs[j], xs[j]}; s -= (f32x2){l[2], l[3]} * (f32x2){xs[j + 1], xs[j + 1]}; }
;                   xs[2 * pr] = s[0];
;                   xs[2 * pr + 1] = s[1] - Ls[pr * 136 + 4 * pr + 1] * s[0]; }
; #pragma unroll
;               for (int pr = 4 * kb + 4; pr < 32; ++pr) {
;                   f32x2 s0 = (f32x2){xs[2 * pr], xs[2 * pr + 1]}, s1 = (f32x2){0.f, 0.f};
; #pragma unroll
;                   for (int q = 0; q < 4; ++q) { const int j = 8 * kb + 2 * q; const f32x4 l = *(const LAS f32x4*)(Ls + pr * 136 + j * 2);
;                       s0 -= (f32x2){l[0], l[1]} * (f32x2){xs[j], xs[j]}; s1 -= (f32x2){l[2], l[3]} * (f32x2){xs[j + 1], xs[j + 1]}; }
;                   const f32x2 s = s0 + s1; xs[2 * pr] = s[0]; xs[2 * pr + 1] = s[1]; }
;           }
;           if (isv) {
; #pragma unroll
;               for (int i8 = 0; i8 < 8; ++i8) { u32x4 w; w.x = pk2(xs[i8 * 8], xs[i8 * 8 + 1]); w.y = pk2(xs[i8 * 8 + 2], xs[i8 * 8 + 3]); w.z = pk2(xs[i8 * 8 + 4], xs[i8 * 8 + 5]); w.w = pk2(xs[i8 * 8 + 6], xs[i8 * 8 + 7]);
;                   *(u32x4*)(Uc + cid * 8192 + ch * 64 + i8 * 8) = w; }
	v_pk_fma_f32 v[216:217], v[202:203], v[112:113], v[216:217] op_sel_hi:[0,1,1] neg_lo:[1,0,0] neg_hi:[1,0,0]
	v_pk_fma_f32 v[218:219], v[198:199], v[114:115], v[218:219] op_sel_hi:[0,1,1] neg_lo:[1,0,0] neg_hi:[1,0,0]
	ds_read_b128 v[112:115], v69 offset:52128
	s_waitcnt lgkmcnt(9)
	v_pk_fma_f32 v[208:209], v[204:205], v[242:243], v[216:217] op_sel_hi:[0,1,1] neg_lo:[1,0,0] neg_hi:[1,0,0]
	v_pk_fma_f32 v[210:211], v[244:245], v[200:201], v[218:219] op_sel_hi:[1,0,1] neg_lo:[1,0,0] neg_hi:[1,0,0]
	v_add_u32_e32 v233, 0xc800, v69
	ds_read2_b32 v[242:243], v233 offset0:105 offset1:245
	v_pk_add_f32 v[216:217], v[208:209], v[210:211]
	s_waitcnt lgkmcnt(9)
	v_pk_fma_f32 v[212:213], v[190:191], v[136:137], v[212:213] op_sel_hi:[0,1,1] neg_lo:[1,0,0] neg_hi:[1,0,0]
	v_pk_fma_f32 v[218:219], v[192:193], v[138:139], 0 op_sel_hi:[0,1,0] neg_lo:[1,0,0] neg_hi:[1,0,0]
	ds_read_b128 v[136:139], v69 offset:52144
	s_waitcnt lgkmcnt(9)
	v_pk_fma_f32 v[212:213], v[196:197], v[238:239], v[212:213] op_sel_hi:[0,1,1] neg_lo:[1,0,0] neg_hi:[1,0,0]
	v_pk_fma_f32 v[218:219], v[194:195], v[240:241], v[218:219] op_sel_hi:[0,1,1] neg_lo:[1,0,0] neg_hi:[1,0,0]
	ds_read_b128 v[238:241], v69 offset:52160
	s_waitcnt lgkmcnt(9)
	v_pk_fma_f32 v[212:213], v[202:203], v[120:121], v[212:213] op_sel_hi:[0,1,1] neg_lo:[1,0,0] neg_hi:[1,0,0]
	v_pk_fma_f32 v[218:219], v[198:199], v[122:123], v[218:219] op_sel_hi:[0,1,1] neg_lo:[1,0,0] neg_hi:[1,0,0]
	s_waitcnt lgkmcnt(8)
	v_pk_fma_f32 v[208:209], v[204:205], v[128:129], v[212:213] op_sel_hi:[0,1,1] neg_lo:[1,0,0] neg_hi:[1,0,0]
	v_pk_fma_f32 v[210:211], v[200:201], v[130:131], v[218:219] op_sel_hi:[0,1,1] neg_lo:[1,0,0] neg_hi:[1,0,0]
	v_pk_add_f32 v[212:213], v[208:209], v[210:211]
	s_waitcnt lgkmcnt(7)
	v_fma_f32 v208, -v124, v206, v207
	s_waitcnt lgkmcnt(6)
	v_pk_fma_f32 v[210:211], v[246:247], v[206:207], v[214:215] op_sel_hi:[1,0,1] neg_lo:[1,0,0] neg_hi:[1,0,0]
	s_nop 0
	v_pk_fma_f32 v[214:215], v[248:249], v[208:209], v[210:211] op_sel_hi:[1,0,1] neg_lo:[1,0,0] neg_hi:[1,0,0]
	s_nop 0
	v_fma_f32 v210, -v125, v214, v215
	s_waitcnt lgkmcnt(5)
	v_pk_fma_f32 v[216:217], v[206:207], v[132:133], v[216:217] op_sel_hi:[0,1,1] neg_lo:[1,0,0] neg_hi:[1,0,0]
	v_pk_fma_f32 v[220:221], v[134:135], v[208:209], v[216:217] op_sel_hi:[1,0,1] neg_lo:[1,0,0] neg_hi:[1,0,0]
	s_waitcnt lgkmcnt(4)
	v_pk_fma_f32 v[216:217], v[116:117], v[214:215], v[220:221] op_sel_hi:[1,0,1] neg_lo:[1,0,0] neg_hi:[1,0,0]
	s_nop 0
	v_pk_fma_f32 v[218:219], v[118:119], v[210:211], v[216:217] op_sel_hi:[1,0,1] neg_lo:[1,0,0] neg_hi:[1,0,0]
	s_waitcnt lgkmcnt(3)
	v_pk_fma_f32 v[212:213], v[206:207], v[112:113], v[212:213] op_sel_hi:[0,1,1] neg_lo:[1,0,0] neg_hi:[1,0,0]
	v_pk_fma_f32 v[212:213], v[114:115], v[208:209], v[212:213] op_sel_hi:[1,0,1] neg_lo:[1,0,0] neg_hi:[1,0,0]
	s_waitcnt lgkmcnt(2)
	v_fma_f32 v216, -v242, v218, v219
	s_waitcnt lgkmcnt(1)
	v_pk_fma_f32 v[212:213], v[136:137], v[214:215], v[212:213] op_sel_hi:[1,0,1] neg_lo:[1,0,0] neg_hi:[1,0,0]
	s_nop 0
	v_pk_fma_f32 v[212:213], v[138:139], v[210:211], v[212:213] op_sel_hi:[1,0,1] neg_lo:[1,0,0] neg_hi:[1,0,0]
	s_waitcnt lgkmcnt(0)
	v_pk_fma_f32 v[212:213], v[238:239], v[218:219], v[212:213] op_sel_hi:[1,0,1] neg_lo:[1,0,0] neg_hi:[1,0,0]
	s_nop 0
	v_pk_fma_f32 v[212:213], v[240:241], v[216:217], v[212:213] op_sel_hi:[1,0,1] neg_lo:[1,0,0] neg_hi:[1,0,0]
	s_nop 0
	v_fma_f32 v1, -v243, v212, v213
	s_and_saveexec_b64 s[0:1], s[40:41]
	s_xor_b64 s[0:1], exec, s[0:1]
	s_cbranch_execz .LBB0_632
	s_mov_b32 s26, 0x5040100
	v_cvt_pk_bf16_f32 v5, v60, s0
	v_perm_b32 v159, v11, v5, s26
	v_cvt_pk_bf16_f32 v5, v56, s0
	v_perm_b32 v160, v7, v5, s26
	v_cvt_pk_bf16_f32 v5, v58, s0
	v_add_co_u32_e32 v60, vcc, 0x20600000, v64
	v_perm_b32 v161, v3, v5, s26
	s_nop 0
	v_addc_co_u32_e32 v61, vcc, 0, v65, vcc
	v_cvt_pk_bf16_f32 v57, v4, v2
	v_cvt_pk_bf16_f32 v2, v14, v16
	v_cvt_pk_bf16_f32 v3, v20, v18
	v_cvt_pk_bf16_f32 v4, v26, v22
	v_cvt_pk_bf16_f32 v5, v28, v24
	global_store_dwordx4 v[60:61], v[2:5], off offset:32
	v_perm_b32 v158, v19, v17, s26
	v_cvt_pk_bf16_f32 v56, v48, v0
	v_cvt_pk_bf16_f32 v2, v30, v32
	v_cvt_pk_bf16_f32 v3, v36, v34
	v_cvt_pk_bf16_f32 v4, v42, v38
	v_cvt_pk_bf16_f32 v5, v44, v40
	global_store_dwordx4 v[60:61], v[2:5], off offset:48
	v_cvt_pk_bf16_f32 v58, v8, v6
	v_cvt_pk_bf16_f32 v59, v12, v10
	v_cvt_pk_bf16_f32 v2, v46, v50
	v_cvt_pk_bf16_f32 v3, v54, v52
	v_cvt_pk_bf16_f32 v4, v168, v164
	v_cvt_pk_bf16_f32 v5, v170, v166
	global_store_dwordx4 v[60:61], v[2:5], off offset:64
	global_store_dwordx4 v[60:61], v[158:161], off
	global_store_dwordx4 v[60:61], v[56:59], off offset:16
	v_cvt_pk_bf16_f32 v2, v172, v174
	v_cvt_pk_bf16_f32 v3, v178, v176
	v_cvt_pk_bf16_f32 v4, v186, v180
	v_cvt_pk_bf16_f32 v5, v188, v184
	global_store_dwordx4 v[60:61], v[2:5], off offset:80
	s_nop 1
	v_cvt_pk_bf16_f32 v2, v190, v192
	v_cvt_pk_bf16_f32 v3, v196, v194
	v_cvt_pk_bf16_f32 v4, v202, v198
	v_cvt_pk_bf16_f32 v5, v204, v200
	global_store_dwordx4 v[60:61], v[2:5], off offset:96
	s_nop 1
	v_cvt_pk_bf16_f32 v2, v206, v208
	v_cvt_pk_bf16_f32 v3, v214, v210
	v_cvt_pk_bf16_f32 v4, v218, v216
	v_cvt_pk_bf16_f32 v5, v212, v1
	global_store_dwordx4 v[60:61], v[2:5], off offset:112
